# all flat_store converted to global_store (stores no longer count on lgkmcnt, so LDS waits after an epilogue do not wait for store completion)
# baseline (speedup 1.0000x reference)
; __device__ __forceinline__ float bflo(unsigned w) { return __uint_as_float(w << 16); }
; __device__ __forceinline__ float bfhi(unsigned w) { return __uint_as_float(w & 0xffff0000u); }
;     __device__ __forceinline__ void fused(f32x4 (&acc)[2][2][4][2], const Unit& u, int wr, int wc, int fr, int fq, LAS unsigned char* lds, int wid, int lane) const {
;     ...
;             const int col = u.pn * 256 + bj * 128 + wc * 32 + 8 * fq;
;             const f32x4 g0 = *(const f32x4*)(gate + boff + col), g1 = *(const f32x4*)(gate + boff + col + 4);
;             if (xin32) {
; #pragma unroll
;                 for (int ai = 0; ai < 2; ++ai)
; #pragma unroll
;                     for (int m = 0; m < 4; ++m) {
;                         const float* xp = xin32 + (unsigned)((row0 + ai * 128 + m * 16) * DM + col);
;                         const f32x4 x0 = *(const f32x4*)xp, x1 = *(const f32x4*)(xp + 4);
;                         acc[ai][bj][m][0] = x0 + g0 * acc[ai][bj][m][0]; acc[ai][bj][m][1] = x1 + g1 * acc[ai][bj][m][1];
;                         asm volatile("" : "+v"(acc[ai][bj][m][0]), "+v"(acc[ai][bj][m][1]));
;                         if (m & 1) asm volatile("" ::: "memory");
;                     }
;             } else {
; #pragma unroll
;                 for (int ai = 0; ai < 2; ++ai)
; #pragma unroll
;                     for (int m = 0; m < 4; ++m) {
;                         const u32x4 xw = *(const u32x4*)(xin16 + (unsigned)((row0 + ai * 128 + m * 16) * DM + col));
;                         const f32x4 x0 = (f32x4){bflo(xw.x), bfhi(xw.x), bflo(xw.y), bfhi(xw.y)}, x1 = (f32x4){bflo(xw.z), bfhi(xw.z), bflo(xw.w), bfhi(xw.w)};
;                         acc[ai][bj][m][0] = x0 + g0 * acc[ai][bj][m][0]; acc[ai][bj][m][1] = x1 + g1 * acc[ai][bj][m][1];
.LBB0_144:
	s_lshl_b32 s12, s22, 8
	s_add_i32 s0, s12, s35
	v_lshrrev_b32_e32 v64, 1, v236
	v_or_b32_e32 v130, s0, v144
	s_lshr_b32 s0, s22, 3
	v_and_b32_e32 v64, 24, v64
	s_mul_i32 s80, s0, 0x1800
	v_lshl_or_b32 v64, s25, 5, v64
	s_lshl_b64 s[2:3], s[80:81], 2
	v_readlane_b32 s0, v255, 48
	v_lshl_or_b32 v154, s8, 8, v64
	s_add_u32 s0, s0, s2
	v_readlane_b32 s1, v255, 49
	s_addc_u32 s1, s1, s3
	v_ashrrev_i32_e32 v155, 31, v154
	v_lshlrev_b32_e32 v141, 10, v130
	v_lshl_add_u64 v[130:131], v[154:155], 2, s[0:1]
	s_mov_b64 s[0:1], 0x5000
	v_lshl_add_u64 v[138:139], v[130:131], 0, s[0:1]
	s_movk_i32 s0, 0x5000
	v_add_co_u32_e32 v130, vcc, s0, v130
	v_add_u32_e32 v64, v141, v154
	s_nop 0
	v_addc_co_u32_e32 v131, vcc, 0, v131, vcc
	v_lshl_add_u64 v[142:143], v[64:65], 1, s[36:37]
	s_barrier
	global_load_dwordx4 v[134:137], v[130:131], off
	s_nop 0
	global_load_dwordx4 v[130:133], v[138:139], off offset:16
	v_lshlrev_b32_e32 v210, 1, v64
	global_load_dwordx4 v[164:167], v210, s[36:37]
	global_load_dwordx4 v[196:199], v210, s[36:37] offset:256
	v_add_u32_e32 v210, 0x8000, v210
	global_load_dwordx4 v[168:171], v210, s[36:37]
	global_load_dwordx4 v[200:203], v210, s[36:37] offset:256
	v_add_u32_e32 v210, 0x8000, v210
	global_load_dwordx4 v[172:175], v210, s[36:37]
	global_load_dwordx4 v[206:209], v210, s[36:37] offset:256
	v_add_u32_e32 v210, 0x8000, v210
	global_load_dwordx4 v[176:179], v210, s[36:37]
	global_load_dwordx4 v[214:217], v210, s[36:37] offset:256
	v_add_u32_e32 v210, 0x28000, v210
	global_load_dwordx4 v[180:183], v210, s[36:37]
	global_load_dwordx4 v[218:221], v210, s[36:37] offset:256
	v_add_u32_e32 v210, 0x8000, v210
	global_load_dwordx4 v[184:187], v210, s[36:37]
	global_load_dwordx4 v[222:225], v210, s[36:37] offset:256
	v_add_u32_e32 v210, 0x8000, v210
	v_mov_b32_e32 v211, v210
	global_load_dwordx4 v[188:191], v210, s[36:37]
	v_add_u32_e32 v210, 0x8000, v210
	global_load_dwordx4 v[192:195], v210, s[36:37]
	v_or_b32_e32 v159, 0x80, v154
	v_and_b32_e32 v140, 63, v236
	s_lshl_b32 s0, s25, 2
	v_cmp_gt_u32_e32 vcc, 16, v140
	s_add_i32 s4, s0, 0
	s_waitcnt vmcnt(13) lgkmcnt(0)
	v_lshlrev_b32_e32 v142, 16, v164
	v_and_b32_e32 v143, 0xffff0000, v164
	v_lshlrev_b32_e32 v146, 16, v165
	v_and_b32_e32 v147, 0xffff0000, v165
	v_lshlrev_b32_e32 v150, 16, v166
	v_and_b32_e32 v151, 0xffff0000, v166
	v_lshlrev_b32_e32 v148, 16, v167
	v_and_b32_e32 v149, 0xffff0000, v167
	global_load_dwordx4 v[164:167], v211, s[36:37] offset:256
	v_pk_fma_f32 v[32:33], v[32:33], v[134:135], v[142:143]
	v_add_u32_e32 v142, 0x4000, v64
	v_mov_b32_e32 v143, v65
	v_pk_fma_f32 v[34:35], v[34:35], v[136:137], v[146:147]
	v_pk_fma_f32 v[38:39], v[38:39], v[132:133], v[148:149]
	v_pk_fma_f32 v[36:37], v[36:37], v[130:131], v[150:151]
	v_lshl_add_u64 v[142:143], v[142:143], 1, s[36:37]
	s_waitcnt vmcnt(12) lgkmcnt(0)
	v_lshlrev_b32_e32 v142, 16, v168
	v_and_b32_e32 v143, 0xffff0000, v168
	v_lshlrev_b32_e32 v146, 16, v169
	v_and_b32_e32 v147, 0xffff0000, v169
	v_lshlrev_b32_e32 v150, 16, v170
	v_and_b32_e32 v151, 0xffff0000, v170
	v_lshlrev_b32_e32 v148, 16, v171
	v_and_b32_e32 v149, 0xffff0000, v171
	global_load_dwordx4 v[168:171], v210, s[36:37] offset:256
	v_pk_fma_f32 v[48:49], v[48:49], v[134:135], v[142:143]
	v_add_u32_e32 v142, 0x8000, v64
	v_mov_b32_e32 v143, v65
	v_pk_fma_f32 v[50:51], v[50:51], v[136:137], v[146:147]
	v_pk_fma_f32 v[54:55], v[54:55], v[132:133], v[148:149]
	v_pk_fma_f32 v[52:53], v[52:53], v[130:131], v[150:151]
	v_lshl_add_u64 v[142:143], v[142:143], 1, s[36:37]
	s_waitcnt vmcnt(11) lgkmcnt(0)
	v_lshlrev_b32_e32 v142, 16, v172
	v_and_b32_e32 v143, 0xffff0000, v172
	v_lshlrev_b32_e32 v146, 16, v173
	v_and_b32_e32 v147, 0xffff0000, v173
	v_lshlrev_b32_e32 v150, 16, v174
	v_and_b32_e32 v151, 0xffff0000, v174
	v_lshlrev_b32_e32 v148, 16, v175
	v_and_b32_e32 v149, 0xffff0000, v175
	v_pk_fma_f32 v[56:57], v[56:57], v[134:135], v[142:143]
	v_add_u32_e32 v142, 0xc000, v64
	v_mov_b32_e32 v143, v65
	v_pk_fma_f32 v[58:59], v[58:59], v[136:137], v[146:147]
	v_pk_fma_f32 v[62:63], v[62:63], v[132:133], v[148:149]
	v_pk_fma_f32 v[60:61], v[60:61], v[130:131], v[150:151]
	v_lshl_add_u64 v[142:143], v[142:143], 1, s[36:37]
	s_waitcnt vmcnt(9) lgkmcnt(0)
	v_lshlrev_b32_e32 v142, 16, v176
	v_and_b32_e32 v143, 0xffff0000, v176
	v_lshlrev_b32_e32 v146, 16, v177
	v_and_b32_e32 v147, 0xffff0000, v177
	v_lshlrev_b32_e32 v150, 16, v178
	v_and_b32_e32 v151, 0xffff0000, v178
	v_lshlrev_b32_e32 v148, 16, v179
	v_and_b32_e32 v149, 0xffff0000, v179
	v_pk_fma_f32 v[74:75], v[74:75], v[134:135], v[142:143]
	v_add_u32_e32 v142, 0x20000, v64
	v_mov_b32_e32 v143, v65
	v_pk_fma_f32 v[76:77], v[76:77], v[136:137], v[146:147]
	v_pk_fma_f32 v[80:81], v[80:81], v[132:133], v[148:149]
	v_pk_fma_f32 v[78:79], v[78:79], v[130:131], v[150:151]
	v_lshl_add_u64 v[142:143], v[142:143], 1, s[36:37]
	s_waitcnt vmcnt(7) lgkmcnt(0)
	v_lshlrev_b32_e32 v142, 16, v180
	v_and_b32_e32 v143, 0xffff0000, v180
	v_lshlrev_b32_e32 v146, 16, v181
	v_and_b32_e32 v147, 0xffff0000, v181
	v_lshlrev_b32_e32 v150, 16, v182
	v_and_b32_e32 v151, 0xffff0000, v182
	v_lshlrev_b32_e32 v148, 16, v183
	v_and_b32_e32 v149, 0xffff0000, v183
	v_pk_fma_f32 v[82:83], v[82:83], v[134:135], v[142:143]
	v_add_u32_e32 v142, 0x24000, v64
	v_mov_b32_e32 v143, v65
	v_pk_fma_f32 v[84:85], v[84:85], v[136:137], v[146:147]
	v_pk_fma_f32 v[88:89], v[88:89], v[132:133], v[148:149]
	v_pk_fma_f32 v[86:87], v[86:87], v[130:131], v[150:151]
	v_lshl_add_u64 v[142:143], v[142:143], 1, s[36:37]
	s_waitcnt vmcnt(5) lgkmcnt(0)
; __device__ __forceinline__ float bflo(unsigned w) { return __uint_as_float(w << 16); }
; __device__ __forceinline__ float bfhi(unsigned w) { return __uint_as_float(w & 0xffff0000u); }
;     __device__ __forceinline__ void fused(f32x4 (&acc)[2][2][4][2], const Unit& u, int wr, int wc, int fr, int fq, LAS unsigned char* lds, int wid, int lane) const {
;     ...
;             const int col = u.pn * 256 + bj * 128 + wc * 32 + 8 * fq;
;             const f32x4 g0 = *(const f32x4*)(gate + boff + col), g1 = *(const f32x4*)(gate + boff + col + 4);
;             if (xin32) {
; #pragma unroll
;                 for (int ai = 0; ai < 2; ++ai)
; #pragma unroll
;                     for (int m = 0; m < 4; ++m) {
;                         const float* xp = xin32 + (unsigned)((row0 + ai * 128 + m * 16) * DM + col);
;                         const f32x4 x0 = *(const f32x4*)xp, x1 = *(const f32x4*)(xp + 4);
;                         acc[ai][bj][m][0] = x0 + g0 * acc[ai][bj][m][0]; acc[ai][bj][m][1] = x1 + g1 * acc[ai][bj][m][1];
;                         asm volatile("" : "+v"(acc[ai][bj][m][0]), "+v"(acc[ai][bj][m][1]));
;                         if (m & 1) asm volatile("" ::: "memory");
;                     }
;             } else {
; #pragma unroll
;                 for (int ai = 0; ai < 2; ++ai)
; #pragma unroll
;                     for (int m = 0; m < 4; ++m) {
;                         const u32x4 xw = *(const u32x4*)(xin16 + (unsigned)((row0 + ai * 128 + m * 16) * DM + col));
;                         const f32x4 x0 = (f32x4){bflo(xw.x), bfhi(xw.x), bflo(xw.y), bfhi(xw.y)}, x1 = (f32x4){bflo(xw.z), bfhi(xw.z), bflo(xw.w), bfhi(xw.w)};
;                         acc[ai][bj][m][0] = x0 + g0 * acc[ai][bj][m][0]; acc[ai][bj][m][1] = x1 + g1 * acc[ai][bj][m][1];
;                         asm volatile("" : "+v"(acc[ai][bj][m][0]), "+v"(acc[ai][bj][m][1]));
;                     }
;             }
	v_lshlrev_b32_e32 v142, 16, v184
	v_and_b32_e32 v143, 0xffff0000, v184
	v_lshlrev_b32_e32 v146, 16, v185
	v_and_b32_e32 v147, 0xffff0000, v185
	v_lshlrev_b32_e32 v150, 16, v186
	v_and_b32_e32 v151, 0xffff0000, v186
	v_lshlrev_b32_e32 v148, 16, v187
	v_and_b32_e32 v149, 0xffff0000, v187
	v_pk_fma_f32 v[90:91], v[90:91], v[134:135], v[142:143]
	v_add_u32_e32 v142, 0x28000, v64
	v_mov_b32_e32 v143, v65
	v_pk_fma_f32 v[92:93], v[92:93], v[136:137], v[146:147]
	v_pk_fma_f32 v[96:97], v[96:97], v[132:133], v[148:149]
	v_pk_fma_f32 v[94:95], v[94:95], v[130:131], v[150:151]
	v_lshl_add_u64 v[142:143], v[142:143], 1, s[36:37]
	v_add_u32_e32 v64, 0x2c000, v64
	s_waitcnt vmcnt(3) lgkmcnt(0)
	v_lshlrev_b32_e32 v142, 16, v188
	v_and_b32_e32 v143, 0xffff0000, v188
	v_lshlrev_b32_e32 v146, 16, v189
	v_and_b32_e32 v147, 0xffff0000, v189
	v_lshlrev_b32_e32 v150, 16, v190
	v_and_b32_e32 v151, 0xffff0000, v190
	v_lshlrev_b32_e32 v148, 16, v191
	v_and_b32_e32 v149, 0xffff0000, v191
	v_pk_fma_f32 v[116:117], v[116:117], v[136:137], v[146:147]
	v_pk_fma_f32 v[114:115], v[114:115], v[134:135], v[142:143]
	v_pk_fma_f32 v[120:121], v[120:121], v[132:133], v[148:149]
	v_pk_fma_f32 v[118:119], v[118:119], v[130:131], v[150:151]
	v_lshl_add_u64 v[142:143], v[64:65], 1, s[36:37]
	v_add_u32_e32 v64, v141, v159
	s_waitcnt vmcnt(2) lgkmcnt(0)
	v_lshlrev_b32_e32 v142, 16, v192
	v_and_b32_e32 v143, 0xffff0000, v192
	v_lshlrev_b32_e32 v146, 16, v193
	v_and_b32_e32 v147, 0xffff0000, v193
	v_lshlrev_b32_e32 v150, 16, v194
	v_and_b32_e32 v151, 0xffff0000, v194
	v_lshlrev_b32_e32 v148, 16, v195
	v_and_b32_e32 v149, 0xffff0000, v195
	v_pk_fma_f32 v[124:125], v[124:125], v[136:137], v[146:147]
	v_pk_fma_f32 v[122:123], v[122:123], v[134:135], v[142:143]
	v_pk_fma_f32 v[128:129], v[128:129], v[132:133], v[148:149]
	v_pk_fma_f32 v[126:127], v[126:127], v[130:131], v[150:151]
	s_nop 0
	flat_load_dwordx4 v[134:137], v[138:139] offset:512
	flat_load_dwordx4 v[130:133], v[138:139] offset:528
	v_lshl_add_u64 v[138:139], v[64:65], 1, s[36:37]
	s_waitcnt vmcnt(0) lgkmcnt(0)
	v_lshlrev_b32_e32 v138, 16, v196
	v_and_b32_e32 v139, 0xffff0000, v196
	v_lshlrev_b32_e32 v142, 16, v197
	v_and_b32_e32 v143, 0xffff0000, v197
	v_lshlrev_b32_e32 v146, 16, v198
	v_and_b32_e32 v147, 0xffff0000, v198
	v_lshlrev_b32_e32 v148, 16, v199
	v_and_b32_e32 v149, 0xffff0000, v199
	v_pk_fma_f32 v[106:107], v[106:107], v[134:135], v[138:139]
	v_add_u32_e32 v138, 0x4000, v64
	v_mov_b32_e32 v139, v65
	v_pk_fma_f32 v[108:109], v[108:109], v[136:137], v[142:143]
	v_pk_fma_f32 v[112:113], v[112:113], v[132:133], v[148:149]
	v_pk_fma_f32 v[110:111], v[110:111], v[130:131], v[146:147]
	v_lshl_add_u64 v[138:139], v[138:139], 1, s[36:37]
	s_waitcnt vmcnt(0) lgkmcnt(0)
	v_lshlrev_b32_e32 v138, 16, v200
	v_and_b32_e32 v139, 0xffff0000, v200
	v_lshlrev_b32_e32 v142, 16, v201
	v_and_b32_e32 v143, 0xffff0000, v201
	v_lshlrev_b32_e32 v146, 16, v202
	v_and_b32_e32 v147, 0xffff0000, v202
	v_lshlrev_b32_e32 v148, 16, v203
	v_and_b32_e32 v149, 0xffff0000, v203
	v_pk_fma_f32 v[102:103], v[102:103], v[134:135], v[138:139]
	v_add_u32_e32 v138, 0x8000, v64
	v_mov_b32_e32 v139, v65
	v_pk_fma_f32 v[104:105], v[104:105], v[136:137], v[142:143]
	v_pk_fma_f32 v[100:101], v[100:101], v[132:133], v[148:149]
	v_pk_fma_f32 v[98:99], v[98:99], v[130:131], v[146:147]
	v_lshl_add_u64 v[138:139], v[138:139], 1, s[36:37]
	s_waitcnt vmcnt(0) lgkmcnt(0)
	v_lshlrev_b32_e32 v138, 16, v206
	v_and_b32_e32 v139, 0xffff0000, v206
	v_lshlrev_b32_e32 v142, 16, v207
	v_and_b32_e32 v143, 0xffff0000, v207
	v_lshlrev_b32_e32 v146, 16, v208
	v_and_b32_e32 v147, 0xffff0000, v208
	v_lshlrev_b32_e32 v148, 16, v209
	v_and_b32_e32 v149, 0xffff0000, v209
	v_pk_fma_f32 v[70:71], v[70:71], v[134:135], v[138:139]
	v_add_u32_e32 v138, 0xc000, v64
	v_mov_b32_e32 v139, v65
	v_pk_fma_f32 v[72:73], v[72:73], v[136:137], v[142:143]
	v_pk_fma_f32 v[68:69], v[68:69], v[132:133], v[148:149]
	v_pk_fma_f32 v[66:67], v[66:67], v[130:131], v[146:147]
	v_lshl_add_u64 v[138:139], v[138:139], 1, s[36:37]
	s_waitcnt vmcnt(0) lgkmcnt(0)
	v_lshlrev_b32_e32 v138, 16, v214
	v_and_b32_e32 v139, 0xffff0000, v214
	v_lshlrev_b32_e32 v142, 16, v215
	v_and_b32_e32 v143, 0xffff0000, v215
	v_lshlrev_b32_e32 v146, 16, v216
	v_and_b32_e32 v147, 0xffff0000, v216
	v_lshlrev_b32_e32 v148, 16, v217
	v_and_b32_e32 v149, 0xffff0000, v217
	v_pk_fma_f32 v[44:45], v[44:45], v[134:135], v[138:139]
	v_add_u32_e32 v138, 0x20000, v64
	v_mov_b32_e32 v139, v65
	v_pk_fma_f32 v[46:47], v[46:47], v[136:137], v[142:143]
	v_pk_fma_f32 v[42:43], v[42:43], v[132:133], v[148:149]
	v_pk_fma_f32 v[40:41], v[40:41], v[130:131], v[146:147]
	v_lshl_add_u64 v[138:139], v[138:139], 1, s[36:37]
	s_waitcnt vmcnt(0) lgkmcnt(0)
	v_lshlrev_b32_e32 v138, 16, v218
	v_and_b32_e32 v139, 0xffff0000, v218
	v_lshlrev_b32_e32 v142, 16, v219
	v_and_b32_e32 v143, 0xffff0000, v219
	v_lshlrev_b32_e32 v146, 16, v220
	v_and_b32_e32 v147, 0xffff0000, v220
	v_lshlrev_b32_e32 v148, 16, v221
	v_and_b32_e32 v149, 0xffff0000, v221
	v_pk_fma_f32 v[28:29], v[28:29], v[134:135], v[138:139]
	v_add_u32_e32 v138, 0x24000, v64
	v_mov_b32_e32 v139, v65
	v_pk_fma_f32 v[30:31], v[30:31], v[136:137], v[142:143]
	v_pk_fma_f32 v[26:27], v[26:27], v[132:133], v[148:149]
	v_pk_fma_f32 v[24:25], v[24:25], v[130:131], v[146:147]
	v_lshl_add_u64 v[138:139], v[138:139], 1, s[36:37]
	s_waitcnt vmcnt(0) lgkmcnt(0)
; template <int K> __device__ __forceinline__ float swz_xor(float v) { return __int_as_float(__builtin_amdgcn_ds_swizzle(__float_as_int(v), (K << 10) | 0x1f)); }
; __device__ __forceinline__ float xor32_sum(float v) { auto rr = __builtin_amdgcn_permlane32_swap(__float_as_uint(v), __float_as_uint(v), false, false); return __uint_as_float(rr[0]) + __uint_as_float(rr[1]); }
;     __device__ __forceinline__ void run(const f32x4 (&v)[2][2][4][2], const Unit& u, int wr, int wc, int fr, int fq, LAS unsigned char* lds, int wid, int lane) const {
;     ...
; #pragma unroll
;         for (int ai = 0; ai < 2; ++ai)
; #pragma unroll
;             for (int m = 0; m < 4; ++m) {
;                 float q = 0.f;
; #pragma unroll
;                 for (int bj = 0; bj < 2; ++bj)
; #pragma unroll
;                     for (int n = 0; n < 2; ++n) { const f32x4 x = v[ai][bj][m][n]; q += (x[0] * x[0] + x[1] * x[1]) + (x[2] * x[2] + x[3] * x[3]); }
;                 q += swz_xor<16>(q); q = xor32_sum(q);
;                 if (fq == 0) P[(ai * 128 + wr * 64 + m * 16 + fr) * 4 + wc] = q;
;             }
	v_lshlrev_b32_e32 v138, 16, v222
	v_and_b32_e32 v139, 0xffff0000, v222
	v_lshlrev_b32_e32 v142, 16, v223
	v_and_b32_e32 v143, 0xffff0000, v223
	v_lshlrev_b32_e32 v146, 16, v224
	v_and_b32_e32 v147, 0xffff0000, v224
	v_lshlrev_b32_e32 v148, 16, v225
	v_and_b32_e32 v149, 0xffff0000, v225
	v_pk_fma_f32 v[20:21], v[20:21], v[134:135], v[138:139]
	v_add_u32_e32 v138, 0x28000, v64
	v_mov_b32_e32 v139, v65
	v_pk_fma_f32 v[22:23], v[22:23], v[136:137], v[142:143]
	v_pk_fma_f32 v[18:19], v[18:19], v[132:133], v[148:149]
	v_pk_fma_f32 v[16:17], v[16:17], v[130:131], v[146:147]
	v_lshl_add_u64 v[138:139], v[138:139], 1, s[36:37]
	v_add_u32_e32 v64, 0x2c000, v64
	s_waitcnt vmcnt(0) lgkmcnt(0)
	v_lshlrev_b32_e32 v138, 16, v164
	v_and_b32_e32 v139, 0xffff0000, v164
	v_lshlrev_b32_e32 v142, 16, v165
	v_and_b32_e32 v143, 0xffff0000, v165
	v_lshlrev_b32_e32 v146, 16, v166
	v_and_b32_e32 v147, 0xffff0000, v166
	v_lshlrev_b32_e32 v148, 16, v167
	v_and_b32_e32 v149, 0xffff0000, v167
	v_pk_fma_f32 v[14:15], v[14:15], v[136:137], v[142:143]
	v_pk_fma_f32 v[12:13], v[12:13], v[134:135], v[138:139]
	v_pk_fma_f32 v[10:11], v[10:11], v[132:133], v[148:149]
	v_pk_fma_f32 v[8:9], v[8:9], v[130:131], v[146:147]
	v_lshl_add_u64 v[138:139], v[64:65], 1, s[36:37]
	v_mul_f32_e32 v64, v33, v33
	v_fmac_f32_e32 v64, v32, v32
	s_waitcnt vmcnt(0) lgkmcnt(0)
	v_lshlrev_b32_e32 v138, 16, v168
	v_and_b32_e32 v139, 0xffff0000, v168
	v_lshlrev_b32_e32 v142, 16, v169
	v_and_b32_e32 v143, 0xffff0000, v169
	v_lshlrev_b32_e32 v146, 16, v170
	v_and_b32_e32 v147, 0xffff0000, v170
	v_pk_fma_f32 v[0:1], v[0:1], v[130:131], v[146:147]
	v_mul_f32_e32 v130, v35, v35
	v_fmac_f32_e32 v130, v34, v34
	v_add_f32_e32 v64, v64, v130
	v_mul_f32_e32 v130, v37, v37
	v_mul_f32_e32 v131, v39, v39
	v_fmac_f32_e32 v130, v36, v36
	v_fmac_f32_e32 v131, v38, v38
	v_add_f32_e32 v130, v130, v131
	v_add_f32_e32 v64, v64, v130
	v_mul_f32_e32 v130, v107, v107
	v_mul_f32_e32 v131, v109, v109
	v_fmac_f32_e32 v130, v106, v106
	v_fmac_f32_e32 v131, v108, v108
	v_add_f32_e32 v130, v130, v131
	v_add_f32_e32 v64, v64, v130
	v_mul_f32_e32 v130, v111, v111
	v_mul_f32_e32 v131, v113, v113
	v_fmac_f32_e32 v130, v110, v110
	v_fmac_f32_e32 v131, v112, v112
	v_add_f32_e32 v130, v130, v131
	v_add_f32_e32 v64, v130, v64
	ds_swizzle_b32 v130, v64 offset:swizzle(SWAP,16)
	v_lshlrev_b32_e32 v148, 16, v171
	v_and_b32_e32 v149, 0xffff0000, v171
	v_pk_fma_f32 v[6:7], v[6:7], v[136:137], v[142:143]
	v_pk_fma_f32 v[4:5], v[4:5], v[134:135], v[138:139]
	v_pk_fma_f32 v[2:3], v[2:3], v[132:133], v[148:149]
	s_waitcnt lgkmcnt(0)
	v_add_f32_e32 v64, v64, v130
	v_mov_b32_e32 v130, v64
	s_nop 1
	v_permlane32_swap_b32_e32 v64, v130
	s_and_saveexec_b64 s[0:1], vcc
	s_lshl_b32 s5, s24, 10
	s_add_i32 s5, s4, s5
	v_lshl_add_u32 v131, v144, 4, s5
	v_add_f32_e32 v64, v64, v130
	ds_write_b32 v131, v64
	s_or_b64 exec, exec, s[0:1]
	v_mul_f32_e32 v64, v49, v49
	v_mul_f32_e32 v130, v51, v51
	v_fmac_f32_e32 v64, v48, v48
	v_fmac_f32_e32 v130, v50, v50
	v_add_f32_e32 v64, v64, v130
	v_mul_f32_e32 v130, v53, v53
	v_mul_f32_e32 v131, v55, v55
	v_fmac_f32_e32 v130, v52, v52
	v_fmac_f32_e32 v131, v54, v54
	v_add_f32_e32 v130, v130, v131
	v_add_f32_e32 v64, v64, v130
	v_mul_f32_e32 v130, v103, v103
	v_mul_f32_e32 v131, v105, v105
	v_fmac_f32_e32 v130, v102, v102
	v_fmac_f32_e32 v131, v104, v104
	v_add_f32_e32 v130, v130, v131
	v_add_f32_e32 v64, v64, v130
	v_mul_f32_e32 v130, v99, v99
	v_mul_f32_e32 v131, v101, v101
	v_fmac_f32_e32 v130, v98, v98
	v_fmac_f32_e32 v131, v100, v100
	v_add_f32_e32 v130, v130, v131
	v_add_f32_e32 v64, v130, v64
	ds_swizzle_b32 v130, v64 offset:swizzle(SWAP,16)
	s_waitcnt lgkmcnt(0)
	v_add_f32_e32 v64, v64, v130
	v_mov_b32_e32 v130, v64
	s_nop 1
	v_permlane32_swap_b32_e32 v64, v130
	s_and_saveexec_b64 s[0:1], vcc
	s_lshl_b32 s5, s24, 10
	s_add_i32 s5, s4, s5
	v_lshl_add_u32 v131, v144, 4, s5
	v_add_f32_e32 v64, v64, v130
	ds_write_b32 v131, v64 offset:256
	s_or_b64 exec, exec, s[0:1]
	v_mul_f32_e32 v64, v57, v57
	v_mul_f32_e32 v130, v59, v59
	v_fmac_f32_e32 v64, v56, v56
	v_fmac_f32_e32 v130, v58, v58
	v_add_f32_e32 v64, v64, v130
	v_mul_f32_e32 v130, v61, v61
	v_mul_f32_e32 v131, v63, v63
	v_fmac_f32_e32 v130, v60, v60
	v_fmac_f32_e32 v131, v62, v62
	v_add_f32_e32 v130, v130, v131
	v_add_f32_e32 v64, v64, v130
	v_mul_f32_e32 v130, v71, v71
	v_mul_f32_e32 v131, v73, v73
	v_fmac_f32_e32 v130, v70, v70
	v_fmac_f32_e32 v131, v72, v72
	v_add_f32_e32 v130, v130, v131
	v_add_f32_e32 v64, v64, v130
	v_mul_f32_e32 v130, v67, v67
	v_mul_f32_e32 v131, v69, v69
	v_fmac_f32_e32 v130, v66, v66
	v_fmac_f32_e32 v131, v68, v68
	v_add_f32_e32 v130, v130, v131
	v_add_f32_e32 v64, v130, v64
	ds_swizzle_b32 v130, v64 offset:swizzle(SWAP,16)
	s_waitcnt lgkmcnt(0)
	v_add_f32_e32 v64, v64, v130
	v_mov_b32_e32 v130, v64
	s_nop 1
	v_permlane32_swap_b32_e32 v64, v130
	s_and_saveexec_b64 s[0:1], vcc
	s_lshl_b32 s5, s24, 10
	s_add_i32 s5, s4, s5
	v_lshl_add_u32 v131, v144, 4, s5
	v_add_f32_e32 v64, v64, v130
	ds_write_b32 v131, v64 offset:512
	s_or_b64 exec, exec, s[0:1]
	v_mul_f32_e32 v64, v75, v75
	v_mul_f32_e32 v130, v77, v77
	v_fmac_f32_e32 v64, v74, v74
	v_fmac_f32_e32 v130, v76, v76
	v_add_f32_e32 v64, v64, v130
	v_mul_f32_e32 v130, v79, v79
	v_mul_f32_e32 v131, v81, v81
	v_fmac_f32_e32 v130, v78, v78
	v_fmac_f32_e32 v131, v80, v80
	v_add_f32_e32 v130, v130, v131
	v_add_f32_e32 v64, v64, v130
	v_mul_f32_e32 v130, v45, v45
	v_mul_f32_e32 v131, v47, v47
	v_fmac_f32_e32 v130, v44, v44
	v_fmac_f32_e32 v131, v46, v46
	v_add_f32_e32 v130, v130, v131
	v_add_f32_e32 v64, v64, v130
	v_mul_f32_e32 v130, v41, v41
	v_mul_f32_e32 v131, v43, v43
	v_fmac_f32_e32 v130, v40, v40
	v_fmac_f32_e32 v131, v42, v42
	v_add_f32_e32 v130, v130, v131
	v_add_f32_e32 v64, v130, v64
	ds_swizzle_b32 v130, v64 offset:swizzle(SWAP,16)
	s_waitcnt lgkmcnt(0)
; template <int K> __device__ __forceinline__ float swz_xor(float v) { return __int_as_float(__builtin_amdgcn_ds_swizzle(__float_as_int(v), (K << 10) | 0x1f)); }
; __device__ __forceinline__ float xor32_sum(float v) { auto rr = __builtin_amdgcn_permlane32_swap(__float_as_uint(v), __float_as_uint(v), false, false); return __uint_as_float(rr[0]) + __uint_as_float(rr[1]); }
;     __device__ __forceinline__ void run(const f32x4 (&v)[2][2][4][2], const Unit& u, int wr, int wc, int fr, int fq, LAS unsigned char* lds, int wid, int lane) const {
;     ...
;                 q += swz_xor<16>(q); q = xor32_sum(q);
;                 if (fq == 0) P[(ai * 128 + wr * 64 + m * 16 + fr) * 4 + wc] = q;
;             }
;         asm volatile("s_waitcnt lgkmcnt(0)" ::: "memory"); __builtin_amdgcn_s_barrier(); asm volatile("" ::: "memory");
;         const int row = wid * 32 + (lane & 31);
;         if (lane < 32) {
;             const float t = (P[row * 4 + 0] + P[row * 4 + 1]) + (P[row * 4 + 2] + P[row * 4 + 3]);
;             __hip_atomic_store(xbuf + ((size_t)(u.pm * 256 + row) * 4 + u.pn), __float_as_uint(t), __ATOMIC_RELAXED, __HIP_MEMORY_SCOPE_AGENT);
;         }
	v_add_f32_e32 v64, v64, v130
	v_mov_b32_e32 v130, v64
	s_nop 1
	v_permlane32_swap_b32_e32 v64, v130
	s_and_saveexec_b64 s[0:1], vcc
	s_lshl_b32 s5, s24, 10
	s_add_i32 s5, s4, s5
	v_lshl_add_u32 v131, v144, 4, s5
	v_add_f32_e32 v64, v64, v130
	ds_write_b32 v131, v64 offset:768
	s_or_b64 exec, exec, s[0:1]
	v_mul_f32_e32 v64, v83, v83
	v_mul_f32_e32 v130, v85, v85
	v_fmac_f32_e32 v64, v82, v82
	v_fmac_f32_e32 v130, v84, v84
	v_add_f32_e32 v64, v64, v130
	v_mul_f32_e32 v130, v87, v87
	v_mul_f32_e32 v131, v89, v89
	v_fmac_f32_e32 v130, v86, v86
	v_fmac_f32_e32 v131, v88, v88
	v_add_f32_e32 v130, v130, v131
	v_add_f32_e32 v64, v64, v130
	v_mul_f32_e32 v130, v29, v29
	v_mul_f32_e32 v131, v31, v31
	v_fmac_f32_e32 v130, v28, v28
	v_fmac_f32_e32 v131, v30, v30
	v_add_f32_e32 v130, v130, v131
	v_add_f32_e32 v64, v64, v130
	v_mul_f32_e32 v130, v25, v25
	v_mul_f32_e32 v131, v27, v27
	v_fmac_f32_e32 v130, v24, v24
	v_fmac_f32_e32 v131, v26, v26
	v_add_f32_e32 v130, v130, v131
	v_add_f32_e32 v64, v130, v64
	ds_swizzle_b32 v130, v64 offset:swizzle(SWAP,16)
	s_waitcnt lgkmcnt(0)
	v_add_f32_e32 v64, v64, v130
	v_mov_b32_e32 v130, v64
	s_nop 1
	v_permlane32_swap_b32_e32 v64, v130
	s_and_saveexec_b64 s[0:1], vcc
	s_lshl_b32 s5, s24, 10
	s_add_i32 s5, s4, s5
	v_lshl_add_u32 v131, v144, 4, s5
	v_add_f32_e32 v64, v64, v130
	ds_write_b32 v131, v64 offset:2048
	s_or_b64 exec, exec, s[0:1]
	v_mul_f32_e32 v64, v91, v91
	v_mul_f32_e32 v130, v93, v93
	v_fmac_f32_e32 v64, v90, v90
	v_fmac_f32_e32 v130, v92, v92
	v_add_f32_e32 v64, v64, v130
	v_mul_f32_e32 v130, v95, v95
	v_mul_f32_e32 v131, v97, v97
	v_fmac_f32_e32 v130, v94, v94
	v_fmac_f32_e32 v131, v96, v96
	v_add_f32_e32 v130, v130, v131
	v_add_f32_e32 v64, v64, v130
	v_mul_f32_e32 v130, v21, v21
	v_mul_f32_e32 v131, v23, v23
	v_fmac_f32_e32 v130, v20, v20
	v_fmac_f32_e32 v131, v22, v22
	v_add_f32_e32 v130, v130, v131
	v_add_f32_e32 v64, v64, v130
	v_mul_f32_e32 v130, v17, v17
	v_mul_f32_e32 v131, v19, v19
	v_fmac_f32_e32 v130, v16, v16
	v_fmac_f32_e32 v131, v18, v18
	v_add_f32_e32 v130, v130, v131
	v_add_f32_e32 v64, v130, v64
	ds_swizzle_b32 v130, v64 offset:swizzle(SWAP,16)
	s_waitcnt lgkmcnt(0)
	v_add_f32_e32 v64, v64, v130
	v_mov_b32_e32 v130, v64
	s_nop 1
	v_permlane32_swap_b32_e32 v64, v130
	s_and_saveexec_b64 s[0:1], vcc
	s_lshl_b32 s5, s24, 10
	s_add_i32 s5, s4, s5
	v_lshl_add_u32 v131, v144, 4, s5
	v_add_f32_e32 v64, v64, v130
	ds_write_b32 v131, v64 offset:2304
	s_or_b64 exec, exec, s[0:1]
	v_mul_f32_e32 v64, v115, v115
	v_mul_f32_e32 v130, v117, v117
	v_fmac_f32_e32 v64, v114, v114
	v_fmac_f32_e32 v130, v116, v116
	v_add_f32_e32 v64, v64, v130
	v_mul_f32_e32 v130, v119, v119
	v_mul_f32_e32 v131, v121, v121
	v_fmac_f32_e32 v130, v118, v118
	v_fmac_f32_e32 v131, v120, v120
	v_add_f32_e32 v130, v130, v131
	v_add_f32_e32 v64, v64, v130
	v_mul_f32_e32 v130, v13, v13
	v_mul_f32_e32 v131, v15, v15
	v_fmac_f32_e32 v130, v12, v12
	v_fmac_f32_e32 v131, v14, v14
	v_add_f32_e32 v130, v130, v131
	v_add_f32_e32 v64, v64, v130
	v_mul_f32_e32 v130, v9, v9
	v_mul_f32_e32 v131, v11, v11
	v_fmac_f32_e32 v130, v8, v8
	v_fmac_f32_e32 v131, v10, v10
	v_add_f32_e32 v130, v130, v131
	v_add_f32_e32 v64, v130, v64
	ds_swizzle_b32 v130, v64 offset:swizzle(SWAP,16)
	s_waitcnt lgkmcnt(0)
	v_add_f32_e32 v64, v64, v130
	v_mov_b32_e32 v130, v64
	s_nop 1
	v_permlane32_swap_b32_e32 v64, v130
	s_and_saveexec_b64 s[0:1], vcc
	s_lshl_b32 s5, s24, 10
	s_add_i32 s5, s4, s5
	v_lshl_add_u32 v131, v144, 4, s5
	v_add_f32_e32 v64, v64, v130
	ds_write_b32 v131, v64 offset:2560
	s_or_b64 exec, exec, s[0:1]
	v_mul_f32_e32 v64, v123, v123
	v_mul_f32_e32 v130, v125, v125
	v_fmac_f32_e32 v64, v122, v122
	v_fmac_f32_e32 v130, v124, v124
	v_add_f32_e32 v64, v64, v130
	v_mul_f32_e32 v130, v127, v127
	v_mul_f32_e32 v131, v129, v129
	v_fmac_f32_e32 v130, v126, v126
	v_fmac_f32_e32 v131, v128, v128
	v_add_f32_e32 v130, v130, v131
	v_add_f32_e32 v64, v64, v130
	v_mul_f32_e32 v130, v5, v5
	v_mul_f32_e32 v131, v7, v7
	v_fmac_f32_e32 v130, v4, v4
	v_fmac_f32_e32 v131, v6, v6
	v_add_f32_e32 v130, v130, v131
	v_add_f32_e32 v64, v64, v130
	v_mul_f32_e32 v130, v1, v1
	v_mul_f32_e32 v131, v3, v3
	v_fmac_f32_e32 v130, v0, v0
	v_fmac_f32_e32 v131, v2, v2
	v_add_f32_e32 v130, v130, v131
	v_add_f32_e32 v64, v130, v64
	ds_swizzle_b32 v130, v64 offset:swizzle(SWAP,16)
	s_waitcnt lgkmcnt(0)
	v_add_f32_e32 v64, v64, v130
	v_mov_b32_e32 v130, v64
	s_nop 1
	v_permlane32_swap_b32_e32 v64, v130
	s_and_saveexec_b64 s[0:1], vcc
	s_lshl_b32 s5, s24, 10
	s_add_i32 s4, s4, s5
	v_lshl_add_u32 v131, v144, 4, s4
	v_add_f32_e32 v64, v64, v130
	ds_write_b32 v131, v64 offset:2816
	s_or_b64 exec, exec, s[0:1]
	s_waitcnt lgkmcnt(0)
	s_barrier
	s_add_u32 s4, s82, 0x240000
	v_and_b32_e32 v64, 31, v236
	s_addc_u32 s5, s83, 0
	v_lshl_or_b32 v64, s9, 5, v64
	v_cmp_gt_u32_e64 s[0:1], 32, v140
	s_and_saveexec_b64 s[10:11], s[0:1]
	s_cbranch_execz .LBB0_162
	v_lshl_add_u32 v130, v64, 4, 0
	ds_read_b128 v[130:133], v130
	s_ashr_i32 s9, s8, 31
	s_waitcnt lgkmcnt(0)
	v_mov_b32_e32 v135, v132
	v_add_u32_e32 v132, s12, v64
	v_mov_b32_e32 v134, v131
	v_mov_b32_e32 v131, v133
	v_ashrrev_i32_e32 v133, 31, v132
	v_pk_add_f32 v[130:131], v[134:135], v[130:131]
	v_lshl_add_u64 v[132:133], v[132:133], 4, s[4:5]
	v_pk_add_f32 v[130:131], v[130:131], v[130:131] op_sel:[0,1] op_sel_hi:[1,0]
	v_lshl_add_u64 v[132:133], s[8:9], 2, v[132:133]
	global_store_dword v[132:133], v130, off sc1

; __device__ __forceinline__ unsigned pk2(float lo, float hi) { f32x2_t v = {lo, hi}; bf16x2_t b = __builtin_convertvector(v, bf16x2_t); return __builtin_bit_cast(unsigned, b); }
;     __device__ __forceinline__ void fused(f32x4 (&acc)[2][2][4][2], const Unit& u, int wr, int wc, int fr, int fq, LAS unsigned char* lds, int wid, int lane) const {
;     ...
;                     const f32x4 x0 = acc[ai][bj][m][0], x1 = acc[ai][bj][m][1];
;                     const float rs = S[r];
;                     const f32x4 y0 = x0 * rs * gv0 + sh0, y1 = x1 * rs * gv1 + sh1;
;                     if (mode == 0) {
;                         u32x4 xw; xw.x = pk2(x0[0], x0[1]); xw.y = pk2(x0[2], x0[3]); xw.z = pk2(x1[0], x1[1]); xw.w = pk2(x1[2], x1[3]);
;                         *(u32x4*)(xout16 + off) = xw;
;                         u32x4 hw; hw.x = pk2(y0[0], y0[1]); hw.y = pk2(y0[2], y0[3]); hw.z = pk2(y1[0], y1[1]); hw.w = pk2(y1[2], y1[3]);
;                         *(u32x4*)(hout + off) = hw;
.LBB0_177:
	s_andn2_b64 vcc, exec, s[0:1]
	s_cbranch_vccnz .LBB0_179
	v_cvt_pk_bf16_f32 v32, v32, v33
	v_cvt_pk_bf16_f32 v33, v34, v35
	v_cvt_pk_bf16_f32 v34, v36, v37
	v_lshlrev_b64 v[36:37], 1, v[64:65]
	v_cvt_pk_bf16_f32 v35, v38, v39
	v_lshl_add_u64 v[38:39], s[4:5], 0, v[36:37]
	global_store_dwordx4 v[38:39], v[32:35], off
	v_lshl_add_u64 v[36:37], s[86:87], 0, v[36:37]
	s_nop 0
	v_cvt_pk_bf16_f32 v32, v146, v147
	v_cvt_pk_bf16_f32 v33, v148, v149
	v_cvt_pk_bf16_f32 v34, v150, v151
	v_cvt_pk_bf16_f32 v35, v152, v153
	global_store_dwordx4 v[36:37], v[32:35], off

; __device__ __forceinline__ unsigned pk2(float lo, float hi) { f32x2_t v = {lo, hi}; bf16x2_t b = __builtin_convertvector(v, bf16x2_t); return __builtin_bit_cast(unsigned, b); }
;     __device__ __forceinline__ void fused(f32x4 (&acc)[2][2][4][2], const Unit& u, int wr, int wc, int fr, int fq, LAS unsigned char* lds, int wid, int lane) const {
;     ...
;                     const f32x4 x0 = acc[ai][bj][m][0], x1 = acc[ai][bj][m][1];
;                     const float rs = S[r];
;                     const f32x4 y0 = x0 * rs * gv0 + sh0, y1 = x1 * rs * gv1 + sh1;
;                     if (mode == 0) {
;                         u32x4 xw; xw.x = pk2(x0[0], x0[1]); xw.y = pk2(x0[2], x0[3]); xw.z = pk2(x1[0], x1[1]); xw.w = pk2(x1[2], x1[3]);
;                         *(u32x4*)(xout16 + off) = xw;
;                         u32x4 hw; hw.x = pk2(y0[0], y0[1]); hw.y = pk2(y0[2], y0[3]); hw.z = pk2(y1[0], y1[1]); hw.w = pk2(y1[2], y1[3]);
;                         *(u32x4*)(hout + off) = hw;
.LBB0_181:
	s_andn2_b64 vcc, exec, s[10:11]
	s_cbranch_vccnz .LBB0_183
	v_cvt_pk_bf16_f32 v48, v48, v49
	v_cvt_pk_bf16_f32 v49, v50, v51
	v_cvt_pk_bf16_f32 v50, v52, v53
	v_lshlrev_b64 v[52:53], 1, v[64:65]
	v_cvt_pk_bf16_f32 v51, v54, v55
	v_lshl_add_u64 v[54:55], s[4:5], 0, v[52:53]
	v_cvt_pk_bf16_f32 v32, v32, v33
	v_cvt_pk_bf16_f32 v33, v34, v35
	v_cvt_pk_bf16_f32 v34, v36, v37
	v_cvt_pk_bf16_f32 v35, v38, v39
	v_lshl_add_u64 v[36:37], s[86:87], 0, v[52:53]
	global_store_dwordx4 v[54:55], v[48:51], off
	global_store_dwordx4 v[36:37], v[32:35], off

; __device__ __forceinline__ unsigned pk2(float lo, float hi) { f32x2_t v = {lo, hi}; bf16x2_t b = __builtin_convertvector(v, bf16x2_t); return __builtin_bit_cast(unsigned, b); }
;     __device__ __forceinline__ void fused(f32x4 (&acc)[2][2][4][2], const Unit& u, int wr, int wc, int fr, int fq, LAS unsigned char* lds, int wid, int lane) const {
;     ...
;                     const f32x4 x0 = acc[ai][bj][m][0], x1 = acc[ai][bj][m][1];
;                     const float rs = S[r];
;                     const f32x4 y0 = x0 * rs * gv0 + sh0, y1 = x1 * rs * gv1 + sh1;
;                     if (mode == 0) {
;                         u32x4 xw; xw.x = pk2(x0[0], x0[1]); xw.y = pk2(x0[2], x0[3]); xw.z = pk2(x1[0], x1[1]); xw.w = pk2(x1[2], x1[3]);
;                         *(u32x4*)(xout16 + off) = xw;
;                         u32x4 hw; hw.x = pk2(y0[0], y0[1]); hw.y = pk2(y0[2], y0[3]); hw.z = pk2(y1[0], y1[1]); hw.w = pk2(y1[2], y1[3]);
;                         *(u32x4*)(hout + off) = hw;
.LBB0_185:
	s_andn2_b64 vcc, exec, s[10:11]
	s_cbranch_vccnz .LBB0_187
	v_lshlrev_b64 v[52:53], 1, v[64:65]
	v_cvt_pk_bf16_f32 v48, v56, v57
	v_cvt_pk_bf16_f32 v49, v58, v59
	v_cvt_pk_bf16_f32 v50, v60, v61
	v_cvt_pk_bf16_f32 v51, v62, v63
	v_lshl_add_u64 v[54:55], s[4:5], 0, v[52:53]
	v_cvt_pk_bf16_f32 v32, v32, v33
	v_cvt_pk_bf16_f32 v33, v34, v35
	v_cvt_pk_bf16_f32 v34, v36, v37
	v_cvt_pk_bf16_f32 v35, v38, v39
	v_lshl_add_u64 v[36:37], s[86:87], 0, v[52:53]
	global_store_dwordx4 v[54:55], v[48:51], off
	global_store_dwordx4 v[36:37], v[32:35], off

; __device__ __forceinline__ unsigned pk2(float lo, float hi) { f32x2_t v = {lo, hi}; bf16x2_t b = __builtin_convertvector(v, bf16x2_t); return __builtin_bit_cast(unsigned, b); }
;     __device__ __forceinline__ void fused(f32x4 (&acc)[2][2][4][2], const Unit& u, int wr, int wc, int fr, int fq, LAS unsigned char* lds, int wid, int lane) const {
;     ...
;                     const f32x4 x0 = acc[ai][bj][m][0], x1 = acc[ai][bj][m][1];
;                     const float rs = S[r];
;                     const f32x4 y0 = x0 * rs * gv0 + sh0, y1 = x1 * rs * gv1 + sh1;
;                     if (mode == 0) {
;                         u32x4 xw; xw.x = pk2(x0[0], x0[1]); xw.y = pk2(x0[2], x0[3]); xw.z = pk2(x1[0], x1[1]); xw.w = pk2(x1[2], x1[3]);
;                         *(u32x4*)(xout16 + off) = xw;
;                         u32x4 hw; hw.x = pk2(y0[0], y0[1]); hw.y = pk2(y0[2], y0[3]); hw.z = pk2(y1[0], y1[1]); hw.w = pk2(y1[2], y1[3]);
;                         *(u32x4*)(hout + off) = hw;
.LBB0_189:
	s_andn2_b64 vcc, exec, s[10:11]
	s_cbranch_vccnz .LBB0_191
	v_lshlrev_b64 v[52:53], 1, v[64:65]
	v_cvt_pk_bf16_f32 v48, v74, v75
	v_cvt_pk_bf16_f32 v49, v76, v77
	v_cvt_pk_bf16_f32 v50, v78, v79
	v_cvt_pk_bf16_f32 v51, v80, v81
	v_lshl_add_u64 v[54:55], s[4:5], 0, v[52:53]
	v_cvt_pk_bf16_f32 v32, v32, v33
	v_cvt_pk_bf16_f32 v33, v34, v35
	v_cvt_pk_bf16_f32 v34, v36, v37
	v_cvt_pk_bf16_f32 v35, v38, v39
	v_lshl_add_u64 v[36:37], s[86:87], 0, v[52:53]
	global_store_dwordx4 v[54:55], v[48:51], off
	global_store_dwordx4 v[36:37], v[32:35], off

; __device__ __forceinline__ unsigned pk2(float lo, float hi) { f32x2_t v = {lo, hi}; bf16x2_t b = __builtin_convertvector(v, bf16x2_t); return __builtin_bit_cast(unsigned, b); }
;     __device__ __forceinline__ void fused(f32x4 (&acc)[2][2][4][2], const Unit& u, int wr, int wc, int fr, int fq, LAS unsigned char* lds, int wid, int lane) const {
;     ...
;                     const f32x4 x0 = acc[ai][bj][m][0], x1 = acc[ai][bj][m][1];
;                     const float rs = S[r];
;                     const f32x4 y0 = x0 * rs * gv0 + sh0, y1 = x1 * rs * gv1 + sh1;
;                     if (mode == 0) {
;                         u32x4 xw; xw.x = pk2(x0[0], x0[1]); xw.y = pk2(x0[2], x0[3]); xw.z = pk2(x1[0], x1[1]); xw.w = pk2(x1[2], x1[3]);
;                         *(u32x4*)(xout16 + off) = xw;
;                         u32x4 hw; hw.x = pk2(y0[0], y0[1]); hw.y = pk2(y0[2], y0[3]); hw.z = pk2(y1[0], y1[1]); hw.w = pk2(y1[2], y1[3]);
;                         *(u32x4*)(hout + off) = hw;
.LBB0_193:
	s_andn2_b64 vcc, exec, s[10:11]
	s_cbranch_vccnz .LBB0_195
	v_lshlrev_b64 v[52:53], 1, v[64:65]
	v_cvt_pk_bf16_f32 v48, v82, v83
	v_cvt_pk_bf16_f32 v49, v84, v85
	v_cvt_pk_bf16_f32 v50, v86, v87
	v_cvt_pk_bf16_f32 v51, v88, v89
	v_lshl_add_u64 v[54:55], s[4:5], 0, v[52:53]
	v_cvt_pk_bf16_f32 v32, v32, v33
	v_cvt_pk_bf16_f32 v33, v34, v35
	v_cvt_pk_bf16_f32 v34, v36, v37
	v_cvt_pk_bf16_f32 v35, v38, v39
	v_lshl_add_u64 v[36:37], s[86:87], 0, v[52:53]
	global_store_dwordx4 v[54:55], v[48:51], off
	global_store_dwordx4 v[36:37], v[32:35], off

; __device__ __forceinline__ unsigned pk2(float lo, float hi) { f32x2_t v = {lo, hi}; bf16x2_t b = __builtin_convertvector(v, bf16x2_t); return __builtin_bit_cast(unsigned, b); }
;     __device__ __forceinline__ void fused(f32x4 (&acc)[2][2][4][2], const Unit& u, int wr, int wc, int fr, int fq, LAS unsigned char* lds, int wid, int lane) const {
;     ...
;                     const f32x4 x0 = acc[ai][bj][m][0], x1 = acc[ai][bj][m][1];
;                     const float rs = S[r];
;                     const f32x4 y0 = x0 * rs * gv0 + sh0, y1 = x1 * rs * gv1 + sh1;
;                     if (mode == 0) {
;                         u32x4 xw; xw.x = pk2(x0[0], x0[1]); xw.y = pk2(x0[2], x0[3]); xw.z = pk2(x1[0], x1[1]); xw.w = pk2(x1[2], x1[3]);
;                         *(u32x4*)(xout16 + off) = xw;
;                         u32x4 hw; hw.x = pk2(y0[0], y0[1]); hw.y = pk2(y0[2], y0[3]); hw.z = pk2(y1[0], y1[1]); hw.w = pk2(y1[2], y1[3]);
;                         *(u32x4*)(hout + off) = hw;
.LBB0_197:
	s_andn2_b64 vcc, exec, s[10:11]
	s_cbranch_vccnz .LBB0_199
	v_lshlrev_b64 v[52:53], 1, v[64:65]
	v_cvt_pk_bf16_f32 v48, v90, v91
	v_cvt_pk_bf16_f32 v49, v92, v93
	v_cvt_pk_bf16_f32 v50, v94, v95
	v_cvt_pk_bf16_f32 v51, v96, v97
	v_lshl_add_u64 v[54:55], s[4:5], 0, v[52:53]
	v_cvt_pk_bf16_f32 v32, v32, v33
	v_cvt_pk_bf16_f32 v33, v34, v35
	v_cvt_pk_bf16_f32 v34, v36, v37
	v_cvt_pk_bf16_f32 v35, v38, v39
	v_lshl_add_u64 v[36:37], s[86:87], 0, v[52:53]
	global_store_dwordx4 v[54:55], v[48:51], off
	global_store_dwordx4 v[36:37], v[32:35], off

; __device__ __forceinline__ unsigned pk2(float lo, float hi) { f32x2_t v = {lo, hi}; bf16x2_t b = __builtin_convertvector(v, bf16x2_t); return __builtin_bit_cast(unsigned, b); }
;     __device__ __forceinline__ void fused(f32x4 (&acc)[2][2][4][2], const Unit& u, int wr, int wc, int fr, int fq, LAS unsigned char* lds, int wid, int lane) const {
;     ...
;                     const f32x4 x0 = acc[ai][bj][m][0], x1 = acc[ai][bj][m][1];
;                     const float rs = S[r];
;                     const f32x4 y0 = x0 * rs * gv0 + sh0, y1 = x1 * rs * gv1 + sh1;
;                     if (mode == 0) {
;                         u32x4 xw; xw.x = pk2(x0[0], x0[1]); xw.y = pk2(x0[2], x0[3]); xw.z = pk2(x1[0], x1[1]); xw.w = pk2(x1[2], x1[3]);
;                         *(u32x4*)(xout16 + off) = xw;
;                         u32x4 hw; hw.x = pk2(y0[0], y0[1]); hw.y = pk2(y0[2], y0[3]); hw.z = pk2(y1[0], y1[1]); hw.w = pk2(y1[2], y1[3]);
;                         *(u32x4*)(hout + off) = hw;
.LBB0_201:
	s_andn2_b64 vcc, exec, s[10:11]
	s_cbranch_vccnz .LBB0_203
	v_lshlrev_b64 v[52:53], 1, v[64:65]
	v_cvt_pk_bf16_f32 v48, v114, v115
	v_cvt_pk_bf16_f32 v49, v116, v117
	v_cvt_pk_bf16_f32 v50, v118, v119
	v_cvt_pk_bf16_f32 v51, v120, v121
	v_lshl_add_u64 v[54:55], s[4:5], 0, v[52:53]
	v_cvt_pk_bf16_f32 v32, v32, v33
	v_cvt_pk_bf16_f32 v33, v34, v35
	v_cvt_pk_bf16_f32 v34, v36, v37
	v_cvt_pk_bf16_f32 v35, v38, v39
	v_lshl_add_u64 v[36:37], s[86:87], 0, v[52:53]
	global_store_dwordx4 v[54:55], v[48:51], off
	global_store_dwordx4 v[36:37], v[32:35], off

; __device__ __forceinline__ unsigned pk2(float lo, float hi) { f32x2_t v = {lo, hi}; bf16x2_t b = __builtin_convertvector(v, bf16x2_t); return __builtin_bit_cast(unsigned, b); }
;     __device__ __forceinline__ void fused(f32x4 (&acc)[2][2][4][2], const Unit& u, int wr, int wc, int fr, int fq, LAS unsigned char* lds, int wid, int lane) const {
;     ...
;                     const f32x4 x0 = acc[ai][bj][m][0], x1 = acc[ai][bj][m][1];
;                     const float rs = S[r];
;                     const f32x4 y0 = x0 * rs * gv0 + sh0, y1 = x1 * rs * gv1 + sh1;
;                     if (mode == 0) {
;                         u32x4 xw; xw.x = pk2(x0[0], x0[1]); xw.y = pk2(x0[2], x0[3]); xw.z = pk2(x1[0], x1[1]); xw.w = pk2(x1[2], x1[3]);
;                         *(u32x4*)(xout16 + off) = xw;
;                         u32x4 hw; hw.x = pk2(y0[0], y0[1]); hw.y = pk2(y0[2], y0[3]); hw.z = pk2(y1[0], y1[1]); hw.w = pk2(y1[2], y1[3]);
;                         *(u32x4*)(hout + off) = hw;
.LBB0_205:
	s_andn2_b64 vcc, exec, s[10:11]
	s_cbranch_vccnz .LBB0_207
	v_lshlrev_b64 v[52:53], 1, v[64:65]
	v_cvt_pk_bf16_f32 v48, v122, v123
	v_cvt_pk_bf16_f32 v49, v124, v125
	v_cvt_pk_bf16_f32 v50, v126, v127
	v_cvt_pk_bf16_f32 v51, v128, v129
	v_lshl_add_u64 v[54:55], s[4:5], 0, v[52:53]
	v_cvt_pk_bf16_f32 v32, v32, v33
	v_cvt_pk_bf16_f32 v33, v34, v35
	v_cvt_pk_bf16_f32 v34, v36, v37
	v_cvt_pk_bf16_f32 v35, v38, v39
	v_lshl_add_u64 v[36:37], s[86:87], 0, v[52:53]
	global_store_dwordx4 v[54:55], v[48:51], off
	global_store_dwordx4 v[36:37], v[32:35], off

; __device__ __forceinline__ unsigned pk2(float lo, float hi) { f32x2_t v = {lo, hi}; bf16x2_t b = __builtin_convertvector(v, bf16x2_t); return __builtin_bit_cast(unsigned, b); }
;     __device__ __forceinline__ void fused(f32x4 (&acc)[2][2][4][2], const Unit& u, int wr, int wc, int fr, int fq, LAS unsigned char* lds, int wid, int lane) const {
;     ...
;                     const f32x4 x0 = acc[ai][bj][m][0], x1 = acc[ai][bj][m][1];
;                     const float rs = S[r];
;                     const f32x4 y0 = x0 * rs * gv0 + sh0, y1 = x1 * rs * gv1 + sh1;
;                     if (mode == 0) {
;                         u32x4 xw; xw.x = pk2(x0[0], x0[1]); xw.y = pk2(x0[2], x0[3]); xw.z = pk2(x1[0], x1[1]); xw.w = pk2(x1[2], x1[3]);
;                         *(u32x4*)(xout16 + off) = xw;
;                         u32x4 hw; hw.x = pk2(y0[0], y0[1]); hw.y = pk2(y0[2], y0[3]); hw.z = pk2(y1[0], y1[1]); hw.w = pk2(y1[2], y1[3]);
;                         *(u32x4*)(hout + off) = hw;
.LBB0_212:
	s_andn2_b64 vcc, exec, s[2:3]
	s_cbranch_vccnz .LBB0_214
	v_lshlrev_b64 v[82:83], 1, v[64:65]
	v_cvt_pk_bf16_f32 v78, v106, v107
	v_cvt_pk_bf16_f32 v79, v108, v109
	v_cvt_pk_bf16_f32 v80, v110, v111
	v_cvt_pk_bf16_f32 v81, v112, v113
	v_lshl_add_u64 v[84:85], s[4:5], 0, v[82:83]
	v_cvt_pk_bf16_f32 v56, v56, v57
	v_cvt_pk_bf16_f32 v57, v58, v59
	v_cvt_pk_bf16_f32 v58, v60, v61
	v_cvt_pk_bf16_f32 v59, v62, v63
	v_lshl_add_u64 v[60:61], s[86:87], 0, v[82:83]
	global_store_dwordx4 v[84:85], v[78:81], off
	global_store_dwordx4 v[60:61], v[56:59], off

; __device__ __forceinline__ unsigned pk2(float lo, float hi) { f32x2_t v = {lo, hi}; bf16x2_t b = __builtin_convertvector(v, bf16x2_t); return __builtin_bit_cast(unsigned, b); }
;     __device__ __forceinline__ void fused(f32x4 (&acc)[2][2][4][2], const Unit& u, int wr, int wc, int fr, int fq, LAS unsigned char* lds, int wid, int lane) const {
;     ...
;                     const f32x4 x0 = acc[ai][bj][m][0], x1 = acc[ai][bj][m][1];
;                     const float rs = S[r];
;                     const f32x4 y0 = x0 * rs * gv0 + sh0, y1 = x1 * rs * gv1 + sh1;
;                     if (mode == 0) {
;                         u32x4 xw; xw.x = pk2(x0[0], x0[1]); xw.y = pk2(x0[2], x0[3]); xw.z = pk2(x1[0], x1[1]); xw.w = pk2(x1[2], x1[3]);
;                         *(u32x4*)(xout16 + off) = xw;
;                         u32x4 hw; hw.x = pk2(y0[0], y0[1]); hw.y = pk2(y0[2], y0[3]); hw.z = pk2(y1[0], y1[1]); hw.w = pk2(y1[2], y1[3]);
;                         *(u32x4*)(hout + off) = hw;
.LBB0_216:
	s_andn2_b64 vcc, exec, s[2:3]
	s_cbranch_vccnz .LBB0_218
	v_lshlrev_b64 v[82:83], 1, v[64:65]
	v_cvt_pk_bf16_f32 v78, v102, v103
	v_cvt_pk_bf16_f32 v79, v104, v105
	v_cvt_pk_bf16_f32 v80, v98, v99
	v_cvt_pk_bf16_f32 v81, v100, v101
	v_lshl_add_u64 v[84:85], s[4:5], 0, v[82:83]
	v_cvt_pk_bf16_f32 v56, v56, v57
	v_cvt_pk_bf16_f32 v57, v58, v59
	v_cvt_pk_bf16_f32 v58, v60, v61
	v_cvt_pk_bf16_f32 v59, v62, v63
	v_lshl_add_u64 v[60:61], s[86:87], 0, v[82:83]
	global_store_dwordx4 v[84:85], v[78:81], off
	global_store_dwordx4 v[60:61], v[56:59], off

; __device__ __forceinline__ unsigned pk2(float lo, float hi) { f32x2_t v = {lo, hi}; bf16x2_t b = __builtin_convertvector(v, bf16x2_t); return __builtin_bit_cast(unsigned, b); }
;     __device__ __forceinline__ void fused(f32x4 (&acc)[2][2][4][2], const Unit& u, int wr, int wc, int fr, int fq, LAS unsigned char* lds, int wid, int lane) const {
;     ...
;                     const f32x4 x0 = acc[ai][bj][m][0], x1 = acc[ai][bj][m][1];
;                     const float rs = S[r];
;                     const f32x4 y0 = x0 * rs * gv0 + sh0, y1 = x1 * rs * gv1 + sh1;
;                     if (mode == 0) {
;                         u32x4 xw; xw.x = pk2(x0[0], x0[1]); xw.y = pk2(x0[2], x0[3]); xw.z = pk2(x1[0], x1[1]); xw.w = pk2(x1[2], x1[3]);
;                         *(u32x4*)(xout16 + off) = xw;
;                         u32x4 hw; hw.x = pk2(y0[0], y0[1]); hw.y = pk2(y0[2], y0[3]); hw.z = pk2(y1[0], y1[1]); hw.w = pk2(y1[2], y1[3]);
;                         *(u32x4*)(hout + off) = hw;
.LBB0_220:
	s_andn2_b64 vcc, exec, s[2:3]
	s_cbranch_vccnz .LBB0_222
	v_cvt_pk_bf16_f32 v70, v70, v71
	v_cvt_pk_bf16_f32 v71, v72, v73
	v_cvt_pk_bf16_f32 v72, v66, v67
	v_lshlrev_b64 v[66:67], 1, v[64:65]
	v_cvt_pk_bf16_f32 v73, v68, v69
	v_lshl_add_u64 v[68:69], s[4:5], 0, v[66:67]
	v_cvt_pk_bf16_f32 v56, v56, v57
	v_cvt_pk_bf16_f32 v57, v58, v59
	v_cvt_pk_bf16_f32 v58, v60, v61
	v_cvt_pk_bf16_f32 v59, v62, v63
	v_lshl_add_u64 v[60:61], s[86:87], 0, v[66:67]
	global_store_dwordx4 v[68:69], v[70:73], off
	global_store_dwordx4 v[60:61], v[56:59], off

; __device__ __forceinline__ unsigned pk2(float lo, float hi) { f32x2_t v = {lo, hi}; bf16x2_t b = __builtin_convertvector(v, bf16x2_t); return __builtin_bit_cast(unsigned, b); }
;     __device__ __forceinline__ void fused(f32x4 (&acc)[2][2][4][2], const Unit& u, int wr, int wc, int fr, int fq, LAS unsigned char* lds, int wid, int lane) const {
;     ...
;                     const f32x4 x0 = acc[ai][bj][m][0], x1 = acc[ai][bj][m][1];
;                     const float rs = S[r];
;                     const f32x4 y0 = x0 * rs * gv0 + sh0, y1 = x1 * rs * gv1 + sh1;
;                     if (mode == 0) {
;                         u32x4 xw; xw.x = pk2(x0[0], x0[1]); xw.y = pk2(x0[2], x0[3]); xw.z = pk2(x1[0], x1[1]); xw.w = pk2(x1[2], x1[3]);
;                         *(u32x4*)(xout16 + off) = xw;
;                         u32x4 hw; hw.x = pk2(y0[0], y0[1]); hw.y = pk2(y0[2], y0[3]); hw.z = pk2(y1[0], y1[1]); hw.w = pk2(y1[2], y1[3]);
;                         *(u32x4*)(hout + off) = hw;
.LBB0_224:
	s_andn2_b64 vcc, exec, s[2:3]
	s_cbranch_vccnz .LBB0_226
	v_lshlrev_b64 v[66:67], 1, v[64:65]
	v_cvt_pk_bf16_f32 v44, v44, v45
	v_cvt_pk_bf16_f32 v45, v46, v47
	v_cvt_pk_bf16_f32 v46, v40, v41
	v_cvt_pk_bf16_f32 v47, v42, v43
	v_lshl_add_u64 v[40:41], s[4:5], 0, v[66:67]
	global_store_dwordx4 v[40:41], v[44:47], off
	v_cvt_pk_bf16_f32 v40, v56, v57
	v_cvt_pk_bf16_f32 v41, v58, v59
	v_cvt_pk_bf16_f32 v42, v60, v61
	v_cvt_pk_bf16_f32 v43, v62, v63
	v_lshl_add_u64 v[44:45], s[86:87], 0, v[66:67]
	global_store_dwordx4 v[44:45], v[40:43], off

; __device__ __forceinline__ unsigned pk2(float lo, float hi) { f32x2_t v = {lo, hi}; bf16x2_t b = __builtin_convertvector(v, bf16x2_t); return __builtin_bit_cast(unsigned, b); }
;     __device__ __forceinline__ void fused(f32x4 (&acc)[2][2][4][2], const Unit& u, int wr, int wc, int fr, int fq, LAS unsigned char* lds, int wid, int lane) const {
;     ...
;                     const f32x4 x0 = acc[ai][bj][m][0], x1 = acc[ai][bj][m][1];
;                     const float rs = S[r];
;                     const f32x4 y0 = x0 * rs * gv0 + sh0, y1 = x1 * rs * gv1 + sh1;
;                     if (mode == 0) {
;                         u32x4 xw; xw.x = pk2(x0[0], x0[1]); xw.y = pk2(x0[2], x0[3]); xw.z = pk2(x1[0], x1[1]); xw.w = pk2(x1[2], x1[3]);
;                         *(u32x4*)(xout16 + off) = xw;
;                         u32x4 hw; hw.x = pk2(y0[0], y0[1]); hw.y = pk2(y0[2], y0[3]); hw.z = pk2(y1[0], y1[1]); hw.w = pk2(y1[2], y1[3]);
;                         *(u32x4*)(hout + off) = hw;
.LBB0_228:
	s_andn2_b64 vcc, exec, s[2:3]
	s_cbranch_vccnz .LBB0_230
	v_lshlrev_b64 v[56:57], 1, v[64:65]
	v_cvt_pk_bf16_f32 v28, v28, v29
	v_cvt_pk_bf16_f32 v29, v30, v31
	v_cvt_pk_bf16_f32 v30, v24, v25
	v_cvt_pk_bf16_f32 v31, v26, v27
	v_lshl_add_u64 v[24:25], s[4:5], 0, v[56:57]
	global_store_dwordx4 v[24:25], v[28:31], off
	v_cvt_pk_bf16_f32 v24, v40, v41
	v_cvt_pk_bf16_f32 v25, v42, v43
	v_cvt_pk_bf16_f32 v26, v44, v45
	v_cvt_pk_bf16_f32 v27, v46, v47
	v_lshl_add_u64 v[28:29], s[86:87], 0, v[56:57]
	global_store_dwordx4 v[28:29], v[24:27], off

; __device__ __forceinline__ unsigned pk2(float lo, float hi) { f32x2_t v = {lo, hi}; bf16x2_t b = __builtin_convertvector(v, bf16x2_t); return __builtin_bit_cast(unsigned, b); }
;     __device__ __forceinline__ void fused(f32x4 (&acc)[2][2][4][2], const Unit& u, int wr, int wc, int fr, int fq, LAS unsigned char* lds, int wid, int lane) const {
;     ...
;                     const f32x4 x0 = acc[ai][bj][m][0], x1 = acc[ai][bj][m][1];
;                     const float rs = S[r];
;                     const f32x4 y0 = x0 * rs * gv0 + sh0, y1 = x1 * rs * gv1 + sh1;
;                     if (mode == 0) {
;                         u32x4 xw; xw.x = pk2(x0[0], x0[1]); xw.y = pk2(x0[2], x0[3]); xw.z = pk2(x1[0], x1[1]); xw.w = pk2(x1[2], x1[3]);
;                         *(u32x4*)(xout16 + off) = xw;
;                         u32x4 hw; hw.x = pk2(y0[0], y0[1]); hw.y = pk2(y0[2], y0[3]); hw.z = pk2(y1[0], y1[1]); hw.w = pk2(y1[2], y1[3]);
;                         *(u32x4*)(hout + off) = hw;
.LBB0_232:
	s_andn2_b64 vcc, exec, s[2:3]
	s_cbranch_vccnz .LBB0_234
	v_lshlrev_b64 v[40:41], 1, v[64:65]
	v_cvt_pk_bf16_f32 v20, v20, v21
	v_cvt_pk_bf16_f32 v21, v22, v23
	v_cvt_pk_bf16_f32 v22, v16, v17
	v_cvt_pk_bf16_f32 v23, v18, v19
	v_lshl_add_u64 v[16:17], s[4:5], 0, v[40:41]
	global_store_dwordx4 v[16:17], v[20:23], off
	v_cvt_pk_bf16_f32 v16, v24, v25
	v_cvt_pk_bf16_f32 v17, v26, v27
	v_cvt_pk_bf16_f32 v18, v28, v29
	v_cvt_pk_bf16_f32 v19, v30, v31
	v_lshl_add_u64 v[20:21], s[86:87], 0, v[40:41]
	global_store_dwordx4 v[20:21], v[16:19], off

; __device__ __forceinline__ unsigned pk2(float lo, float hi) { f32x2_t v = {lo, hi}; bf16x2_t b = __builtin_convertvector(v, bf16x2_t); return __builtin_bit_cast(unsigned, b); }
;     __device__ __forceinline__ void fused(f32x4 (&acc)[2][2][4][2], const Unit& u, int wr, int wc, int fr, int fq, LAS unsigned char* lds, int wid, int lane) const {
;     ...
;                     const f32x4 x0 = acc[ai][bj][m][0], x1 = acc[ai][bj][m][1];
;                     const float rs = S[r];
;                     const f32x4 y0 = x0 * rs * gv0 + sh0, y1 = x1 * rs * gv1 + sh1;
;                     if (mode == 0) {
;                         u32x4 xw; xw.x = pk2(x0[0], x0[1]); xw.y = pk2(x0[2], x0[3]); xw.z = pk2(x1[0], x1[1]); xw.w = pk2(x1[2], x1[3]);
;                         *(u32x4*)(xout16 + off) = xw;
;                         u32x4 hw; hw.x = pk2(y0[0], y0[1]); hw.y = pk2(y0[2], y0[3]); hw.z = pk2(y1[0], y1[1]); hw.w = pk2(y1[2], y1[3]);
;                         *(u32x4*)(hout + off) = hw;
.LBB0_236:
	s_andn2_b64 vcc, exec, s[2:3]
	s_cbranch_vccnz .LBB0_238
	v_lshlrev_b64 v[24:25], 1, v[64:65]
	v_cvt_pk_bf16_f32 v12, v12, v13
	v_cvt_pk_bf16_f32 v13, v14, v15
	v_cvt_pk_bf16_f32 v14, v8, v9
	v_cvt_pk_bf16_f32 v15, v10, v11
	v_lshl_add_u64 v[8:9], s[4:5], 0, v[24:25]
	global_store_dwordx4 v[8:9], v[12:15], off
	v_cvt_pk_bf16_f32 v8, v16, v17
	v_cvt_pk_bf16_f32 v9, v18, v19
	v_cvt_pk_bf16_f32 v10, v20, v21
	v_cvt_pk_bf16_f32 v11, v22, v23
	v_lshl_add_u64 v[12:13], s[86:87], 0, v[24:25]
	global_store_dwordx4 v[12:13], v[8:11], off

; __device__ __forceinline__ unsigned pk2(float lo, float hi) { f32x2_t v = {lo, hi}; bf16x2_t b = __builtin_convertvector(v, bf16x2_t); return __builtin_bit_cast(unsigned, b); }
;     __device__ __forceinline__ void fused(f32x4 (&acc)[2][2][4][2], const Unit& u, int wr, int wc, int fr, int fq, LAS unsigned char* lds, int wid, int lane) const {
;     ...
;                     const f32x4 x0 = acc[ai][bj][m][0], x1 = acc[ai][bj][m][1];
;                     const float rs = S[r];
;                     const f32x4 y0 = x0 * rs * gv0 + sh0, y1 = x1 * rs * gv1 + sh1;
;                     if (mode == 0) {
;                         u32x4 xw; xw.x = pk2(x0[0], x0[1]); xw.y = pk2(x0[2], x0[3]); xw.z = pk2(x1[0], x1[1]); xw.w = pk2(x1[2], x1[3]);
;                         *(u32x4*)(xout16 + off) = xw;
;                         u32x4 hw; hw.x = pk2(y0[0], y0[1]); hw.y = pk2(y0[2], y0[3]); hw.z = pk2(y1[0], y1[1]); hw.w = pk2(y1[2], y1[3]);
;                         *(u32x4*)(hout + off) = hw;
.LBB0_240:
	s_andn2_b64 vcc, exec, s[0:1]
	s_cbranch_vccnz .LBB0_242
	v_lshlrev_b64 v[16:17], 1, v[64:65]
	v_cvt_pk_bf16_f32 v4, v4, v5
	v_cvt_pk_bf16_f32 v5, v6, v7
	v_cvt_pk_bf16_f32 v6, v0, v1
	v_cvt_pk_bf16_f32 v7, v2, v3
	v_lshl_add_u64 v[0:1], s[4:5], 0, v[16:17]
	global_store_dwordx4 v[0:1], v[4:7], off
	v_cvt_pk_bf16_f32 v0, v8, v9
	v_cvt_pk_bf16_f32 v1, v10, v11
	v_cvt_pk_bf16_f32 v2, v12, v13
	v_cvt_pk_bf16_f32 v3, v14, v15
	v_lshl_add_u64 v[4:5], s[86:87], 0, v[16:17]
	global_store_dwordx4 v[4:5], v[0:3], off

; __device__ __forceinline__ unsigned pk2(float lo, float hi) { f32x2_t v = {lo, hi}; bf16x2_t b = __builtin_convertvector(v, bf16x2_t); return __builtin_bit_cast(unsigned, b); }
; __device__ __forceinline__ float sigmoidf_(float x) { return __builtin_amdgcn_rcpf(1.0f + __expf(-x)); }
;     __device__ __forceinline__ void operator()(const f32x4 (&acc)[2][2][4][2], const Unit& u, int wr, int wc, int fr, int fq) const {
;     ...
;                 const int row = row0 + ai * 128 + m * 16;
;                 float o[8];
; #pragma unroll
;                 for (int n = 0; n < 2; ++n)
; #pragma unroll
;                     for (int j = 0; j < 4; ++j) { const float gt = acc[ai][0][m][n][j], up = acc[ai][1][m][n][j]; o[4 * n + j] = gt * sigmoidf_(gt) * up; }
;                 u32x4 w; w.x = pk2(o[0], o[1]); w.y = pk2(o[2], o[3]); w.z = pk2(o[4], o[5]); w.w = pk2(o[6], o[7]);
;                 __builtin_nontemporal_store(w, (u32x4*)(act + (unsigned)(row * DFF + col)));
.LBB0_257:
	v_mul_f32_e32 v64, 0xbfb8aa3b, v126
	v_mul_f32_e32 v146, 0xbfb8aa3b, v127
	v_exp_f32_e32 v64, v64
	v_exp_f32_e32 v146, v146
	v_lshl_add_u32 v148, s35, 8, v142
	s_movk_i32 s9, 0xb00
	v_add_f32_e32 v64, 1.0, v64
	v_add_f32_e32 v147, 1.0, v146
	v_rcp_f32_e32 v146, v64
	v_rcp_f32_e32 v147, v147
	v_lshl_or_b32 v64, s34, 7, v144
	s_andn2_b64 vcc, exec, s[0:1]
	s_mov_b64 s[0:1], -1
	v_pk_mul_f32 v[126:127], v[126:127], v[146:147]
	v_mul_f32_e32 v146, 0xbfb8aa3b, v128
	v_mul_f32_e32 v147, 0xbfb8aa3b, v129
	v_exp_f32_e32 v146, v146
	v_exp_f32_e32 v147, v147
	v_pk_mul_f32 v[118:119], v[126:127], v[118:119]
	v_add_f32_e32 v126, 1.0, v146
	v_add_f32_e32 v127, 1.0, v147
	v_mul_f32_e32 v146, 0xbfb8aa3b, v122
	v_mul_f32_e32 v147, 0xbfb8aa3b, v123
	v_rcp_f32_e32 v126, v126
	v_rcp_f32_e32 v127, v127
	v_exp_f32_e32 v146, v146
	v_exp_f32_e32 v147, v147
	v_pk_mul_f32 v[126:127], v[128:129], v[126:127]
	v_add_f32_e32 v128, 1.0, v146
	v_add_f32_e32 v129, 1.0, v147
	v_mul_f32_e32 v146, 0xbfb8aa3b, v124
	v_mul_f32_e32 v147, 0xbfb8aa3b, v125
	v_exp_f32_e32 v146, v146
	v_exp_f32_e32 v147, v147
	v_rcp_f32_e32 v128, v128
	v_rcp_f32_e32 v129, v129
	v_add_f32_e32 v146, 1.0, v146
	v_add_f32_e32 v147, 1.0, v147
	v_rcp_f32_e32 v146, v146
	v_rcp_f32_e32 v147, v147
	v_pk_mul_f32 v[122:123], v[122:123], v[128:129]
	v_pk_mul_f32 v[120:121], v[126:127], v[120:121]
	v_pk_mul_f32 v[114:115], v[122:123], v[114:115]
	v_pk_mul_f32 v[122:123], v[124:125], v[146:147]
	s_nop 0
	v_pk_mul_f32 v[122:123], v[122:123], v[116:117]
	v_cvt_pk_bf16_f32 v116, v118, v119
	v_cvt_pk_bf16_f32 v118, v114, v115
	v_mad_u64_u32 v[114:115], s[16:17], v148, s9, v[64:65]
	v_mul_f32_e32 v64, 0xbfb8aa3b, v110
	v_exp_f32_e32 v64, v64
	v_mul_f32_e32 v115, 0xbfb8aa3b, v111
	v_cvt_pk_bf16_f32 v117, v120, v121
	v_exp_f32_e32 v121, v115
	v_add_f32_e32 v64, 1.0, v64
	v_rcp_f32_e32 v120, v64
	v_mov_b32_e32 v115, v65
	v_add_f32_e32 v64, 1.0, v121
	v_rcp_f32_e32 v121, v64
	v_mul_f32_e32 v64, 0xbfb8aa3b, v112
	v_cvt_pk_bf16_f32 v119, v122, v123
	v_lshl_add_u64 v[122:123], v[114:115], 1, s[84:85]
	v_exp_f32_e32 v64, v64
	v_mul_f32_e32 v115, 0xbfb8aa3b, v113
	v_exp_f32_e32 v115, v115
	v_pk_mul_f32 v[110:111], v[110:111], v[120:121]
	v_add_f32_e32 v64, 1.0, v64
	v_pk_mul_f32 v[102:103], v[110:111], v[102:103]
	v_rcp_f32_e32 v110, v64
	v_add_f32_e32 v64, 1.0, v115
	v_rcp_f32_e32 v111, v64
	v_mul_f32_e32 v64, 0xbfb8aa3b, v106
	v_exp_f32_e32 v64, v64
	v_mul_f32_e32 v115, 0xbfb8aa3b, v107
	v_exp_f32_e32 v115, v115
	v_pk_mul_f32 v[110:111], v[112:113], v[110:111]
	v_add_f32_e32 v64, 1.0, v64
	v_mul_f32_e32 v113, 0xbfb8aa3b, v108
	v_rcp_f32_e32 v112, v64
	v_add_f32_e32 v64, 1.0, v115
	v_exp_f32_e32 v115, v113
	v_mul_f32_e32 v113, 0xbfb8aa3b, v109
	global_store_dwordx4 v[122:123], v[116:119], off nt
	v_pk_mul_f32 v[104:105], v[110:111], v[104:105]
	s_nop 0
	v_exp_f32_e32 v117, v113
	v_rcp_f32_e32 v113, v64
	v_add_f32_e32 v64, 1.0, v115
	v_rcp_f32_e32 v116, v64
	v_add_f32_e32 v64, 1.0, v117
	v_rcp_f32_e32 v117, v64
	v_pk_mul_f32 v[106:107], v[106:107], v[112:113]
	v_mul_f32_e32 v64, 0xbfb8aa3b, v94
	v_pk_mul_f32 v[106:107], v[106:107], v[98:99]
	v_pk_mul_f32 v[98:99], v[108:109], v[116:117]
	s_nop 0
	v_pk_mul_f32 v[108:109], v[98:99], v[100:101]
	v_cvt_pk_bf16_f32 v98, v102, v103
	v_exp_f32_e32 v102, v64
	v_mul_f32_e32 v64, 0xbfb8aa3b, v95
	v_exp_f32_e32 v103, v64
	v_add_u32_e32 v64, 0xb000, v114
	v_cvt_pk_bf16_f32 v99, v104, v105
	v_cvt_pk_bf16_f32 v100, v106, v107
	v_cvt_pk_bf16_f32 v101, v108, v109
	v_add_f32_e32 v102, 1.0, v102
	v_add_f32_e32 v103, 1.0, v103
	v_lshl_add_u64 v[104:105], v[64:65], 1, s[84:85]
	v_mul_f32_e32 v64, 0xbfb8aa3b, v96
	v_rcp_f32_e32 v102, v102
	v_rcp_f32_e32 v103, v103
	global_store_dwordx4 v[104:105], v[98:101], off nt
	v_exp_f32_e32 v64, v64
	v_pk_mul_f32 v[94:95], v[94:95], v[102:103]
	v_mul_f32_e32 v98, 0xbfb8aa3b, v97
	v_exp_f32_e32 v98, v98
	v_add_f32_e32 v64, 1.0, v64
	v_pk_mul_f32 v[86:87], v[94:95], v[86:87]
	v_rcp_f32_e32 v94, v64
	v_add_f32_e32 v64, 1.0, v98
	v_rcp_f32_e32 v95, v64
	v_mul_f32_e32 v64, 0xbfb8aa3b, v90
	v_exp_f32_e32 v64, v64
	v_mul_f32_e32 v98, 0xbfb8aa3b, v91
	v_exp_f32_e32 v98, v98
	v_pk_mul_f32 v[94:95], v[96:97], v[94:95]
	v_add_f32_e32 v64, 1.0, v64
	v_mul_f32_e32 v97, 0xbfb8aa3b, v92
	v_rcp_f32_e32 v96, v64
	v_add_f32_e32 v64, 1.0, v98
	v_exp_f32_e32 v98, v97
	v_mul_f32_e32 v97, 0xbfb8aa3b, v93
	v_exp_f32_e32 v99, v97
	v_rcp_f32_e32 v97, v64
	v_add_f32_e32 v64, 1.0, v98
	v_rcp_f32_e32 v98, v64
	v_add_f32_e32 v64, 1.0, v99
	v_rcp_f32_e32 v99, v64
	v_pk_mul_f32 v[90:91], v[90:91], v[96:97]
	v_mul_f32_e32 v64, 0xbfb8aa3b, v78
	v_pk_mul_f32 v[90:91], v[90:91], v[82:83]
	v_pk_mul_f32 v[82:83], v[92:93], v[98:99]
	v_pk_mul_f32 v[88:89], v[94:95], v[88:89]
	v_pk_mul_f32 v[92:93], v[82:83], v[84:85]
	v_cvt_pk_bf16_f32 v82, v86, v87
	v_exp_f32_e32 v86, v64
	v_mul_f32_e32 v64, 0xbfb8aa3b, v79
	v_exp_f32_e32 v87, v64
	v_add_u32_e32 v64, 0x16000, v114
	v_cvt_pk_bf16_f32 v83, v88, v89
	v_cvt_pk_bf16_f32 v84, v90, v91
	v_cvt_pk_bf16_f32 v85, v92, v93
	v_add_f32_e32 v86, 1.0, v86
	v_add_f32_e32 v87, 1.0, v87
	v_lshl_add_u64 v[88:89], v[64:65], 1, s[84:85]
	v_mul_f32_e32 v64, 0xbfb8aa3b, v80
	v_rcp_f32_e32 v86, v86
	v_rcp_f32_e32 v87, v87
	global_store_dwordx4 v[88:89], v[82:85], off nt
	v_exp_f32_e32 v64, v64
	v_pk_mul_f32 v[78:79], v[78:79], v[86:87]
	v_mul_f32_e32 v82, 0xbfb8aa3b, v81
	v_exp_f32_e32 v82, v82
	v_add_f32_e32 v64, 1.0, v64
	v_pk_mul_f32 v[70:71], v[78:79], v[70:71]
	v_rcp_f32_e32 v78, v64
	v_add_f32_e32 v64, 1.0, v82
	v_rcp_f32_e32 v79, v64
	v_mul_f32_e32 v64, 0xbfb8aa3b, v74
	v_exp_f32_e32 v64, v64
	v_mul_f32_e32 v82, 0xbfb8aa3b, v75
	v_exp_f32_e32 v82, v82
; __device__ __forceinline__ unsigned pk2(float lo, float hi) { f32x2_t v = {lo, hi}; bf16x2_t b = __builtin_convertvector(v, bf16x2_t); return __builtin_bit_cast(unsigned, b); }
; __device__ __forceinline__ float sigmoidf_(float x) { return __builtin_amdgcn_rcpf(1.0f + __expf(-x)); }
;     __device__ __forceinline__ void operator()(const f32x4 (&acc)[2][2][4][2], const Unit& u, int wr, int wc, int fr, int fq) const {
;     ...
;         for (int ai = 0; ai < 2; ++ai)
; #pragma unroll
;             for (int m = 0; m < 4; ++m) {
;                 const int row = row0 + ai * 128 + m * 16;
;                 float o[8];
; #pragma unroll
;                 for (int n = 0; n < 2; ++n)
; #pragma unroll
;                     for (int j = 0; j < 4; ++j) { const float gt = acc[ai][0][m][n][j], up = acc[ai][1][m][n][j]; o[4 * n + j] = gt * sigmoidf_(gt) * up; }
;                 u32x4 w; w.x = pk2(o[0], o[1]); w.y = pk2(o[2], o[3]); w.z = pk2(o[4], o[5]); w.w = pk2(o[6], o[7]);
;                 __builtin_nontemporal_store(w, (u32x4*)(act + (unsigned)(row * DFF + col)));
;                 asm volatile("" ::: "memory");
;             }
	v_pk_mul_f32 v[78:79], v[80:81], v[78:79]
	v_add_f32_e32 v64, 1.0, v64
	v_mul_f32_e32 v81, 0xbfb8aa3b, v76
	v_rcp_f32_e32 v80, v64
	v_add_f32_e32 v64, 1.0, v82
	v_exp_f32_e32 v82, v81
	v_mul_f32_e32 v81, 0xbfb8aa3b, v77
	v_exp_f32_e32 v83, v81
	v_rcp_f32_e32 v81, v64
	v_add_f32_e32 v64, 1.0, v82
	v_rcp_f32_e32 v82, v64
	v_add_f32_e32 v64, 1.0, v83
	v_rcp_f32_e32 v83, v64
	v_pk_mul_f32 v[74:75], v[74:75], v[80:81]
	v_mul_f32_e32 v64, 0xbfb8aa3b, v60
	v_pk_mul_f32 v[74:75], v[74:75], v[66:67]
	v_pk_mul_f32 v[66:67], v[76:77], v[82:83]
	v_pk_mul_f32 v[72:73], v[78:79], v[72:73]
	v_pk_mul_f32 v[76:77], v[66:67], v[68:69]
	v_cvt_pk_bf16_f32 v66, v70, v71
	v_exp_f32_e32 v70, v64
	v_mul_f32_e32 v64, 0xbfb8aa3b, v61
	v_exp_f32_e32 v71, v64
	v_add_u32_e32 v64, 0x21000, v114
	v_cvt_pk_bf16_f32 v67, v72, v73
	v_cvt_pk_bf16_f32 v68, v74, v75
	v_cvt_pk_bf16_f32 v69, v76, v77
	v_add_f32_e32 v70, 1.0, v70
	v_add_f32_e32 v71, 1.0, v71
	v_lshl_add_u64 v[72:73], v[64:65], 1, s[84:85]
	v_rcp_f32_e32 v70, v70
	v_rcp_f32_e32 v71, v71
	global_store_dwordx4 v[72:73], v[66:69], off nt
	v_mul_f32_e32 v64, 0xbfb8aa3b, v62
	v_exp_f32_e32 v64, v64
	v_mul_f32_e32 v66, 0xbfb8aa3b, v63
	v_exp_f32_e32 v66, v66
	v_pk_mul_f32 v[60:61], v[60:61], v[70:71]
	s_nop 0
	v_pk_mul_f32 v[52:53], v[60:61], v[52:53]
	v_add_f32_e32 v60, 1.0, v64
	v_add_f32_e32 v61, 1.0, v66
	v_mul_f32_e32 v64, 0xbfb8aa3b, v56
	v_rcp_f32_e32 v60, v60
	v_rcp_f32_e32 v61, v61
	v_exp_f32_e32 v64, v64
	v_mul_f32_e32 v66, 0xbfb8aa3b, v57
	v_exp_f32_e32 v66, v66
	v_pk_mul_f32 v[60:61], v[62:63], v[60:61]
	v_add_f32_e32 v62, 1.0, v64
	v_mul_f32_e32 v64, 0xbfb8aa3b, v58
	v_add_f32_e32 v63, 1.0, v66
	v_exp_f32_e32 v64, v64
	v_mul_f32_e32 v66, 0xbfb8aa3b, v59
	v_exp_f32_e32 v67, v66
	v_rcp_f32_e32 v62, v62
	v_add_f32_e32 v64, 1.0, v64
	v_rcp_f32_e32 v63, v63
	v_rcp_f32_e32 v66, v64
	v_add_f32_e32 v64, 1.0, v67
	v_rcp_f32_e32 v67, v64
	v_pk_mul_f32 v[56:57], v[56:57], v[62:63]
	v_pk_mul_f32 v[54:55], v[60:61], v[54:55]
	v_pk_mul_f32 v[56:57], v[56:57], v[48:49]
	v_pk_mul_f32 v[48:49], v[58:59], v[66:67]
	v_add_u32_e32 v64, 0x58000, v114
	v_pk_mul_f32 v[58:59], v[48:49], v[50:51]
	v_cvt_pk_bf16_f32 v48, v52, v53
	v_mul_f32_e32 v52, 0xbfb8aa3b, v44
	v_mul_f32_e32 v53, 0xbfb8aa3b, v45
	v_exp_f32_e32 v52, v52
	v_exp_f32_e32 v53, v53
	v_cvt_pk_bf16_f32 v49, v54, v55
	v_cvt_pk_bf16_f32 v50, v56, v57
	v_cvt_pk_bf16_f32 v51, v58, v59
	v_add_f32_e32 v52, 1.0, v52
	v_add_f32_e32 v53, 1.0, v53
	v_lshl_add_u64 v[54:55], v[64:65], 1, s[84:85]
	v_rcp_f32_e32 v52, v52
	v_rcp_f32_e32 v53, v53
	global_store_dwordx4 v[54:55], v[48:51], off nt
	v_add_u32_e32 v64, 0x63000, v114
	v_pk_mul_f32 v[44:45], v[44:45], v[52:53]
	v_mul_f32_e32 v48, 0xbfb8aa3b, v46
	v_mul_f32_e32 v49, 0xbfb8aa3b, v47
	v_exp_f32_e32 v48, v48
	v_exp_f32_e32 v49, v49
	v_pk_mul_f32 v[36:37], v[44:45], v[36:37]
	v_add_f32_e32 v44, 1.0, v48
	v_add_f32_e32 v45, 1.0, v49
	v_mul_f32_e32 v48, 0xbfb8aa3b, v40
	v_mul_f32_e32 v49, 0xbfb8aa3b, v41
	v_rcp_f32_e32 v44, v44
	v_rcp_f32_e32 v45, v45
	v_exp_f32_e32 v48, v48
	v_exp_f32_e32 v49, v49
	v_pk_mul_f32 v[44:45], v[46:47], v[44:45]
	v_add_f32_e32 v46, 1.0, v48
	v_add_f32_e32 v47, 1.0, v49
	v_mul_f32_e32 v48, 0xbfb8aa3b, v42
	v_mul_f32_e32 v49, 0xbfb8aa3b, v43
	v_exp_f32_e32 v48, v48
	v_exp_f32_e32 v49, v49
	v_rcp_f32_e32 v46, v46
	v_rcp_f32_e32 v47, v47
	v_add_f32_e32 v48, 1.0, v48
	v_add_f32_e32 v49, 1.0, v49
	v_rcp_f32_e32 v48, v48
	v_rcp_f32_e32 v49, v49
	v_pk_mul_f32 v[40:41], v[40:41], v[46:47]
	v_pk_mul_f32 v[38:39], v[44:45], v[38:39]
	v_pk_mul_f32 v[40:41], v[40:41], v[32:33]
	v_pk_mul_f32 v[32:33], v[42:43], v[48:49]
	s_nop 0
	v_pk_mul_f32 v[42:43], v[32:33], v[34:35]
	v_cvt_pk_bf16_f32 v32, v36, v37
	v_mul_f32_e32 v36, 0xbfb8aa3b, v28
	v_mul_f32_e32 v37, 0xbfb8aa3b, v29
	v_exp_f32_e32 v36, v36
	v_exp_f32_e32 v37, v37
	v_cvt_pk_bf16_f32 v33, v38, v39
	v_cvt_pk_bf16_f32 v34, v40, v41
	v_cvt_pk_bf16_f32 v35, v42, v43
	v_add_f32_e32 v36, 1.0, v36
	v_add_f32_e32 v37, 1.0, v37
	v_lshl_add_u64 v[38:39], v[64:65], 1, s[84:85]
	v_rcp_f32_e32 v36, v36
	v_rcp_f32_e32 v37, v37
	global_store_dwordx4 v[38:39], v[32:35], off nt
	v_add_u32_e32 v64, 0x6e000, v114
	v_pk_mul_f32 v[28:29], v[28:29], v[36:37]
	v_mul_f32_e32 v32, 0xbfb8aa3b, v30
	v_mul_f32_e32 v33, 0xbfb8aa3b, v31
	v_exp_f32_e32 v32, v32
	v_exp_f32_e32 v33, v33
	v_pk_mul_f32 v[20:21], v[28:29], v[20:21]
	v_add_f32_e32 v28, 1.0, v32
	v_add_f32_e32 v29, 1.0, v33
	v_mul_f32_e32 v32, 0xbfb8aa3b, v24
	v_mul_f32_e32 v33, 0xbfb8aa3b, v25
	v_rcp_f32_e32 v28, v28
	v_rcp_f32_e32 v29, v29
	v_exp_f32_e32 v32, v32
	v_exp_f32_e32 v33, v33
	v_pk_mul_f32 v[28:29], v[30:31], v[28:29]
	v_add_f32_e32 v30, 1.0, v32
	v_add_f32_e32 v31, 1.0, v33
	v_mul_f32_e32 v32, 0xbfb8aa3b, v26
	v_mul_f32_e32 v33, 0xbfb8aa3b, v27
	v_exp_f32_e32 v32, v32
	v_exp_f32_e32 v33, v33
	v_rcp_f32_e32 v30, v30
	v_rcp_f32_e32 v31, v31
	v_add_f32_e32 v32, 1.0, v32
	v_add_f32_e32 v33, 1.0, v33
	v_rcp_f32_e32 v32, v32
	v_rcp_f32_e32 v33, v33
	v_pk_mul_f32 v[24:25], v[24:25], v[30:31]
	v_pk_mul_f32 v[22:23], v[28:29], v[22:23]
	v_pk_mul_f32 v[24:25], v[24:25], v[16:17]
	v_pk_mul_f32 v[16:17], v[26:27], v[32:33]
	s_nop 0
	v_pk_mul_f32 v[26:27], v[16:17], v[18:19]
	v_cvt_pk_bf16_f32 v16, v20, v21
	v_mul_f32_e32 v20, 0xbfb8aa3b, v12
	v_mul_f32_e32 v21, 0xbfb8aa3b, v13
	v_exp_f32_e32 v20, v20
	v_exp_f32_e32 v21, v21
	v_cvt_pk_bf16_f32 v17, v22, v23
	v_cvt_pk_bf16_f32 v18, v24, v25
	v_cvt_pk_bf16_f32 v19, v26, v27
	v_add_f32_e32 v20, 1.0, v20
	v_add_f32_e32 v21, 1.0, v21
	v_lshl_add_u64 v[22:23], v[64:65], 1, s[84:85]
	v_rcp_f32_e32 v20, v20
	v_rcp_f32_e32 v21, v21
	global_store_dwordx4 v[22:23], v[16:19], off nt
	v_add_u32_e32 v64, 0x79000, v114
	v_pk_mul_f32 v[12:13], v[12:13], v[20:21]
	v_mul_f32_e32 v16, 0xbfb8aa3b, v14
	v_mul_f32_e32 v17, 0xbfb8aa3b, v15
	v_exp_f32_e32 v16, v16
	v_exp_f32_e32 v17, v17
	v_pk_mul_f32 v[4:5], v[12:13], v[4:5]
	v_add_f32_e32 v12, 1.0, v16
	v_add_f32_e32 v13, 1.0, v17
	v_mul_f32_e32 v16, 0xbfb8aa3b, v8
	v_mul_f32_e32 v17, 0xbfb8aa3b, v9
	v_rcp_f32_e32 v12, v12
	v_rcp_f32_e32 v13, v13
	v_exp_f32_e32 v16, v16
	v_exp_f32_e32 v17, v17
	v_pk_mul_f32 v[12:13], v[14:15], v[12:13]
	v_add_f32_e32 v14, 1.0, v16
	v_add_f32_e32 v15, 1.0, v17
	v_mul_f32_e32 v16, 0xbfb8aa3b, v10
	v_mul_f32_e32 v17, 0xbfb8aa3b, v11
	v_exp_f32_e32 v16, v16
	v_exp_f32_e32 v17, v17
	v_rcp_f32_e32 v14, v14
	v_rcp_f32_e32 v15, v15
	v_add_f32_e32 v16, 1.0, v16
	v_add_f32_e32 v17, 1.0, v17
	v_rcp_f32_e32 v16, v16
	v_rcp_f32_e32 v17, v17
	v_pk_mul_f32 v[8:9], v[8:9], v[14:15]
	v_pk_mul_f32 v[6:7], v[12:13], v[6:7]
	v_pk_mul_f32 v[8:9], v[8:9], v[0:1]
	v_pk_mul_f32 v[0:1], v[10:11], v[16:17]
	s_nop 0
	v_pk_mul_f32 v[10:11], v[0:1], v[2:3]
	v_cvt_pk_bf16_f32 v0, v4, v5
	v_cvt_pk_bf16_f32 v1, v6, v7
	v_cvt_pk_bf16_f32 v2, v8, v9
	v_cvt_pk_bf16_f32 v3, v10, v11
	v_lshl_add_u64 v[4:5], v[64:65], 1, s[84:85]
	global_store_dwordx4 v[4:5], v[0:3], off nt
	s_cbranch_vccnz .LBB0_250
	s_andn2_b64 vcc, exec, s[2:3]
	s_cbranch_vccnz .LBB0_249
	s_barrier
	s_branch .LBB0_249

; template <int K> __device__ __forceinline__ float swz_xor(float v) { return __int_as_float(__builtin_amdgcn_ds_swizzle(__float_as_int(v), (K << 10) | 0x1f)); }
; __device__ __forceinline__ float xor32_sum(float v) { auto rr = __builtin_amdgcn_permlane32_swap(__float_as_uint(v), __float_as_uint(v), false, false); return __uint_as_float(rr[0]) + __uint_as_float(rr[1]); }
;     __device__ __forceinline__ void run(const f32x4 (&v)[2][2][4][2], const Unit& u, int wr, int wc, int fr, int fq, LAS unsigned char* lds, int wid, int lane) const {
;     ...
; #pragma unroll
;         for (int ai = 0; ai < 2; ++ai)
; #pragma unroll
;             for (int m = 0; m < 4; ++m) {
;                 float q = 0.f;
; #pragma unroll
;                 for (int bj = 0; bj < 2; ++bj)
; #pragma unroll
;                     for (int n = 0; n < 2; ++n) { const f32x4 x = v[ai][bj][m][n]; q += (x[0] * x[0] + x[1] * x[1]) + (x[2] * x[2] + x[3] * x[3]); }
;                 q += swz_xor<16>(q); q = xor32_sum(q);
;                 if (fq == 0) P[(ai * 128 + wr * 64 + m * 16 + fr) * 4 + wc] = q;
;             }
.LBB0_299:
	v_mul_f32_e32 v1, v67, v67
	v_mul_f32_e32 v2, v69, v69
	v_fmac_f32_e32 v1, v66, v66
	v_fmac_f32_e32 v2, v68, v68
	v_add_f32_e32 v1, v1, v2
	v_mul_f32_e32 v2, v71, v71
	v_mul_f32_e32 v3, v73, v73
	v_fmac_f32_e32 v2, v70, v70
	v_fmac_f32_e32 v3, v72, v72
	v_add_f32_e32 v2, v2, v3
	v_add_f32_e32 v1, v1, v2
	v_mul_f32_e32 v2, v131, v131
	v_mul_f32_e32 v3, v133, v133
	v_fmac_f32_e32 v2, v130, v130
	v_fmac_f32_e32 v3, v132, v132
	v_add_f32_e32 v2, v2, v3
	v_add_f32_e32 v1, v1, v2
	v_mul_f32_e32 v2, v135, v135
	v_mul_f32_e32 v3, v137, v137
	v_fmac_f32_e32 v2, v134, v134
	v_fmac_f32_e32 v3, v136, v136
	v_add_f32_e32 v2, v2, v3
	v_add_f32_e32 v1, v2, v1
	ds_swizzle_b32 v2, v1 offset:swizzle(SWAP,16)
	v_and_b32_e32 v0, 63, v236
	s_lshl_b32 s0, s27, 2
	v_cmp_gt_u32_e32 vcc, 16, v0
	s_waitcnt lgkmcnt(0)
	v_add_f32_e32 v1, v1, v2
	v_mov_b32_e32 v2, v1
	s_add_i32 s8, s0, 0
	s_nop 0
	v_permlane32_swap_b32_e32 v1, v2
	s_and_saveexec_b64 s[0:1], vcc
	s_xor_b64 s[0:1], exec, s[0:1]
	s_lshl_b32 s9, s26, 10
	s_add_i32 s9, s8, s9
	v_lshl_add_u32 v3, v247, 4, s9
	v_add_f32_e32 v1, v1, v2
	ds_write_b32 v3, v1
	s_or_b64 exec, exec, s[0:1]
	v_mul_f32_e32 v1, v75, v75
	v_mul_f32_e32 v2, v77, v77
	v_fmac_f32_e32 v1, v74, v74
	v_fmac_f32_e32 v2, v76, v76
	v_add_f32_e32 v1, v1, v2
	v_mul_f32_e32 v2, v79, v79
	v_mul_f32_e32 v3, v81, v81
	v_fmac_f32_e32 v2, v78, v78
	v_fmac_f32_e32 v3, v80, v80
	v_add_f32_e32 v2, v2, v3
	v_add_f32_e32 v1, v1, v2
	v_mul_f32_e32 v2, v139, v139
	v_mul_f32_e32 v3, v141, v141
	v_fmac_f32_e32 v2, v138, v138
	v_fmac_f32_e32 v3, v140, v140
	v_add_f32_e32 v2, v2, v3
	v_add_f32_e32 v1, v1, v2
	v_mul_f32_e32 v2, v143, v143
	v_mul_f32_e32 v3, v145, v145
	v_fmac_f32_e32 v2, v142, v142
	v_fmac_f32_e32 v3, v144, v144
	v_add_f32_e32 v2, v2, v3
	v_add_f32_e32 v1, v2, v1
	ds_swizzle_b32 v2, v1 offset:swizzle(SWAP,16)
	s_waitcnt lgkmcnt(0)
	v_add_f32_e32 v1, v1, v2
	v_mov_b32_e32 v2, v1
	s_nop 1
	v_permlane32_swap_b32_e32 v1, v2
	s_and_saveexec_b64 s[0:1], vcc
	s_lshl_b32 s9, s26, 10
	s_add_i32 s9, s8, s9
	v_lshl_add_u32 v3, v247, 4, s9
	v_add_f32_e32 v1, v1, v2
	ds_write_b32 v3, v1 offset:256
	s_or_b64 exec, exec, s[0:1]
	v_mul_f32_e32 v1, v91, v91
	v_mul_f32_e32 v2, v93, v93
	v_fmac_f32_e32 v1, v90, v90
	v_fmac_f32_e32 v2, v92, v92
	v_add_f32_e32 v1, v1, v2
	v_mul_f32_e32 v2, v95, v95
	v_mul_f32_e32 v3, v97, v97
	v_fmac_f32_e32 v2, v94, v94
	v_fmac_f32_e32 v3, v96, v96
	v_add_f32_e32 v2, v2, v3
	v_add_f32_e32 v1, v1, v2
	v_mul_f32_e32 v2, v147, v147
	v_mul_f32_e32 v3, v149, v149
	v_fmac_f32_e32 v2, v146, v146
	v_fmac_f32_e32 v3, v148, v148
	v_add_f32_e32 v2, v2, v3
	v_add_f32_e32 v1, v1, v2
	v_mul_f32_e32 v2, v151, v151
	v_mul_f32_e32 v3, v153, v153
	v_fmac_f32_e32 v2, v150, v150
	v_fmac_f32_e32 v3, v152, v152
	v_add_f32_e32 v2, v2, v3
	v_add_f32_e32 v1, v2, v1
	ds_swizzle_b32 v2, v1 offset:swizzle(SWAP,16)
	s_waitcnt lgkmcnt(0)
	v_add_f32_e32 v1, v1, v2
	v_mov_b32_e32 v2, v1
	s_nop 1
	v_permlane32_swap_b32_e32 v1, v2
	s_and_saveexec_b64 s[0:1], vcc
	s_lshl_b32 s9, s26, 10
	s_add_i32 s9, s8, s9
	v_lshl_add_u32 v3, v247, 4, s9
	v_add_f32_e32 v1, v1, v2
	ds_write_b32 v3, v1 offset:512
	s_or_b64 exec, exec, s[0:1]
	v_mul_f32_e32 v1, v53, v53
	v_mul_f32_e32 v2, v55, v55
	v_fmac_f32_e32 v1, v52, v52
	v_fmac_f32_e32 v2, v54, v54
	v_add_f32_e32 v1, v1, v2
	v_mul_f32_e32 v2, v61, v61
	v_mul_f32_e32 v3, v63, v63
	v_fmac_f32_e32 v2, v60, v60
	v_fmac_f32_e32 v3, v62, v62
	v_add_f32_e32 v2, v2, v3
	v_add_f32_e32 v1, v1, v2
	v_mul_f32_e32 v2, v155, v155
	v_mul_f32_e32 v3, v157, v157
	v_fmac_f32_e32 v2, v154, v154
	v_fmac_f32_e32 v3, v156, v156
	v_add_f32_e32 v2, v2, v3
	v_add_f32_e32 v1, v1, v2
	v_mul_f32_e32 v2, v159, v159
	v_mul_f32_e32 v3, v161, v161
	v_fmac_f32_e32 v2, v158, v158
	v_fmac_f32_e32 v3, v160, v160
	v_add_f32_e32 v2, v2, v3
	v_add_f32_e32 v1, v2, v1
	ds_swizzle_b32 v2, v1 offset:swizzle(SWAP,16)
	s_waitcnt lgkmcnt(0)
	v_add_f32_e32 v1, v1, v2
	v_mov_b32_e32 v2, v1
	s_nop 1
	v_permlane32_swap_b32_e32 v1, v2
	s_and_saveexec_b64 s[0:1], vcc
	s_lshl_b32 s9, s26, 10
	s_add_i32 s9, s8, s9
	v_lshl_add_u32 v3, v247, 4, s9
	v_add_f32_e32 v1, v1, v2
	ds_write_b32 v3, v1 offset:768
	s_or_b64 exec, exec, s[0:1]
	v_mul_f32_e32 v1, v83, v83
	v_mul_f32_e32 v2, v85, v85
	v_fmac_f32_e32 v1, v82, v82
	v_fmac_f32_e32 v2, v84, v84
	v_add_f32_e32 v1, v1, v2
	v_mul_f32_e32 v2, v87, v87
	v_mul_f32_e32 v3, v89, v89
	v_fmac_f32_e32 v2, v86, v86
	v_fmac_f32_e32 v3, v88, v88
	v_add_f32_e32 v2, v2, v3
	v_add_f32_e32 v1, v1, v2
	v_mul_f32_e32 v2, v163, v163
	v_mul_f32_e32 v3, v165, v165
	v_fmac_f32_e32 v2, v162, v162
	v_fmac_f32_e32 v3, v164, v164
	v_add_f32_e32 v2, v2, v3
	v_add_f32_e32 v1, v1, v2
	v_mul_f32_e32 v2, v167, v167
	v_mul_f32_e32 v3, v169, v169
	v_fmac_f32_e32 v2, v166, v166
	v_fmac_f32_e32 v3, v168, v168
	v_add_f32_e32 v2, v2, v3
	v_add_f32_e32 v1, v2, v1
	ds_swizzle_b32 v2, v1 offset:swizzle(SWAP,16)
	s_waitcnt lgkmcnt(0)
; template <int K> __device__ __forceinline__ float swz_xor(float v) { return __int_as_float(__builtin_amdgcn_ds_swizzle(__float_as_int(v), (K << 10) | 0x1f)); }
; __device__ __forceinline__ float xor32_sum(float v) { auto rr = __builtin_amdgcn_permlane32_swap(__float_as_uint(v), __float_as_uint(v), false, false); return __uint_as_float(rr[0]) + __uint_as_float(rr[1]); }
;     __device__ __forceinline__ void run(const f32x4 (&v)[2][2][4][2], const Unit& u, int wr, int wc, int fr, int fq, LAS unsigned char* lds, int wid, int lane) const {
;     ...
;                 q += swz_xor<16>(q); q = xor32_sum(q);
;                 if (fq == 0) P[(ai * 128 + wr * 64 + m * 16 + fr) * 4 + wc] = q;
;             }
;         asm volatile("s_waitcnt lgkmcnt(0)" ::: "memory"); __builtin_amdgcn_s_barrier(); asm volatile("" ::: "memory");
;         const int row = wid * 32 + (lane & 31);
;         if (lane < 32) {
;             const float t = (P[row * 4 + 0] + P[row * 4 + 1]) + (P[row * 4 + 2] + P[row * 4 + 3]);
;             __hip_atomic_store(xbuf + ((size_t)(u.pm * 256 + row) * 4 + u.pn), __float_as_uint(t), __ATOMIC_RELAXED, __HIP_MEMORY_SCOPE_AGENT);
;         }
	v_add_f32_e32 v1, v1, v2
	v_mov_b32_e32 v2, v1
	s_nop 1
	v_permlane32_swap_b32_e32 v1, v2
	s_and_saveexec_b64 s[0:1], vcc
	s_lshl_b32 s9, s26, 10
	s_add_i32 s9, s8, s9
	v_lshl_add_u32 v3, v247, 4, s9
	v_add_f32_e32 v1, v1, v2
	ds_write_b32 v3, v1 offset:2048
	s_or_b64 exec, exec, s[0:1]
	v_mul_f32_e32 v1, v107, v107
	v_mul_f32_e32 v2, v109, v109
	v_fmac_f32_e32 v1, v106, v106
	v_fmac_f32_e32 v2, v108, v108
	v_add_f32_e32 v1, v1, v2
	v_mul_f32_e32 v2, v111, v111
	v_mul_f32_e32 v3, v113, v113
	v_fmac_f32_e32 v2, v110, v110
	v_fmac_f32_e32 v3, v112, v112
	v_add_f32_e32 v2, v2, v3
	v_add_f32_e32 v1, v1, v2
	v_mul_f32_e32 v2, v171, v171
	v_mul_f32_e32 v3, v173, v173
	v_fmac_f32_e32 v2, v170, v170
	v_fmac_f32_e32 v3, v172, v172
	v_add_f32_e32 v2, v2, v3
	v_add_f32_e32 v1, v1, v2
	v_mul_f32_e32 v2, v175, v175
	v_mul_f32_e32 v3, v177, v177
	v_fmac_f32_e32 v2, v174, v174
	v_fmac_f32_e32 v3, v176, v176
	v_add_f32_e32 v2, v2, v3
	v_add_f32_e32 v1, v2, v1
	ds_swizzle_b32 v2, v1 offset:swizzle(SWAP,16)
	s_waitcnt lgkmcnt(0)
	v_add_f32_e32 v1, v1, v2
	v_mov_b32_e32 v2, v1
	s_nop 1
	v_permlane32_swap_b32_e32 v1, v2
	s_and_saveexec_b64 s[0:1], vcc
	s_lshl_b32 s9, s26, 10
	s_add_i32 s9, s8, s9
	v_lshl_add_u32 v3, v247, 4, s9
	v_add_f32_e32 v1, v1, v2
	ds_write_b32 v3, v1 offset:2304
	s_or_b64 exec, exec, s[0:1]
	v_mul_f32_e32 v1, v115, v115
	v_mul_f32_e32 v2, v117, v117
	v_fmac_f32_e32 v1, v114, v114
	v_fmac_f32_e32 v2, v116, v116
	v_add_f32_e32 v1, v1, v2
	v_mul_f32_e32 v2, v119, v119
	v_mul_f32_e32 v3, v121, v121
	v_fmac_f32_e32 v2, v118, v118
	v_fmac_f32_e32 v3, v120, v120
	v_add_f32_e32 v2, v2, v3
	v_add_f32_e32 v1, v1, v2
	v_mul_f32_e32 v2, v179, v179
	v_mul_f32_e32 v3, v181, v181
	v_fmac_f32_e32 v2, v178, v178
	v_fmac_f32_e32 v3, v180, v180
	v_add_f32_e32 v2, v2, v3
	v_add_f32_e32 v1, v1, v2
	v_mul_f32_e32 v2, v183, v183
	v_mul_f32_e32 v3, v185, v185
	v_fmac_f32_e32 v2, v182, v182
	v_fmac_f32_e32 v3, v184, v184
	v_add_f32_e32 v2, v2, v3
	v_add_f32_e32 v1, v2, v1
	ds_swizzle_b32 v2, v1 offset:swizzle(SWAP,16)
	s_waitcnt lgkmcnt(0)
	v_add_f32_e32 v1, v1, v2
	v_mov_b32_e32 v2, v1
	s_nop 1
	v_permlane32_swap_b32_e32 v1, v2
	s_and_saveexec_b64 s[0:1], vcc
	s_lshl_b32 s9, s26, 10
	s_add_i32 s9, s8, s9
	v_lshl_add_u32 v3, v247, 4, s9
	v_add_f32_e32 v1, v1, v2
	ds_write_b32 v3, v1 offset:2560
	s_or_b64 exec, exec, s[0:1]
	v_mul_f32_e32 v1, v123, v123
	v_mul_f32_e32 v2, v125, v125
	v_fmac_f32_e32 v1, v122, v122
	v_fmac_f32_e32 v2, v124, v124
	v_add_f32_e32 v1, v1, v2
	v_mul_f32_e32 v2, v127, v127
	v_mul_f32_e32 v3, v129, v129
	v_fmac_f32_e32 v2, v126, v126
	v_fmac_f32_e32 v3, v128, v128
	v_add_f32_e32 v2, v2, v3
	v_add_f32_e32 v1, v1, v2
	v_mul_f32_e32 v2, v187, v187
	v_mul_f32_e32 v3, v189, v189
	v_fmac_f32_e32 v2, v186, v186
	v_fmac_f32_e32 v3, v188, v188
	v_add_f32_e32 v2, v2, v3
	v_add_f32_e32 v1, v1, v2
	v_mul_f32_e32 v2, v191, v191
	v_mul_f32_e32 v3, v193, v193
	v_fmac_f32_e32 v2, v190, v190
	v_fmac_f32_e32 v3, v192, v192
	v_add_f32_e32 v2, v2, v3
	v_add_f32_e32 v1, v2, v1
	ds_swizzle_b32 v2, v1 offset:swizzle(SWAP,16)
	s_waitcnt lgkmcnt(0)
	v_add_f32_e32 v1, v1, v2
	v_mov_b32_e32 v2, v1
	s_nop 1
	v_permlane32_swap_b32_e32 v1, v2
	s_and_saveexec_b64 s[0:1], vcc
	s_lshl_b32 s9, s26, 10
	s_add_i32 s8, s8, s9
	v_lshl_add_u32 v3, v247, 4, s8
	v_add_f32_e32 v1, v1, v2
	ds_write_b32 v3, v1 offset:2816
	s_or_b64 exec, exec, s[0:1]
	s_waitcnt lgkmcnt(0)
	s_barrier
	s_add_u32 s8, s82, 0x240000
	v_and_b32_e32 v1, 31, v236
	s_addc_u32 s9, s83, 0
	v_lshl_or_b32 v1, s5, 5, v1
	v_cmp_gt_u32_e64 s[0:1], 32, v0
	s_and_saveexec_b64 s[10:11], s[0:1]
	s_cbranch_execz .LBB0_317
	v_lshl_add_u32 v2, v1, 4, 0
	ds_read_b128 v[2:5], v2
	s_ashr_i32 s5, s4, 31
	s_waitcnt lgkmcnt(0)
	v_mov_b32_e32 v7, v4
	v_add_u32_e32 v4, s14, v1
	v_mov_b32_e32 v6, v3
	v_mov_b32_e32 v3, v5
	v_ashrrev_i32_e32 v5, 31, v4
	v_pk_add_f32 v[2:3], v[6:7], v[2:3]
	v_lshl_add_u64 v[4:5], v[4:5], 4, s[8:9]
	v_pk_add_f32 v[2:3], v[2:3], v[2:3] op_sel:[0,1] op_sel_hi:[1,0]
	v_lshl_add_u64 v[4:5], s[4:5], 2, v[4:5]
	global_store_dword v[4:5], v2, off sc1

; __device__ __forceinline__ unsigned pk2(float lo, float hi) { f32x2_t v = {lo, hi}; bf16x2_t b = __builtin_convertvector(v, bf16x2_t); return __builtin_bit_cast(unsigned, b); }
;     __device__ __forceinline__ void fused(f32x4 (&acc)[2][2][4][2], const Unit& u, int wr, int wc, int fr, int fq, LAS unsigned char* lds, int wid, int lane) const {
;     ...
;         for (int bj = 0; bj < 2; ++bj) {
;             const int col = u.pn * 256 + bj * 128 + wc * 32 + 8 * fq;
;             f32x4 gv0 = *(const f32x4*)(ng + col), gv1 = *(const f32x4*)(ng + col + 4), sh0 = (f32x4){0.f, 0.f, 0.f, 0.f}, sh1 = sh0;
;             if (mode == 0) { gv0 = gv0 * (*(const f32x4*)(sc + boff + col) + 1.0f); gv1 = gv1 * (*(const f32x4*)(sc + boff + col + 4) + 1.0f);
;                              sh0 = *(const f32x4*)(sh + boff + col); sh1 = *(const f32x4*)(sh + boff + col + 4); }
; #pragma unroll
;             for (int ai = 0; ai < 2; ++ai)
; #pragma unroll
;                 for (int m = 0; m < 4; ++m) {
;                     const int r = ai * 128 + wr * 64 + m * 16 + fr;
;                     const unsigned off = (unsigned)((u.pm * 256 + r) * DM + col);
;                     const f32x4 x0 = acc[ai][bj][m][0], x1 = acc[ai][bj][m][1];
;                     const float rs = S[r];
;                     const f32x4 y0 = x0 * rs * gv0 + sh0, y1 = x1 * rs * gv1 + sh1;
;                     if (mode == 0) {
;                         u32x4 xw; xw.x = pk2(x0[0], x0[1]); xw.y = pk2(x0[2], x0[3]); xw.z = pk2(x1[0], x1[1]); xw.w = pk2(x1[2], x1[3]);
;                         *(u32x4*)(xout16 + off) = xw;
;                         u32x4 hw; hw.x = pk2(y0[0], y0[1]); hw.y = pk2(y0[2], y0[3]); hw.z = pk2(y1[0], y1[1]); hw.w = pk2(y1[2], y1[3]);
;                         *(u32x4*)(hout + off) = hw;
.LBB0_327:
	s_or_b64 exec, exec, s[4:5]
	v_readlane_b32 s8, v255, 13
	s_lshl_b64 s[0:1], s[38:39], 12
	v_readlane_b32 s16, v255, 21
	v_readlane_b32 s17, v255, 22
	s_add_u32 s0, s16, s0
	s_addc_u32 s1, s17, s1
	v_lshlrev_b64 v[8:9], 2, v[214:215]
	v_lshl_add_u64 v[12:13], s[0:1], 0, v[8:9]
	v_readlane_b32 s0, v255, 48
	s_add_u32 s0, s0, s2
	v_readlane_b32 s1, v255, 49
	s_addc_u32 s1, s1, s3
	s_waitcnt lgkmcnt(0)
	s_barrier
	v_lshl_add_u64 v[22:23], s[0:1], 0, v[8:9]
	s_mov_b64 s[0:1], 0x4000
	v_lshl_add_u64 v[8:9], v[22:23], 0, s[0:1]
	s_movk_i32 s0, 0x4000
	v_add_co_u32_e32 v10, vcc, s0, v22
	global_load_dwordx4 v[0:3], v[12:13], off offset:16
	global_load_dwordx4 v[4:7], v[12:13], off
	v_addc_co_u32_e32 v11, vcc, 0, v23, vcc
	flat_load_dwordx4 v[14:17], v[10:11]
	s_mov_b64 s[0:1], 0x3000
	v_lshl_add_u32 v30, v213, 2, 0
	v_lshlrev_b32_e32 v32, 10, v213
	v_or_b32_e32 v31, 0x4000, v32
	v_or_b32_e32 v33, 0x8000, v32
	v_add_u32_e32 v44, 0x20000, v32
	v_add_u32_e32 v45, 0x24000, v32
	v_add_u32_e32 v46, 0x28000, v32
	v_readlane_b32 s9, v255, 14
	v_readlane_b32 s10, v255, 15
	v_readlane_b32 s11, v255, 16
	v_readlane_b32 s12, v255, 17
	v_readlane_b32 s13, v255, 18
	v_readlane_b32 s14, v255, 19
	v_readlane_b32 s15, v255, 20
	v_readlane_b32 s18, v255, 23
	v_readlane_b32 s19, v255, 24
	v_readlane_b32 s20, v255, 25
	v_readlane_b32 s21, v255, 26
	v_readlane_b32 s22, v255, 27
	v_readlane_b32 s23, v255, 28
	s_waitcnt vmcnt(0) lgkmcnt(0)
	v_pk_add_f32 v[10:11], v[16:17], 1.0 op_sel_hi:[1,0]
	v_pk_add_f32 v[16:17], v[14:15], 1.0 op_sel_hi:[1,0]
	v_pk_mul_f32 v[14:15], v[6:7], v[10:11]
	v_pk_mul_f32 v[16:17], v[4:5], v[16:17]
	flat_load_dwordx4 v[4:7], v[8:9] offset:16
	v_lshl_add_u64 v[10:11], v[22:23], 0, s[0:1]
	s_lshl_b32 s0, s24, 18
	v_add3_u32 v64, v214, v32, s0
	v_lshlrev_b64 v[38:39], 1, v[64:65]
	v_lshl_add_u64 v[40:41], s[36:37], 0, v[38:39]
	v_add3_u32 v64, v214, v31, s0
	s_waitcnt vmcnt(0) lgkmcnt(0)
	v_pk_add_f32 v[4:5], v[4:5], 1.0 op_sel_hi:[1,0]
	s_nop 0
	v_pk_mul_f32 v[20:21], v[0:1], v[4:5]
	v_add_co_u32_e32 v0, vcc, s88, v22
	v_pk_add_f32 v[6:7], v[6:7], 1.0 op_sel_hi:[1,0]
	s_nop 0
	v_addc_co_u32_e32 v1, vcc, 0, v23, vcc
	v_pk_mul_f32 v[18:19], v[2:3], v[6:7]
	flat_load_dwordx4 v[0:3], v[0:1]
	s_nop 0
	flat_load_dwordx4 v[4:7], v[10:11] offset:16
	ds_read_b32 v22, v30 offset:4096
	s_waitcnt lgkmcnt(0)
	v_pk_mul_f32 v[24:25], v[66:67], v[22:23] op_sel_hi:[1,0]
	v_pk_mul_f32 v[26:27], v[68:69], v[22:23] op_sel_hi:[1,0]
	s_waitcnt vmcnt(0)
	v_pk_fma_f32 v[28:29], v[16:17], v[24:25], v[0:1]
	v_pk_mul_f32 v[24:25], v[70:71], v[22:23] op_sel_hi:[1,0]
	v_pk_mul_f32 v[22:23], v[72:73], v[22:23] op_sel_hi:[1,0]
	v_pk_fma_f32 v[26:27], v[14:15], v[26:27], v[2:3]
	v_pk_fma_f32 v[34:35], v[18:19], v[22:23], v[6:7]
	v_pk_fma_f32 v[36:37], v[20:21], v[24:25], v[4:5]
	v_cvt_pk_bf16_f32 v22, v66, v67
	v_cvt_pk_bf16_f32 v23, v68, v69
	v_cvt_pk_bf16_f32 v24, v70, v71
	v_cvt_pk_bf16_f32 v25, v72, v73
	global_store_dwordx4 v[40:41], v[22:25], off
	s_nop 1
	v_cvt_pk_bf16_f32 v22, v28, v29
	v_cvt_pk_bf16_f32 v23, v26, v27
	v_cvt_pk_bf16_f32 v24, v36, v37
	v_cvt_pk_bf16_f32 v25, v34, v35
	v_lshl_add_u64 v[26:27], s[86:87], 0, v[38:39]
	global_store_dwordx4 v[26:27], v[22:25], off
	ds_read_b32 v22, v30 offset:4160
	v_lshlrev_b64 v[38:39], 1, v[64:65]
	v_lshl_add_u64 v[40:41], s[36:37], 0, v[38:39]
	v_add3_u32 v64, v214, v33, s0
	s_waitcnt lgkmcnt(0)
	v_pk_mul_f32 v[24:25], v[74:75], v[22:23] op_sel_hi:[1,0]
	v_pk_mul_f32 v[26:27], v[76:77], v[22:23] op_sel_hi:[1,0]
	v_pk_fma_f32 v[28:29], v[16:17], v[24:25], v[0:1]
	v_pk_mul_f32 v[24:25], v[78:79], v[22:23] op_sel_hi:[1,0]
	v_pk_mul_f32 v[22:23], v[80:81], v[22:23] op_sel_hi:[1,0]
	v_pk_fma_f32 v[26:27], v[14:15], v[26:27], v[2:3]
	v_pk_fma_f32 v[34:35], v[18:19], v[22:23], v[6:7]
	v_pk_fma_f32 v[36:37], v[20:21], v[24:25], v[4:5]
	v_cvt_pk_bf16_f32 v22, v74, v75
	v_cvt_pk_bf16_f32 v23, v76, v77
	v_cvt_pk_bf16_f32 v24, v78, v79
	v_cvt_pk_bf16_f32 v25, v80, v81
	global_store_dwordx4 v[40:41], v[22:25], off
	s_nop 1
	v_cvt_pk_bf16_f32 v22, v28, v29
	v_cvt_pk_bf16_f32 v23, v26, v27
	v_cvt_pk_bf16_f32 v24, v36, v37
	v_cvt_pk_bf16_f32 v25, v34, v35
	v_lshl_add_u64 v[26:27], s[86:87], 0, v[38:39]
	global_store_dwordx4 v[26:27], v[22:25], off
	ds_read_b32 v26, v30 offset:4224
	v_lshlrev_b64 v[38:39], 1, v[64:65]
	v_cvt_pk_bf16_f32 v34, v90, v91
	v_cvt_pk_bf16_f32 v35, v92, v93
	v_cvt_pk_bf16_f32 v36, v94, v95
	s_waitcnt lgkmcnt(0)
	v_pk_mul_f32 v[24:25], v[90:91], v[26:27] op_sel_hi:[1,0]
	v_pk_mul_f32 v[22:23], v[92:93], v[26:27] op_sel_hi:[1,0]
	v_pk_mul_f32 v[28:29], v[94:95], v[26:27] op_sel_hi:[1,0]
	v_pk_mul_f32 v[26:27], v[96:97], v[26:27] op_sel_hi:[1,0]
	v_pk_fma_f32 v[22:23], v[14:15], v[22:23], v[2:3]
	v_pk_fma_f32 v[24:25], v[16:17], v[24:25], v[0:1]
	v_pk_fma_f32 v[26:27], v[18:19], v[26:27], v[6:7]
	v_pk_fma_f32 v[28:29], v[20:21], v[28:29], v[4:5]
	v_cvt_pk_bf16_f32 v37, v96, v97
	v_lshl_add_u64 v[40:41], s[36:37], 0, v[38:39]
	global_store_dwordx4 v[40:41], v[34:37], off
	s_nop 1
	v_cvt_pk_bf16_f32 v34, v24, v25
	v_cvt_pk_bf16_f32 v35, v22, v23
	v_cvt_pk_bf16_f32 v36, v28, v29
	v_cvt_pk_bf16_f32 v37, v26, v27
	v_lshl_add_u64 v[22:23], s[86:87], 0, v[38:39]
	global_store_dwordx4 v[22:23], v[34:37], off
	ds_read_b32 v24, v30 offset:4288
	v_or_b32_e32 v22, 0xc000, v32
	v_add3_u32 v64, v214, v22, s0
	v_lshlrev_b64 v[40:41], 1, v[64:65]
	v_lshl_add_u64 v[42:43], s[36:37], 0, v[40:41]
	s_waitcnt lgkmcnt(0)
; __device__ __forceinline__ unsigned pk2(float lo, float hi) { f32x2_t v = {lo, hi}; bf16x2_t b = __builtin_convertvector(v, bf16x2_t); return __builtin_bit_cast(unsigned, b); }
;     __device__ __forceinline__ void fused(f32x4 (&acc)[2][2][4][2], const Unit& u, int wr, int wc, int fr, int fq, LAS unsigned char* lds, int wid, int lane) const {
;     ...
; #pragma unroll
;             for (int ai = 0; ai < 2; ++ai)
; #pragma unroll
;                 for (int m = 0; m < 4; ++m) {
;                     const int r = ai * 128 + wr * 64 + m * 16 + fr;
;                     const unsigned off = (unsigned)((u.pm * 256 + r) * DM + col);
;                     const f32x4 x0 = acc[ai][bj][m][0], x1 = acc[ai][bj][m][1];
;                     const float rs = S[r];
;                     const f32x4 y0 = x0 * rs * gv0 + sh0, y1 = x1 * rs * gv1 + sh1;
;                     if (mode == 0) {
;                         u32x4 xw; xw.x = pk2(x0[0], x0[1]); xw.y = pk2(x0[2], x0[3]); xw.z = pk2(x1[0], x1[1]); xw.w = pk2(x1[2], x1[3]);
;                         *(u32x4*)(xout16 + off) = xw;
;                         u32x4 hw; hw.x = pk2(y0[0], y0[1]); hw.y = pk2(y0[2], y0[3]); hw.z = pk2(y1[0], y1[1]); hw.w = pk2(y1[2], y1[3]);
;                         *(u32x4*)(hout + off) = hw;
	v_pk_mul_f32 v[26:27], v[52:53], v[24:25] op_sel_hi:[1,0]
	v_pk_mul_f32 v[28:29], v[54:55], v[24:25] op_sel_hi:[1,0]
	v_pk_fma_f32 v[34:35], v[16:17], v[26:27], v[0:1]
	v_pk_mul_f32 v[26:27], v[60:61], v[24:25] op_sel_hi:[1,0]
	v_pk_mul_f32 v[24:25], v[62:63], v[24:25] op_sel_hi:[1,0]
	v_pk_fma_f32 v[28:29], v[14:15], v[28:29], v[2:3]
	v_pk_fma_f32 v[36:37], v[18:19], v[24:25], v[6:7]
	v_pk_fma_f32 v[38:39], v[20:21], v[26:27], v[4:5]
	v_cvt_pk_bf16_f32 v24, v52, v53
	v_cvt_pk_bf16_f32 v25, v54, v55
	v_cvt_pk_bf16_f32 v26, v60, v61
	v_cvt_pk_bf16_f32 v27, v62, v63
	global_store_dwordx4 v[42:43], v[24:27], off
	v_add3_u32 v64, v214, v44, s0
	s_nop 0
	v_cvt_pk_bf16_f32 v24, v34, v35
	v_cvt_pk_bf16_f32 v25, v28, v29
	v_cvt_pk_bf16_f32 v26, v38, v39
	v_cvt_pk_bf16_f32 v27, v36, v37
	v_lshl_add_u64 v[28:29], s[86:87], 0, v[40:41]
	global_store_dwordx4 v[28:29], v[24:27], off
	ds_read_b32 v24, v30 offset:4608
	v_lshlrev_b64 v[40:41], 1, v[64:65]
	v_lshl_add_u64 v[42:43], s[36:37], 0, v[40:41]
	v_add3_u32 v64, v214, v45, s0
	s_waitcnt lgkmcnt(0)
	v_pk_mul_f32 v[26:27], v[82:83], v[24:25] op_sel_hi:[1,0]
	v_pk_mul_f32 v[28:29], v[84:85], v[24:25] op_sel_hi:[1,0]
	v_pk_fma_f32 v[34:35], v[16:17], v[26:27], v[0:1]
	v_pk_mul_f32 v[26:27], v[86:87], v[24:25] op_sel_hi:[1,0]
	v_pk_mul_f32 v[24:25], v[88:89], v[24:25] op_sel_hi:[1,0]
	v_pk_fma_f32 v[28:29], v[14:15], v[28:29], v[2:3]
	v_pk_fma_f32 v[36:37], v[18:19], v[24:25], v[6:7]
	v_pk_fma_f32 v[38:39], v[20:21], v[26:27], v[4:5]
	v_cvt_pk_bf16_f32 v24, v82, v83
	v_cvt_pk_bf16_f32 v25, v84, v85
	v_cvt_pk_bf16_f32 v26, v86, v87
	v_cvt_pk_bf16_f32 v27, v88, v89
	global_store_dwordx4 v[42:43], v[24:27], off
	s_nop 1
	v_cvt_pk_bf16_f32 v24, v34, v35
	v_cvt_pk_bf16_f32 v25, v28, v29
	v_cvt_pk_bf16_f32 v26, v38, v39
	v_cvt_pk_bf16_f32 v27, v36, v37
	v_lshl_add_u64 v[28:29], s[86:87], 0, v[40:41]
	global_store_dwordx4 v[28:29], v[24:27], off
	ds_read_b32 v24, v30 offset:4672
	v_lshlrev_b64 v[40:41], 1, v[64:65]
	v_lshl_add_u64 v[42:43], s[36:37], 0, v[40:41]
	v_add3_u32 v64, v214, v46, s0
	s_waitcnt lgkmcnt(0)
	v_pk_mul_f32 v[26:27], v[106:107], v[24:25] op_sel_hi:[1,0]
	v_pk_mul_f32 v[28:29], v[108:109], v[24:25] op_sel_hi:[1,0]
	v_pk_fma_f32 v[34:35], v[16:17], v[26:27], v[0:1]
	v_pk_mul_f32 v[26:27], v[110:111], v[24:25] op_sel_hi:[1,0]
	v_pk_mul_f32 v[24:25], v[112:113], v[24:25] op_sel_hi:[1,0]
	v_pk_fma_f32 v[28:29], v[14:15], v[28:29], v[2:3]
	v_pk_fma_f32 v[36:37], v[18:19], v[24:25], v[6:7]
	v_pk_fma_f32 v[38:39], v[20:21], v[26:27], v[4:5]
	v_cvt_pk_bf16_f32 v24, v106, v107
	v_cvt_pk_bf16_f32 v25, v108, v109
	v_cvt_pk_bf16_f32 v26, v110, v111
	v_cvt_pk_bf16_f32 v27, v112, v113
	global_store_dwordx4 v[42:43], v[24:27], off
	s_nop 1
	v_cvt_pk_bf16_f32 v24, v34, v35
	v_cvt_pk_bf16_f32 v25, v28, v29
	v_cvt_pk_bf16_f32 v26, v38, v39
	v_cvt_pk_bf16_f32 v27, v36, v37
	v_lshl_add_u64 v[28:29], s[86:87], 0, v[40:41]
	global_store_dwordx4 v[28:29], v[24:27], off
	ds_read_b32 v24, v30 offset:4736
	v_lshlrev_b64 v[40:41], 1, v[64:65]
	v_lshl_add_u64 v[42:43], s[36:37], 0, v[40:41]
	s_waitcnt lgkmcnt(0)
	v_pk_mul_f32 v[26:27], v[114:115], v[24:25] op_sel_hi:[1,0]
	v_pk_mul_f32 v[28:29], v[116:117], v[24:25] op_sel_hi:[1,0]
	v_pk_fma_f32 v[34:35], v[16:17], v[26:27], v[0:1]
	v_pk_mul_f32 v[26:27], v[118:119], v[24:25] op_sel_hi:[1,0]
	v_pk_mul_f32 v[24:25], v[120:121], v[24:25] op_sel_hi:[1,0]
	v_pk_fma_f32 v[28:29], v[14:15], v[28:29], v[2:3]
	v_pk_fma_f32 v[36:37], v[18:19], v[24:25], v[6:7]
	v_pk_fma_f32 v[38:39], v[20:21], v[26:27], v[4:5]
	v_cvt_pk_bf16_f32 v24, v114, v115
	v_cvt_pk_bf16_f32 v25, v116, v117
	v_cvt_pk_bf16_f32 v26, v118, v119
	v_cvt_pk_bf16_f32 v27, v120, v121
	global_store_dwordx4 v[42:43], v[24:27], off
	s_nop 1
	v_cvt_pk_bf16_f32 v24, v34, v35
	v_cvt_pk_bf16_f32 v25, v28, v29
	v_cvt_pk_bf16_f32 v26, v38, v39
	v_cvt_pk_bf16_f32 v27, v36, v37
	v_lshl_add_u64 v[28:29], s[86:87], 0, v[40:41]
	global_store_dwordx4 v[28:29], v[24:27], off
	ds_read_b32 v24, v30 offset:4800
	v_add_u32_e32 v38, 0x2c000, v32
	v_add3_u32 v64, v214, v38, s0
	s_waitcnt lgkmcnt(0)
	v_pk_mul_f32 v[28:29], v[124:125], v[24:25] op_sel_hi:[1,0]
	v_pk_mul_f32 v[26:27], v[122:123], v[24:25] op_sel_hi:[1,0]
	v_pk_fma_f32 v[14:15], v[14:15], v[28:29], v[2:3]
	v_pk_mul_f32 v[2:3], v[128:129], v[24:25] op_sel_hi:[1,0]
	v_pk_fma_f32 v[16:17], v[16:17], v[26:27], v[0:1]
	v_pk_mul_f32 v[0:1], v[126:127], v[24:25] op_sel_hi:[1,0]
	v_pk_fma_f32 v[6:7], v[18:19], v[2:3], v[6:7]
	v_lshlrev_b64 v[18:19], 1, v[64:65]
	v_pk_fma_f32 v[4:5], v[20:21], v[0:1], v[4:5]
	v_cvt_pk_bf16_f32 v0, v122, v123
	v_cvt_pk_bf16_f32 v1, v124, v125
	v_cvt_pk_bf16_f32 v2, v126, v127
	v_cvt_pk_bf16_f32 v3, v128, v129
	v_lshl_add_u64 v[20:21], s[36:37], 0, v[18:19]
	global_store_dwordx4 v[20:21], v[0:3], off
	v_add3_u32 v64, s0, v32, v230
	v_lshlrev_b64 v[34:35], 1, v[64:65]
	v_cvt_pk_bf16_f32 v0, v16, v17
	v_cvt_pk_bf16_f32 v1, v14, v15
	v_cvt_pk_bf16_f32 v2, v4, v5
	v_cvt_pk_bf16_f32 v3, v6, v7
	v_lshl_add_u64 v[4:5], s[86:87], 0, v[18:19]
	global_store_dwordx4 v[4:5], v[0:3], off
	global_load_dwordx4 v[0:3], v[12:13], off offset:528
	global_load_dwordx4 v[4:7], v[12:13], off offset:512
	s_nop 0
	flat_load_dwordx4 v[12:15], v[8:9] offset:512
	v_lshl_add_u64 v[36:37], s[36:37], 0, v[34:35]
	v_add3_u32 v64, s0, v31, v230
	s_waitcnt vmcnt(0) lgkmcnt(0)
	v_pk_add_f32 v[14:15], v[14:15], 1.0 op_sel_hi:[1,0]
	v_pk_add_f32 v[16:17], v[12:13], 1.0 op_sel_hi:[1,0]
	v_pk_mul_f32 v[12:13], v[6:7], v[14:15]
	v_pk_mul_f32 v[14:15], v[4:5], v[16:17]
	flat_load_dwordx4 v[4:7], v[8:9] offset:528
	s_waitcnt vmcnt(0) lgkmcnt(0)
; __device__ __forceinline__ unsigned pk2(float lo, float hi) { f32x2_t v = {lo, hi}; bf16x2_t b = __builtin_convertvector(v, bf16x2_t); return __builtin_bit_cast(unsigned, b); }
;     __device__ __forceinline__ void fused(f32x4 (&acc)[2][2][4][2], const Unit& u, int wr, int wc, int fr, int fq, LAS unsigned char* lds, int wid, int lane) const {
;     ...
; #pragma unroll
;             for (int ai = 0; ai < 2; ++ai)
; #pragma unroll
;                 for (int m = 0; m < 4; ++m) {
;                     const int r = ai * 128 + wr * 64 + m * 16 + fr;
;                     const unsigned off = (unsigned)((u.pm * 256 + r) * DM + col);
;                     const f32x4 x0 = acc[ai][bj][m][0], x1 = acc[ai][bj][m][1];
;                     const float rs = S[r];
;                     const f32x4 y0 = x0 * rs * gv0 + sh0, y1 = x1 * rs * gv1 + sh1;
;                     if (mode == 0) {
;                         u32x4 xw; xw.x = pk2(x0[0], x0[1]); xw.y = pk2(x0[2], x0[3]); xw.z = pk2(x1[0], x1[1]); xw.w = pk2(x1[2], x1[3]);
;                         *(u32x4*)(xout16 + off) = xw;
;                         u32x4 hw; hw.x = pk2(y0[0], y0[1]); hw.y = pk2(y0[2], y0[3]); hw.z = pk2(y1[0], y1[1]); hw.w = pk2(y1[2], y1[3]);
;                         *(u32x4*)(hout + off) = hw;
	v_pk_add_f32 v[6:7], v[6:7], 1.0 op_sel_hi:[1,0]
	v_pk_add_f32 v[4:5], v[4:5], 1.0 op_sel_hi:[1,0]
	v_pk_mul_f32 v[8:9], v[2:3], v[6:7]
	v_pk_mul_f32 v[16:17], v[0:1], v[4:5]
	flat_load_dwordx4 v[4:7], v[10:11] offset:512
	flat_load_dwordx4 v[0:3], v[10:11] offset:528
	ds_read_b32 v10, v30 offset:4096
	s_waitcnt lgkmcnt(0)
	v_pk_mul_f32 v[18:19], v[130:131], v[10:11] op_sel_hi:[1,0]
	v_pk_mul_f32 v[20:21], v[132:133], v[10:11] op_sel_hi:[1,0]
	s_waitcnt vmcnt(0)
	v_pk_fma_f32 v[26:27], v[14:15], v[18:19], v[4:5]
	v_pk_mul_f32 v[18:19], v[134:135], v[10:11] op_sel_hi:[1,0]
	v_pk_mul_f32 v[10:11], v[136:137], v[10:11] op_sel_hi:[1,0]
	v_pk_fma_f32 v[24:25], v[12:13], v[20:21], v[6:7]
	v_pk_fma_f32 v[10:11], v[8:9], v[10:11], v[2:3]
	v_pk_fma_f32 v[28:29], v[16:17], v[18:19], v[0:1]
	v_cvt_pk_bf16_f32 v18, v130, v131
	v_cvt_pk_bf16_f32 v19, v132, v133
	v_cvt_pk_bf16_f32 v20, v134, v135
	v_cvt_pk_bf16_f32 v21, v136, v137
	global_store_dwordx4 v[36:37], v[18:21], off
	s_nop 1
	v_cvt_pk_bf16_f32 v18, v26, v27
	v_cvt_pk_bf16_f32 v19, v24, v25
	v_cvt_pk_bf16_f32 v20, v28, v29
	v_cvt_pk_bf16_f32 v21, v10, v11
	v_lshl_add_u64 v[10:11], s[86:87], 0, v[34:35]
	global_store_dwordx4 v[10:11], v[18:21], off
	ds_read_b32 v10, v30 offset:4160
	v_lshlrev_b64 v[34:35], 1, v[64:65]
	v_lshl_add_u64 v[36:37], s[36:37], 0, v[34:35]
	v_add3_u32 v64, s0, v33, v230
	v_lshlrev_b64 v[32:33], 1, v[64:65]
	s_waitcnt lgkmcnt(0)
	v_pk_mul_f32 v[18:19], v[138:139], v[10:11] op_sel_hi:[1,0]
	v_pk_mul_f32 v[20:21], v[140:141], v[10:11] op_sel_hi:[1,0]
	v_pk_fma_f32 v[26:27], v[14:15], v[18:19], v[4:5]
	v_pk_mul_f32 v[18:19], v[142:143], v[10:11] op_sel_hi:[1,0]
	v_pk_mul_f32 v[10:11], v[144:145], v[10:11] op_sel_hi:[1,0]
	v_pk_fma_f32 v[24:25], v[12:13], v[20:21], v[6:7]
	v_pk_fma_f32 v[10:11], v[8:9], v[10:11], v[2:3]
	v_pk_fma_f32 v[28:29], v[16:17], v[18:19], v[0:1]
	v_cvt_pk_bf16_f32 v18, v138, v139
	v_cvt_pk_bf16_f32 v19, v140, v141
	v_cvt_pk_bf16_f32 v20, v142, v143
	v_cvt_pk_bf16_f32 v21, v144, v145
	global_store_dwordx4 v[36:37], v[18:21], off
	v_add3_u32 v64, s0, v22, v230
	s_nop 0
	v_cvt_pk_bf16_f32 v18, v26, v27
	v_cvt_pk_bf16_f32 v19, v24, v25
	v_cvt_pk_bf16_f32 v20, v28, v29
	v_cvt_pk_bf16_f32 v21, v10, v11
	v_lshl_add_u64 v[10:11], s[86:87], 0, v[34:35]
	global_store_dwordx4 v[10:11], v[18:21], off
	ds_read_b32 v10, v30 offset:4224
	v_lshl_add_u64 v[34:35], s[36:37], 0, v[32:33]
	s_waitcnt lgkmcnt(0)
	v_pk_mul_f32 v[18:19], v[146:147], v[10:11] op_sel_hi:[1,0]
	v_pk_mul_f32 v[20:21], v[148:149], v[10:11] op_sel_hi:[1,0]
	v_pk_fma_f32 v[26:27], v[14:15], v[18:19], v[4:5]
	v_pk_mul_f32 v[18:19], v[150:151], v[10:11] op_sel_hi:[1,0]
	v_pk_mul_f32 v[10:11], v[152:153], v[10:11] op_sel_hi:[1,0]
	v_pk_fma_f32 v[24:25], v[12:13], v[20:21], v[6:7]
	v_pk_fma_f32 v[10:11], v[8:9], v[10:11], v[2:3]
	v_pk_fma_f32 v[28:29], v[16:17], v[18:19], v[0:1]
	v_cvt_pk_bf16_f32 v18, v146, v147
	v_cvt_pk_bf16_f32 v19, v148, v149
	v_cvt_pk_bf16_f32 v20, v150, v151
	v_cvt_pk_bf16_f32 v21, v152, v153
	global_store_dwordx4 v[34:35], v[18:21], off
	s_nop 1
	v_cvt_pk_bf16_f32 v18, v26, v27
	v_cvt_pk_bf16_f32 v19, v24, v25
	v_cvt_pk_bf16_f32 v20, v28, v29
	v_cvt_pk_bf16_f32 v21, v10, v11
	v_lshl_add_u64 v[10:11], s[86:87], 0, v[32:33]
	global_store_dwordx4 v[10:11], v[18:21], off
	ds_read_b32 v10, v30 offset:4288
	v_lshlrev_b64 v[28:29], 1, v[64:65]
	v_lshl_add_u64 v[32:33], s[36:37], 0, v[28:29]
	v_add3_u32 v64, s0, v44, v230
	s_waitcnt lgkmcnt(0)
	v_pk_mul_f32 v[18:19], v[154:155], v[10:11] op_sel_hi:[1,0]
	v_pk_mul_f32 v[20:21], v[156:157], v[10:11] op_sel_hi:[1,0]
	v_pk_fma_f32 v[24:25], v[14:15], v[18:19], v[4:5]
	v_pk_mul_f32 v[18:19], v[158:159], v[10:11] op_sel_hi:[1,0]
	v_pk_mul_f32 v[10:11], v[160:161], v[10:11] op_sel_hi:[1,0]
	v_pk_fma_f32 v[22:23], v[12:13], v[20:21], v[6:7]
	v_pk_fma_f32 v[10:11], v[8:9], v[10:11], v[2:3]
	v_pk_fma_f32 v[26:27], v[16:17], v[18:19], v[0:1]
	v_cvt_pk_bf16_f32 v18, v154, v155
	v_cvt_pk_bf16_f32 v19, v156, v157
	v_cvt_pk_bf16_f32 v20, v158, v159
	v_cvt_pk_bf16_f32 v21, v160, v161
	global_store_dwordx4 v[32:33], v[18:21], off
	s_nop 1
	v_cvt_pk_bf16_f32 v18, v24, v25
	v_cvt_pk_bf16_f32 v19, v22, v23
	v_cvt_pk_bf16_f32 v20, v26, v27
	v_cvt_pk_bf16_f32 v21, v10, v11
	v_lshl_add_u64 v[10:11], s[86:87], 0, v[28:29]
	global_store_dwordx4 v[10:11], v[18:21], off
	ds_read_b32 v10, v30 offset:4608
	v_lshlrev_b64 v[28:29], 1, v[64:65]
	v_lshl_add_u64 v[32:33], s[36:37], 0, v[28:29]
	v_add3_u32 v64, s0, v45, v230
	s_waitcnt lgkmcnt(0)
; __device__ __forceinline__ unsigned pk2(float lo, float hi) { f32x2_t v = {lo, hi}; bf16x2_t b = __builtin_convertvector(v, bf16x2_t); return __builtin_bit_cast(unsigned, b); }
;     __device__ __forceinline__ void fused(f32x4 (&acc)[2][2][4][2], const Unit& u, int wr, int wc, int fr, int fq, LAS unsigned char* lds, int wid, int lane) const {
;     ...
; #pragma unroll
;             for (int ai = 0; ai < 2; ++ai)
; #pragma unroll
;                 for (int m = 0; m < 4; ++m) {
;                     const int r = ai * 128 + wr * 64 + m * 16 + fr;
;                     const unsigned off = (unsigned)((u.pm * 256 + r) * DM + col);
;                     const f32x4 x0 = acc[ai][bj][m][0], x1 = acc[ai][bj][m][1];
;                     const float rs = S[r];
;                     const f32x4 y0 = x0 * rs * gv0 + sh0, y1 = x1 * rs * gv1 + sh1;
;                     if (mode == 0) {
;                         u32x4 xw; xw.x = pk2(x0[0], x0[1]); xw.y = pk2(x0[2], x0[3]); xw.z = pk2(x1[0], x1[1]); xw.w = pk2(x1[2], x1[3]);
;                         *(u32x4*)(xout16 + off) = xw;
;                         u32x4 hw; hw.x = pk2(y0[0], y0[1]); hw.y = pk2(y0[2], y0[3]); hw.z = pk2(y1[0], y1[1]); hw.w = pk2(y1[2], y1[3]);
;                         *(u32x4*)(hout + off) = hw;
	v_pk_mul_f32 v[18:19], v[162:163], v[10:11] op_sel_hi:[1,0]
	v_pk_mul_f32 v[20:21], v[164:165], v[10:11] op_sel_hi:[1,0]
	v_pk_fma_f32 v[24:25], v[14:15], v[18:19], v[4:5]
	v_pk_mul_f32 v[18:19], v[166:167], v[10:11] op_sel_hi:[1,0]
	v_pk_mul_f32 v[10:11], v[168:169], v[10:11] op_sel_hi:[1,0]
	v_pk_fma_f32 v[22:23], v[12:13], v[20:21], v[6:7]
	v_pk_fma_f32 v[10:11], v[8:9], v[10:11], v[2:3]
	v_pk_fma_f32 v[26:27], v[16:17], v[18:19], v[0:1]
	v_cvt_pk_bf16_f32 v18, v162, v163
	v_cvt_pk_bf16_f32 v19, v164, v165
	v_cvt_pk_bf16_f32 v20, v166, v167
	v_cvt_pk_bf16_f32 v21, v168, v169
	global_store_dwordx4 v[32:33], v[18:21], off
	s_nop 1
	v_cvt_pk_bf16_f32 v18, v24, v25
	v_cvt_pk_bf16_f32 v19, v22, v23
	v_cvt_pk_bf16_f32 v20, v26, v27
	v_cvt_pk_bf16_f32 v21, v10, v11
	v_lshl_add_u64 v[10:11], s[86:87], 0, v[28:29]
	global_store_dwordx4 v[10:11], v[18:21], off
	ds_read_b32 v10, v30 offset:4672
	v_lshlrev_b64 v[28:29], 1, v[64:65]
	v_lshl_add_u64 v[32:33], s[36:37], 0, v[28:29]
	v_add3_u32 v64, s0, v46, v230
	s_waitcnt lgkmcnt(0)
	v_pk_mul_f32 v[18:19], v[170:171], v[10:11] op_sel_hi:[1,0]
	v_pk_mul_f32 v[20:21], v[172:173], v[10:11] op_sel_hi:[1,0]
	v_pk_fma_f32 v[24:25], v[14:15], v[18:19], v[4:5]
	v_pk_mul_f32 v[18:19], v[174:175], v[10:11] op_sel_hi:[1,0]
	v_pk_mul_f32 v[10:11], v[176:177], v[10:11] op_sel_hi:[1,0]
	v_pk_fma_f32 v[22:23], v[12:13], v[20:21], v[6:7]
	v_pk_fma_f32 v[10:11], v[8:9], v[10:11], v[2:3]
	v_pk_fma_f32 v[26:27], v[16:17], v[18:19], v[0:1]
	v_cvt_pk_bf16_f32 v18, v170, v171
	v_cvt_pk_bf16_f32 v19, v172, v173
	v_cvt_pk_bf16_f32 v20, v174, v175
	v_cvt_pk_bf16_f32 v21, v176, v177
	global_store_dwordx4 v[32:33], v[18:21], off
	s_nop 1
	v_cvt_pk_bf16_f32 v18, v24, v25
	v_cvt_pk_bf16_f32 v19, v22, v23
	v_cvt_pk_bf16_f32 v20, v26, v27
	v_cvt_pk_bf16_f32 v21, v10, v11
	v_lshl_add_u64 v[10:11], s[86:87], 0, v[28:29]
	global_store_dwordx4 v[10:11], v[18:21], off
	ds_read_b32 v10, v30 offset:4736
	v_lshlrev_b64 v[28:29], 1, v[64:65]
	v_lshl_add_u64 v[32:33], s[36:37], 0, v[28:29]
	v_add3_u32 v64, s0, v38, v230
	s_waitcnt lgkmcnt(0)
	v_pk_mul_f32 v[18:19], v[178:179], v[10:11] op_sel_hi:[1,0]
	v_pk_mul_f32 v[20:21], v[180:181], v[10:11] op_sel_hi:[1,0]
	v_pk_fma_f32 v[24:25], v[14:15], v[18:19], v[4:5]
	v_pk_mul_f32 v[18:19], v[182:183], v[10:11] op_sel_hi:[1,0]
	v_pk_mul_f32 v[10:11], v[184:185], v[10:11] op_sel_hi:[1,0]
	v_pk_fma_f32 v[22:23], v[12:13], v[20:21], v[6:7]
	v_pk_fma_f32 v[10:11], v[8:9], v[10:11], v[2:3]
	v_pk_fma_f32 v[26:27], v[16:17], v[18:19], v[0:1]
	v_cvt_pk_bf16_f32 v18, v178, v179
	v_cvt_pk_bf16_f32 v19, v180, v181
	v_cvt_pk_bf16_f32 v20, v182, v183
	v_cvt_pk_bf16_f32 v21, v184, v185
	global_store_dwordx4 v[32:33], v[18:21], off
	s_nop 1
	v_cvt_pk_bf16_f32 v18, v24, v25
	v_cvt_pk_bf16_f32 v19, v22, v23
	v_cvt_pk_bf16_f32 v20, v26, v27
	v_cvt_pk_bf16_f32 v21, v10, v11
	v_lshl_add_u64 v[10:11], s[86:87], 0, v[28:29]
	global_store_dwordx4 v[10:11], v[18:21], off
	ds_read_b32 v10, v30 offset:4800
	s_waitcnt lgkmcnt(0)
	v_pk_mul_f32 v[20:21], v[188:189], v[10:11] op_sel_hi:[1,0]
	v_pk_mul_f32 v[18:19], v[186:187], v[10:11] op_sel_hi:[1,0]
	v_pk_fma_f32 v[6:7], v[12:13], v[20:21], v[6:7]
	v_pk_mul_f32 v[12:13], v[190:191], v[10:11] op_sel_hi:[1,0]
	v_pk_mul_f32 v[10:11], v[192:193], v[10:11] op_sel_hi:[1,0]
	v_pk_fma_f32 v[4:5], v[14:15], v[18:19], v[4:5]
	v_pk_fma_f32 v[8:9], v[8:9], v[10:11], v[2:3]
	v_pk_fma_f32 v[10:11], v[16:17], v[12:13], v[0:1]
	v_lshlrev_b64 v[12:13], 1, v[64:65]
	v_cvt_pk_bf16_f32 v0, v186, v187
	v_cvt_pk_bf16_f32 v1, v188, v189
	v_cvt_pk_bf16_f32 v2, v190, v191
	v_cvt_pk_bf16_f32 v3, v192, v193
	v_lshl_add_u64 v[14:15], s[36:37], 0, v[12:13]
	global_store_dwordx4 v[14:15], v[0:3], off
	s_nop 1
	v_cvt_pk_bf16_f32 v0, v4, v5
	v_cvt_pk_bf16_f32 v1, v6, v7
	v_cvt_pk_bf16_f32 v2, v10, v11
	v_cvt_pk_bf16_f32 v3, v8, v9
	v_lshl_add_u64 v[4:5], s[86:87], 0, v[12:13]
	global_store_dwordx4 v[4:5], v[0:3], off

; __device__ __forceinline__ unsigned pk2(float lo, float hi) { f32x2_t v = {lo, hi}; bf16x2_t b = __builtin_convertvector(v, bf16x2_t); return __builtin_bit_cast(unsigned, b); }
; __device__ __forceinline__ void store_o(const f32x16 (&o)[2], float inv, bf16_t* orow, const WaveCtx& c) {
; #pragma unroll
;     for (int dt = 0; dt < 2; ++dt)
; #pragma unroll
;         for (int r4 = 0; r4 < 4; ++r4) {
;             u32x2 w; w.x = pk2(o[dt][4 * r4] * inv, o[dt][4 * r4 + 1] * inv); w.y = pk2(o[dt][4 * r4 + 2] * inv, o[dt][4 * r4 + 3] * inv);
;             *(u32x2*)(orow + 32 * dt + 8 * r4 + 4 * c.h) = w;
;         }
; }
.LBB0_439:
	v_readlane_b32 s0, v254, 27
	v_readlane_b32 s1, v254, 28
	s_lshl_b64 s[0:1], s[0:1], 1
	s_waitcnt lgkmcnt(0)
	v_rcp_f32_e32 v32, v170
	s_add_u32 s0, s30, s0
	s_addc_u32 s1, s31, s1
	v_readlane_b32 s2, v254, 31
	v_mov_b64_e32 v[34:35], s[0:1]
	v_lshlrev_b32_e32 v64, 1, v213
	v_add_u32_e32 v33, s2, v172
	v_mad_i64_i32 v[34:35], s[0:1], v33, s96, v[34:35]
	v_pk_mul_f32 v[16:17], v[16:17], v[32:33] op_sel_hi:[1,0]
	v_pk_mul_f32 v[18:19], v[18:19], v[32:33] op_sel_hi:[1,0]
	v_pk_mul_f32 v[0:1], v[0:1], v[32:33] op_sel_hi:[1,0]
	v_pk_mul_f32 v[2:3], v[2:3], v[32:33] op_sel_hi:[1,0]
	v_cvt_pk_bf16_f32 v16, v16, v17
	v_cvt_pk_bf16_f32 v17, v18, v19
	v_lshl_add_u64 v[18:19], v[34:35], 0, v[64:65]
	v_cvt_pk_bf16_f32 v0, v0, v1
	v_cvt_pk_bf16_f32 v1, v2, v3
	global_store_dwordx2 v[18:19], v[16:17], off
	v_pk_mul_f32 v[16:17], v[20:21], v[32:33] op_sel_hi:[1,0]
	v_pk_mul_f32 v[20:21], v[22:23], v[32:33] op_sel_hi:[1,0]
	global_store_dwordx2 v[18:19], v[0:1], off offset:64
	v_pk_mul_f32 v[0:1], v[4:5], v[32:33] op_sel_hi:[1,0]
	v_pk_mul_f32 v[2:3], v[6:7], v[32:33] op_sel_hi:[1,0]
	v_cvt_pk_bf16_f32 v16, v16, v17
	v_cvt_pk_bf16_f32 v17, v20, v21
	v_cvt_pk_bf16_f32 v0, v0, v1
	v_cvt_pk_bf16_f32 v1, v2, v3
	global_store_dwordx2 v[18:19], v[16:17], off offset:16
	v_pk_mul_f32 v[16:17], v[24:25], v[32:33] op_sel_hi:[1,0]
	v_pk_mul_f32 v[20:21], v[26:27], v[32:33] op_sel_hi:[1,0]
	global_store_dwordx2 v[18:19], v[0:1], off offset:80
	v_pk_mul_f32 v[0:1], v[8:9], v[32:33] op_sel_hi:[1,0]
	v_pk_mul_f32 v[2:3], v[10:11], v[32:33] op_sel_hi:[1,0]
	v_cvt_pk_bf16_f32 v16, v16, v17
	v_cvt_pk_bf16_f32 v17, v20, v21
	v_cvt_pk_bf16_f32 v0, v0, v1
	v_cvt_pk_bf16_f32 v1, v2, v3
	global_store_dwordx2 v[18:19], v[16:17], off offset:32
	v_pk_mul_f32 v[16:17], v[28:29], v[32:33] op_sel_hi:[1,0]
	v_pk_mul_f32 v[20:21], v[30:31], v[32:33] op_sel_hi:[1,0]
	global_store_dwordx2 v[18:19], v[0:1], off offset:96
	v_pk_mul_f32 v[0:1], v[12:13], v[32:33] op_sel_hi:[1,0]
	v_pk_mul_f32 v[2:3], v[14:15], v[32:33] op_sel_hi:[1,0]
	v_cvt_pk_bf16_f32 v16, v16, v17
	v_cvt_pk_bf16_f32 v17, v20, v21
	v_cvt_pk_bf16_f32 v0, v0, v1
	v_cvt_pk_bf16_f32 v1, v2, v3
	s_movk_i32 s46, 0x80
	global_store_dwordx2 v[18:19], v[16:17], off offset:48
	global_store_dwordx2 v[18:19], v[0:1], off offset:112
	s_waitcnt lgkmcnt(0)
	s_barrier

; __device__ __forceinline__ unsigned pk2(float lo, float hi) { f32x2_t v = {lo, hi}; bf16x2_t b = __builtin_convertvector(v, bf16x2_t); return __builtin_bit_cast(unsigned, b); }
; __device__ __forceinline__ void store_o(const f32x16 (&o)[2], float inv, bf16_t* orow, const WaveCtx& c) {
; #pragma unroll
;     for (int dt = 0; dt < 2; ++dt)
; #pragma unroll
;         for (int r4 = 0; r4 < 4; ++r4) {
;             u32x2 w; w.x = pk2(o[dt][4 * r4] * inv, o[dt][4 * r4 + 1] * inv); w.y = pk2(o[dt][4 * r4 + 2] * inv, o[dt][4 * r4 + 3] * inv);
;             *(u32x2*)(orow + 32 * dt + 8 * r4 + 4 * c.h) = w;
;         }
; }
.LBB0_506:
	v_rcp_f32_e32 v0, v162
	v_lshl_add_u32 v1, s91, 11, v151
	v_mov_b64_e32 v[2:3], s[50:51]
	s_movk_i32 s96, 0x300
	v_mad_i64_i32 v[2:3], s[0:1], v1, s96, v[2:3]
	s_mov_b32 s59, s81
	v_lshl_add_u64 v[2:3], v[2:3], 0, s[58:59]
	v_pk_mul_f32 v[4:5], v[0:1], v[66:67] op_sel_hi:[0,1]
	v_pk_mul_f32 v[6:7], v[0:1], v[68:69] op_sel_hi:[0,1]
	v_lshlrev_b32_e32 v64, 1, v154
	v_cvt_pk_bf16_f32 v4, v4, v5
	v_cvt_pk_bf16_f32 v5, v6, v7
	v_lshl_add_u64 v[2:3], v[2:3], 0, v[64:65]
	global_store_dwordx2 v[2:3], v[4:5], off
	v_pk_mul_f32 v[4:5], v[0:1], v[70:71] op_sel_hi:[0,1]
	v_pk_mul_f32 v[6:7], v[0:1], v[72:73] op_sel_hi:[0,1]
	v_cvt_pk_bf16_f32 v4, v4, v5
	v_cvt_pk_bf16_f32 v5, v6, v7
	global_store_dwordx2 v[2:3], v[4:5], off offset:16
	v_pk_mul_f32 v[4:5], v[0:1], v[74:75] op_sel_hi:[0,1]
	v_pk_mul_f32 v[6:7], v[0:1], v[76:77] op_sel_hi:[0,1]
	v_cvt_pk_bf16_f32 v4, v4, v5
	v_cvt_pk_bf16_f32 v5, v6, v7
	global_store_dwordx2 v[2:3], v[4:5], off offset:32
	v_pk_mul_f32 v[4:5], v[0:1], v[78:79] op_sel_hi:[0,1]
	v_pk_mul_f32 v[6:7], v[0:1], v[80:81] op_sel_hi:[0,1]
	v_cvt_pk_bf16_f32 v4, v4, v5
	v_cvt_pk_bf16_f32 v5, v6, v7
	global_store_dwordx2 v[2:3], v[4:5], off offset:48
	v_pk_mul_f32 v[4:5], v[0:1], v[48:49] op_sel_hi:[0,1]
	v_pk_mul_f32 v[6:7], v[0:1], v[50:51] op_sel_hi:[0,1]
	v_cvt_pk_bf16_f32 v4, v4, v5
	v_cvt_pk_bf16_f32 v5, v6, v7
	global_store_dwordx2 v[2:3], v[4:5], off offset:64
	v_pk_mul_f32 v[4:5], v[0:1], v[52:53] op_sel_hi:[0,1]
	v_pk_mul_f32 v[6:7], v[0:1], v[54:55] op_sel_hi:[0,1]
	v_cvt_pk_bf16_f32 v4, v4, v5
	v_cvt_pk_bf16_f32 v5, v6, v7
	global_store_dwordx2 v[2:3], v[4:5], off offset:80
	v_pk_mul_f32 v[4:5], v[0:1], v[56:57] op_sel_hi:[0,1]
	v_pk_mul_f32 v[6:7], v[0:1], v[58:59] op_sel_hi:[0,1]
	v_cvt_pk_bf16_f32 v4, v4, v5
	v_cvt_pk_bf16_f32 v5, v6, v7
	global_store_dwordx2 v[2:3], v[4:5], off offset:96
	v_pk_mul_f32 v[4:5], v[0:1], v[60:61] op_sel_hi:[0,1]
	v_pk_mul_f32 v[0:1], v[0:1], v[62:63] op_sel_hi:[0,1]
	v_readlane_b32 s62, v255, 29
	v_cvt_pk_bf16_f32 v4, v4, v5
	v_cvt_pk_bf16_f32 v5, v0, v1
	s_mov_b64 s[2:3], 0
	v_readlane_b32 s63, v255, 30
	s_movk_i32 s58, 0x90
	v_readlane_b32 s34, v255, 63
	global_store_dwordx2 v[2:3], v[4:5], off offset:112

; #define PG8_STAGE(bufoff, gbase, voff) do { _Pragma("unroll") for (int _i = 0; _i < 2; ++_i) \
;         __builtin_amdgcn_global_load_lds((const unsigned*)((const char*)(gbase) + (voff)[_i]), (PG8_LAS unsigned*)(lds + (bufoff) + ldsw + _i * 8192), 16, 0, 0); } while (0)
; #define PG8_LDA(dst, b, h) do { _Pragma("unroll") for (int m = 0; m < 4; ++m) _Pragma("unroll") for (int k = 0; k < 2; ++k) dst[m][k] = *(const PG8_LAS bf16x8*)(lds + PG8_SA(b, h) + aoff + m * 2048 + k * 1024); } while (0)
; #define PG8_LDB(dst, b, h) do { _Pragma("unroll") for (int n = 0; n < 2; ++n) _Pragma("unroll") for (int k = 0; k < 2; ++k) dst[n][k] = *(const PG8_LAS bf16x8*)(lds + PG8_SB(b, h) + boff + n * 2048 + k * 1024); } while (0)
; #define PG8_MMA(ai, bj, At, Bt) do { __builtin_amdgcn_s_setprio(1); _Pragma("unroll") for (int m = 0; m < 4; ++m) _Pragma("unroll") for (int n = 0; n < 2; ++n) _Pragma("unroll") for (int k = 0; k < 2; ++k) \
;         acc[ai][bj][m][n] = __builtin_amdgcn_mfma_f32_16x16x32_bf16(Bt[n][k], At[m][k], acc[ai][bj][m][n], 0, 0, 0); __builtin_amdgcn_s_setprio(0); } while (0)
; #define PG8_WAIT_V(n) asm volatile("s_waitcnt vmcnt(" #n ")" ::: "memory")
; #define PG8_WAIT_L(n) asm volatile("s_waitcnt lgkmcnt(" #n ")" ::: "memory")
; #define PG8_BAR __builtin_amdgcn_s_barrier()
; #define PG8_SCHED __builtin_amdgcn_sched_barrier(0)
; template <class Epi, class Sched, bool ALIGN_EPI = false, bool SP2 = false>
; __device__ __forceinline__ void gemm_phase(PG8_LAS unsigned char* lds, const Gemm g, const Sched& S, const Epi& E, const int tid) {
;     ...
;             PG8_LDB(B0, 0, 0); PG8_LDB(B1, 0, 1); PG8_SCHED; PG8_LDA(At, 0, 0); PG8_STAGE(PG8_SA(1, 1), a1 + hstep, voffA);
;             PG8_WAIT_V(8); PG8_WAIT_L(0); PG8_BAR; PG8_MMA(0, 0, At, B0); PG8_MMA(0, 1, At, B1); PG8_BAR; PG8_SCHED;
;             PG8_LDA(At, 0, 1); PG8_STAGE(PG8_SB(0, 0), b2, voffB); PG8_STAGE(PG8_SB(0, 1), b2 + hstep, voffB); PG8_STAGE(PG8_SA(0, 0), a2, voffA);
.LBB0_511:
	s_add_u32 s6, s24, s4
	s_addc_u32 s7, s25, s5
	s_add_u32 s6, s6, 0x2c00100
	s_addc_u32 s7, s7, 0
	s_add_u32 s27, s22, s4
	s_addc_u32 s28, s23, s5
	s_add_i32 s29, 0, 0x10000
	s_cmpk_eq_i32 s4, 0x700
	s_cselect_b32 s9, s3, s7
	s_cselect_b32 s8, s2, s6
	v_add_u32_e32 v149, s29, v142
	s_cselect_b32 s7, s1, s28
	s_cselect_b32 s6, s0, s27
	s_add_i32 s27, 0, 0x14000
	ds_read_b128 v[144:147], v149
	ds_read_b128 v[150:153], v149 offset:1024
	ds_read_b128 v[154:157], v149 offset:2048
	ds_read_b128 v[158:161], v149 offset:3072
	v_add_u32_e32 v149, s27, v142
	ds_read_b128 v[162:165], v149
	ds_read_b128 v[166:169], v149 offset:1024
	ds_read_b128 v[170:173], v149 offset:2048
	ds_read_b128 v[174:177], v149 offset:3072
	v_lshl_add_u64 v[202:203], v[138:139], 0, s[4:5]
	s_add_i32 m0, s13, 0xc000
	ds_read_b128 v[178:181], v143
	ds_read_b128 v[182:185], v143 offset:1024
	ds_read_b128 v[186:189], v143 offset:2048
	ds_read_b128 v[190:193], v143 offset:3072
	ds_read_b128 v[194:197], v143 offset:4096
	ds_read_b128 v[198:201], v143 offset:5120
	ds_read_b128 v[214:217], v143 offset:6144
	ds_read_b128 v[218:221], v143 offset:7168
	global_load_lds_dwordx4 v[202:203], off
	v_lshl_add_u64 v[202:203], v[136:137], 0, s[4:5]
	s_add_i32 m0, s13, 0xe000
	s_nop 0
	global_load_lds_dwordx4 v[202:203], off
	s_waitcnt vmcnt(8)
	s_waitcnt lgkmcnt(0)
	s_barrier
	s_setprio 1
	s_waitcnt lgkmcnt(0)
	v_mfma_f32_16x16x32_bf16 v[126:129], v[144:147], v[178:181], v[126:129]
	v_mfma_f32_16x16x32_bf16 v[122:125], v[154:157], v[178:181], v[122:125]
	v_mfma_f32_16x16x32_bf16 v[118:121], v[144:147], v[186:189], v[118:121]
	v_mfma_f32_16x16x32_bf16 v[114:117], v[154:157], v[186:189], v[114:117]
	v_mfma_f32_16x16x32_bf16 v[110:113], v[144:147], v[194:197], v[110:113]
	v_mfma_f32_16x16x32_bf16 v[106:109], v[154:157], v[194:197], v[106:109]
	v_mfma_f32_16x16x32_bf16 v[102:105], v[144:147], v[214:217], v[102:105]
	v_mfma_f32_16x16x32_bf16 v[98:101], v[154:157], v[214:217], v[98:101]
	v_mfma_f32_16x16x32_bf16 v[126:129], v[150:153], v[182:185], v[126:129]
	v_mfma_f32_16x16x32_bf16 v[122:125], v[158:161], v[182:185], v[122:125]
	v_mfma_f32_16x16x32_bf16 v[118:121], v[150:153], v[190:193], v[118:121]
	v_mfma_f32_16x16x32_bf16 v[114:117], v[158:161], v[190:193], v[114:117]
	v_mfma_f32_16x16x32_bf16 v[110:113], v[150:153], v[198:201], v[110:113]
	v_mfma_f32_16x16x32_bf16 v[106:109], v[158:161], v[198:201], v[106:109]
	v_mfma_f32_16x16x32_bf16 v[102:105], v[150:153], v[218:221], v[102:105]
	v_mfma_f32_16x16x32_bf16 v[98:101], v[158:161], v[218:221], v[98:101]
	s_setprio 0
	s_setprio 1
	v_mfma_f32_16x16x32_bf16 v[60:63], v[162:165], v[178:181], v[60:63]
	v_mfma_f32_16x16x32_bf16 v[56:59], v[170:173], v[178:181], v[56:59]
	v_mfma_f32_16x16x32_bf16 v[52:55], v[162:165], v[186:189], v[52:55]
	v_mfma_f32_16x16x32_bf16 v[48:51], v[170:173], v[186:189], v[48:51]
	v_mfma_f32_16x16x32_bf16 v[44:47], v[162:165], v[194:197], v[44:47]
	v_mfma_f32_16x16x32_bf16 v[40:43], v[170:173], v[194:197], v[40:43]
	v_mfma_f32_16x16x32_bf16 v[36:39], v[162:165], v[214:217], v[36:39]
	v_mfma_f32_16x16x32_bf16 v[32:35], v[170:173], v[214:217], v[32:35]
	v_mfma_f32_16x16x32_bf16 v[60:63], v[166:169], v[182:185], v[60:63]
	v_mfma_f32_16x16x32_bf16 v[56:59], v[174:177], v[182:185], v[56:59]
	v_mfma_f32_16x16x32_bf16 v[52:55], v[166:169], v[190:193], v[52:55]
	v_mfma_f32_16x16x32_bf16 v[48:51], v[174:177], v[190:193], v[48:51]
	v_mfma_f32_16x16x32_bf16 v[44:47], v[166:169], v[198:201], v[44:47]
	v_mfma_f32_16x16x32_bf16 v[40:43], v[174:177], v[198:201], v[40:43]
	v_mfma_f32_16x16x32_bf16 v[36:39], v[166:169], v[218:221], v[36:39]
	v_mfma_f32_16x16x32_bf16 v[32:35], v[174:177], v[218:221], v[32:35]
	s_setprio 0
	s_barrier
	s_add_i32 s28, s29, s12
	v_lshl_add_u64 v[202:203], s[6:7], 0, v[64:65]
	s_mov_b32 m0, s28
	ds_read_b128 v[178:181], v143 offset:16384
	ds_read_b128 v[182:185], v143 offset:17408
	ds_read_b128 v[186:189], v143 offset:18432
	ds_read_b128 v[190:193], v143 offset:19456
	ds_read_b128 v[194:197], v143 offset:20480
	ds_read_b128 v[198:201], v143 offset:21504
	ds_read_b128 v[214:217], v143 offset:22528
	ds_read_b128 v[218:221], v143 offset:23552
	global_load_lds_dwordx4 v[202:203], off
	s_add_i32 m0, s28, 0x2000
	s_add_u32 s28, s6, 0x40000
	v_lshl_add_u64 v[206:207], s[6:7], 0, v[134:135]
	s_addc_u32 s29, s7, 0
	s_add_i32 s27, s27, s12
	global_load_lds_dwordx4 v[206:207], off
	v_lshl_add_u64 v[208:209], s[28:29], 0, v[64:65]
	s_mov_b32 m0, s27
	v_lshl_add_u64 v[222:223], s[8:9], 0, v[132:133]
	global_load_lds_dwordx4 v[208:209], off
	v_lshl_add_u64 v[208:209], s[28:29], 0, v[134:135]
	s_add_i32 m0, s27, 0x2000
	s_nop 0
	global_load_lds_dwordx4 v[208:209], off
	v_lshl_add_u64 v[208:209], s[8:9], 0, v[130:131]
	s_mov_b32 m0, s13
	s_nop 0
	global_load_lds_dwordx4 v[208:209], off
	s_mov_b32 m0, s16
	s_nop 0
	global_load_lds_dwordx4 v[222:223], off
	s_waitcnt vmcnt(8)
	s_waitcnt lgkmcnt(0)
	s_barrier
; #define PG8_STAGE(bufoff, gbase, voff) do { _Pragma("unroll") for (int _i = 0; _i < 2; ++_i) \
;         __builtin_amdgcn_global_load_lds((const unsigned*)((const char*)(gbase) + (voff)[_i]), (PG8_LAS unsigned*)(lds + (bufoff) + ldsw + _i * 8192), 16, 0, 0); } while (0)
; #define PG8_LDA(dst, b, h) do { _Pragma("unroll") for (int m = 0; m < 4; ++m) _Pragma("unroll") for (int k = 0; k < 2; ++k) dst[m][k] = *(const PG8_LAS bf16x8*)(lds + PG8_SA(b, h) + aoff + m * 2048 + k * 1024); } while (0)
; #define PG8_LDB(dst, b, h) do { _Pragma("unroll") for (int n = 0; n < 2; ++n) _Pragma("unroll") for (int k = 0; k < 2; ++k) dst[n][k] = *(const PG8_LAS bf16x8*)(lds + PG8_SB(b, h) + boff + n * 2048 + k * 1024); } while (0)
; #define PG8_MMA(ai, bj, At, Bt) do { __builtin_amdgcn_s_setprio(1); _Pragma("unroll") for (int m = 0; m < 4; ++m) _Pragma("unroll") for (int n = 0; n < 2; ++n) _Pragma("unroll") for (int k = 0; k < 2; ++k) \
;         acc[ai][bj][m][n] = __builtin_amdgcn_mfma_f32_16x16x32_bf16(Bt[n][k], At[m][k], acc[ai][bj][m][n], 0, 0, 0); __builtin_amdgcn_s_setprio(0); } while (0)
; #define PG8_WAIT_V(n) asm volatile("s_waitcnt vmcnt(" #n ")" ::: "memory")
; #define PG8_WAIT_L(n) asm volatile("s_waitcnt lgkmcnt(" #n ")" ::: "memory")
; #define PG8_BAR __builtin_amdgcn_s_barrier()
; #define PG8_SCHED __builtin_amdgcn_sched_barrier(0)
; template <class Epi, class Sched, bool ALIGN_EPI = false, bool SP2 = false>
; __device__ __forceinline__ void gemm_phase(PG8_LAS unsigned char* lds, const Gemm g, const Sched& S, const Epi& E, const int tid) {
;     ...
;             PG8_WAIT_V(8); PG8_WAIT_L(0); PG8_BAR; PG8_MMA(1, 0, At, B0); PG8_MMA(1, 1, At, B1); PG8_BAR; PG8_SCHED;
;             PG8_LDB(B0, 1, 0); PG8_LDB(B1, 1, 1); PG8_SCHED; PG8_LDA(At, 1, 0); PG8_STAGE(PG8_SA(0, 1), a2 + hstep, voffA);
;             PG8_WAIT_V(8); PG8_WAIT_L(0); PG8_BAR; PG8_MMA(0, 0, At, B0); PG8_MMA(0, 1, At, B1); PG8_BAR; PG8_SCHED;
	s_setprio 1
	s_waitcnt lgkmcnt(0)
	v_mfma_f32_16x16x32_bf16 v[94:97], v[144:147], v[178:181], v[94:97]
	v_mfma_f32_16x16x32_bf16 v[90:93], v[154:157], v[178:181], v[90:93]
	v_mfma_f32_16x16x32_bf16 v[86:89], v[144:147], v[186:189], v[86:89]
	v_mfma_f32_16x16x32_bf16 v[82:85], v[154:157], v[186:189], v[82:85]
	v_mfma_f32_16x16x32_bf16 v[78:81], v[144:147], v[194:197], v[78:81]
	v_mfma_f32_16x16x32_bf16 v[74:77], v[154:157], v[194:197], v[74:77]
	v_mfma_f32_16x16x32_bf16 v[70:73], v[144:147], v[214:217], v[70:73]
	v_mfma_f32_16x16x32_bf16 v[66:69], v[154:157], v[214:217], v[66:69]
	v_mfma_f32_16x16x32_bf16 v[94:97], v[150:153], v[182:185], v[94:97]
	v_mfma_f32_16x16x32_bf16 v[90:93], v[158:161], v[182:185], v[90:93]
	v_mfma_f32_16x16x32_bf16 v[86:89], v[150:153], v[190:193], v[86:89]
	v_mfma_f32_16x16x32_bf16 v[82:85], v[158:161], v[190:193], v[82:85]
	v_mfma_f32_16x16x32_bf16 v[78:81], v[150:153], v[198:201], v[78:81]
	v_mfma_f32_16x16x32_bf16 v[74:77], v[158:161], v[198:201], v[74:77]
	v_mfma_f32_16x16x32_bf16 v[70:73], v[150:153], v[218:221], v[70:73]
	v_mfma_f32_16x16x32_bf16 v[66:69], v[158:161], v[218:221], v[66:69]
	s_setprio 0
	s_setprio 1
	v_mfma_f32_16x16x32_bf16 v[28:31], v[162:165], v[178:181], v[28:31]
	v_mfma_f32_16x16x32_bf16 v[24:27], v[170:173], v[178:181], v[24:27]
	v_mfma_f32_16x16x32_bf16 v[20:23], v[162:165], v[186:189], v[20:23]
	v_mfma_f32_16x16x32_bf16 v[16:19], v[170:173], v[186:189], v[16:19]
	v_mfma_f32_16x16x32_bf16 v[12:15], v[162:165], v[194:197], v[12:15]
	v_mfma_f32_16x16x32_bf16 v[8:11], v[170:173], v[194:197], v[8:11]
	v_mfma_f32_16x16x32_bf16 v[4:7], v[162:165], v[214:217], v[4:7]
	v_mfma_f32_16x16x32_bf16 v[0:3], v[170:173], v[214:217], v[0:3]
	v_mfma_f32_16x16x32_bf16 v[28:31], v[166:169], v[182:185], v[28:31]
	v_mfma_f32_16x16x32_bf16 v[24:27], v[174:177], v[182:185], v[24:27]
	v_mfma_f32_16x16x32_bf16 v[20:23], v[166:169], v[190:193], v[20:23]
	v_mfma_f32_16x16x32_bf16 v[16:19], v[174:177], v[190:193], v[16:19]
	v_mfma_f32_16x16x32_bf16 v[12:15], v[166:169], v[198:201], v[12:15]
	v_mfma_f32_16x16x32_bf16 v[8:11], v[174:177], v[198:201], v[8:11]
	v_mfma_f32_16x16x32_bf16 v[4:7], v[166:169], v[218:221], v[4:7]
	v_mfma_f32_16x16x32_bf16 v[0:3], v[174:177], v[218:221], v[0:3]
	s_setprio 0
	s_barrier
	s_add_i32 s27, 0, 0x18000
	v_add_u32_e32 v149, s27, v142
	s_add_i32 s28, 0, 0x1c000
	ds_read_b128 v[144:147], v149
	ds_read_b128 v[150:153], v149 offset:1024
	ds_read_b128 v[154:157], v149 offset:2048
	ds_read_b128 v[158:161], v149 offset:3072
	v_add_u32_e32 v149, s28, v142
	ds_read_b128 v[162:165], v149
	ds_read_b128 v[166:169], v149 offset:1024
	ds_read_b128 v[170:173], v149 offset:2048
	ds_read_b128 v[174:177], v149 offset:3072
	s_add_u32 s8, s8, 0x40000
	s_addc_u32 s9, s9, 0
	s_mov_b32 m0, s17
	v_lshl_add_u64 v[224:225], s[8:9], 0, v[130:131]
	ds_read_b128 v[178:181], v143 offset:32768
	ds_read_b128 v[182:185], v143 offset:33792
	ds_read_b128 v[186:189], v143 offset:34816
	ds_read_b128 v[190:193], v143 offset:35840
	ds_read_b128 v[194:197], v143 offset:36864
	ds_read_b128 v[198:201], v143 offset:37888
	ds_read_b128 v[214:217], v143 offset:38912
	ds_read_b128 v[218:221], v143 offset:39936
	global_load_lds_dwordx4 v[224:225], off
	v_lshl_add_u64 v[224:225], s[8:9], 0, v[132:133]
	s_mov_b32 m0, s18
	s_nop 0
	global_load_lds_dwordx4 v[224:225], off
	s_waitcnt vmcnt(8)
	s_waitcnt lgkmcnt(0)
	s_barrier
	s_setprio 1
	s_waitcnt lgkmcnt(0)
	v_mfma_f32_16x16x32_bf16 v[126:129], v[144:147], v[178:181], v[126:129]
	v_mfma_f32_16x16x32_bf16 v[122:125], v[154:157], v[178:181], v[122:125]
	v_mfma_f32_16x16x32_bf16 v[118:121], v[144:147], v[186:189], v[118:121]
	v_mfma_f32_16x16x32_bf16 v[114:117], v[154:157], v[186:189], v[114:117]
	v_mfma_f32_16x16x32_bf16 v[110:113], v[144:147], v[194:197], v[110:113]
	v_mfma_f32_16x16x32_bf16 v[106:109], v[154:157], v[194:197], v[106:109]
	v_mfma_f32_16x16x32_bf16 v[102:105], v[144:147], v[214:217], v[102:105]
	v_mfma_f32_16x16x32_bf16 v[98:101], v[154:157], v[214:217], v[98:101]
	v_mfma_f32_16x16x32_bf16 v[126:129], v[150:153], v[182:185], v[126:129]
	v_mfma_f32_16x16x32_bf16 v[122:125], v[158:161], v[182:185], v[122:125]
	v_mfma_f32_16x16x32_bf16 v[118:121], v[150:153], v[190:193], v[118:121]
	v_mfma_f32_16x16x32_bf16 v[114:117], v[158:161], v[190:193], v[114:117]
	v_mfma_f32_16x16x32_bf16 v[110:113], v[150:153], v[198:201], v[110:113]
	v_mfma_f32_16x16x32_bf16 v[106:109], v[158:161], v[198:201], v[106:109]
	v_mfma_f32_16x16x32_bf16 v[102:105], v[150:153], v[218:221], v[102:105]
	v_mfma_f32_16x16x32_bf16 v[98:101], v[158:161], v[218:221], v[98:101]
	s_setprio 0
	s_setprio 1
	v_mfma_f32_16x16x32_bf16 v[60:63], v[162:165], v[178:181], v[60:63]
	v_mfma_f32_16x16x32_bf16 v[56:59], v[170:173], v[178:181], v[56:59]
	v_mfma_f32_16x16x32_bf16 v[52:55], v[162:165], v[186:189], v[52:55]
	v_mfma_f32_16x16x32_bf16 v[48:51], v[170:173], v[186:189], v[48:51]
	v_mfma_f32_16x16x32_bf16 v[44:47], v[162:165], v[194:197], v[44:47]
	v_mfma_f32_16x16x32_bf16 v[40:43], v[170:173], v[194:197], v[40:43]
	v_mfma_f32_16x16x32_bf16 v[36:39], v[162:165], v[214:217], v[36:39]
	v_mfma_f32_16x16x32_bf16 v[32:35], v[170:173], v[214:217], v[32:35]
	v_mfma_f32_16x16x32_bf16 v[60:63], v[166:169], v[182:185], v[60:63]
	v_mfma_f32_16x16x32_bf16 v[56:59], v[174:177], v[182:185], v[56:59]
	v_mfma_f32_16x16x32_bf16 v[52:55], v[166:169], v[190:193], v[52:55]
	v_mfma_f32_16x16x32_bf16 v[48:51], v[174:177], v[190:193], v[48:51]
	v_mfma_f32_16x16x32_bf16 v[44:47], v[166:169], v[198:201], v[44:47]
	v_mfma_f32_16x16x32_bf16 v[40:43], v[174:177], v[198:201], v[40:43]
	v_mfma_f32_16x16x32_bf16 v[36:39], v[166:169], v[218:221], v[36:39]
	v_mfma_f32_16x16x32_bf16 v[32:35], v[174:177], v[218:221], v[32:35]
	s_setprio 0
	s_barrier
; #define PG8_STAGE(bufoff, gbase, voff) do { _Pragma("unroll") for (int _i = 0; _i < 2; ++_i) \
;         __builtin_amdgcn_global_load_lds((const unsigned*)((const char*)(gbase) + (voff)[_i]), (PG8_LAS unsigned*)(lds + (bufoff) + ldsw + _i * 8192), 16, 0, 0); } while (0)
; #define PG8_LDA(dst, b, h) do { _Pragma("unroll") for (int m = 0; m < 4; ++m) _Pragma("unroll") for (int k = 0; k < 2; ++k) dst[m][k] = *(const PG8_LAS bf16x8*)(lds + PG8_SA(b, h) + aoff + m * 2048 + k * 1024); } while (0)
; #define PG8_MMA(ai, bj, At, Bt) do { __builtin_amdgcn_s_setprio(1); _Pragma("unroll") for (int m = 0; m < 4; ++m) _Pragma("unroll") for (int n = 0; n < 2; ++n) _Pragma("unroll") for (int k = 0; k < 2; ++k) \
;         acc[ai][bj][m][n] = __builtin_amdgcn_mfma_f32_16x16x32_bf16(Bt[n][k], At[m][k], acc[ai][bj][m][n], 0, 0, 0); __builtin_amdgcn_s_setprio(0); } while (0)
; #define PG8_WAIT_V(n) asm volatile("s_waitcnt vmcnt(" #n ")" ::: "memory")
; #define PG8_WAIT_L(n) asm volatile("s_waitcnt lgkmcnt(" #n ")" ::: "memory")
; #define PG8_BAR __builtin_amdgcn_s_barrier()
; #define PG8_SCHED __builtin_amdgcn_sched_barrier(0)
; template <class Epi, class Sched, bool ALIGN_EPI = false, bool SP2 = false>
; __device__ __forceinline__ void gemm_phase(PG8_LAS unsigned char* lds, const Gemm g, const Sched& S, const Epi& E, const int tid) {
;     ...
;             PG8_LDA(At, 1, 1); PG8_STAGE(PG8_SB(1, 0), b3, voffB); PG8_STAGE(PG8_SB(1, 1), b3 + hstep, voffB); PG8_STAGE(PG8_SA(1, 0), a3, voffA);
;             PG8_WAIT_V(8); PG8_WAIT_L(0); PG8_BAR; PG8_MMA(1, 0, At, B0); PG8_MMA(1, 1, At, B1); PG8_BAR; PG8_SCHED;
;     __device__ __forceinline__ void operator()(const f32x4 (&acc)[2][2][4][2], const Unit& u, int wr, int wc, int fr, int fq) const {
;     ...
;                 const int gcol = col - LDQ;
;                 const f32x4 b0 = *(const f32x4*)(bgate + gcol), b1 = *(const f32x4*)(bgate + gcol + 4);
	s_add_i32 s8, s27, s12
	v_lshl_add_u64 v[202:203], v[202:203], 0, s[94:95]
	s_mov_b32 m0, s8
	ds_read_b128 v[178:181], v143 offset:49152
	ds_read_b128 v[182:185], v143 offset:50176
	ds_read_b128 v[186:189], v143 offset:51200
	ds_read_b128 v[190:193], v143 offset:52224
	ds_read_b128 v[194:197], v143 offset:53248
	ds_read_b128 v[198:201], v143 offset:54272
	ds_read_b128 v[214:217], v143 offset:55296
	ds_read_b128 v[218:221], v143 offset:56320
	global_load_lds_dwordx4 v[202:203], off
	s_add_i32 m0, s8, 0x2000
	s_add_u32 s6, s6, 0x40080
	v_lshl_add_u64 v[202:203], v[206:207], 0, s[94:95]
	s_addc_u32 s7, s7, 0
	s_add_i32 s8, s28, s12
	global_load_lds_dwordx4 v[202:203], off
	v_lshl_add_u64 v[202:203], s[6:7], 0, v[64:65]
	s_mov_b32 m0, s8
	s_nop 0
	global_load_lds_dwordx4 v[202:203], off
	v_lshl_add_u64 v[202:203], s[6:7], 0, v[134:135]
	s_add_i32 m0, s8, 0x2000
	s_nop 0
	global_load_lds_dwordx4 v[202:203], off
	v_lshl_add_u64 v[202:203], v[208:209], 0, s[94:95]
	s_mov_b32 m0, s20
	s_nop 0
	global_load_lds_dwordx4 v[202:203], off
	v_lshl_add_u64 v[202:203], v[222:223], 0, s[94:95]
	s_mov_b32 m0, s21
	s_nop 0
	global_load_lds_dwordx4 v[202:203], off
	s_waitcnt vmcnt(8)
	s_waitcnt lgkmcnt(0)
	s_barrier
	s_setprio 1
	s_waitcnt lgkmcnt(0)
	v_mfma_f32_16x16x32_bf16 v[94:97], v[144:147], v[178:181], v[94:97]
	v_mfma_f32_16x16x32_bf16 v[90:93], v[154:157], v[178:181], v[90:93]
	v_mfma_f32_16x16x32_bf16 v[86:89], v[144:147], v[186:189], v[86:89]
	v_mfma_f32_16x16x32_bf16 v[82:85], v[154:157], v[186:189], v[82:85]
	v_mfma_f32_16x16x32_bf16 v[78:81], v[144:147], v[194:197], v[78:81]
	v_mfma_f32_16x16x32_bf16 v[74:77], v[154:157], v[194:197], v[74:77]
	v_mfma_f32_16x16x32_bf16 v[70:73], v[144:147], v[214:217], v[70:73]
	v_mfma_f32_16x16x32_bf16 v[66:69], v[154:157], v[214:217], v[66:69]
	v_mfma_f32_16x16x32_bf16 v[94:97], v[150:153], v[182:185], v[94:97]
	v_mfma_f32_16x16x32_bf16 v[90:93], v[158:161], v[182:185], v[90:93]
	v_mfma_f32_16x16x32_bf16 v[86:89], v[150:153], v[190:193], v[86:89]
	v_mfma_f32_16x16x32_bf16 v[82:85], v[158:161], v[190:193], v[82:85]
	v_mfma_f32_16x16x32_bf16 v[78:81], v[150:153], v[198:201], v[78:81]
	v_mfma_f32_16x16x32_bf16 v[74:77], v[158:161], v[198:201], v[74:77]
	v_mfma_f32_16x16x32_bf16 v[70:73], v[150:153], v[218:221], v[70:73]
	v_mfma_f32_16x16x32_bf16 v[66:69], v[158:161], v[218:221], v[66:69]
	s_setprio 0
	s_setprio 1
	v_mfma_f32_16x16x32_bf16 v[28:31], v[162:165], v[178:181], v[28:31]
	v_mfma_f32_16x16x32_bf16 v[24:27], v[170:173], v[178:181], v[24:27]
	v_mfma_f32_16x16x32_bf16 v[20:23], v[162:165], v[186:189], v[20:23]
	v_mfma_f32_16x16x32_bf16 v[16:19], v[170:173], v[186:189], v[16:19]
	v_mfma_f32_16x16x32_bf16 v[12:15], v[162:165], v[194:197], v[12:15]
	v_mfma_f32_16x16x32_bf16 v[8:11], v[170:173], v[194:197], v[8:11]
	v_mfma_f32_16x16x32_bf16 v[4:7], v[162:165], v[214:217], v[4:7]
	v_mfma_f32_16x16x32_bf16 v[0:3], v[170:173], v[214:217], v[0:3]
	v_mfma_f32_16x16x32_bf16 v[28:31], v[166:169], v[182:185], v[28:31]
	v_mfma_f32_16x16x32_bf16 v[24:27], v[174:177], v[182:185], v[24:27]
	v_mfma_f32_16x16x32_bf16 v[20:23], v[166:169], v[190:193], v[20:23]
	v_mfma_f32_16x16x32_bf16 v[16:19], v[174:177], v[190:193], v[16:19]
	v_mfma_f32_16x16x32_bf16 v[12:15], v[166:169], v[198:201], v[12:15]
	v_mfma_f32_16x16x32_bf16 v[8:11], v[174:177], v[198:201], v[8:11]
	v_mfma_f32_16x16x32_bf16 v[4:7], v[166:169], v[218:221], v[4:7]
	v_mfma_f32_16x16x32_bf16 v[0:3], v[174:177], v[218:221], v[0:3]
	s_setprio 0
	s_barrier
	s_add_i32 s26, s26, 2
	s_add_u32 s4, s4, 0x100
	s_addc_u32 s5, s5, 0
	s_cmp_gt_u32 s26, 13
	s_cbranch_scc0 .LBB0_511
	s_and_b32 s12, 0xffff, s11
	s_lshl_b32 s13, s19, 8
	s_lshl_b32 s11, s12, 8
	s_and_b32 s2, s13, 0xff00
	s_and_b32 s14, 0xffff, s14
	v_or_b32_e32 v64, s15, v148
	s_cmpk_gt_u32 s14, 0x8f
	v_or_b32_e32 v186, s2, v64
	s_cselect_b64 s[2:3], -1, 0
	v_cmp_eq_u32_e64 s[0:1], 0, v141
	v_add_u32_e32 v187, s11, v140
	s_mov_b64 s[4:5], -1
	s_and_b64 vcc, exec, s[2:3]
	s_cbranch_vccz .LBB0_514
	v_add_u32_e32 v138, 0xffffee00, v186
	v_ashrrev_i32_e32 v139, 31, v138
	v_lshl_add_u64 v[134:135], v[138:139], 2, s[52:53]
	global_load_dwordx4 v[130:133], v[134:135], off offset:16
	s_nop 0
	global_load_dwordx4 v[134:137], v[134:135], off
	s_waitcnt vmcnt(0)
; __device__ __forceinline__ unsigned pk2(float lo, float hi) { f32x2_t v = {lo, hi}; bf16x2_t b = __builtin_convertvector(v, bf16x2_t); return __builtin_bit_cast(unsigned, b); }
; __device__ __forceinline__ float sigmoidf_(float x) { return __builtin_amdgcn_rcpf(1.0f + __expf(-x)); }
;     __device__ __forceinline__ void operator()(const f32x4 (&acc)[2][2][4][2], const Unit& u, int wr, int wc, int fr, int fq) const {
;     ...
;                 const int gcol = col - LDQ;
;                 const f32x4 b0 = *(const f32x4*)(bgate + gcol), b1 = *(const f32x4*)(bgate + gcol + 4);
; #pragma unroll
;                 for (int ai = 0; ai < 2; ++ai)
; #pragma unroll
;                     for (int m = 0; m < 4; ++m) {
;                         const int row = row0 + ai * 128 + m * 16;
;                         const f32x4 v0 = acc[ai][bj][m][0] + b0, v1 = acc[ai][bj][m][1] + b1;
;                         u32x4 w; w.x = pk2(sigmoidf_(v0[0]), sigmoidf_(v0[1])); w.y = pk2(sigmoidf_(v0[2]), sigmoidf_(v0[3]));
;                         w.z = pk2(sigmoidf_(v1[0]), sigmoidf_(v1[1])); w.w = pk2(sigmoidf_(v1[2]), sigmoidf_(v1[3]));
;                         __builtin_nontemporal_store(w, (u32x4*)(gates + (unsigned)(row * NG + gcol)));
;                     }
	v_pk_add_f32 v[146:147], v[122:123], v[130:131]
	v_pk_add_f32 v[140:141], v[126:127], v[134:135]
	v_pk_add_f32 v[142:143], v[128:129], v[136:137]
	v_mul_f32_e32 v64, 0xbfb8aa3b, v140
	v_mul_f32_e32 v139, 0xbfb8aa3b, v141
	v_exp_f32_e32 v64, v64
	v_exp_f32_e32 v139, v139
	v_pk_add_f32 v[144:145], v[124:125], v[132:133]
	v_add_f32_e32 v64, 1.0, v64
	v_add_f32_e32 v139, 1.0, v139
	v_rcp_f32_e32 v64, v64
	v_rcp_f32_e32 v139, v139
	s_nop 0
	v_cvt_pk_bf16_f32 v140, v64, v139
	v_mul_f32_e32 v64, 0xbfb8aa3b, v142
	v_mul_f32_e32 v139, 0xbfb8aa3b, v143
	v_exp_f32_e32 v64, v64
	v_exp_f32_e32 v139, v139
	v_add_f32_e32 v64, 1.0, v64
	v_add_f32_e32 v139, 1.0, v139
	v_rcp_f32_e32 v64, v64
	v_rcp_f32_e32 v139, v139
	s_nop 0
	v_cvt_pk_bf16_f32 v141, v64, v139
	v_mul_f32_e32 v64, 0xbfb8aa3b, v146
	v_mul_f32_e32 v139, 0xbfb8aa3b, v147
	v_exp_f32_e32 v64, v64
	v_exp_f32_e32 v139, v139
	v_pk_add_f32 v[146:147], v[114:115], v[130:131]
	v_add_f32_e32 v64, 1.0, v64
	v_add_f32_e32 v139, 1.0, v139
	v_rcp_f32_e32 v64, v64
	v_rcp_f32_e32 v139, v139
	s_nop 0
	v_cvt_pk_bf16_f32 v142, v64, v139
	v_mul_f32_e32 v64, 0xbfb8aa3b, v144
	v_mul_f32_e32 v139, 0xbfb8aa3b, v145
	v_exp_f32_e32 v64, v64
	v_exp_f32_e32 v139, v139
	v_add_f32_e32 v64, 1.0, v64
	v_add_f32_e32 v139, 1.0, v139
	v_rcp_f32_e32 v64, v64
	v_rcp_f32_e32 v139, v139
	s_nop 0
	v_cvt_pk_bf16_f32 v143, v64, v139
	v_mad_u64_u32 v[138:139], s[4:5], v187, s76, v[138:139]
	v_mov_b32_e32 v139, v65
	v_lshl_add_u64 v[144:145], v[138:139], 1, s[36:37]
	global_store_dwordx4 v[144:145], v[140:143], off nt
	v_pk_add_f32 v[144:145], v[116:117], v[132:133]
	s_mov_b64 s[4:5], 0
	v_pk_add_f32 v[140:141], v[118:119], v[134:135]
	v_pk_add_f32 v[142:143], v[120:121], v[136:137]
	v_mul_f32_e32 v64, 0xbfb8aa3b, v140
	v_mul_f32_e32 v139, 0xbfb8aa3b, v141
	v_exp_f32_e32 v64, v64
	v_exp_f32_e32 v139, v139
	v_add_f32_e32 v64, 1.0, v64
	v_add_f32_e32 v139, 1.0, v139
	v_rcp_f32_e32 v64, v64
	v_rcp_f32_e32 v139, v139
	s_nop 0
	v_cvt_pk_bf16_f32 v140, v64, v139
	v_mul_f32_e32 v64, 0xbfb8aa3b, v142
	v_mul_f32_e32 v139, 0xbfb8aa3b, v143
	v_exp_f32_e32 v64, v64
	v_exp_f32_e32 v139, v139
	v_add_f32_e32 v64, 1.0, v64
	v_add_f32_e32 v139, 1.0, v139
	v_rcp_f32_e32 v64, v64
	v_rcp_f32_e32 v139, v139
	s_nop 0
	v_cvt_pk_bf16_f32 v141, v64, v139
	v_mul_f32_e32 v64, 0xbfb8aa3b, v146
	v_mul_f32_e32 v139, 0xbfb8aa3b, v147
	v_exp_f32_e32 v64, v64
	v_exp_f32_e32 v139, v139
	v_pk_add_f32 v[146:147], v[110:111], v[134:135]
	v_add_f32_e32 v64, 1.0, v64
	v_add_f32_e32 v139, 1.0, v139
	v_rcp_f32_e32 v64, v64
	v_rcp_f32_e32 v139, v139
	s_nop 0
	v_cvt_pk_bf16_f32 v142, v64, v139
	v_mul_f32_e32 v64, 0xbfb8aa3b, v144
	v_mul_f32_e32 v139, 0xbfb8aa3b, v145
	v_exp_f32_e32 v64, v64
	v_exp_f32_e32 v139, v139
	v_add_f32_e32 v64, 1.0, v64
	v_add_f32_e32 v139, 1.0, v139
	v_rcp_f32_e32 v64, v64
	v_rcp_f32_e32 v139, v139
	s_nop 0
	v_cvt_pk_bf16_f32 v143, v64, v139
	v_add_u32_e32 v64, 0xc000, v138
	v_lshl_add_u64 v[144:145], v[64:65], 1, s[36:37]
	v_mul_f32_e32 v64, 0xbfb8aa3b, v146
	v_mul_f32_e32 v139, 0xbfb8aa3b, v147
	v_exp_f32_e32 v64, v64
	v_exp_f32_e32 v139, v139
	global_store_dwordx4 v[144:145], v[140:143], off nt
	v_pk_add_f32 v[144:145], v[112:113], v[136:137]
	v_add_f32_e32 v64, 1.0, v64
	v_add_f32_e32 v139, 1.0, v139
	v_rcp_f32_e32 v64, v64
	v_rcp_f32_e32 v139, v139
	v_pk_add_f32 v[142:143], v[106:107], v[130:131]
	v_pk_add_f32 v[140:141], v[108:109], v[132:133]
	v_pk_add_f32 v[146:147], v[98:99], v[130:131]
	v_cvt_pk_bf16_f32 v150, v64, v139
	v_mul_f32_e32 v64, 0xbfb8aa3b, v144
	v_mul_f32_e32 v139, 0xbfb8aa3b, v145
	v_exp_f32_e32 v64, v64
	v_exp_f32_e32 v139, v139
	v_pk_add_f32 v[144:145], v[100:101], v[132:133]
	v_add_f32_e32 v64, 1.0, v64
	v_add_f32_e32 v139, 1.0, v139
	v_rcp_f32_e32 v64, v64
	v_rcp_f32_e32 v139, v139
	s_nop 0
	v_cvt_pk_bf16_f32 v151, v64, v139
	v_mul_f32_e32 v64, 0xbfb8aa3b, v142
	v_mul_f32_e32 v139, 0xbfb8aa3b, v143
	v_exp_f32_e32 v64, v64
	v_exp_f32_e32 v139, v139
	v_pk_add_f32 v[142:143], v[104:105], v[136:137]
	v_add_f32_e32 v64, 1.0, v64
	v_add_f32_e32 v139, 1.0, v139
	v_rcp_f32_e32 v64, v64
	v_rcp_f32_e32 v139, v139
	s_nop 0
	v_cvt_pk_bf16_f32 v152, v64, v139
	v_mul_f32_e32 v64, 0xbfb8aa3b, v140
	v_mul_f32_e32 v139, 0xbfb8aa3b, v141
	v_exp_f32_e32 v64, v64
	v_exp_f32_e32 v139, v139
	v_add_f32_e32 v64, 1.0, v64
	v_add_f32_e32 v139, 1.0, v139
	v_rcp_f32_e32 v64, v64
	v_rcp_f32_e32 v139, v139
	s_nop 0
	v_cvt_pk_bf16_f32 v153, v64, v139
	v_add_u32_e32 v64, 0x18000, v138
	v_lshl_add_u64 v[140:141], v[64:65], 1, s[36:37]
	global_store_dwordx4 v[140:141], v[150:153], off nt
	v_pk_add_f32 v[140:141], v[102:103], v[134:135]
	s_nop 0
	v_mul_f32_e32 v64, 0xbfb8aa3b, v140
	v_mul_f32_e32 v139, 0xbfb8aa3b, v141
	v_exp_f32_e32 v64, v64
	v_exp_f32_e32 v139, v139
	v_add_f32_e32 v64, 1.0, v64
	v_add_f32_e32 v139, 1.0, v139
	v_rcp_f32_e32 v64, v64
	v_rcp_f32_e32 v139, v139
	s_nop 0
	v_cvt_pk_bf16_f32 v140, v64, v139
	v_mul_f32_e32 v64, 0xbfb8aa3b, v142
	v_mul_f32_e32 v139, 0xbfb8aa3b, v143
	v_exp_f32_e32 v64, v64
	v_exp_f32_e32 v139, v139
	v_add_f32_e32 v64, 1.0, v64
	v_add_f32_e32 v139, 1.0, v139
	v_rcp_f32_e32 v64, v64
	v_rcp_f32_e32 v139, v139
	s_nop 0
	v_cvt_pk_bf16_f32 v141, v64, v139
	v_mul_f32_e32 v64, 0xbfb8aa3b, v146
	v_mul_f32_e32 v139, 0xbfb8aa3b, v147
	v_exp_f32_e32 v64, v64
	v_exp_f32_e32 v139, v139
	v_pk_add_f32 v[146:147], v[90:91], v[130:131]
	v_add_f32_e32 v64, 1.0, v64
	v_add_f32_e32 v139, 1.0, v139
	v_rcp_f32_e32 v64, v64
	v_rcp_f32_e32 v139, v139
	s_nop 0
	v_cvt_pk_bf16_f32 v142, v64, v139
	v_mul_f32_e32 v64, 0xbfb8aa3b, v144
	v_mul_f32_e32 v139, 0xbfb8aa3b, v145
	v_exp_f32_e32 v64, v64
	v_exp_f32_e32 v139, v139
	v_add_f32_e32 v64, 1.0, v64
; __device__ __forceinline__ unsigned pk2(float lo, float hi) { f32x2_t v = {lo, hi}; bf16x2_t b = __builtin_convertvector(v, bf16x2_t); return __builtin_bit_cast(unsigned, b); }
; __device__ __forceinline__ float sigmoidf_(float x) { return __builtin_amdgcn_rcpf(1.0f + __expf(-x)); }
;     __device__ __forceinline__ void operator()(const f32x4 (&acc)[2][2][4][2], const Unit& u, int wr, int wc, int fr, int fq) const {
;     ...
;                 const int gcol = col - LDQ;
;                 const f32x4 b0 = *(const f32x4*)(bgate + gcol), b1 = *(const f32x4*)(bgate + gcol + 4);
; #pragma unroll
;                 for (int ai = 0; ai < 2; ++ai)
; #pragma unroll
;                     for (int m = 0; m < 4; ++m) {
;                         const int row = row0 + ai * 128 + m * 16;
;                         const f32x4 v0 = acc[ai][bj][m][0] + b0, v1 = acc[ai][bj][m][1] + b1;
;                         u32x4 w; w.x = pk2(sigmoidf_(v0[0]), sigmoidf_(v0[1])); w.y = pk2(sigmoidf_(v0[2]), sigmoidf_(v0[3]));
;                         w.z = pk2(sigmoidf_(v1[0]), sigmoidf_(v1[1])); w.w = pk2(sigmoidf_(v1[2]), sigmoidf_(v1[3]));
;                         __builtin_nontemporal_store(w, (u32x4*)(gates + (unsigned)(row * NG + gcol)));
;                     }
	v_add_f32_e32 v139, 1.0, v139
	v_rcp_f32_e32 v64, v64
	v_rcp_f32_e32 v139, v139
	s_nop 0
	v_cvt_pk_bf16_f32 v143, v64, v139
	v_add_u32_e32 v64, 0x24000, v138
	v_lshl_add_u64 v[144:145], v[64:65], 1, s[36:37]
	global_store_dwordx4 v[144:145], v[140:143], off nt
	v_pk_add_f32 v[144:145], v[92:93], v[132:133]
	s_nop 0
	v_pk_add_f32 v[140:141], v[94:95], v[134:135]
	v_pk_add_f32 v[142:143], v[96:97], v[136:137]
	v_mul_f32_e32 v64, 0xbfb8aa3b, v140
	v_mul_f32_e32 v139, 0xbfb8aa3b, v141
	v_exp_f32_e32 v64, v64
	v_exp_f32_e32 v139, v139
	v_add_f32_e32 v64, 1.0, v64
	v_add_f32_e32 v139, 1.0, v139
	v_rcp_f32_e32 v64, v64
	v_rcp_f32_e32 v139, v139
	s_nop 0
	v_cvt_pk_bf16_f32 v140, v64, v139
	v_mul_f32_e32 v64, 0xbfb8aa3b, v142
	v_mul_f32_e32 v139, 0xbfb8aa3b, v143
	v_exp_f32_e32 v64, v64
	v_exp_f32_e32 v139, v139
	v_add_f32_e32 v64, 1.0, v64
	v_add_f32_e32 v139, 1.0, v139
	v_rcp_f32_e32 v64, v64
	v_rcp_f32_e32 v139, v139
	s_nop 0
	v_cvt_pk_bf16_f32 v141, v64, v139
	v_mul_f32_e32 v64, 0xbfb8aa3b, v146
	v_mul_f32_e32 v139, 0xbfb8aa3b, v147
	v_exp_f32_e32 v64, v64
	v_exp_f32_e32 v139, v139
	v_pk_add_f32 v[146:147], v[82:83], v[130:131]
	v_add_f32_e32 v64, 1.0, v64
	v_add_f32_e32 v139, 1.0, v139
	v_rcp_f32_e32 v64, v64
	v_rcp_f32_e32 v139, v139
	s_nop 0
	v_cvt_pk_bf16_f32 v142, v64, v139
	v_mul_f32_e32 v64, 0xbfb8aa3b, v144
	v_mul_f32_e32 v139, 0xbfb8aa3b, v145
	v_exp_f32_e32 v64, v64
	v_exp_f32_e32 v139, v139
	v_add_f32_e32 v64, 1.0, v64
	v_add_f32_e32 v139, 1.0, v139
	v_rcp_f32_e32 v64, v64
	v_rcp_f32_e32 v139, v139
	s_nop 0
	v_cvt_pk_bf16_f32 v143, v64, v139
	v_add_u32_e32 v64, 0x60000, v138
	v_lshl_add_u64 v[144:145], v[64:65], 1, s[36:37]
	global_store_dwordx4 v[144:145], v[140:143], off nt
	v_pk_add_f32 v[144:145], v[84:85], v[132:133]
	s_nop 0
	v_pk_add_f32 v[140:141], v[86:87], v[134:135]
	v_pk_add_f32 v[142:143], v[88:89], v[136:137]
	v_mul_f32_e32 v64, 0xbfb8aa3b, v140
	v_mul_f32_e32 v139, 0xbfb8aa3b, v141
	v_exp_f32_e32 v64, v64
	v_exp_f32_e32 v139, v139
	v_add_f32_e32 v64, 1.0, v64
	v_add_f32_e32 v139, 1.0, v139
	v_rcp_f32_e32 v64, v64
	v_rcp_f32_e32 v139, v139
	s_nop 0
	v_cvt_pk_bf16_f32 v140, v64, v139
	v_mul_f32_e32 v64, 0xbfb8aa3b, v142
	v_mul_f32_e32 v139, 0xbfb8aa3b, v143
	v_exp_f32_e32 v64, v64
	v_exp_f32_e32 v139, v139
	v_add_f32_e32 v64, 1.0, v64
	v_add_f32_e32 v139, 1.0, v139
	v_rcp_f32_e32 v64, v64
	v_rcp_f32_e32 v139, v139
	s_nop 0
	v_cvt_pk_bf16_f32 v141, v64, v139
	v_mul_f32_e32 v64, 0xbfb8aa3b, v146
	v_mul_f32_e32 v139, 0xbfb8aa3b, v147
	v_exp_f32_e32 v64, v64
	v_exp_f32_e32 v139, v139
	v_pk_add_f32 v[146:147], v[74:75], v[130:131]
	v_add_f32_e32 v64, 1.0, v64
	v_add_f32_e32 v139, 1.0, v139
	v_rcp_f32_e32 v64, v64
	v_rcp_f32_e32 v139, v139
	s_nop 0
	v_cvt_pk_bf16_f32 v142, v64, v139
	v_mul_f32_e32 v64, 0xbfb8aa3b, v144
	v_mul_f32_e32 v139, 0xbfb8aa3b, v145
	v_exp_f32_e32 v64, v64
	v_exp_f32_e32 v139, v139
	v_add_f32_e32 v64, 1.0, v64
	v_add_f32_e32 v139, 1.0, v139
	v_rcp_f32_e32 v64, v64
	v_rcp_f32_e32 v139, v139
	s_nop 0
	v_cvt_pk_bf16_f32 v143, v64, v139
	v_add_u32_e32 v64, 0x6c000, v138
	v_lshl_add_u64 v[144:145], v[64:65], 1, s[36:37]
	global_store_dwordx4 v[144:145], v[140:143], off nt
	v_pk_add_f32 v[144:145], v[76:77], v[132:133]
	s_nop 0
	v_pk_add_f32 v[140:141], v[78:79], v[134:135]
	v_pk_add_f32 v[142:143], v[80:81], v[136:137]
	v_mul_f32_e32 v64, 0xbfb8aa3b, v140
	v_mul_f32_e32 v139, 0xbfb8aa3b, v141
	v_exp_f32_e32 v64, v64
	v_exp_f32_e32 v139, v139
	v_pk_add_f32 v[134:135], v[70:71], v[134:135]
	v_pk_add_f32 v[136:137], v[72:73], v[136:137]
	v_add_f32_e32 v64, 1.0, v64
	v_add_f32_e32 v139, 1.0, v139
	v_rcp_f32_e32 v64, v64
	v_rcp_f32_e32 v139, v139
	s_nop 0
	v_cvt_pk_bf16_f32 v140, v64, v139
	v_mul_f32_e32 v64, 0xbfb8aa3b, v142
	v_mul_f32_e32 v139, 0xbfb8aa3b, v143
	v_exp_f32_e32 v64, v64
	v_exp_f32_e32 v139, v139
	v_add_f32_e32 v64, 1.0, v64
	v_add_f32_e32 v139, 1.0, v139
	v_rcp_f32_e32 v64, v64
	v_rcp_f32_e32 v139, v139
	s_nop 0
	v_cvt_pk_bf16_f32 v141, v64, v139
	v_mul_f32_e32 v64, 0xbfb8aa3b, v146
	v_mul_f32_e32 v139, 0xbfb8aa3b, v147
	v_exp_f32_e32 v64, v64
	v_exp_f32_e32 v139, v139
	v_add_f32_e32 v64, 1.0, v64
	v_add_f32_e32 v139, 1.0, v139
	v_rcp_f32_e32 v64, v64
	v_rcp_f32_e32 v139, v139
	s_nop 0
	v_cvt_pk_bf16_f32 v142, v64, v139
	v_mul_f32_e32 v64, 0xbfb8aa3b, v144
	v_mul_f32_e32 v139, 0xbfb8aa3b, v145
	v_exp_f32_e32 v64, v64
	v_exp_f32_e32 v139, v139
	v_add_f32_e32 v64, 1.0, v64
	v_add_f32_e32 v139, 1.0, v139
	v_rcp_f32_e32 v64, v64
	v_rcp_f32_e32 v139, v139
	s_nop 0
	v_cvt_pk_bf16_f32 v143, v64, v139
	v_add_u32_e32 v64, 0x78000, v138
	v_lshl_add_u64 v[144:145], v[64:65], 1, s[36:37]
	global_store_dwordx4 v[144:145], v[140:143], off nt
	v_mul_f32_e32 v64, 0xbfb8aa3b, v134
	v_exp_f32_e32 v64, v64
	v_pk_add_f32 v[140:141], v[68:69], v[132:133]
	v_pk_add_f32 v[132:133], v[66:67], v[130:131]
	v_mul_f32_e32 v130, 0xbfb8aa3b, v135
	v_exp_f32_e32 v130, v130
	v_add_f32_e32 v64, 1.0, v64
	v_rcp_f32_e32 v64, v64
	v_mul_f32_e32 v131, 0xbfb8aa3b, v137
	v_add_f32_e32 v130, 1.0, v130
	v_rcp_f32_e32 v130, v130
	v_exp_f32_e32 v131, v131
	v_cvt_pk_bf16_f32 v130, v64, v130
	v_mul_f32_e32 v64, 0xbfb8aa3b, v136
	v_exp_f32_e32 v64, v64
	v_add_f32_e32 v131, 1.0, v131
	v_rcp_f32_e32 v131, v131
	v_add_f32_e32 v64, 1.0, v64
	v_rcp_f32_e32 v64, v64
	s_nop 0
	v_cvt_pk_bf16_f32 v131, v64, v131
	v_mul_f32_e32 v64, 0xbfb8aa3b, v132
	v_mul_f32_e32 v132, 0xbfb8aa3b, v133
	v_exp_f32_e32 v64, v64
	v_exp_f32_e32 v132, v132
	v_mul_f32_e32 v133, 0xbfb8aa3b, v141
	v_exp_f32_e32 v133, v133
	v_add_f32_e32 v64, 1.0, v64
	v_add_f32_e32 v132, 1.0, v132
	v_rcp_f32_e32 v64, v64
	v_rcp_f32_e32 v132, v132
	v_add_f32_e32 v133, 1.0, v133
	v_rcp_f32_e32 v133, v133
	v_cvt_pk_bf16_f32 v132, v64, v132
	v_mul_f32_e32 v64, 0xbfb8aa3b, v140
	v_exp_f32_e32 v64, v64
	s_nop 0
	v_add_f32_e32 v64, 1.0, v64
	v_rcp_f32_e32 v64, v64
	s_nop 0
	v_cvt_pk_bf16_f32 v133, v64, v133
	v_add_u32_e32 v64, 0x84000, v138
	v_lshl_add_u64 v[134:135], v[64:65], 1, s[36:37]
	global_store_dwordx4 v[134:135], v[130:133], off nt
; __device__ __forceinline__ unsigned pk2(float lo, float hi) { f32x2_t v = {lo, hi}; bf16x2_t b = __builtin_convertvector(v, bf16x2_t); return __builtin_bit_cast(unsigned, b); }
;     __device__ __forceinline__ void operator()(const f32x4 (&acc)[2][2][4][2], const Unit& u, int wr, int wc, int fr, int fq) const {
;     ...
;             if (u.pn < 18) {
;                 const int which = col / MIXW, rem = col - which * MIXW, head = rem >> 6, dc = rem & 63;
;                 const bool rope = (which < 2) && (head < 18);
;                 const bool ksum_on = (which == 1) && (head >= 12) && (head < 18);
;                 const float sc = (which == 0) ? 0.125f * 1.4426950408889634f : 1.0f;
;     ...
; #pragma unroll
;                     for (int i = 0; i < 8; ++i) {
;                         const int ai = i >> 2, m = i & 3, row = row0 + ai * 128 + m * 16;
;                         const f32x4 v0 = acc[ai][bj][m][0] * sc, v1 = acc[ai][bj][m][1] * sc;
;                         u32x4 w; w.x = pk2(v0[0], v0[1]); w.y = pk2(v0[2], v0[3]); w.z = pk2(v1[0], v1[1]); w.w = pk2(v1[2], v1[3]);
;                         __builtin_nontemporal_store(w, (u32x4*)(qkv + (unsigned)(row * LDQ + col)));
;                     }
.LBB0_514:
	v_bitop3_b32 v191, s15, 56, v148 bitop3:0xc8
	s_andn2_b64 vcc, exec, s[4:5]
	v_lshrrev_b32_e32 v200, 1, v191
	s_cbranch_vccnz .LBB0_539
	v_mul_u32_u24_e32 v64, 0xaaab, v186
	v_lshrrev_b32_e32 v64, 26, v64
	v_mul_lo_u16_e32 v64, 0x600, v64
	v_sub_u16_e32 v64, v186, v64
	s_cmpk_gt_u32 s14, 0x5f
	s_movk_i32 s6, 0x47f
	s_cselect_b64 s[4:5], -1, 0
	v_cmp_lt_u16_e32 vcc, s6, v64
	s_or_b64 s[4:5], s[4:5], vcc
	s_cmp_lt_u32 s14, 48
	s_cselect_b64 vcc, -1, 0
	v_mov_b32_e32 v130, 0x3e38aa3b
	v_cndmask_b32_e32 v188, 1.0, v130, vcc
	s_and_saveexec_b64 s[6:7], s[4:5]
	s_xor_b64 s[4:5], exec, s[6:7]
	s_cbranch_execz .LBB0_517
	v_pk_mul_f32 v[132:133], v[188:189], v[128:129] op_sel_hi:[0,1]
	v_pk_mul_f32 v[130:131], v[188:189], v[126:127] op_sel_hi:[0,1]
	v_pk_mul_f32 v[134:135], v[188:189], v[124:125] op_sel_hi:[0,1]
	s_movk_i32 s6, 0x1200
	v_cvt_pk_bf16_f32 v130, v130, v131
	v_cvt_pk_bf16_f32 v131, v132, v133
	v_cvt_pk_bf16_f32 v133, v134, v135
	v_mad_u64_u32 v[134:135], s[6:7], v187, s6, v[186:187]
	v_pk_mul_f32 v[136:137], v[188:189], v[122:123] op_sel_hi:[0,1]
	v_mov_b32_e32 v135, v65
	v_cvt_pk_bf16_f32 v132, v136, v137
	v_lshl_add_u64 v[136:137], v[134:135], 1, s[84:85]
	global_store_dwordx4 v[136:137], v[130:133], off nt
	v_pk_mul_f32 v[136:137], v[188:189], v[116:117] op_sel_hi:[0,1]
	v_pk_mul_f32 v[138:139], v[188:189], v[114:115] op_sel_hi:[0,1]
	v_pk_mul_f32 v[132:133], v[188:189], v[120:121] op_sel_hi:[0,1]
	v_pk_mul_f32 v[130:131], v[188:189], v[118:119] op_sel_hi:[0,1]
	v_add_u32_e32 v64, 0x12000, v134
	v_cvt_pk_bf16_f32 v130, v130, v131
	v_cvt_pk_bf16_f32 v131, v132, v133
	v_cvt_pk_bf16_f32 v132, v138, v139
	v_cvt_pk_bf16_f32 v133, v136, v137
	v_lshl_add_u64 v[136:137], v[64:65], 1, s[84:85]
	global_store_dwordx4 v[136:137], v[130:133], off nt
	v_pk_mul_f32 v[136:137], v[188:189], v[108:109] op_sel_hi:[0,1]
	v_pk_mul_f32 v[138:139], v[188:189], v[106:107] op_sel_hi:[0,1]
	v_pk_mul_f32 v[132:133], v[188:189], v[112:113] op_sel_hi:[0,1]
	v_pk_mul_f32 v[130:131], v[188:189], v[110:111] op_sel_hi:[0,1]
	v_add_u32_e32 v64, 0x24000, v134
	v_cvt_pk_bf16_f32 v130, v130, v131
	v_cvt_pk_bf16_f32 v131, v132, v133
	v_cvt_pk_bf16_f32 v132, v138, v139
	v_cvt_pk_bf16_f32 v133, v136, v137
	v_lshl_add_u64 v[136:137], v[64:65], 1, s[84:85]
	global_store_dwordx4 v[136:137], v[130:133], off nt
	v_pk_mul_f32 v[136:137], v[188:189], v[100:101] op_sel_hi:[0,1]
	v_pk_mul_f32 v[138:139], v[188:189], v[98:99] op_sel_hi:[0,1]
	v_pk_mul_f32 v[132:133], v[188:189], v[104:105] op_sel_hi:[0,1]
	v_pk_mul_f32 v[130:131], v[188:189], v[102:103] op_sel_hi:[0,1]
	v_add_u32_e32 v64, 0x36000, v134
	v_cvt_pk_bf16_f32 v130, v130, v131
	v_cvt_pk_bf16_f32 v131, v132, v133
	v_cvt_pk_bf16_f32 v132, v138, v139
	v_cvt_pk_bf16_f32 v133, v136, v137
	v_lshl_add_u64 v[136:137], v[64:65], 1, s[84:85]
	global_store_dwordx4 v[136:137], v[130:133], off nt
	v_pk_mul_f32 v[136:137], v[188:189], v[92:93] op_sel_hi:[0,1]
	v_pk_mul_f32 v[138:139], v[188:189], v[90:91] op_sel_hi:[0,1]
	v_pk_mul_f32 v[132:133], v[188:189], v[96:97] op_sel_hi:[0,1]
	v_pk_mul_f32 v[130:131], v[188:189], v[94:95] op_sel_hi:[0,1]
	v_add_u32_e32 v64, 0x90000, v134
	v_cvt_pk_bf16_f32 v130, v130, v131
	v_cvt_pk_bf16_f32 v131, v132, v133
	v_cvt_pk_bf16_f32 v132, v138, v139
	v_cvt_pk_bf16_f32 v133, v136, v137
	v_lshl_add_u64 v[136:137], v[64:65], 1, s[84:85]
	global_store_dwordx4 v[136:137], v[130:133], off nt
	v_pk_mul_f32 v[136:137], v[188:189], v[84:85] op_sel_hi:[0,1]
	v_pk_mul_f32 v[138:139], v[188:189], v[82:83] op_sel_hi:[0,1]
	v_pk_mul_f32 v[132:133], v[188:189], v[88:89] op_sel_hi:[0,1]
	v_pk_mul_f32 v[130:131], v[188:189], v[86:87] op_sel_hi:[0,1]
	v_add_u32_e32 v64, 0xa2000, v134
	v_cvt_pk_bf16_f32 v130, v130, v131
	v_cvt_pk_bf16_f32 v131, v132, v133
	v_cvt_pk_bf16_f32 v132, v138, v139
	v_cvt_pk_bf16_f32 v133, v136, v137
	v_lshl_add_u64 v[136:137], v[64:65], 1, s[84:85]
	global_store_dwordx4 v[136:137], v[130:133], off nt
	v_pk_mul_f32 v[136:137], v[188:189], v[76:77] op_sel_hi:[0,1]
	v_pk_mul_f32 v[138:139], v[188:189], v[74:75] op_sel_hi:[0,1]
	v_pk_mul_f32 v[132:133], v[188:189], v[80:81] op_sel_hi:[0,1]
	v_pk_mul_f32 v[130:131], v[188:189], v[78:79] op_sel_hi:[0,1]
	v_add_u32_e32 v64, 0xb4000, v134
	v_cvt_pk_bf16_f32 v130, v130, v131
	v_cvt_pk_bf16_f32 v131, v132, v133
	v_cvt_pk_bf16_f32 v132, v138, v139
	v_cvt_pk_bf16_f32 v133, v136, v137
	v_lshl_add_u64 v[136:137], v[64:65], 1, s[84:85]
	global_store_dwordx4 v[136:137], v[130:133], off nt
	v_pk_mul_f32 v[136:137], v[188:189], v[68:69] op_sel_hi:[0,1]
	v_pk_mul_f32 v[138:139], v[188:189], v[66:67] op_sel_hi:[0,1]
	v_pk_mul_f32 v[132:133], v[188:189], v[72:73] op_sel_hi:[0,1]
	v_pk_mul_f32 v[130:131], v[188:189], v[70:71] op_sel_hi:[0,1]
	v_add_u32_e32 v64, 0xc6000, v134
	v_cvt_pk_bf16_f32 v130, v130, v131
	v_cvt_pk_bf16_f32 v131, v132, v133
	v_cvt_pk_bf16_f32 v132, v138, v139
	v_cvt_pk_bf16_f32 v133, v136, v137
	v_lshl_add_u64 v[134:135], v[64:65], 1, s[84:85]
	global_store_dwordx4 v[134:135], v[130:133], off nt
; __device__ __forceinline__ unsigned pk2(float lo, float hi) { f32x2_t v = {lo, hi}; bf16x2_t b = __builtin_convertvector(v, bf16x2_t); return __builtin_bit_cast(unsigned, b); }
;     __device__ __forceinline__ void operator()(const f32x4 (&acc)[2][2][4][2], const Unit& u, int wr, int wc, int fr, int fq) const {
;     ...
;                 if (rope) {
;                     f32x4 c4[8], s4[8];
; #pragma unroll
;                     for (int i = 0; i < 8; ++i) { const int pos = (row0 + (i >> 2) * 128 + (i & 3) * 16) & (SEQ - 1);
;                         c4[i] = *(const f32x4*)(cosT + (unsigned)(pos * 32 + (dc >> 1))); s4[i] = *(const f32x4*)(sinT + (unsigned)(pos * 32 + (dc >> 1))); }
;                     float ks[8];
; #pragma unroll
;                     for (int j = 0; j < 8; ++j) ks[j] = 0.f;
; #pragma unroll
;                     for (int i = 0; i < 8; ++i) {
;                         const int ai = i >> 2, m = i & 3, row = row0 + ai * 128 + m * 16;
;                         const f32x4 v0 = acc[ai][bj][m][0], v1 = acc[ai][bj][m][1];
;                         float r[8];
;                         r[0] = v0[0] * c4[i][0] - v0[1] * s4[i][0]; r[1] = v0[0] * s4[i][0] + v0[1] * c4[i][0];
;                         r[2] = v0[2] * c4[i][1] - v0[3] * s4[i][1]; r[3] = v0[2] * s4[i][1] + v0[3] * c4[i][1];
;                         r[4] = v1[0] * c4[i][2] - v1[1] * s4[i][2]; r[5] = v1[0] * s4[i][2] + v1[1] * c4[i][2];
;                         r[6] = v1[2] * c4[i][3] - v1[3] * s4[i][3]; r[7] = v1[2] * s4[i][3] + v1[3] * c4[i][3];
;                         if (ksum_on) {
; #pragma unroll
;                             for (int j = 0; j < 8; ++j) ks[j] += r[j];
;                         }
;                         u32x4 w; w.x = pk2(r[0] * sc, r[1] * sc); w.y = pk2(r[2] * sc, r[3] * sc); w.z = pk2(r[4] * sc, r[5] * sc); w.w = pk2(r[6] * sc, r[7] * sc);
;                         __builtin_nontemporal_store(w, (u32x4*)(qkv + (unsigned)(row * LDQ + col)));
.LBB0_517:
	s_andn2_saveexec_b64 s[4:5], s[4:5]
	s_cbranch_execz .LBB0_538
	v_lshrrev_b16_e32 v64, 6, v64
	v_lshlrev_b32_e32 v134, 5, v187
	s_mov_b32 s8, 0xf9e0
	v_add_u32_e32 v190, -12, v64
	v_and_or_b32 v64, v134, s8, v200
	v_lshlrev_b32_e32 v64, 2, v64
	v_lshl_add_u64 v[130:131], s[54:55], 0, v[64:65]
	flat_load_dwordx4 v[196:199], v[130:131]
	v_lshl_add_u64 v[130:131], s[56:57], 0, v[64:65]
	flat_load_dwordx4 v[214:217], v[130:131]
	v_or_b32_e32 v130, 0x800, v64
	v_mov_b32_e32 v131, v65
	v_lshl_add_u64 v[132:133], s[54:55], 0, v[130:131]
	v_lshl_add_u64 v[130:131], s[56:57], 0, v[130:131]
	flat_load_dwordx4 v[178:181], v[132:133]
	flat_load_dwordx4 v[182:185], v[130:131]
	v_or_b32_e32 v130, 0x1000, v64
	v_mov_b32_e32 v131, v65
	v_lshl_add_u64 v[132:133], s[54:55], 0, v[130:131]
	v_lshl_add_u64 v[130:131], s[56:57], 0, v[130:131]
	v_or_b32_e32 v64, 0x1800, v64
	flat_load_dwordx4 v[170:173], v[132:133]
	flat_load_dwordx4 v[174:177], v[130:131]
	v_lshl_add_u64 v[130:131], s[54:55], 0, v[64:65]
	flat_load_dwordx4 v[162:165], v[130:131]
	v_lshl_add_u64 v[130:131], s[56:57], 0, v[64:65]
	v_add_u32_e32 v64, 0x1000, v134
	v_and_or_b32 v64, v64, s8, v200
	v_lshlrev_b32_e32 v64, 2, v64
	flat_load_dwordx4 v[166:169], v[130:131]
	v_lshl_add_u64 v[130:131], s[54:55], 0, v[64:65]
	flat_load_dwordx4 v[154:157], v[130:131]
	v_lshl_add_u64 v[130:131], s[56:57], 0, v[64:65]
	flat_load_dwordx4 v[158:161], v[130:131]
	v_or_b32_e32 v130, 0x800, v64
	v_mov_b32_e32 v131, v65
	v_lshl_add_u64 v[132:133], s[54:55], 0, v[130:131]
	v_lshl_add_u64 v[130:131], s[56:57], 0, v[130:131]
	flat_load_dwordx4 v[146:149], v[132:133]
	flat_load_dwordx4 v[150:153], v[130:131]
	v_or_b32_e32 v130, 0x1000, v64
	v_mov_b32_e32 v131, v65
	v_lshl_add_u64 v[132:133], s[54:55], 0, v[130:131]
	v_lshl_add_u64 v[130:131], s[56:57], 0, v[130:131]
	v_or_b32_e32 v64, 0x1800, v64
	flat_load_dwordx4 v[138:141], v[132:133]
	flat_load_dwordx4 v[142:145], v[130:131]
	v_lshl_add_u64 v[130:131], s[54:55], 0, v[64:65]
	v_lshl_add_u64 v[134:135], s[56:57], 0, v[64:65]
	flat_load_dwordx4 v[130:133], v[130:131]
	s_add_i32 s6, s13, 0xfa00
	flat_load_dwordx4 v[134:137], v[134:135]
	s_and_b32 s6, s6, 0xffff
	s_cmpk_lt_u32 s6, 0x600
	s_cselect_b64 s[6:7], -1, 0
	v_cmp_gt_u32_e32 vcc, 6, v190
	s_and_b64 s[6:7], s[6:7], vcc
	s_waitcnt vmcnt(0) lgkmcnt(0)
	v_pk_mul_f32 v[194:195], v[126:127], v[214:215] op_sel_hi:[1,0]
	s_nop 0
	v_pk_fma_f32 v[192:193], v[126:127], v[196:197], v[194:195] op_sel:[1,0,0] op_sel_hi:[0,1,1]
	v_pk_fma_f32 v[126:127], v[126:127], v[196:197], v[194:195] op_sel:[1,0,0] op_sel_hi:[0,0,1] neg_lo:[0,0,1] neg_hi:[0,0,1]
	v_mov_b32_e32 v193, v127
	v_pk_mul_f32 v[126:127], v[128:129], v[214:215] op_sel:[0,1]
	v_mov_b32_e32 v64, v217
	v_pk_fma_f32 v[194:195], v[128:129], v[196:197], v[126:127] op_sel:[1,1,0] op_sel_hi:[0,1,1]
	v_pk_fma_f32 v[126:127], v[128:129], v[196:197], v[126:127] op_sel:[1,1,0] op_sel_hi:[0,1,1] neg_lo:[0,0,1] neg_hi:[0,0,1]
	v_mov_b32_e32 v195, v127
	v_pk_mul_f32 v[126:127], v[122:123], v[216:217] op_sel_hi:[1,0]
	s_nop 0
	v_pk_fma_f32 v[196:197], v[122:123], v[198:199], v[126:127] op_sel:[1,0,0] op_sel_hi:[0,1,1]
	v_pk_fma_f32 v[122:123], v[122:123], v[198:199], v[126:127] op_sel:[1,0,0] op_sel_hi:[0,0,1] neg_lo:[0,0,1] neg_hi:[0,0,1]
	v_mov_b32_e32 v197, v123
	v_pk_mul_f32 v[122:123], v[124:125], v[64:65] op_sel_hi:[1,0]
	v_mov_b32_e32 v64, v199
	v_pk_fma_f32 v[198:199], v[124:125], v[64:65], v[122:123] op_sel:[1,0,0] op_sel_hi:[0,0,1]
	v_pk_fma_f32 v[122:123], v[124:125], v[64:65], v[122:123] op_sel:[1,0,0] op_sel_hi:[0,0,1] neg_lo:[0,0,1] neg_hi:[0,0,1]
	v_mov_b32_e32 v64, v65
	v_mov_b32_e32 v199, v123
	v_mov_b64_e32 v[126:127], v[64:65]
	v_mov_b64_e32 v[124:125], v[64:65]
	v_mov_b64_e32 v[122:123], v[64:65]
	v_mov_b64_e32 v[128:129], v[64:65]
	s_and_saveexec_b64 s[8:9], s[6:7]
	v_pk_add_f32 v[126:127], v[192:193], 0 op_sel_hi:[1,0]
	v_pk_add_f32 v[124:125], v[194:195], 0 op_sel_hi:[1,0]
	v_pk_add_f32 v[122:123], v[196:197], 0 op_sel_hi:[1,0]
	v_pk_add_f32 v[128:129], v[198:199], 0 op_sel_hi:[1,0]
	s_or_b64 exec, exec, s[8:9]
	v_pk_mul_f32 v[192:193], v[188:189], v[192:193] op_sel_hi:[0,1]
	v_pk_mul_f32 v[194:195], v[188:189], v[194:195] op_sel_hi:[0,1]
	v_pk_mov_b32 v[192:193], v[192:193], v[192:193] op_sel:[1,0]
	v_pk_mov_b32 v[194:195], v[194:195], v[194:195] op_sel:[1,0]
	v_cvt_pk_bf16_f32 v192, v192, v193
	v_cvt_pk_bf16_f32 v193, v194, v195
	v_pk_mul_f32 v[194:195], v[188:189], v[196:197] op_sel_hi:[0,1]
	v_pk_mul_f32 v[196:197], v[188:189], v[198:199] op_sel_hi:[0,1]
	v_pk_mov_b32 v[194:195], v[194:195], v[194:195] op_sel:[1,0]
	v_pk_mov_b32 v[196:197], v[196:197], v[196:197] op_sel:[1,0]
	s_movk_i32 s8, 0x1200
	v_cvt_pk_bf16_f32 v194, v194, v195
	v_cvt_pk_bf16_f32 v195, v196, v197
	v_mul_lo_u32 v196, v187, s8
	v_add_u32_e32 v64, v196, v186
	v_lshl_add_u64 v[198:199], v[64:65], 1, s[84:85]
	global_store_dwordx4 v[198:199], v[192:195], off nt
	v_mov_b32_e32 v64, v185
	s_nop 0
	v_pk_mul_f32 v[194:195], v[118:119], v[182:183] op_sel:[1,0] op_sel_hi:[0,0]
	v_pk_mul_f32 v[182:183], v[120:121], v[182:183] op_sel:[1,1] op_sel_hi:[0,1]
	v_pk_fma_f32 v[192:193], v[118:119], v[178:179], v[194:195] op_sel_hi:[1,0,1] neg_lo:[0,0,1] neg_hi:[0,0,1]
	v_pk_fma_f32 v[194:195], v[118:119], v[178:179], v[194:195] op_sel_hi:[1,0,1]
	v_pk_fma_f32 v[118:119], v[120:121], v[178:179], v[182:183] op_sel:[0,1,0] neg_lo:[0,0,1] neg_hi:[0,0,1]
	v_pk_fma_f32 v[178:179], v[120:121], v[178:179], v[182:183] op_sel:[0,1,0]
	v_pk_mul_f32 v[182:183], v[114:115], v[184:185] op_sel:[1,0] op_sel_hi:[0,0]
	v_pk_mul_f32 v[184:185], v[116:117], v[64:65] op_sel:[1,0] op_sel_hi:[0,0]
; __device__ __forceinline__ unsigned pk2(float lo, float hi) { f32x2_t v = {lo, hi}; bf16x2_t b = __builtin_convertvector(v, bf16x2_t); return __builtin_bit_cast(unsigned, b); }
;     __device__ __forceinline__ void operator()(const f32x4 (&acc)[2][2][4][2], const Unit& u, int wr, int wc, int fr, int fq) const {
;     ...
;                     for (int i = 0; i < 8; ++i) {
;                         const int ai = i >> 2, m = i & 3, row = row0 + ai * 128 + m * 16;
;                         const f32x4 v0 = acc[ai][bj][m][0], v1 = acc[ai][bj][m][1];
;                         float r[8];
;                         r[0] = v0[0] * c4[i][0] - v0[1] * s4[i][0]; r[1] = v0[0] * s4[i][0] + v0[1] * c4[i][0];
;                         r[2] = v0[2] * c4[i][1] - v0[3] * s4[i][1]; r[3] = v0[2] * s4[i][1] + v0[3] * c4[i][1];
;                         r[4] = v1[0] * c4[i][2] - v1[1] * s4[i][2]; r[5] = v1[0] * s4[i][2] + v1[1] * c4[i][2];
;                         r[6] = v1[2] * c4[i][3] - v1[3] * s4[i][3]; r[7] = v1[2] * s4[i][3] + v1[3] * c4[i][3];
;                         if (ksum_on) {
; #pragma unroll
;                             for (int j = 0; j < 8; ++j) ks[j] += r[j];
;                         }
;                         u32x4 w; w.x = pk2(r[0] * sc, r[1] * sc); w.y = pk2(r[2] * sc, r[3] * sc); w.z = pk2(r[4] * sc, r[5] * sc); w.w = pk2(r[6] * sc, r[7] * sc);
;                         __builtin_nontemporal_store(w, (u32x4*)(qkv + (unsigned)(row * LDQ + col)));
	v_mov_b32_e32 v64, v181
	v_pk_fma_f32 v[120:121], v[114:115], v[180:181], v[182:183] op_sel_hi:[1,0,1] neg_lo:[0,0,1] neg_hi:[0,0,1]
	v_pk_fma_f32 v[182:183], v[114:115], v[180:181], v[182:183] op_sel_hi:[1,0,1]
	v_pk_fma_f32 v[114:115], v[116:117], v[64:65], v[184:185] op_sel_hi:[1,0,1] neg_lo:[0,0,1] neg_hi:[0,0,1]
	v_pk_fma_f32 v[116:117], v[116:117], v[64:65], v[184:185] op_sel_hi:[1,0,1]
	s_and_saveexec_b64 s[8:9], s[6:7]
	v_pk_mov_b32 v[180:181], v[194:195], v[192:193] op_sel:[1,0]
	s_nop 0
	v_pk_add_f32 v[126:127], v[180:181], v[126:127]
	v_pk_mov_b32 v[180:181], v[178:179], v[118:119] op_sel:[1,0]
	s_nop 0
	v_pk_add_f32 v[124:125], v[180:181], v[124:125]
	v_pk_mov_b32 v[180:181], v[182:183], v[120:121] op_sel:[1,0]
	s_nop 0
	v_pk_add_f32 v[122:123], v[180:181], v[122:123]
	v_pk_mov_b32 v[180:181], v[116:117], v[114:115] op_sel:[1,0]
	s_nop 0
	v_pk_add_f32 v[128:129], v[180:181], v[128:129]
	s_or_b64 exec, exec, s[8:9]
	v_mov_b32_e32 v189, v188
	v_mov_b32_e32 v193, v195
	v_mov_b32_e32 v119, v179
	v_mov_b32_e32 v121, v183
	v_mov_b32_e32 v115, v117
	v_pk_mul_f32 v[116:117], v[188:189], v[192:193]
	v_pk_mul_f32 v[118:119], v[188:189], v[118:119]
	v_or_b32_e32 v178, 0x12000, v186
	v_cvt_pk_bf16_f32 v116, v116, v117
	v_cvt_pk_bf16_f32 v117, v118, v119
	v_pk_mul_f32 v[118:119], v[188:189], v[120:121]
	v_pk_mul_f32 v[114:115], v[188:189], v[114:115]
	v_add_u32_e32 v64, v178, v196
	v_cvt_pk_bf16_f32 v118, v118, v119
	v_cvt_pk_bf16_f32 v119, v114, v115
	v_lshl_add_u64 v[114:115], v[64:65], 1, s[84:85]
	global_store_dwordx4 v[114:115], v[116:119], off nt
	v_mov_b32_e32 v64, v177
	v_pk_mul_f32 v[120:121], v[106:107], v[176:177] op_sel:[1,0] op_sel_hi:[0,0]
	v_pk_mul_f32 v[116:117], v[110:111], v[174:175] op_sel:[1,0] op_sel_hi:[0,0]
	v_pk_mul_f32 v[118:119], v[112:113], v[174:175] op_sel:[1,1] op_sel_hi:[0,1]
	v_pk_fma_f32 v[114:115], v[110:111], v[170:171], v[116:117] op_sel_hi:[1,0,1] neg_lo:[0,0,1] neg_hi:[0,0,1]
	v_pk_fma_f32 v[116:117], v[110:111], v[170:171], v[116:117] op_sel_hi:[1,0,1]
	v_pk_fma_f32 v[110:111], v[112:113], v[170:171], v[118:119] op_sel:[0,1,0] neg_lo:[0,0,1] neg_hi:[0,0,1]
	v_pk_fma_f32 v[118:119], v[112:113], v[170:171], v[118:119] op_sel:[0,1,0]
	v_pk_mul_f32 v[170:171], v[108:109], v[64:65] op_sel:[1,0] op_sel_hi:[0,0]
	v_mov_b32_e32 v64, v173
	v_pk_fma_f32 v[112:113], v[106:107], v[172:173], v[120:121] op_sel_hi:[1,0,1] neg_lo:[0,0,1] neg_hi:[0,0,1]
	v_pk_fma_f32 v[120:121], v[106:107], v[172:173], v[120:121] op_sel_hi:[1,0,1]
	v_pk_fma_f32 v[106:107], v[108:109], v[64:65], v[170:171] op_sel_hi:[1,0,1] neg_lo:[0,0,1] neg_hi:[0,0,1]
	v_pk_fma_f32 v[108:109], v[108:109], v[64:65], v[170:171] op_sel_hi:[1,0,1]
	s_and_saveexec_b64 s[8:9], s[6:7]
	v_pk_mov_b32 v[170:171], v[116:117], v[114:115] op_sel:[1,0]
	s_nop 0
	v_pk_add_f32 v[126:127], v[170:171], v[126:127]
	v_pk_mov_b32 v[170:171], v[118:119], v[110:111] op_sel:[1,0]
	s_nop 0
	v_pk_add_f32 v[124:125], v[170:171], v[124:125]
	v_pk_mov_b32 v[170:171], v[120:121], v[112:113] op_sel:[1,0]
	s_nop 0
	v_pk_add_f32 v[122:123], v[170:171], v[122:123]
	v_pk_mov_b32 v[170:171], v[108:109], v[106:107] op_sel:[1,0]
	s_nop 0
	v_pk_add_f32 v[128:129], v[170:171], v[128:129]
	s_or_b64 exec, exec, s[8:9]
	v_mov_b32_e32 v115, v117
	v_mov_b32_e32 v111, v119
	v_mov_b32_e32 v107, v109
	v_pk_mul_f32 v[108:109], v[188:189], v[114:115]
	v_mov_b32_e32 v113, v121
	v_cvt_pk_bf16_f32 v114, v108, v109
	v_pk_mul_f32 v[108:109], v[188:189], v[110:111]
	v_pk_mul_f32 v[106:107], v[188:189], v[106:107]
	v_cvt_pk_bf16_f32 v115, v108, v109
	v_pk_mul_f32 v[108:109], v[188:189], v[112:113]
	v_cvt_pk_bf16_f32 v117, v106, v107
	v_cvt_pk_bf16_f32 v116, v108, v109
	v_or_b32_e32 v108, 0x24000, v186
	v_add_u32_e32 v64, v108, v196
	v_lshl_add_u64 v[106:107], v[64:65], 1, s[84:85]
	v_pk_mul_f32 v[110:111], v[102:103], v[166:167] op_sel_hi:[1,0]
	global_store_dwordx4 v[106:107], v[114:117], off nt
	v_pk_fma_f32 v[106:107], v[102:103], v[162:163], v[110:111] op_sel:[1,0,0] op_sel_hi:[0,1,1]
	v_pk_fma_f32 v[102:103], v[102:103], v[162:163], v[110:111] op_sel:[1,0,0] op_sel_hi:[0,0,1] neg_lo:[0,0,1] neg_hi:[0,0,1]
	v_pk_mul_f32 v[110:111], v[104:105], v[166:167] op_sel:[0,1]
	v_mov_b32_e32 v107, v103
	v_pk_fma_f32 v[102:103], v[104:105], v[162:163], v[110:111] op_sel:[1,1,0] op_sel_hi:[0,1,1]
	v_pk_fma_f32 v[104:105], v[104:105], v[162:163], v[110:111] op_sel:[1,1,0] op_sel_hi:[0,1,1] neg_lo:[0,0,1] neg_hi:[0,0,1]
	v_pk_mul_f32 v[110:111], v[98:99], v[168:169] op_sel_hi:[1,0]
	v_mov_b32_e32 v64, v169
	v_mov_b32_e32 v103, v105
	v_pk_fma_f32 v[104:105], v[98:99], v[164:165], v[110:111] op_sel:[1,0,0] op_sel_hi:[0,1,1]
	v_pk_fma_f32 v[98:99], v[98:99], v[164:165], v[110:111] op_sel:[1,0,0] op_sel_hi:[0,0,1] neg_lo:[0,0,1] neg_hi:[0,0,1]
	v_pk_mul_f32 v[110:111], v[100:101], v[64:65] op_sel_hi:[1,0]
	v_mov_b32_e32 v64, v165
	v_mov_b32_e32 v105, v99
	v_pk_fma_f32 v[98:99], v[100:101], v[64:65], v[110:111] op_sel:[1,0,0] op_sel_hi:[0,0,1]
	v_pk_fma_f32 v[100:101], v[100:101], v[64:65], v[110:111] op_sel:[1,0,0] op_sel_hi:[0,0,1] neg_lo:[0,0,1] neg_hi:[0,0,1]
	v_mov_b32_e32 v99, v101
	s_and_saveexec_b64 s[8:9], s[6:7]
	v_pk_add_f32 v[126:127], v[106:107], v[126:127]
	v_pk_add_f32 v[124:125], v[102:103], v[124:125]
	v_pk_add_f32 v[122:123], v[104:105], v[122:123]
	v_pk_add_f32 v[128:129], v[98:99], v[128:129]
	s_or_b64 exec, exec, s[8:9]
	v_pk_mul_f32 v[100:101], v[188:189], v[106:107]
	v_pk_mul_f32 v[98:99], v[188:189], v[98:99]
	v_pk_mov_b32 v[100:101], v[100:101], v[100:101] op_sel:[1,0]
	v_pk_mov_b32 v[98:99], v[98:99], v[98:99] op_sel:[1,0]
	v_cvt_pk_bf16_f32 v110, v100, v101
	v_pk_mul_f32 v[100:101], v[188:189], v[102:103]
; __device__ __forceinline__ unsigned pk2(float lo, float hi) { f32x2_t v = {lo, hi}; bf16x2_t b = __builtin_convertvector(v, bf16x2_t); return __builtin_bit_cast(unsigned, b); }
;     __device__ __forceinline__ void operator()(const f32x4 (&acc)[2][2][4][2], const Unit& u, int wr, int wc, int fr, int fq) const {
;     ...
;                     for (int i = 0; i < 8; ++i) {
;                         const int ai = i >> 2, m = i & 3, row = row0 + ai * 128 + m * 16;
;                         const f32x4 v0 = acc[ai][bj][m][0], v1 = acc[ai][bj][m][1];
;                         float r[8];
;                         r[0] = v0[0] * c4[i][0] - v0[1] * s4[i][0]; r[1] = v0[0] * s4[i][0] + v0[1] * c4[i][0];
;                         r[2] = v0[2] * c4[i][1] - v0[3] * s4[i][1]; r[3] = v0[2] * s4[i][1] + v0[3] * c4[i][1];
;                         r[4] = v1[0] * c4[i][2] - v1[1] * s4[i][2]; r[5] = v1[0] * s4[i][2] + v1[1] * c4[i][2];
;                         r[6] = v1[2] * c4[i][3] - v1[3] * s4[i][3]; r[7] = v1[2] * s4[i][3] + v1[3] * c4[i][3];
;                         if (ksum_on) {
; #pragma unroll
;                             for (int j = 0; j < 8; ++j) ks[j] += r[j];
;                         }
;                         u32x4 w; w.x = pk2(r[0] * sc, r[1] * sc); w.y = pk2(r[2] * sc, r[3] * sc); w.z = pk2(r[4] * sc, r[5] * sc); w.w = pk2(r[6] * sc, r[7] * sc);
;                         __builtin_nontemporal_store(w, (u32x4*)(qkv + (unsigned)(row * LDQ + col)));
	v_cvt_pk_bf16_f32 v113, v98, v99
	v_pk_mov_b32 v[100:101], v[100:101], v[100:101] op_sel:[1,0]
	v_pk_mul_f32 v[102:103], v[94:95], v[158:159] op_sel_hi:[1,0]
	v_cvt_pk_bf16_f32 v111, v100, v101
	v_pk_mul_f32 v[100:101], v[188:189], v[104:105]
	s_nop 0
	v_pk_mov_b32 v[100:101], v[100:101], v[100:101] op_sel:[1,0]
	s_nop 0
	v_cvt_pk_bf16_f32 v112, v100, v101
	v_or_b32_e32 v100, 0x36000, v186
	v_add_u32_e32 v64, v100, v196
	v_lshl_add_u64 v[98:99], v[64:65], 1, s[84:85]
	global_store_dwordx4 v[98:99], v[110:113], off nt
	v_pk_fma_f32 v[98:99], v[94:95], v[154:155], v[102:103] op_sel:[1,0,0] op_sel_hi:[0,1,1]
	v_pk_fma_f32 v[94:95], v[94:95], v[154:155], v[102:103] op_sel:[1,0,0] op_sel_hi:[0,0,1] neg_lo:[0,0,1] neg_hi:[0,0,1]
	v_pk_mul_f32 v[102:103], v[96:97], v[158:159] op_sel:[0,1]
	v_mov_b32_e32 v99, v95
	v_pk_fma_f32 v[94:95], v[96:97], v[154:155], v[102:103] op_sel:[1,1,0] op_sel_hi:[0,1,1]
	v_pk_fma_f32 v[96:97], v[96:97], v[154:155], v[102:103] op_sel:[1,1,0] op_sel_hi:[0,1,1] neg_lo:[0,0,1] neg_hi:[0,0,1]
	v_pk_mul_f32 v[102:103], v[90:91], v[160:161] op_sel_hi:[1,0]
	v_mov_b32_e32 v64, v161
	v_mov_b32_e32 v95, v97
	v_pk_fma_f32 v[96:97], v[90:91], v[156:157], v[102:103] op_sel:[1,0,0] op_sel_hi:[0,1,1]
	v_pk_fma_f32 v[90:91], v[90:91], v[156:157], v[102:103] op_sel:[1,0,0] op_sel_hi:[0,0,1] neg_lo:[0,0,1] neg_hi:[0,0,1]
	v_pk_mul_f32 v[102:103], v[92:93], v[64:65] op_sel_hi:[1,0]
	v_mov_b32_e32 v64, v157
	v_mov_b32_e32 v97, v91
	v_pk_fma_f32 v[90:91], v[92:93], v[64:65], v[102:103] op_sel:[1,0,0] op_sel_hi:[0,0,1]
	v_pk_fma_f32 v[92:93], v[92:93], v[64:65], v[102:103] op_sel:[1,0,0] op_sel_hi:[0,0,1] neg_lo:[0,0,1] neg_hi:[0,0,1]
	v_mov_b32_e32 v91, v93
	s_and_saveexec_b64 s[8:9], s[6:7]
	v_pk_add_f32 v[126:127], v[98:99], v[126:127]
	v_pk_add_f32 v[124:125], v[94:95], v[124:125]
	v_pk_add_f32 v[122:123], v[96:97], v[122:123]
	v_pk_add_f32 v[128:129], v[90:91], v[128:129]
	s_or_b64 exec, exec, s[8:9]
	v_pk_mul_f32 v[92:93], v[188:189], v[98:99]
	v_pk_mul_f32 v[90:91], v[188:189], v[90:91]
	v_pk_mov_b32 v[92:93], v[92:93], v[92:93] op_sel:[1,0]
	v_pk_mov_b32 v[90:91], v[90:91], v[90:91] op_sel:[1,0]
	v_cvt_pk_bf16_f32 v102, v92, v93
	v_pk_mul_f32 v[92:93], v[188:189], v[94:95]
	v_cvt_pk_bf16_f32 v105, v90, v91
	v_pk_mov_b32 v[92:93], v[92:93], v[92:93] op_sel:[1,0]
	v_pk_mul_f32 v[94:95], v[86:87], v[150:151] op_sel_hi:[1,0]
	v_cvt_pk_bf16_f32 v103, v92, v93
	v_pk_mul_f32 v[92:93], v[188:189], v[96:97]
	s_nop 0
	v_pk_mov_b32 v[92:93], v[92:93], v[92:93] op_sel:[1,0]
	s_nop 0
	v_cvt_pk_bf16_f32 v104, v92, v93
	v_add_u32_e32 v92, 0x90000, v196
	v_add_u32_e32 v64, v92, v186
	v_lshl_add_u64 v[90:91], v[64:65], 1, s[84:85]
	global_store_dwordx4 v[90:91], v[102:105], off nt
	v_pk_fma_f32 v[90:91], v[86:87], v[146:147], v[94:95] op_sel:[1,0,0] op_sel_hi:[0,1,1]
	v_pk_fma_f32 v[86:87], v[86:87], v[146:147], v[94:95] op_sel:[1,0,0] op_sel_hi:[0,0,1] neg_lo:[0,0,1] neg_hi:[0,0,1]
	v_pk_mul_f32 v[94:95], v[88:89], v[150:151] op_sel:[0,1]
	v_mov_b32_e32 v91, v87
	v_pk_fma_f32 v[86:87], v[88:89], v[146:147], v[94:95] op_sel:[1,1,0] op_sel_hi:[0,1,1]
	v_pk_fma_f32 v[88:89], v[88:89], v[146:147], v[94:95] op_sel:[1,1,0] op_sel_hi:[0,1,1] neg_lo:[0,0,1] neg_hi:[0,0,1]
	v_pk_mul_f32 v[94:95], v[82:83], v[152:153] op_sel_hi:[1,0]
	v_mov_b32_e32 v64, v153
	v_mov_b32_e32 v87, v89
	v_pk_fma_f32 v[88:89], v[82:83], v[148:149], v[94:95] op_sel:[1,0,0] op_sel_hi:[0,1,1]
	v_pk_fma_f32 v[82:83], v[82:83], v[148:149], v[94:95] op_sel:[1,0,0] op_sel_hi:[0,0,1] neg_lo:[0,0,1] neg_hi:[0,0,1]
	v_pk_mul_f32 v[94:95], v[84:85], v[64:65] op_sel_hi:[1,0]
	v_mov_b32_e32 v64, v149
	v_mov_b32_e32 v89, v83
	v_pk_fma_f32 v[82:83], v[84:85], v[64:65], v[94:95] op_sel:[1,0,0] op_sel_hi:[0,0,1]
	v_pk_fma_f32 v[84:85], v[84:85], v[64:65], v[94:95] op_sel:[1,0,0] op_sel_hi:[0,0,1] neg_lo:[0,0,1] neg_hi:[0,0,1]
	v_mov_b32_e32 v83, v85
	s_and_saveexec_b64 s[8:9], s[6:7]
	v_pk_add_f32 v[126:127], v[90:91], v[126:127]
	v_pk_add_f32 v[124:125], v[86:87], v[124:125]
	v_pk_add_f32 v[122:123], v[88:89], v[122:123]
	v_pk_add_f32 v[128:129], v[82:83], v[128:129]
	s_or_b64 exec, exec, s[8:9]
	v_pk_mul_f32 v[84:85], v[188:189], v[90:91]
	v_pk_mul_f32 v[86:87], v[188:189], v[86:87]
	v_pk_mov_b32 v[84:85], v[84:85], v[84:85] op_sel:[1,0]
	v_pk_mov_b32 v[86:87], v[86:87], v[86:87] op_sel:[1,0]
	v_cvt_pk_bf16_f32 v84, v84, v85
	v_cvt_pk_bf16_f32 v85, v86, v87
	v_pk_mul_f32 v[86:87], v[188:189], v[88:89]
	v_pk_mul_f32 v[82:83], v[188:189], v[82:83]
	v_pk_mov_b32 v[86:87], v[86:87], v[86:87] op_sel:[1,0]
	v_pk_mov_b32 v[82:83], v[82:83], v[82:83] op_sel:[1,0]
	v_add_u32_e32 v64, v178, v92
	v_cvt_pk_bf16_f32 v86, v86, v87
	v_cvt_pk_bf16_f32 v87, v82, v83
	v_lshl_add_u64 v[82:83], v[64:65], 1, s[84:85]
	global_store_dwordx4 v[82:83], v[84:87], off nt
	v_mov_b32_e32 v64, v145
	s_nop 0
	v_pk_mul_f32 v[84:85], v[78:79], v[142:143] op_sel_hi:[1,0]
	s_nop 0
	v_pk_fma_f32 v[82:83], v[78:79], v[138:139], v[84:85] op_sel:[1,0,0] op_sel_hi:[0,1,1]
	v_pk_fma_f32 v[78:79], v[78:79], v[138:139], v[84:85] op_sel:[1,0,0] op_sel_hi:[0,0,1] neg_lo:[0,0,1] neg_hi:[0,0,1]
	v_pk_mul_f32 v[84:85], v[80:81], v[142:143] op_sel:[0,1]
	v_mov_b32_e32 v83, v79
	v_pk_fma_f32 v[78:79], v[80:81], v[138:139], v[84:85] op_sel:[1,1,0] op_sel_hi:[0,1,1]
	v_pk_fma_f32 v[80:81], v[80:81], v[138:139], v[84:85] op_sel:[1,1,0] op_sel_hi:[0,1,1] neg_lo:[0,0,1] neg_hi:[0,0,1]
	v_pk_mul_f32 v[84:85], v[74:75], v[144:145] op_sel_hi:[1,0]
	v_mov_b32_e32 v79, v81
	v_pk_fma_f32 v[80:81], v[74:75], v[140:141], v[84:85] op_sel:[1,0,0] op_sel_hi:[0,1,1]
	v_pk_fma_f32 v[74:75], v[74:75], v[140:141], v[84:85] op_sel:[1,0,0] op_sel_hi:[0,0,1] neg_lo:[0,0,1] neg_hi:[0,0,1]
; __device__ __forceinline__ unsigned pk2(float lo, float hi) { f32x2_t v = {lo, hi}; bf16x2_t b = __builtin_convertvector(v, bf16x2_t); return __builtin_bit_cast(unsigned, b); }
; template <int K> __device__ __forceinline__ float swz_xor(float v) { return __int_as_float(__builtin_amdgcn_ds_swizzle(__float_as_int(v), (K << 10) | 0x1f)); }
;     __device__ __forceinline__ void operator()(const f32x4 (&acc)[2][2][4][2], const Unit& u, int wr, int wc, int fr, int fq) const {
;     ...
;                     for (int i = 0; i < 8; ++i) {
;                         const int ai = i >> 2, m = i & 3, row = row0 + ai * 128 + m * 16;
;                         const f32x4 v0 = acc[ai][bj][m][0], v1 = acc[ai][bj][m][1];
;                         float r[8];
;                         r[0] = v0[0] * c4[i][0] - v0[1] * s4[i][0]; r[1] = v0[0] * s4[i][0] + v0[1] * c4[i][0];
;                         r[2] = v0[2] * c4[i][1] - v0[3] * s4[i][1]; r[3] = v0[2] * s4[i][1] + v0[3] * c4[i][1];
;                         r[4] = v1[0] * c4[i][2] - v1[1] * s4[i][2]; r[5] = v1[0] * s4[i][2] + v1[1] * c4[i][2];
;                         r[6] = v1[2] * c4[i][3] - v1[3] * s4[i][3]; r[7] = v1[2] * s4[i][3] + v1[3] * c4[i][3];
;                         if (ksum_on) {
; #pragma unroll
;                             for (int j = 0; j < 8; ++j) ks[j] += r[j];
;                         }
;                         u32x4 w; w.x = pk2(r[0] * sc, r[1] * sc); w.y = pk2(r[2] * sc, r[3] * sc); w.z = pk2(r[4] * sc, r[5] * sc); w.w = pk2(r[6] * sc, r[7] * sc);
;                         __builtin_nontemporal_store(w, (u32x4*)(qkv + (unsigned)(row * LDQ + col)));
;                     }
;                     if (ksum_on) {
; #pragma unroll
;                         for (int j = 0; j < 8; ++j) {
;                             float v = ks[j];
;                             v += swz_xor<1>(v); v += swz_xor<2>(v); v += swz_xor<4>(v); v += swz_xor<8>(v);
;                             ks[j] = v;
;                         }
;                         if (fr == 0) {
;                             float* dst = kmean + (size_t)(((u.pm >> 3) * 6 + (head - 12)) * 8 + (u.pm & 7)) * 64 + dc;
; #pragma unroll
;                             for (int j = 0; j < 8; ++j) atomicAdd(dst + j, ks[j]);
;                         }
	v_pk_mul_f32 v[84:85], v[76:77], v[64:65] op_sel_hi:[1,0]
	v_mov_b32_e32 v64, v141
	v_mov_b32_e32 v81, v75
	v_pk_fma_f32 v[74:75], v[76:77], v[64:65], v[84:85] op_sel:[1,0,0] op_sel_hi:[0,0,1]
	v_pk_fma_f32 v[76:77], v[76:77], v[64:65], v[84:85] op_sel:[1,0,0] op_sel_hi:[0,0,1] neg_lo:[0,0,1] neg_hi:[0,0,1]
	v_mov_b32_e32 v75, v77
	s_and_saveexec_b64 s[8:9], s[6:7]
	v_pk_add_f32 v[126:127], v[82:83], v[126:127]
	v_pk_add_f32 v[124:125], v[78:79], v[124:125]
	v_pk_add_f32 v[122:123], v[80:81], v[122:123]
	v_pk_add_f32 v[128:129], v[74:75], v[128:129]
	s_or_b64 exec, exec, s[8:9]
	v_pk_mul_f32 v[76:77], v[188:189], v[82:83]
	v_pk_mul_f32 v[78:79], v[188:189], v[78:79]
	v_pk_mov_b32 v[76:77], v[76:77], v[76:77] op_sel:[1,0]
	v_pk_mov_b32 v[78:79], v[78:79], v[78:79] op_sel:[1,0]
	v_cvt_pk_bf16_f32 v76, v76, v77
	v_cvt_pk_bf16_f32 v77, v78, v79
	v_pk_mul_f32 v[78:79], v[188:189], v[80:81]
	v_pk_mul_f32 v[74:75], v[188:189], v[74:75]
	v_pk_mov_b32 v[78:79], v[78:79], v[78:79] op_sel:[1,0]
	v_pk_mov_b32 v[74:75], v[74:75], v[74:75] op_sel:[1,0]
	v_add_u32_e32 v64, v108, v92
	v_cvt_pk_bf16_f32 v78, v78, v79
	v_cvt_pk_bf16_f32 v79, v74, v75
	v_lshl_add_u64 v[74:75], v[64:65], 1, s[84:85]
	global_store_dwordx4 v[74:75], v[76:79], off nt
	v_mov_b32_e32 v64, v137
	s_nop 0
	v_pk_mul_f32 v[76:77], v[70:71], v[134:135] op_sel_hi:[1,0]
	s_nop 0
	v_pk_fma_f32 v[74:75], v[70:71], v[130:131], v[76:77] op_sel:[1,0,0] op_sel_hi:[0,1,1]
	v_pk_fma_f32 v[70:71], v[70:71], v[130:131], v[76:77] op_sel:[1,0,0] op_sel_hi:[0,0,1] neg_lo:[0,0,1] neg_hi:[0,0,1]
	v_pk_mul_f32 v[76:77], v[72:73], v[134:135] op_sel:[0,1]
	v_mov_b32_e32 v75, v71
	v_pk_fma_f32 v[70:71], v[72:73], v[130:131], v[76:77] op_sel:[1,1,0] op_sel_hi:[0,1,1]
	v_pk_fma_f32 v[72:73], v[72:73], v[130:131], v[76:77] op_sel:[1,1,0] op_sel_hi:[0,1,1] neg_lo:[0,0,1] neg_hi:[0,0,1]
	v_pk_mul_f32 v[76:77], v[66:67], v[136:137] op_sel_hi:[1,0]
	v_mov_b32_e32 v71, v73
	v_pk_fma_f32 v[72:73], v[66:67], v[132:133], v[76:77] op_sel:[1,0,0] op_sel_hi:[0,1,1]
	v_pk_fma_f32 v[66:67], v[66:67], v[132:133], v[76:77] op_sel:[1,0,0] op_sel_hi:[0,0,1] neg_lo:[0,0,1] neg_hi:[0,0,1]
	v_pk_mul_f32 v[76:77], v[68:69], v[64:65] op_sel_hi:[1,0]
	v_mov_b32_e32 v64, v133
	v_mov_b32_e32 v73, v67
	v_pk_fma_f32 v[66:67], v[68:69], v[64:65], v[76:77] op_sel:[1,0,0] op_sel_hi:[0,0,1]
	v_pk_fma_f32 v[68:69], v[68:69], v[64:65], v[76:77] op_sel:[1,0,0] op_sel_hi:[0,0,1] neg_lo:[0,0,1] neg_hi:[0,0,1]
	v_mov_b32_e32 v67, v69
	s_and_saveexec_b64 s[8:9], s[6:7]
	v_pk_add_f32 v[126:127], v[74:75], v[126:127]
	v_pk_add_f32 v[124:125], v[70:71], v[124:125]
	v_pk_add_f32 v[122:123], v[72:73], v[122:123]
	v_pk_add_f32 v[128:129], v[66:67], v[128:129]
	s_or_b64 exec, exec, s[8:9]
	v_pk_mul_f32 v[68:69], v[188:189], v[74:75]
	v_pk_mul_f32 v[70:71], v[188:189], v[70:71]
	v_pk_mov_b32 v[68:69], v[68:69], v[68:69] op_sel:[1,0]
	v_pk_mov_b32 v[70:71], v[70:71], v[70:71] op_sel:[1,0]
	v_cvt_pk_bf16_f32 v68, v68, v69
	v_cvt_pk_bf16_f32 v69, v70, v71
	v_pk_mul_f32 v[70:71], v[188:189], v[72:73]
	v_pk_mul_f32 v[66:67], v[188:189], v[66:67]
	v_pk_mov_b32 v[70:71], v[70:71], v[70:71] op_sel:[1,0]
	v_pk_mov_b32 v[66:67], v[66:67], v[66:67] op_sel:[1,0]
	v_add_u32_e32 v64, v100, v92
	v_cvt_pk_bf16_f32 v70, v70, v71
	v_cvt_pk_bf16_f32 v71, v66, v67
	v_lshl_add_u64 v[66:67], v[64:65], 1, s[84:85]
	global_store_dwordx4 v[66:67], v[68:71], off nt
	s_and_saveexec_b64 s[8:9], s[6:7]
	s_cbranch_execz .LBB0_537
	ds_swizzle_b32 v66, v126 offset:swizzle(SWAP,1)
	ds_swizzle_b32 v67, v125 offset:swizzle(SWAP,1)
	ds_swizzle_b32 v71, v124 offset:swizzle(SWAP,1)
	ds_swizzle_b32 v64, v127 offset:swizzle(SWAP,1)
	ds_swizzle_b32 v72, v123 offset:swizzle(SWAP,1)
	s_waitcnt lgkmcnt(0)
	v_add_f32_e32 v66, v126, v66
	ds_swizzle_b32 v69, v66 offset:swizzle(SWAP,2)
	v_add_f32_e32 v67, v125, v67
	ds_swizzle_b32 v70, v67 offset:swizzle(SWAP,2)
	ds_swizzle_b32 v76, v129 offset:swizzle(SWAP,1)
	ds_swizzle_b32 v77, v128 offset:swizzle(SWAP,1)
	s_waitcnt lgkmcnt(0)
	v_add_f32_e32 v66, v66, v69
	ds_swizzle_b32 v69, v66 offset:swizzle(SWAP,4)
	v_add_f32_e32 v70, v67, v70
	v_add_f32_e32 v64, v127, v64
	v_add_f32_e32 v72, v123, v72
	v_add_f32_e32 v76, v129, v76
	s_waitcnt lgkmcnt(0)
	v_add_f32_e32 v67, v66, v69
	v_add_f32_e32 v69, v124, v71
	ds_swizzle_b32 v71, v69 offset:swizzle(SWAP,2)
	v_add_f32_e32 v77, v128, v77
	ds_swizzle_b32 v68, v64 offset:swizzle(SWAP,2)
	ds_swizzle_b32 v73, v70 offset:swizzle(SWAP,4)
	ds_swizzle_b32 v74, v72 offset:swizzle(SWAP,2)
	s_waitcnt lgkmcnt(0)
	v_add_f32_e32 v71, v69, v71
	ds_swizzle_b32 v75, v71 offset:swizzle(SWAP,4)
	ds_swizzle_b32 v79, v76 offset:swizzle(SWAP,2)
	ds_swizzle_b32 v80, v77 offset:swizzle(SWAP,2)
	v_add_f32_e32 v64, v64, v68
	v_add_f32_e32 v69, v70, v73
	s_waitcnt lgkmcnt(0)
	v_add_f32_e32 v71, v71, v75
	ds_swizzle_b32 v75, v122 offset:swizzle(SWAP,1)
	v_add_f32_e32 v73, v72, v74
	v_add_f32_e32 v79, v76, v79
	v_add_f32_e32 v80, v77, v80
	ds_swizzle_b32 v68, v64 offset:swizzle(SWAP,4)
	s_waitcnt lgkmcnt(0)
	v_add_f32_e32 v75, v122, v75
	ds_swizzle_b32 v78, v75 offset:swizzle(SWAP,2)
	ds_swizzle_b32 v74, v73 offset:swizzle(SWAP,4)
	ds_swizzle_b32 v81, v79 offset:swizzle(SWAP,4)
	ds_swizzle_b32 v82, v80 offset:swizzle(SWAP,4)
	v_add_f32_e32 v64, v64, v68
	s_waitcnt lgkmcnt(0)
	v_add_f32_e32 v75, v75, v78
	ds_swizzle_b32 v78, v75 offset:swizzle(SWAP,4)
	v_add_f32_e32 v73, v73, v74
	v_add_f32_e32 v77, v79, v81
	v_add_f32_e32 v79, v80, v82
	ds_swizzle_b32 v66, v64 offset:swizzle(SWAP,8)
	s_waitcnt lgkmcnt(0)
	v_add_f32_e32 v75, v75, v78
	ds_swizzle_b32 v68, v67 offset:swizzle(SWAP,8)
	ds_swizzle_b32 v70, v69 offset:swizzle(SWAP,8)
	ds_swizzle_b32 v72, v71 offset:swizzle(SWAP,8)
	ds_swizzle_b32 v74, v73 offset:swizzle(SWAP,8)
	ds_swizzle_b32 v76, v75 offset:swizzle(SWAP,8)
	ds_swizzle_b32 v78, v77 offset:swizzle(SWAP,8)
	ds_swizzle_b32 v80, v79 offset:swizzle(SWAP,8)
	s_and_b64 exec, exec, s[0:1]
	s_cbranch_execz .LBB0_537
	s_lshr_b32 s6, s12, 3
	s_waitcnt lgkmcnt(0)
	v_add_f32_e32 v69, v69, v70
	v_add_f32_e32 v68, v67, v68
	v_add_f32_e32 v70, v64, v66
	v_mad_u64_u32 v[66:67], s[6:7], s6, 6, v[190:191]
	s_and_b32 s6, s11, 0x700
	s_nop 0
	v_lshl_or_b32 v64, v66, 11, s6
	v_lshl_add_u64 v[66:67], s[48:49], 0, v[64:65]
	v_lshlrev_b32_e32 v64, 2, v191
	v_lshl_add_u64 v[66:67], v[66:67], 0, v[64:65]
	v_add_f32_e32 v79, v79, v80
	v_add_f32_e32 v77, v77, v78
	v_add_f32_e32 v75, v75, v76
	v_add_f32_e32 v73, v73, v74
	v_add_f32_e32 v71, v71, v72
	flat_atomic_add_f32 v[66:67], v70
	flat_atomic_add_f32 v[66:67], v68 offset:4
	flat_atomic_add_f32 v[66:67], v69 offset:8
	flat_atomic_add_f32 v[66:67], v71 offset:12
	flat_atomic_add_f32 v[66:67], v73 offset:16
	flat_atomic_add_f32 v[66:67], v75 offset:20
	flat_atomic_add_f32 v[66:67], v77 offset:24
	flat_atomic_add_f32 v[66:67], v79 offset:28

; __device__ __forceinline__ unsigned pk2(float lo, float hi) { f32x2_t v = {lo, hi}; bf16x2_t b = __builtin_convertvector(v, bf16x2_t); return __builtin_bit_cast(unsigned, b); }
; __device__ __forceinline__ float sigmoidf_(float x) { return __builtin_amdgcn_rcpf(1.0f + __expf(-x)); }
;     __device__ __forceinline__ void operator()(const f32x4 (&acc)[2][2][4][2], const Unit& u, int wr, int wc, int fr, int fq) const {
;     ...
;             } else {
;                 const int gcol = col - LDQ;
;                 const f32x4 b0 = *(const f32x4*)(bgate + gcol), b1 = *(const f32x4*)(bgate + gcol + 4);
; #pragma unroll
;                 for (int ai = 0; ai < 2; ++ai)
; #pragma unroll
;                     for (int m = 0; m < 4; ++m) {
;                         const int row = row0 + ai * 128 + m * 16;
;                         const f32x4 v0 = acc[ai][bj][m][0] + b0, v1 = acc[ai][bj][m][1] + b1;
;                         u32x4 w; w.x = pk2(sigmoidf_(v0[0]), sigmoidf_(v0[1])); w.y = pk2(sigmoidf_(v0[2]), sigmoidf_(v0[3]));
;                         w.z = pk2(sigmoidf_(v1[0]), sigmoidf_(v1[1])); w.w = pk2(sigmoidf_(v1[2]), sigmoidf_(v1[3]));
;                         __builtin_nontemporal_store(w, (u32x4*)(gates + (unsigned)(row * NG + gcol)));
;                     }
.LBB0_539:
	s_andn2_b64 vcc, exec, s[2:3]
	s_mov_b64 s[2:3], -1
	s_cbranch_vccnz .LBB0_541
	s_waitcnt lgkmcnt(0)
	v_add_u32_e32 v74, 0xffffee80, v186
	v_ashrrev_i32_e32 v75, 31, v74
	v_lshl_add_u64 v[70:71], v[74:75], 2, s[52:53]
	global_load_dwordx4 v[66:69], v[70:71], off offset:16
	s_nop 0
	global_load_dwordx4 v[70:73], v[70:71], off
	s_waitcnt vmcnt(0)
	v_pk_add_f32 v[82:83], v[56:57], v[66:67]
	v_pk_add_f32 v[76:77], v[60:61], v[70:71]
	v_pk_add_f32 v[78:79], v[62:63], v[72:73]
	v_mul_f32_e32 v64, 0xbfb8aa3b, v76
	v_mul_f32_e32 v75, 0xbfb8aa3b, v77
	v_exp_f32_e32 v64, v64
	v_exp_f32_e32 v75, v75
	v_pk_add_f32 v[80:81], v[58:59], v[68:69]
	v_add_f32_e32 v64, 1.0, v64
	v_add_f32_e32 v75, 1.0, v75
	v_rcp_f32_e32 v64, v64
	v_rcp_f32_e32 v75, v75
	s_nop 0
	v_cvt_pk_bf16_f32 v76, v64, v75
	v_mul_f32_e32 v64, 0xbfb8aa3b, v78
	v_mul_f32_e32 v75, 0xbfb8aa3b, v79
	v_exp_f32_e32 v64, v64
	v_exp_f32_e32 v75, v75
	v_add_f32_e32 v64, 1.0, v64
	v_add_f32_e32 v75, 1.0, v75
	v_rcp_f32_e32 v64, v64
	v_rcp_f32_e32 v75, v75
	s_nop 0
	v_cvt_pk_bf16_f32 v77, v64, v75
	v_mul_f32_e32 v64, 0xbfb8aa3b, v82
	v_mul_f32_e32 v75, 0xbfb8aa3b, v83
	v_exp_f32_e32 v64, v64
	v_exp_f32_e32 v75, v75
	v_pk_add_f32 v[82:83], v[48:49], v[66:67]
	v_add_f32_e32 v64, 1.0, v64
	v_add_f32_e32 v75, 1.0, v75
	v_rcp_f32_e32 v64, v64
	v_rcp_f32_e32 v75, v75
	s_nop 0
	v_cvt_pk_bf16_f32 v78, v64, v75
	v_mul_f32_e32 v64, 0xbfb8aa3b, v80
	v_mul_f32_e32 v75, 0xbfb8aa3b, v81
	v_exp_f32_e32 v64, v64
	v_exp_f32_e32 v75, v75
	v_add_f32_e32 v64, 1.0, v64
	v_add_f32_e32 v75, 1.0, v75
	v_rcp_f32_e32 v64, v64
	v_rcp_f32_e32 v75, v75
	s_nop 0
	v_cvt_pk_bf16_f32 v79, v64, v75
	v_mad_u64_u32 v[74:75], s[2:3], v187, s76, v[74:75]
	v_mov_b32_e32 v75, v65
	v_lshl_add_u64 v[80:81], v[74:75], 1, s[36:37]
	global_store_dwordx4 v[80:81], v[76:79], off nt
	v_pk_add_f32 v[80:81], v[50:51], v[68:69]
	s_mov_b64 s[2:3], 0
	v_pk_add_f32 v[76:77], v[52:53], v[70:71]
	v_pk_add_f32 v[78:79], v[54:55], v[72:73]
	v_mul_f32_e32 v64, 0xbfb8aa3b, v76
	v_mul_f32_e32 v75, 0xbfb8aa3b, v77
	v_exp_f32_e32 v64, v64
	v_exp_f32_e32 v75, v75
	v_add_f32_e32 v64, 1.0, v64
	v_add_f32_e32 v75, 1.0, v75
	v_rcp_f32_e32 v64, v64
	v_rcp_f32_e32 v75, v75
	s_nop 0
	v_cvt_pk_bf16_f32 v76, v64, v75
	v_mul_f32_e32 v64, 0xbfb8aa3b, v78
	v_mul_f32_e32 v75, 0xbfb8aa3b, v79
	v_exp_f32_e32 v64, v64
	v_exp_f32_e32 v75, v75
	v_add_f32_e32 v64, 1.0, v64
	v_add_f32_e32 v75, 1.0, v75
	v_rcp_f32_e32 v64, v64
	v_rcp_f32_e32 v75, v75
	s_nop 0
	v_cvt_pk_bf16_f32 v77, v64, v75
	v_mul_f32_e32 v64, 0xbfb8aa3b, v82
	v_mul_f32_e32 v75, 0xbfb8aa3b, v83
	v_exp_f32_e32 v64, v64
	v_exp_f32_e32 v75, v75
	v_pk_add_f32 v[82:83], v[44:45], v[70:71]
	v_add_f32_e32 v64, 1.0, v64
	v_add_f32_e32 v75, 1.0, v75
	v_rcp_f32_e32 v64, v64
	v_rcp_f32_e32 v75, v75
	s_nop 0
	v_cvt_pk_bf16_f32 v78, v64, v75
	v_mul_f32_e32 v64, 0xbfb8aa3b, v80
	v_mul_f32_e32 v75, 0xbfb8aa3b, v81
	v_exp_f32_e32 v64, v64
	v_exp_f32_e32 v75, v75
	v_add_f32_e32 v64, 1.0, v64
	v_add_f32_e32 v75, 1.0, v75
	v_rcp_f32_e32 v64, v64
	v_rcp_f32_e32 v75, v75
	s_nop 0
	v_cvt_pk_bf16_f32 v79, v64, v75
	v_add_u32_e32 v64, 0xc000, v74
	v_lshl_add_u64 v[80:81], v[64:65], 1, s[36:37]
	v_mul_f32_e32 v64, 0xbfb8aa3b, v82
	v_mul_f32_e32 v75, 0xbfb8aa3b, v83
	v_exp_f32_e32 v64, v64
	v_exp_f32_e32 v75, v75
	global_store_dwordx4 v[80:81], v[76:79], off nt
	v_pk_add_f32 v[80:81], v[46:47], v[72:73]
	v_add_f32_e32 v64, 1.0, v64
	v_add_f32_e32 v75, 1.0, v75
	v_rcp_f32_e32 v64, v64
	v_rcp_f32_e32 v75, v75
	v_pk_add_f32 v[78:79], v[40:41], v[66:67]
	v_pk_add_f32 v[76:77], v[42:43], v[68:69]
	v_cvt_pk_bf16_f32 v82, v64, v75
	v_mul_f32_e32 v64, 0xbfb8aa3b, v80
	v_mul_f32_e32 v75, 0xbfb8aa3b, v81
	v_exp_f32_e32 v64, v64
	v_exp_f32_e32 v75, v75
	v_pk_add_f32 v[80:81], v[34:35], v[68:69]
	v_add_f32_e32 v64, 1.0, v64
	v_add_f32_e32 v75, 1.0, v75
	v_rcp_f32_e32 v64, v64
	v_rcp_f32_e32 v75, v75
	s_nop 0
	v_cvt_pk_bf16_f32 v83, v64, v75
	v_mul_f32_e32 v64, 0xbfb8aa3b, v78
	v_mul_f32_e32 v75, 0xbfb8aa3b, v79
	v_exp_f32_e32 v64, v64
	v_exp_f32_e32 v75, v75
	v_pk_add_f32 v[78:79], v[38:39], v[72:73]
	v_add_f32_e32 v64, 1.0, v64
	v_add_f32_e32 v75, 1.0, v75
	v_rcp_f32_e32 v64, v64
	v_rcp_f32_e32 v75, v75
	s_nop 0
	v_cvt_pk_bf16_f32 v84, v64, v75
	v_mul_f32_e32 v64, 0xbfb8aa3b, v76
	v_mul_f32_e32 v75, 0xbfb8aa3b, v77
	v_exp_f32_e32 v64, v64
	v_exp_f32_e32 v75, v75
	v_add_f32_e32 v64, 1.0, v64
	v_add_f32_e32 v75, 1.0, v75
	v_rcp_f32_e32 v64, v64
	v_rcp_f32_e32 v75, v75
	s_nop 0
	v_cvt_pk_bf16_f32 v85, v64, v75
	v_add_u32_e32 v64, 0x18000, v74
	v_lshl_add_u64 v[76:77], v[64:65], 1, s[36:37]
	global_store_dwordx4 v[76:77], v[82:85], off nt
	v_pk_add_f32 v[76:77], v[36:37], v[70:71]
	s_nop 0
	v_mul_f32_e32 v64, 0xbfb8aa3b, v76
	v_mul_f32_e32 v75, 0xbfb8aa3b, v77
	v_exp_f32_e32 v64, v64
	v_exp_f32_e32 v75, v75
	v_pk_add_f32 v[82:83], v[32:33], v[66:67]
	v_add_f32_e32 v64, 1.0, v64
	v_add_f32_e32 v75, 1.0, v75
	v_rcp_f32_e32 v64, v64
	v_rcp_f32_e32 v75, v75
	s_nop 0
	v_cvt_pk_bf16_f32 v76, v64, v75
	v_mul_f32_e32 v64, 0xbfb8aa3b, v78
	v_mul_f32_e32 v75, 0xbfb8aa3b, v79
	v_exp_f32_e32 v64, v64
	v_exp_f32_e32 v75, v75
	v_add_f32_e32 v64, 1.0, v64
	v_add_f32_e32 v75, 1.0, v75
	v_rcp_f32_e32 v64, v64
	v_rcp_f32_e32 v75, v75
	s_nop 0
	v_cvt_pk_bf16_f32 v77, v64, v75
	v_mul_f32_e32 v64, 0xbfb8aa3b, v82
	v_mul_f32_e32 v75, 0xbfb8aa3b, v83
	v_exp_f32_e32 v64, v64
	v_exp_f32_e32 v75, v75
	v_pk_add_f32 v[82:83], v[24:25], v[66:67]
	v_add_f32_e32 v64, 1.0, v64
	v_add_f32_e32 v75, 1.0, v75
	v_rcp_f32_e32 v64, v64
	v_rcp_f32_e32 v75, v75
	s_nop 0
	v_cvt_pk_bf16_f32 v78, v64, v75
	v_mul_f32_e32 v64, 0xbfb8aa3b, v80
	v_mul_f32_e32 v75, 0xbfb8aa3b, v81
; __device__ __forceinline__ unsigned pk2(float lo, float hi) { f32x2_t v = {lo, hi}; bf16x2_t b = __builtin_convertvector(v, bf16x2_t); return __builtin_bit_cast(unsigned, b); }
; __device__ __forceinline__ float sigmoidf_(float x) { return __builtin_amdgcn_rcpf(1.0f + __expf(-x)); }
;     __device__ __forceinline__ void operator()(const f32x4 (&acc)[2][2][4][2], const Unit& u, int wr, int wc, int fr, int fq) const {
;     ...
;                 for (int ai = 0; ai < 2; ++ai)
; #pragma unroll
;                     for (int m = 0; m < 4; ++m) {
;                         const int row = row0 + ai * 128 + m * 16;
;                         const f32x4 v0 = acc[ai][bj][m][0] + b0, v1 = acc[ai][bj][m][1] + b1;
;                         u32x4 w; w.x = pk2(sigmoidf_(v0[0]), sigmoidf_(v0[1])); w.y = pk2(sigmoidf_(v0[2]), sigmoidf_(v0[3]));
;                         w.z = pk2(sigmoidf_(v1[0]), sigmoidf_(v1[1])); w.w = pk2(sigmoidf_(v1[2]), sigmoidf_(v1[3]));
;                         __builtin_nontemporal_store(w, (u32x4*)(gates + (unsigned)(row * NG + gcol)));
;                     }
	v_exp_f32_e32 v64, v64
	v_exp_f32_e32 v75, v75
	v_add_f32_e32 v64, 1.0, v64
	v_add_f32_e32 v75, 1.0, v75
	v_rcp_f32_e32 v64, v64
	v_rcp_f32_e32 v75, v75
	s_nop 0
	v_cvt_pk_bf16_f32 v79, v64, v75
	v_add_u32_e32 v64, 0x24000, v74
	v_lshl_add_u64 v[80:81], v[64:65], 1, s[36:37]
	global_store_dwordx4 v[80:81], v[76:79], off nt
	v_pk_add_f32 v[80:81], v[26:27], v[68:69]
	s_nop 0
	v_pk_add_f32 v[76:77], v[28:29], v[70:71]
	v_pk_add_f32 v[78:79], v[30:31], v[72:73]
	v_mul_f32_e32 v64, 0xbfb8aa3b, v76
	v_mul_f32_e32 v75, 0xbfb8aa3b, v77
	v_exp_f32_e32 v64, v64
	v_exp_f32_e32 v75, v75
	v_add_f32_e32 v64, 1.0, v64
	v_add_f32_e32 v75, 1.0, v75
	v_rcp_f32_e32 v64, v64
	v_rcp_f32_e32 v75, v75
	s_nop 0
	v_cvt_pk_bf16_f32 v76, v64, v75
	v_mul_f32_e32 v64, 0xbfb8aa3b, v78
	v_mul_f32_e32 v75, 0xbfb8aa3b, v79
	v_exp_f32_e32 v64, v64
	v_exp_f32_e32 v75, v75
	v_add_f32_e32 v64, 1.0, v64
	v_add_f32_e32 v75, 1.0, v75
	v_rcp_f32_e32 v64, v64
	v_rcp_f32_e32 v75, v75
	s_nop 0
	v_cvt_pk_bf16_f32 v77, v64, v75
	v_mul_f32_e32 v64, 0xbfb8aa3b, v82
	v_mul_f32_e32 v75, 0xbfb8aa3b, v83
	v_exp_f32_e32 v64, v64
	v_exp_f32_e32 v75, v75
	v_pk_add_f32 v[82:83], v[16:17], v[66:67]
	v_add_f32_e32 v64, 1.0, v64
	v_add_f32_e32 v75, 1.0, v75
	v_rcp_f32_e32 v64, v64
	v_rcp_f32_e32 v75, v75
	s_nop 0
	v_cvt_pk_bf16_f32 v78, v64, v75
	v_mul_f32_e32 v64, 0xbfb8aa3b, v80
	v_mul_f32_e32 v75, 0xbfb8aa3b, v81
	v_exp_f32_e32 v64, v64
	v_exp_f32_e32 v75, v75
	v_add_f32_e32 v64, 1.0, v64
	v_add_f32_e32 v75, 1.0, v75
	v_rcp_f32_e32 v64, v64
	v_rcp_f32_e32 v75, v75
	s_nop 0
	v_cvt_pk_bf16_f32 v79, v64, v75
	v_add_u32_e32 v64, 0x60000, v74
	v_lshl_add_u64 v[80:81], v[64:65], 1, s[36:37]
	global_store_dwordx4 v[80:81], v[76:79], off nt
	v_pk_add_f32 v[80:81], v[18:19], v[68:69]
	s_nop 0
	v_pk_add_f32 v[76:77], v[20:21], v[70:71]
	v_pk_add_f32 v[78:79], v[22:23], v[72:73]
	v_mul_f32_e32 v64, 0xbfb8aa3b, v76
	v_mul_f32_e32 v75, 0xbfb8aa3b, v77
	v_exp_f32_e32 v64, v64
	v_exp_f32_e32 v75, v75
	v_add_f32_e32 v64, 1.0, v64
	v_add_f32_e32 v75, 1.0, v75
	v_rcp_f32_e32 v64, v64
	v_rcp_f32_e32 v75, v75
	s_nop 0
	v_cvt_pk_bf16_f32 v76, v64, v75
	v_mul_f32_e32 v64, 0xbfb8aa3b, v78
	v_mul_f32_e32 v75, 0xbfb8aa3b, v79
	v_exp_f32_e32 v64, v64
	v_exp_f32_e32 v75, v75
	v_add_f32_e32 v64, 1.0, v64
	v_add_f32_e32 v75, 1.0, v75
	v_rcp_f32_e32 v64, v64
	v_rcp_f32_e32 v75, v75
	s_nop 0
	v_cvt_pk_bf16_f32 v77, v64, v75
	v_mul_f32_e32 v64, 0xbfb8aa3b, v82
	v_mul_f32_e32 v75, 0xbfb8aa3b, v83
	v_exp_f32_e32 v64, v64
	v_exp_f32_e32 v75, v75
	v_pk_add_f32 v[82:83], v[8:9], v[66:67]
	v_add_f32_e32 v64, 1.0, v64
	v_add_f32_e32 v75, 1.0, v75
	v_rcp_f32_e32 v64, v64
	v_rcp_f32_e32 v75, v75
	s_nop 0
	v_cvt_pk_bf16_f32 v78, v64, v75
	v_mul_f32_e32 v64, 0xbfb8aa3b, v80
	v_mul_f32_e32 v75, 0xbfb8aa3b, v81
	v_exp_f32_e32 v64, v64
	v_exp_f32_e32 v75, v75
	v_add_f32_e32 v64, 1.0, v64
	v_add_f32_e32 v75, 1.0, v75
	v_rcp_f32_e32 v64, v64
	v_rcp_f32_e32 v75, v75
	s_nop 0
	v_cvt_pk_bf16_f32 v79, v64, v75
	v_add_u32_e32 v64, 0x6c000, v74
	v_lshl_add_u64 v[80:81], v[64:65], 1, s[36:37]
	global_store_dwordx4 v[80:81], v[76:79], off nt
	v_pk_add_f32 v[80:81], v[10:11], v[68:69]
	s_nop 0
	v_pk_add_f32 v[76:77], v[12:13], v[70:71]
	v_pk_add_f32 v[78:79], v[14:15], v[72:73]
	v_mul_f32_e32 v64, 0xbfb8aa3b, v76
	v_mul_f32_e32 v75, 0xbfb8aa3b, v77
	v_exp_f32_e32 v64, v64
	v_exp_f32_e32 v75, v75
	v_pk_add_f32 v[70:71], v[4:5], v[70:71]
	v_pk_add_f32 v[72:73], v[6:7], v[72:73]
	v_add_f32_e32 v64, 1.0, v64
	v_add_f32_e32 v75, 1.0, v75
	v_rcp_f32_e32 v64, v64
	v_rcp_f32_e32 v75, v75
	s_nop 0
	v_cvt_pk_bf16_f32 v76, v64, v75
	v_mul_f32_e32 v64, 0xbfb8aa3b, v78
	v_mul_f32_e32 v75, 0xbfb8aa3b, v79
	v_exp_f32_e32 v64, v64
	v_exp_f32_e32 v75, v75
	v_add_f32_e32 v64, 1.0, v64
	v_add_f32_e32 v75, 1.0, v75
	v_rcp_f32_e32 v64, v64
	v_rcp_f32_e32 v75, v75
	s_nop 0
	v_cvt_pk_bf16_f32 v77, v64, v75
	v_mul_f32_e32 v64, 0xbfb8aa3b, v82
	v_mul_f32_e32 v75, 0xbfb8aa3b, v83
	v_exp_f32_e32 v64, v64
	v_exp_f32_e32 v75, v75
	v_add_f32_e32 v64, 1.0, v64
	v_add_f32_e32 v75, 1.0, v75
	v_rcp_f32_e32 v64, v64
	v_rcp_f32_e32 v75, v75
	s_nop 0
	v_cvt_pk_bf16_f32 v78, v64, v75
	v_mul_f32_e32 v64, 0xbfb8aa3b, v80
	v_mul_f32_e32 v75, 0xbfb8aa3b, v81
	v_exp_f32_e32 v64, v64
	v_exp_f32_e32 v75, v75
	v_add_f32_e32 v64, 1.0, v64
	v_add_f32_e32 v75, 1.0, v75
	v_rcp_f32_e32 v64, v64
	v_rcp_f32_e32 v75, v75
	s_nop 0
	v_cvt_pk_bf16_f32 v79, v64, v75
	v_add_u32_e32 v64, 0x78000, v74
	v_lshl_add_u64 v[80:81], v[64:65], 1, s[36:37]
	global_store_dwordx4 v[80:81], v[76:79], off nt
	v_mul_f32_e32 v64, 0xbfb8aa3b, v70
	v_exp_f32_e32 v64, v64
	v_pk_add_f32 v[76:77], v[2:3], v[68:69]
	v_pk_add_f32 v[68:69], v[0:1], v[66:67]
	v_mul_f32_e32 v66, 0xbfb8aa3b, v71
	v_exp_f32_e32 v66, v66
	v_add_f32_e32 v64, 1.0, v64
	v_rcp_f32_e32 v64, v64
	v_mul_f32_e32 v67, 0xbfb8aa3b, v73
	v_add_f32_e32 v66, 1.0, v66
	v_rcp_f32_e32 v66, v66
	v_exp_f32_e32 v67, v67
	v_cvt_pk_bf16_f32 v66, v64, v66
	v_mul_f32_e32 v64, 0xbfb8aa3b, v72
	v_exp_f32_e32 v64, v64
	v_add_f32_e32 v67, 1.0, v67
	v_rcp_f32_e32 v67, v67
	v_add_f32_e32 v64, 1.0, v64
	v_rcp_f32_e32 v64, v64
	s_nop 0
	v_cvt_pk_bf16_f32 v67, v64, v67
	v_mul_f32_e32 v64, 0xbfb8aa3b, v68
	v_mul_f32_e32 v68, 0xbfb8aa3b, v69
	v_exp_f32_e32 v64, v64
	v_exp_f32_e32 v68, v68
	v_mul_f32_e32 v69, 0xbfb8aa3b, v77
	v_exp_f32_e32 v69, v69
	v_add_f32_e32 v64, 1.0, v64
	v_add_f32_e32 v68, 1.0, v68
	v_rcp_f32_e32 v64, v64
	v_rcp_f32_e32 v68, v68
	v_add_f32_e32 v69, 1.0, v69
	v_rcp_f32_e32 v69, v69
	v_cvt_pk_bf16_f32 v68, v64, v68
	v_mul_f32_e32 v64, 0xbfb8aa3b, v76
	v_exp_f32_e32 v64, v64
	s_nop 0
	v_add_f32_e32 v64, 1.0, v64
	v_rcp_f32_e32 v64, v64
	s_nop 0
	v_cvt_pk_bf16_f32 v69, v64, v69
	v_add_u32_e32 v64, 0x84000, v74
	v_lshl_add_u64 v[70:71], v[64:65], 1, s[36:37]
	global_store_dwordx4 v[70:71], v[66:69], off nt
; __device__ __forceinline__ unsigned pk2(float lo, float hi) { f32x2_t v = {lo, hi}; bf16x2_t b = __builtin_convertvector(v, bf16x2_t); return __builtin_bit_cast(unsigned, b); }
;     __device__ __forceinline__ void operator()(const f32x4 (&acc)[2][2][4][2], const Unit& u, int wr, int wc, int fr, int fq) const {
;     ...
;             const int col = u.pn * 256 + bj * 128 + wc * 32 + 8 * fq;
;             if (u.pn < 18) {
;                 const int which = col / MIXW, rem = col - which * MIXW, head = rem >> 6, dc = rem & 63;
;                 const bool rope = (which < 2) && (head < 18);
;                 const bool ksum_on = (which == 1) && (head >= 12) && (head < 18);
;                 const float sc = (which == 0) ? 0.125f * 1.4426950408889634f : 1.0f;
;     ...
; #pragma unroll
;                     for (int i = 0; i < 8; ++i) {
;                         const int ai = i >> 2, m = i & 3, row = row0 + ai * 128 + m * 16;
;                         const f32x4 v0 = acc[ai][bj][m][0] * sc, v1 = acc[ai][bj][m][1] * sc;
;                         u32x4 w; w.x = pk2(v0[0], v0[1]); w.y = pk2(v0[2], v0[3]); w.z = pk2(v1[0], v1[1]); w.w = pk2(v1[2], v1[3]);
;                         __builtin_nontemporal_store(w, (u32x4*)(qkv + (unsigned)(row * LDQ + col)));
;                     }
.LBB0_541:
	s_andn2_b64 vcc, exec, s[2:3]
	s_cbranch_vccnz .LBB0_566
	v_or_b32_e32 v134, 0x80, v186
	v_mul_u32_u24_e32 v64, 0xaaab, v134
	v_lshrrev_b32_e32 v64, 26, v64
	v_mul_lo_u16_e32 v64, 0x600, v64
	v_sub_u16_e32 v66, v134, v64
	s_cmpk_gt_u32 s14, 0x5f
	s_movk_i32 s4, 0x47f
	s_cselect_b64 s[2:3], -1, 0
	v_cmp_lt_u16_e32 vcc, s4, v66
	s_or_b64 s[2:3], s[2:3], vcc
	s_cmp_lt_u32 s14, 48
	s_movk_i32 s4, 0x1200
	s_cselect_b64 vcc, -1, 0
	v_mov_b32_e32 v64, 0x3e38aa3b
	v_mul_lo_u32 v125, v187, s4
	v_cndmask_b32_e32 v122, 1.0, v64, vcc
	v_add_u32_e32 v64, v134, v125
	s_and_saveexec_b64 s[4:5], s[2:3]
	s_xor_b64 s[2:3], exec, s[4:5]
	s_cbranch_execz .LBB0_544
	s_waitcnt lgkmcnt(0)
	v_pk_mul_f32 v[68:69], v[122:123], v[62:63] op_sel_hi:[0,1]
	v_pk_mul_f32 v[66:67], v[122:123], v[60:61] op_sel_hi:[0,1]
	v_pk_mul_f32 v[70:71], v[122:123], v[58:59] op_sel_hi:[0,1]
	v_pk_mul_f32 v[72:73], v[122:123], v[56:57] op_sel_hi:[0,1]
	v_cvt_pk_bf16_f32 v66, v66, v67
	v_cvt_pk_bf16_f32 v67, v68, v69
	v_cvt_pk_bf16_f32 v68, v72, v73
	v_cvt_pk_bf16_f32 v69, v70, v71
	v_lshl_add_u64 v[70:71], v[64:65], 1, s[84:85]
	v_add_u32_e32 v74, v125, v186
	global_store_dwordx4 v[70:71], v[66:69], off nt
	v_pk_mul_f32 v[70:71], v[122:123], v[50:51] op_sel_hi:[0,1]
	v_pk_mul_f32 v[72:73], v[122:123], v[48:49] op_sel_hi:[0,1]
	v_pk_mul_f32 v[68:69], v[122:123], v[54:55] op_sel_hi:[0,1]
	v_pk_mul_f32 v[66:67], v[122:123], v[52:53] op_sel_hi:[0,1]
	v_add_u32_e32 v64, 0x12080, v74
	v_cvt_pk_bf16_f32 v66, v66, v67
	v_cvt_pk_bf16_f32 v67, v68, v69
	v_cvt_pk_bf16_f32 v68, v72, v73
	v_cvt_pk_bf16_f32 v69, v70, v71
	v_lshl_add_u64 v[70:71], v[64:65], 1, s[84:85]
	global_store_dwordx4 v[70:71], v[66:69], off nt
	v_pk_mul_f32 v[70:71], v[122:123], v[42:43] op_sel_hi:[0,1]
	v_pk_mul_f32 v[72:73], v[122:123], v[40:41] op_sel_hi:[0,1]
	v_pk_mul_f32 v[68:69], v[122:123], v[46:47] op_sel_hi:[0,1]
	v_pk_mul_f32 v[66:67], v[122:123], v[44:45] op_sel_hi:[0,1]
	v_add_u32_e32 v64, 0x24080, v74
	v_cvt_pk_bf16_f32 v66, v66, v67
	v_cvt_pk_bf16_f32 v67, v68, v69
	v_cvt_pk_bf16_f32 v68, v72, v73
	v_cvt_pk_bf16_f32 v69, v70, v71
	v_lshl_add_u64 v[70:71], v[64:65], 1, s[84:85]
	global_store_dwordx4 v[70:71], v[66:69], off nt
	v_pk_mul_f32 v[70:71], v[122:123], v[34:35] op_sel_hi:[0,1]
	v_pk_mul_f32 v[72:73], v[122:123], v[32:33] op_sel_hi:[0,1]
	v_pk_mul_f32 v[68:69], v[122:123], v[38:39] op_sel_hi:[0,1]
	v_pk_mul_f32 v[66:67], v[122:123], v[36:37] op_sel_hi:[0,1]
	v_add_u32_e32 v64, 0x36080, v74
	v_cvt_pk_bf16_f32 v66, v66, v67
	v_cvt_pk_bf16_f32 v67, v68, v69
	v_cvt_pk_bf16_f32 v68, v72, v73
	v_cvt_pk_bf16_f32 v69, v70, v71
	v_lshl_add_u64 v[70:71], v[64:65], 1, s[84:85]
	global_store_dwordx4 v[70:71], v[66:69], off nt
	v_pk_mul_f32 v[70:71], v[122:123], v[26:27] op_sel_hi:[0,1]
	v_pk_mul_f32 v[72:73], v[122:123], v[24:25] op_sel_hi:[0,1]
	v_pk_mul_f32 v[68:69], v[122:123], v[30:31] op_sel_hi:[0,1]
	v_pk_mul_f32 v[66:67], v[122:123], v[28:29] op_sel_hi:[0,1]
	v_add_u32_e32 v64, 0x90080, v74
	v_cvt_pk_bf16_f32 v66, v66, v67
	v_cvt_pk_bf16_f32 v67, v68, v69
	v_cvt_pk_bf16_f32 v68, v72, v73
	v_cvt_pk_bf16_f32 v69, v70, v71
	v_lshl_add_u64 v[70:71], v[64:65], 1, s[84:85]
	global_store_dwordx4 v[70:71], v[66:69], off nt
	v_pk_mul_f32 v[70:71], v[122:123], v[18:19] op_sel_hi:[0,1]
	v_pk_mul_f32 v[72:73], v[122:123], v[16:17] op_sel_hi:[0,1]
	v_pk_mul_f32 v[68:69], v[122:123], v[22:23] op_sel_hi:[0,1]
	v_pk_mul_f32 v[66:67], v[122:123], v[20:21] op_sel_hi:[0,1]
	v_add_u32_e32 v64, 0xa2080, v74
	v_cvt_pk_bf16_f32 v66, v66, v67
	v_cvt_pk_bf16_f32 v67, v68, v69
	v_cvt_pk_bf16_f32 v68, v72, v73
	v_cvt_pk_bf16_f32 v69, v70, v71
	v_lshl_add_u64 v[70:71], v[64:65], 1, s[84:85]
	global_store_dwordx4 v[70:71], v[66:69], off nt
	v_pk_mul_f32 v[70:71], v[122:123], v[10:11] op_sel_hi:[0,1]
	v_pk_mul_f32 v[72:73], v[122:123], v[8:9] op_sel_hi:[0,1]
	v_pk_mul_f32 v[68:69], v[122:123], v[14:15] op_sel_hi:[0,1]
	v_pk_mul_f32 v[66:67], v[122:123], v[12:13] op_sel_hi:[0,1]
	v_add_u32_e32 v64, 0xb4080, v74
	v_cvt_pk_bf16_f32 v66, v66, v67
	v_cvt_pk_bf16_f32 v67, v68, v69
	v_cvt_pk_bf16_f32 v68, v72, v73
	v_cvt_pk_bf16_f32 v69, v70, v71
	v_lshl_add_u64 v[70:71], v[64:65], 1, s[84:85]
	global_store_dwordx4 v[70:71], v[66:69], off nt
	v_pk_mul_f32 v[70:71], v[122:123], v[2:3] op_sel_hi:[0,1]
	v_pk_mul_f32 v[72:73], v[122:123], v[0:1] op_sel_hi:[0,1]
	v_pk_mul_f32 v[68:69], v[122:123], v[6:7] op_sel_hi:[0,1]
	v_pk_mul_f32 v[66:67], v[122:123], v[4:5] op_sel_hi:[0,1]
	v_add_u32_e32 v64, 0xc6080, v74
	v_cvt_pk_bf16_f32 v66, v66, v67
	v_cvt_pk_bf16_f32 v67, v68, v69
	v_cvt_pk_bf16_f32 v68, v72, v73
	v_cvt_pk_bf16_f32 v69, v70, v71
	v_lshl_add_u64 v[70:71], v[64:65], 1, s[84:85]
	global_store_dwordx4 v[70:71], v[66:69], off nt
; __device__ __forceinline__ unsigned pk2(float lo, float hi) { f32x2_t v = {lo, hi}; bf16x2_t b = __builtin_convertvector(v, bf16x2_t); return __builtin_bit_cast(unsigned, b); }
;     __device__ __forceinline__ void operator()(const f32x4 (&acc)[2][2][4][2], const Unit& u, int wr, int wc, int fr, int fq) const {
;     ...
;                 if (rope) {
;                     f32x4 c4[8], s4[8];
; #pragma unroll
;                     for (int i = 0; i < 8; ++i) { const int pos = (row0 + (i >> 2) * 128 + (i & 3) * 16) & (SEQ - 1);
;                         c4[i] = *(const f32x4*)(cosT + (unsigned)(pos * 32 + (dc >> 1))); s4[i] = *(const f32x4*)(sinT + (unsigned)(pos * 32 + (dc >> 1))); }
;                     float ks[8];
; #pragma unroll
;                     for (int j = 0; j < 8; ++j) ks[j] = 0.f;
; #pragma unroll
;                     for (int i = 0; i < 8; ++i) {
;                         const int ai = i >> 2, m = i & 3, row = row0 + ai * 128 + m * 16;
;                         const f32x4 v0 = acc[ai][bj][m][0], v1 = acc[ai][bj][m][1];
;                         float r[8];
;                         r[0] = v0[0] * c4[i][0] - v0[1] * s4[i][0]; r[1] = v0[0] * s4[i][0] + v0[1] * c4[i][0];
;                         r[2] = v0[2] * c4[i][1] - v0[3] * s4[i][1]; r[3] = v0[2] * s4[i][1] + v0[3] * c4[i][1];
;                         r[4] = v1[0] * c4[i][2] - v1[1] * s4[i][2]; r[5] = v1[0] * s4[i][2] + v1[1] * c4[i][2];
;                         r[6] = v1[2] * c4[i][3] - v1[3] * s4[i][3]; r[7] = v1[2] * s4[i][3] + v1[3] * c4[i][3];
;                         if (ksum_on) {
; #pragma unroll
;                             for (int j = 0; j < 8; ++j) ks[j] += r[j];
;                         }
;                         u32x4 w; w.x = pk2(r[0] * sc, r[1] * sc); w.y = pk2(r[2] * sc, r[3] * sc); w.z = pk2(r[4] * sc, r[5] * sc); w.w = pk2(r[6] * sc, r[7] * sc);
;                         __builtin_nontemporal_store(w, (u32x4*)(qkv + (unsigned)(row * LDQ + col)));
.LBB0_544:
	s_andn2_saveexec_b64 s[2:3], s[2:3]
	s_cbranch_execz .LBB0_565
	v_lshrrev_b16_e32 v66, 6, v66
	s_waitcnt lgkmcnt(0)
	v_lshlrev_b32_e32 v72, 5, v187
	s_mov_b32 s6, 0xf9e0
	v_add_u32_e32 v124, -12, v66
	v_and_or_b32 v66, v72, s6, v200
	v_lshlrev_b32_e32 v66, 2, v66
	v_mov_b32_e32 v67, v65
	v_lshl_add_u64 v[68:69], s[54:55], 0, v[66:67]
	flat_load_dwordx4 v[130:133], v[68:69]
	v_lshl_add_u64 v[68:69], s[56:57], 0, v[66:67]
	flat_load_dwordx4 v[136:139], v[68:69]
	v_or_b32_e32 v68, 0x800, v66
	v_mov_b32_e32 v69, v65
	v_lshl_add_u64 v[70:71], s[54:55], 0, v[68:69]
	v_lshl_add_u64 v[68:69], s[56:57], 0, v[68:69]
	flat_load_dwordx4 v[114:117], v[70:71]
	flat_load_dwordx4 v[118:121], v[68:69]
	v_or_b32_e32 v68, 0x1000, v66
	v_mov_b32_e32 v69, v65
	v_lshl_add_u64 v[70:71], s[54:55], 0, v[68:69]
	v_lshl_add_u64 v[68:69], s[56:57], 0, v[68:69]
	v_or_b32_e32 v66, 0x1800, v66
	flat_load_dwordx4 v[106:109], v[70:71]
	flat_load_dwordx4 v[110:113], v[68:69]
	v_lshl_add_u64 v[68:69], s[54:55], 0, v[66:67]
	v_lshl_add_u64 v[66:67], s[56:57], 0, v[66:67]
	flat_load_dwordx4 v[98:101], v[68:69]
	flat_load_dwordx4 v[102:105], v[66:67]
	v_add_u32_e32 v66, 0x1000, v72
	v_and_or_b32 v66, v66, s6, v200
	v_lshlrev_b32_e32 v66, 2, v66
	v_mov_b32_e32 v67, v65
	v_lshl_add_u64 v[68:69], s[54:55], 0, v[66:67]
	flat_load_dwordx4 v[90:93], v[68:69]
	v_lshl_add_u64 v[68:69], s[56:57], 0, v[66:67]
	flat_load_dwordx4 v[94:97], v[68:69]
	v_or_b32_e32 v68, 0x800, v66
	v_mov_b32_e32 v69, v65
	v_lshl_add_u64 v[70:71], s[54:55], 0, v[68:69]
	v_lshl_add_u64 v[68:69], s[56:57], 0, v[68:69]
	flat_load_dwordx4 v[82:85], v[70:71]
	flat_load_dwordx4 v[86:89], v[68:69]
	v_or_b32_e32 v68, 0x1000, v66
	v_mov_b32_e32 v69, v65
	v_lshl_add_u64 v[70:71], s[54:55], 0, v[68:69]
	v_lshl_add_u64 v[68:69], s[56:57], 0, v[68:69]
	flat_load_dwordx4 v[74:77], v[70:71]
	flat_load_dwordx4 v[78:81], v[68:69]
	v_or_b32_e32 v70, 0x1800, v66
	v_mov_b32_e32 v71, v65
	v_lshl_add_u64 v[66:67], s[54:55], 0, v[70:71]
	v_lshl_add_u64 v[70:71], s[56:57], 0, v[70:71]
	flat_load_dwordx4 v[66:69], v[66:67]
	s_add_i32 s13, s13, 0xfa80
	flat_load_dwordx4 v[70:73], v[70:71]
	s_and_b32 s4, s13, 0xffff
	s_cmpk_lt_u32 s4, 0x600
	s_cselect_b64 s[4:5], -1, 0
	v_cmp_gt_u32_e32 vcc, 6, v124
	s_and_b64 s[4:5], s[4:5], vcc
	s_waitcnt vmcnt(0) lgkmcnt(0)
	v_pk_mul_f32 v[128:129], v[60:61], v[136:137] op_sel_hi:[1,0]
	s_nop 0
	v_pk_fma_f32 v[126:127], v[60:61], v[130:131], v[128:129] op_sel:[1,0,0] op_sel_hi:[0,1,1]
	v_pk_fma_f32 v[60:61], v[60:61], v[130:131], v[128:129] op_sel:[1,0,0] op_sel_hi:[0,0,1] neg_lo:[0,0,1] neg_hi:[0,0,1]
	v_mov_b32_e32 v127, v61
	v_pk_mul_f32 v[60:61], v[62:63], v[136:137] op_sel:[0,1]
	s_nop 0
	v_pk_fma_f32 v[128:129], v[62:63], v[130:131], v[60:61] op_sel:[1,1,0] op_sel_hi:[0,1,1]
	v_pk_fma_f32 v[60:61], v[62:63], v[130:131], v[60:61] op_sel:[1,1,0] op_sel_hi:[0,1,1] neg_lo:[0,0,1] neg_hi:[0,0,1]
	v_mov_b32_e32 v129, v61
	v_pk_mul_f32 v[60:61], v[56:57], v[138:139] op_sel_hi:[1,0]
	s_nop 0
	v_pk_fma_f32 v[130:131], v[56:57], v[132:133], v[60:61] op_sel:[1,0,0] op_sel_hi:[0,1,1]
	v_pk_fma_f32 v[56:57], v[56:57], v[132:133], v[60:61] op_sel:[1,0,0] op_sel_hi:[0,0,1] neg_lo:[0,0,1] neg_hi:[0,0,1]
	v_mov_b32_e32 v56, v139
	v_mov_b32_e32 v131, v57
	v_pk_mul_f32 v[56:57], v[58:59], v[56:57] op_sel_hi:[1,0]
	v_mov_b32_e32 v60, v133
	v_pk_fma_f32 v[132:133], v[58:59], v[60:61], v[56:57] op_sel:[1,0,0] op_sel_hi:[0,0,1]
	v_pk_fma_f32 v[56:57], v[58:59], v[60:61], v[56:57] op_sel:[1,0,0] op_sel_hi:[0,0,1] neg_lo:[0,0,1] neg_hi:[0,0,1]
	v_mov_b32_e32 v60, v65
	v_mov_b32_e32 v61, v65
	v_mov_b32_e32 v133, v57
	v_mov_b64_e32 v[58:59], v[60:61]
	v_mov_b64_e32 v[56:57], v[60:61]
	v_mov_b64_e32 v[62:63], v[60:61]
	s_and_saveexec_b64 s[6:7], s[4:5]
	v_pk_add_f32 v[60:61], v[126:127], 0 op_sel_hi:[1,0]
	v_pk_add_f32 v[58:59], v[128:129], 0 op_sel_hi:[1,0]
	v_pk_add_f32 v[56:57], v[130:131], 0 op_sel_hi:[1,0]
	v_pk_add_f32 v[62:63], v[132:133], 0 op_sel_hi:[1,0]
	s_or_b64 exec, exec, s[6:7]
	v_pk_mul_f32 v[126:127], v[122:123], v[126:127] op_sel_hi:[0,1]
	v_pk_mul_f32 v[128:129], v[122:123], v[128:129] op_sel_hi:[0,1]
	v_pk_mov_b32 v[126:127], v[126:127], v[126:127] op_sel:[1,0]
	v_pk_mov_b32 v[128:129], v[128:129], v[128:129] op_sel:[1,0]
	v_cvt_pk_bf16_f32 v126, v126, v127
	v_cvt_pk_bf16_f32 v127, v128, v129
	v_pk_mul_f32 v[128:129], v[122:123], v[130:131] op_sel_hi:[0,1]
	v_pk_mul_f32 v[130:131], v[122:123], v[132:133] op_sel_hi:[0,1]
	v_pk_mov_b32 v[128:129], v[128:129], v[128:129] op_sel:[1,0]
	v_pk_mov_b32 v[130:131], v[130:131], v[130:131] op_sel:[1,0]
	v_cvt_pk_bf16_f32 v128, v128, v129
	v_cvt_pk_bf16_f32 v129, v130, v131
	v_lshl_add_u64 v[130:131], v[64:65], 1, s[84:85]
	global_store_dwordx4 v[130:131], v[126:129], off nt
	v_mov_b32_e32 v64, v117
	s_nop 0
	v_pk_mul_f32 v[128:129], v[52:53], v[118:119] op_sel:[1,0] op_sel_hi:[0,0]
	v_pk_mul_f32 v[118:119], v[54:55], v[118:119] op_sel:[1,1] op_sel_hi:[0,1]
	v_pk_fma_f32 v[126:127], v[52:53], v[114:115], v[128:129] op_sel_hi:[1,0,1] neg_lo:[0,0,1] neg_hi:[0,0,1]
	v_pk_fma_f32 v[128:129], v[52:53], v[114:115], v[128:129] op_sel_hi:[1,0,1]
	v_pk_fma_f32 v[52:53], v[54:55], v[114:115], v[118:119] op_sel:[0,1,0] neg_lo:[0,0,1] neg_hi:[0,0,1]
	v_pk_fma_f32 v[114:115], v[54:55], v[114:115], v[118:119] op_sel:[0,1,0]
	v_pk_mul_f32 v[118:119], v[48:49], v[120:121] op_sel:[1,0] op_sel_hi:[0,0]
	v_pk_fma_f32 v[54:55], v[48:49], v[116:117], v[118:119] op_sel_hi:[1,0,1] neg_lo:[0,0,1] neg_hi:[0,0,1]
	v_pk_fma_f32 v[118:119], v[48:49], v[116:117], v[118:119] op_sel_hi:[1,0,1]
	v_mov_b32_e32 v48, v121
	v_pk_mul_f32 v[120:121], v[50:51], v[48:49] op_sel:[1,0] op_sel_hi:[0,0]
; __device__ __forceinline__ unsigned pk2(float lo, float hi) { f32x2_t v = {lo, hi}; bf16x2_t b = __builtin_convertvector(v, bf16x2_t); return __builtin_bit_cast(unsigned, b); }
;     __device__ __forceinline__ void operator()(const f32x4 (&acc)[2][2][4][2], const Unit& u, int wr, int wc, int fr, int fq) const {
;     ...
;                     for (int i = 0; i < 8; ++i) {
;                         const int ai = i >> 2, m = i & 3, row = row0 + ai * 128 + m * 16;
;                         const f32x4 v0 = acc[ai][bj][m][0], v1 = acc[ai][bj][m][1];
;                         float r[8];
;                         r[0] = v0[0] * c4[i][0] - v0[1] * s4[i][0]; r[1] = v0[0] * s4[i][0] + v0[1] * c4[i][0];
;                         r[2] = v0[2] * c4[i][1] - v0[3] * s4[i][1]; r[3] = v0[2] * s4[i][1] + v0[3] * c4[i][1];
;                         r[4] = v1[0] * c4[i][2] - v1[1] * s4[i][2]; r[5] = v1[0] * s4[i][2] + v1[1] * c4[i][2];
;                         r[6] = v1[2] * c4[i][3] - v1[3] * s4[i][3]; r[7] = v1[2] * s4[i][3] + v1[3] * c4[i][3];
;                         if (ksum_on) {
; #pragma unroll
;                             for (int j = 0; j < 8; ++j) ks[j] += r[j];
;                         }
;                         u32x4 w; w.x = pk2(r[0] * sc, r[1] * sc); w.y = pk2(r[2] * sc, r[3] * sc); w.z = pk2(r[4] * sc, r[5] * sc); w.w = pk2(r[6] * sc, r[7] * sc);
;                         __builtin_nontemporal_store(w, (u32x4*)(qkv + (unsigned)(row * LDQ + col)));
	v_pk_fma_f32 v[48:49], v[50:51], v[64:65], v[120:121] op_sel_hi:[1,0,1] neg_lo:[0,0,1] neg_hi:[0,0,1]
	v_pk_fma_f32 v[50:51], v[50:51], v[64:65], v[120:121] op_sel_hi:[1,0,1]
	s_and_saveexec_b64 s[6:7], s[4:5]
	v_pk_mov_b32 v[116:117], v[128:129], v[126:127] op_sel:[1,0]
	s_nop 0
	v_pk_add_f32 v[60:61], v[116:117], v[60:61]
	v_pk_mov_b32 v[116:117], v[114:115], v[52:53] op_sel:[1,0]
	s_nop 0
	v_pk_add_f32 v[58:59], v[116:117], v[58:59]
	v_pk_mov_b32 v[116:117], v[118:119], v[54:55] op_sel:[1,0]
	s_nop 0
	v_pk_add_f32 v[56:57], v[116:117], v[56:57]
	v_pk_mov_b32 v[116:117], v[50:51], v[48:49] op_sel:[1,0]
	s_nop 0
	v_pk_add_f32 v[62:63], v[116:117], v[62:63]
	s_or_b64 exec, exec, s[6:7]
	v_mov_b32_e32 v123, v122
	v_mov_b32_e32 v127, v129
	v_mov_b32_e32 v53, v115
	v_mov_b32_e32 v55, v119
	v_mov_b32_e32 v49, v51
	v_pk_mul_f32 v[50:51], v[122:123], v[126:127]
	v_pk_mul_f32 v[52:53], v[122:123], v[52:53]
	v_or_b32_e32 v114, 0x12080, v186
	v_cvt_pk_bf16_f32 v50, v50, v51
	v_cvt_pk_bf16_f32 v51, v52, v53
	v_pk_mul_f32 v[52:53], v[122:123], v[54:55]
	v_pk_mul_f32 v[48:49], v[122:123], v[48:49]
	v_add_u32_e32 v64, v114, v125
	v_cvt_pk_bf16_f32 v52, v52, v53
	v_cvt_pk_bf16_f32 v53, v48, v49
	v_lshl_add_u64 v[48:49], v[64:65], 1, s[84:85]
	global_store_dwordx4 v[48:49], v[50:53], off nt
	v_pk_mul_f32 v[54:55], v[40:41], v[112:113] op_sel:[1,0] op_sel_hi:[0,0]
	v_mov_b32_e32 v64, v109
	v_pk_mul_f32 v[50:51], v[44:45], v[110:111] op_sel:[1,0] op_sel_hi:[0,0]
	v_pk_mul_f32 v[52:53], v[46:47], v[110:111] op_sel:[1,1] op_sel_hi:[0,1]
	v_pk_fma_f32 v[48:49], v[44:45], v[106:107], v[50:51] op_sel_hi:[1,0,1] neg_lo:[0,0,1] neg_hi:[0,0,1]
	v_pk_fma_f32 v[50:51], v[44:45], v[106:107], v[50:51] op_sel_hi:[1,0,1]
	v_pk_fma_f32 v[44:45], v[46:47], v[106:107], v[52:53] op_sel:[0,1,0] neg_lo:[0,0,1] neg_hi:[0,0,1]
	v_pk_fma_f32 v[52:53], v[46:47], v[106:107], v[52:53] op_sel:[0,1,0]
	v_pk_fma_f32 v[46:47], v[40:41], v[108:109], v[54:55] op_sel_hi:[1,0,1] neg_lo:[0,0,1] neg_hi:[0,0,1]
	v_pk_fma_f32 v[54:55], v[40:41], v[108:109], v[54:55] op_sel_hi:[1,0,1]
	v_mov_b32_e32 v40, v113
	v_pk_mul_f32 v[106:107], v[42:43], v[40:41] op_sel:[1,0] op_sel_hi:[0,0]
	v_pk_fma_f32 v[40:41], v[42:43], v[64:65], v[106:107] op_sel_hi:[1,0,1] neg_lo:[0,0,1] neg_hi:[0,0,1]
	v_pk_fma_f32 v[42:43], v[42:43], v[64:65], v[106:107] op_sel_hi:[1,0,1]
	s_and_saveexec_b64 s[6:7], s[4:5]
	v_pk_mov_b32 v[106:107], v[50:51], v[48:49] op_sel:[1,0]
	s_nop 0
	v_pk_add_f32 v[60:61], v[106:107], v[60:61]
	v_pk_mov_b32 v[106:107], v[52:53], v[44:45] op_sel:[1,0]
	s_nop 0
	v_pk_add_f32 v[58:59], v[106:107], v[58:59]
	v_pk_mov_b32 v[106:107], v[54:55], v[46:47] op_sel:[1,0]
	s_nop 0
	v_pk_add_f32 v[56:57], v[106:107], v[56:57]
	v_pk_mov_b32 v[106:107], v[42:43], v[40:41] op_sel:[1,0]
	s_nop 0
	v_pk_add_f32 v[62:63], v[106:107], v[62:63]
	s_or_b64 exec, exec, s[6:7]
	v_mov_b32_e32 v49, v51
	v_mov_b32_e32 v45, v53
	v_mov_b32_e32 v41, v43
	v_pk_mul_f32 v[42:43], v[122:123], v[48:49]
	v_mov_b32_e32 v47, v55
	v_cvt_pk_bf16_f32 v48, v42, v43
	v_pk_mul_f32 v[42:43], v[122:123], v[44:45]
	v_pk_mul_f32 v[40:41], v[122:123], v[40:41]
	v_cvt_pk_bf16_f32 v49, v42, v43
	v_pk_mul_f32 v[42:43], v[122:123], v[46:47]
	v_cvt_pk_bf16_f32 v51, v40, v41
	v_cvt_pk_bf16_f32 v50, v42, v43
	v_or_b32_e32 v42, 0x24080, v186
	v_add_u32_e32 v64, v42, v125
	v_lshl_add_u64 v[40:41], v[64:65], 1, s[84:85]
	v_pk_mul_f32 v[44:45], v[36:37], v[102:103] op_sel_hi:[1,0]
	global_store_dwordx4 v[40:41], v[48:51], off nt
	v_pk_fma_f32 v[40:41], v[36:37], v[98:99], v[44:45] op_sel:[1,0,0] op_sel_hi:[0,1,1]
	v_pk_fma_f32 v[36:37], v[36:37], v[98:99], v[44:45] op_sel:[1,0,0] op_sel_hi:[0,0,1] neg_lo:[0,0,1] neg_hi:[0,0,1]
	v_pk_mul_f32 v[44:45], v[38:39], v[102:103] op_sel:[0,1]
	v_mov_b32_e32 v41, v37
	v_pk_fma_f32 v[36:37], v[38:39], v[98:99], v[44:45] op_sel:[1,1,0] op_sel_hi:[0,1,1]
	v_pk_fma_f32 v[38:39], v[38:39], v[98:99], v[44:45] op_sel:[1,1,0] op_sel_hi:[0,1,1] neg_lo:[0,0,1] neg_hi:[0,0,1]
	v_pk_mul_f32 v[44:45], v[32:33], v[104:105] op_sel_hi:[1,0]
	v_mov_b32_e32 v37, v39
	v_pk_fma_f32 v[38:39], v[32:33], v[100:101], v[44:45] op_sel:[1,0,0] op_sel_hi:[0,1,1]
	v_pk_fma_f32 v[32:33], v[32:33], v[100:101], v[44:45] op_sel:[1,0,0] op_sel_hi:[0,0,1] neg_lo:[0,0,1] neg_hi:[0,0,1]
	v_mov_b32_e32 v32, v105
	v_pk_mul_f32 v[44:45], v[34:35], v[32:33] op_sel_hi:[1,0]
	v_mov_b32_e32 v46, v101
	v_mov_b32_e32 v39, v33
	v_pk_fma_f32 v[32:33], v[34:35], v[46:47], v[44:45] op_sel:[1,0,0] op_sel_hi:[0,0,1]
	v_pk_fma_f32 v[34:35], v[34:35], v[46:47], v[44:45] op_sel:[1,0,0] op_sel_hi:[0,0,1] neg_lo:[0,0,1] neg_hi:[0,0,1]
	v_mov_b32_e32 v33, v35
	s_and_saveexec_b64 s[6:7], s[4:5]
	v_pk_add_f32 v[60:61], v[40:41], v[60:61]
	v_pk_add_f32 v[58:59], v[36:37], v[58:59]
	v_pk_add_f32 v[56:57], v[38:39], v[56:57]
	v_pk_add_f32 v[62:63], v[32:33], v[62:63]
	s_or_b64 exec, exec, s[6:7]
	v_pk_mul_f32 v[34:35], v[122:123], v[40:41]
	v_pk_mul_f32 v[32:33], v[122:123], v[32:33]
	v_pk_mov_b32 v[34:35], v[34:35], v[34:35] op_sel:[1,0]
	v_pk_mov_b32 v[32:33], v[32:33], v[32:33] op_sel:[1,0]
	v_cvt_pk_bf16_f32 v44, v34, v35
	v_pk_mul_f32 v[34:35], v[122:123], v[36:37]
	v_cvt_pk_bf16_f32 v47, v32, v33
	v_pk_mov_b32 v[34:35], v[34:35], v[34:35] op_sel:[1,0]
	v_pk_mul_f32 v[36:37], v[28:29], v[94:95] op_sel_hi:[1,0]
	v_cvt_pk_bf16_f32 v45, v34, v35
	v_pk_mul_f32 v[34:35], v[122:123], v[38:39]
	v_mov_b32_e32 v38, v93
	v_pk_mov_b32 v[34:35], v[34:35], v[34:35] op_sel:[1,0]
	s_nop 0
	v_cvt_pk_bf16_f32 v46, v34, v35
	v_or_b32_e32 v34, 0x36080, v186
	v_add_u32_e32 v64, v34, v125
	v_lshl_add_u64 v[32:33], v[64:65], 1, s[84:85]
	global_store_dwordx4 v[32:33], v[44:47], off nt
; __device__ __forceinline__ unsigned pk2(float lo, float hi) { f32x2_t v = {lo, hi}; bf16x2_t b = __builtin_convertvector(v, bf16x2_t); return __builtin_bit_cast(unsigned, b); }
;     __device__ __forceinline__ void operator()(const f32x4 (&acc)[2][2][4][2], const Unit& u, int wr, int wc, int fr, int fq) const {
;     ...
;                     for (int i = 0; i < 8; ++i) {
;                         const int ai = i >> 2, m = i & 3, row = row0 + ai * 128 + m * 16;
;                         const f32x4 v0 = acc[ai][bj][m][0], v1 = acc[ai][bj][m][1];
;                         float r[8];
;                         r[0] = v0[0] * c4[i][0] - v0[1] * s4[i][0]; r[1] = v0[0] * s4[i][0] + v0[1] * c4[i][0];
;                         r[2] = v0[2] * c4[i][1] - v0[3] * s4[i][1]; r[3] = v0[2] * s4[i][1] + v0[3] * c4[i][1];
;                         r[4] = v1[0] * c4[i][2] - v1[1] * s4[i][2]; r[5] = v1[0] * s4[i][2] + v1[1] * c4[i][2];
;                         r[6] = v1[2] * c4[i][3] - v1[3] * s4[i][3]; r[7] = v1[2] * s4[i][3] + v1[3] * c4[i][3];
;                         if (ksum_on) {
; #pragma unroll
;                             for (int j = 0; j < 8; ++j) ks[j] += r[j];
;                         }
;                         u32x4 w; w.x = pk2(r[0] * sc, r[1] * sc); w.y = pk2(r[2] * sc, r[3] * sc); w.z = pk2(r[4] * sc, r[5] * sc); w.w = pk2(r[6] * sc, r[7] * sc);
;                         __builtin_nontemporal_store(w, (u32x4*)(qkv + (unsigned)(row * LDQ + col)));
	v_pk_fma_f32 v[32:33], v[28:29], v[90:91], v[36:37] op_sel:[1,0,0] op_sel_hi:[0,1,1]
	v_pk_fma_f32 v[28:29], v[28:29], v[90:91], v[36:37] op_sel:[1,0,0] op_sel_hi:[0,0,1] neg_lo:[0,0,1] neg_hi:[0,0,1]
	v_pk_mul_f32 v[36:37], v[30:31], v[94:95] op_sel:[0,1]
	v_mov_b32_e32 v33, v29
	v_pk_fma_f32 v[28:29], v[30:31], v[90:91], v[36:37] op_sel:[1,1,0] op_sel_hi:[0,1,1]
	v_pk_fma_f32 v[30:31], v[30:31], v[90:91], v[36:37] op_sel:[1,1,0] op_sel_hi:[0,1,1] neg_lo:[0,0,1] neg_hi:[0,0,1]
	v_pk_mul_f32 v[36:37], v[24:25], v[96:97] op_sel_hi:[1,0]
	v_mov_b32_e32 v29, v31
	v_pk_fma_f32 v[30:31], v[24:25], v[92:93], v[36:37] op_sel:[1,0,0] op_sel_hi:[0,1,1]
	v_pk_fma_f32 v[24:25], v[24:25], v[92:93], v[36:37] op_sel:[1,0,0] op_sel_hi:[0,0,1] neg_lo:[0,0,1] neg_hi:[0,0,1]
	v_mov_b32_e32 v24, v97
	v_pk_mul_f32 v[36:37], v[26:27], v[24:25] op_sel_hi:[1,0]
	v_mov_b32_e32 v31, v25
	v_pk_fma_f32 v[24:25], v[26:27], v[38:39], v[36:37] op_sel:[1,0,0] op_sel_hi:[0,0,1]
	v_pk_fma_f32 v[26:27], v[26:27], v[38:39], v[36:37] op_sel:[1,0,0] op_sel_hi:[0,0,1] neg_lo:[0,0,1] neg_hi:[0,0,1]
	v_mov_b32_e32 v25, v27
	s_and_saveexec_b64 s[6:7], s[4:5]
	v_pk_add_f32 v[60:61], v[32:33], v[60:61]
	v_pk_add_f32 v[58:59], v[28:29], v[58:59]
	v_pk_add_f32 v[56:57], v[30:31], v[56:57]
	v_pk_add_f32 v[62:63], v[24:25], v[62:63]
	s_or_b64 exec, exec, s[6:7]
	v_pk_mul_f32 v[26:27], v[122:123], v[32:33]
	v_pk_mul_f32 v[24:25], v[122:123], v[24:25]
	v_pk_mov_b32 v[26:27], v[26:27], v[26:27] op_sel:[1,0]
	v_pk_mov_b32 v[24:25], v[24:25], v[24:25] op_sel:[1,0]
	v_cvt_pk_bf16_f32 v36, v26, v27
	v_pk_mul_f32 v[26:27], v[122:123], v[28:29]
	v_cvt_pk_bf16_f32 v39, v24, v25
	v_pk_mov_b32 v[26:27], v[26:27], v[26:27] op_sel:[1,0]
	v_pk_mul_f32 v[28:29], v[20:21], v[86:87] op_sel_hi:[1,0]
	v_cvt_pk_bf16_f32 v37, v26, v27
	v_pk_mul_f32 v[26:27], v[122:123], v[30:31]
	v_mov_b32_e32 v30, v85
	v_pk_mov_b32 v[26:27], v[26:27], v[26:27] op_sel:[1,0]
	s_nop 0
	v_cvt_pk_bf16_f32 v38, v26, v27
	v_add_u32_e32 v26, 0x90000, v125
	v_add_u32_e32 v64, v26, v134
	v_lshl_add_u64 v[24:25], v[64:65], 1, s[84:85]
	global_store_dwordx4 v[24:25], v[36:39], off nt
	v_pk_fma_f32 v[24:25], v[20:21], v[82:83], v[28:29] op_sel:[1,0,0] op_sel_hi:[0,1,1]
	v_pk_fma_f32 v[20:21], v[20:21], v[82:83], v[28:29] op_sel:[1,0,0] op_sel_hi:[0,0,1] neg_lo:[0,0,1] neg_hi:[0,0,1]
	v_pk_mul_f32 v[28:29], v[22:23], v[86:87] op_sel:[0,1]
	v_mov_b32_e32 v25, v21
	v_pk_fma_f32 v[20:21], v[22:23], v[82:83], v[28:29] op_sel:[1,1,0] op_sel_hi:[0,1,1]
	v_pk_fma_f32 v[22:23], v[22:23], v[82:83], v[28:29] op_sel:[1,1,0] op_sel_hi:[0,1,1] neg_lo:[0,0,1] neg_hi:[0,0,1]
	v_pk_mul_f32 v[28:29], v[16:17], v[88:89] op_sel_hi:[1,0]
	v_mov_b32_e32 v21, v23
	v_pk_fma_f32 v[22:23], v[16:17], v[84:85], v[28:29] op_sel:[1,0,0] op_sel_hi:[0,1,1]
	v_pk_fma_f32 v[16:17], v[16:17], v[84:85], v[28:29] op_sel:[1,0,0] op_sel_hi:[0,0,1] neg_lo:[0,0,1] neg_hi:[0,0,1]
	v_mov_b32_e32 v16, v89
	v_pk_mul_f32 v[28:29], v[18:19], v[16:17] op_sel_hi:[1,0]
	v_mov_b32_e32 v23, v17
	v_pk_fma_f32 v[16:17], v[18:19], v[30:31], v[28:29] op_sel:[1,0,0] op_sel_hi:[0,0,1]
	v_pk_fma_f32 v[18:19], v[18:19], v[30:31], v[28:29] op_sel:[1,0,0] op_sel_hi:[0,0,1] neg_lo:[0,0,1] neg_hi:[0,0,1]
	v_mov_b32_e32 v17, v19
	s_and_saveexec_b64 s[6:7], s[4:5]
	v_pk_add_f32 v[60:61], v[24:25], v[60:61]
	v_pk_add_f32 v[58:59], v[20:21], v[58:59]
	v_pk_add_f32 v[56:57], v[22:23], v[56:57]
	v_pk_add_f32 v[62:63], v[16:17], v[62:63]
	s_or_b64 exec, exec, s[6:7]
	v_pk_mul_f32 v[18:19], v[122:123], v[24:25]
	v_pk_mul_f32 v[20:21], v[122:123], v[20:21]
	v_pk_mov_b32 v[18:19], v[18:19], v[18:19] op_sel:[1,0]
	v_pk_mov_b32 v[20:21], v[20:21], v[20:21] op_sel:[1,0]
	v_cvt_pk_bf16_f32 v18, v18, v19
	v_cvt_pk_bf16_f32 v19, v20, v21
	v_pk_mul_f32 v[20:21], v[122:123], v[22:23]
	v_pk_mul_f32 v[16:17], v[122:123], v[16:17]
	v_pk_mov_b32 v[20:21], v[20:21], v[20:21] op_sel:[1,0]
	v_pk_mov_b32 v[16:17], v[16:17], v[16:17] op_sel:[1,0]
	v_add_u32_e32 v64, v114, v26
	v_cvt_pk_bf16_f32 v20, v20, v21
	v_cvt_pk_bf16_f32 v21, v16, v17
	v_lshl_add_u64 v[16:17], v[64:65], 1, s[84:85]
	global_store_dwordx4 v[16:17], v[18:21], off nt
	s_nop 1
	v_pk_mul_f32 v[18:19], v[12:13], v[78:79] op_sel_hi:[1,0]
	v_mov_b32_e32 v20, v77
	v_pk_fma_f32 v[16:17], v[12:13], v[74:75], v[18:19] op_sel:[1,0,0] op_sel_hi:[0,1,1]
	v_pk_fma_f32 v[12:13], v[12:13], v[74:75], v[18:19] op_sel:[1,0,0] op_sel_hi:[0,0,1] neg_lo:[0,0,1] neg_hi:[0,0,1]
	v_pk_mul_f32 v[18:19], v[14:15], v[78:79] op_sel:[0,1]
	v_mov_b32_e32 v17, v13
	v_pk_fma_f32 v[12:13], v[14:15], v[74:75], v[18:19] op_sel:[1,1,0] op_sel_hi:[0,1,1]
	v_pk_fma_f32 v[14:15], v[14:15], v[74:75], v[18:19] op_sel:[1,1,0] op_sel_hi:[0,1,1] neg_lo:[0,0,1] neg_hi:[0,0,1]
	v_pk_mul_f32 v[18:19], v[8:9], v[80:81] op_sel_hi:[1,0]
	v_mov_b32_e32 v13, v15
	v_pk_fma_f32 v[14:15], v[8:9], v[76:77], v[18:19] op_sel:[1,0,0] op_sel_hi:[0,1,1]
	v_pk_fma_f32 v[8:9], v[8:9], v[76:77], v[18:19] op_sel:[1,0,0] op_sel_hi:[0,0,1] neg_lo:[0,0,1] neg_hi:[0,0,1]
	v_mov_b32_e32 v8, v81
	v_pk_mul_f32 v[18:19], v[10:11], v[8:9] op_sel_hi:[1,0]
	v_mov_b32_e32 v15, v9
	v_pk_fma_f32 v[8:9], v[10:11], v[20:21], v[18:19] op_sel:[1,0,0] op_sel_hi:[0,0,1]
	v_pk_fma_f32 v[10:11], v[10:11], v[20:21], v[18:19] op_sel:[1,0,0] op_sel_hi:[0,0,1] neg_lo:[0,0,1] neg_hi:[0,0,1]
	v_mov_b32_e32 v9, v11
	s_and_saveexec_b64 s[6:7], s[4:5]
	v_pk_add_f32 v[60:61], v[16:17], v[60:61]
	v_pk_add_f32 v[58:59], v[12:13], v[58:59]
	v_pk_add_f32 v[56:57], v[14:15], v[56:57]
	v_pk_add_f32 v[62:63], v[8:9], v[62:63]
	s_or_b64 exec, exec, s[6:7]
	v_pk_mul_f32 v[10:11], v[122:123], v[16:17]
	v_pk_mul_f32 v[12:13], v[122:123], v[12:13]
; __device__ __forceinline__ unsigned pk2(float lo, float hi) { f32x2_t v = {lo, hi}; bf16x2_t b = __builtin_convertvector(v, bf16x2_t); return __builtin_bit_cast(unsigned, b); }
; template <int K> __device__ __forceinline__ float swz_xor(float v) { return __int_as_float(__builtin_amdgcn_ds_swizzle(__float_as_int(v), (K << 10) | 0x1f)); }
;     __device__ __forceinline__ void operator()(const f32x4 (&acc)[2][2][4][2], const Unit& u, int wr, int wc, int fr, int fq) const {
;     ...
;                     for (int i = 0; i < 8; ++i) {
;                         const int ai = i >> 2, m = i & 3, row = row0 + ai * 128 + m * 16;
;                         const f32x4 v0 = acc[ai][bj][m][0], v1 = acc[ai][bj][m][1];
;                         float r[8];
;                         r[0] = v0[0] * c4[i][0] - v0[1] * s4[i][0]; r[1] = v0[0] * s4[i][0] + v0[1] * c4[i][0];
;                         r[2] = v0[2] * c4[i][1] - v0[3] * s4[i][1]; r[3] = v0[2] * s4[i][1] + v0[3] * c4[i][1];
;                         r[4] = v1[0] * c4[i][2] - v1[1] * s4[i][2]; r[5] = v1[0] * s4[i][2] + v1[1] * c4[i][2];
;                         r[6] = v1[2] * c4[i][3] - v1[3] * s4[i][3]; r[7] = v1[2] * s4[i][3] + v1[3] * c4[i][3];
;                         if (ksum_on) {
; #pragma unroll
;                             for (int j = 0; j < 8; ++j) ks[j] += r[j];
;                         }
;                         u32x4 w; w.x = pk2(r[0] * sc, r[1] * sc); w.y = pk2(r[2] * sc, r[3] * sc); w.z = pk2(r[4] * sc, r[5] * sc); w.w = pk2(r[6] * sc, r[7] * sc);
;                         __builtin_nontemporal_store(w, (u32x4*)(qkv + (unsigned)(row * LDQ + col)));
;                     }
;                     if (ksum_on) {
; #pragma unroll
;                         for (int j = 0; j < 8; ++j) {
;                             float v = ks[j];
;                             v += swz_xor<1>(v); v += swz_xor<2>(v); v += swz_xor<4>(v); v += swz_xor<8>(v);
;                             ks[j] = v;
;                         }
;                         if (fr == 0) {
;                             float* dst = kmean + (size_t)(((u.pm >> 3) * 6 + (head - 12)) * 8 + (u.pm & 7)) * 64 + dc;
; #pragma unroll
;                             for (int j = 0; j < 8; ++j) atomicAdd(dst + j, ks[j]);
;                         }
	v_pk_mov_b32 v[10:11], v[10:11], v[10:11] op_sel:[1,0]
	v_pk_mov_b32 v[12:13], v[12:13], v[12:13] op_sel:[1,0]
	v_cvt_pk_bf16_f32 v10, v10, v11
	v_cvt_pk_bf16_f32 v11, v12, v13
	v_pk_mul_f32 v[12:13], v[122:123], v[14:15]
	v_pk_mul_f32 v[8:9], v[122:123], v[8:9]
	v_pk_mov_b32 v[12:13], v[12:13], v[12:13] op_sel:[1,0]
	v_pk_mov_b32 v[8:9], v[8:9], v[8:9] op_sel:[1,0]
	v_add_u32_e32 v64, v42, v26
	v_cvt_pk_bf16_f32 v12, v12, v13
	v_cvt_pk_bf16_f32 v13, v8, v9
	v_lshl_add_u64 v[8:9], v[64:65], 1, s[84:85]
	global_store_dwordx4 v[8:9], v[10:13], off nt
	s_nop 1
	v_pk_mul_f32 v[10:11], v[4:5], v[70:71] op_sel_hi:[1,0]
	v_mov_b32_e32 v12, v69
	v_pk_fma_f32 v[8:9], v[4:5], v[66:67], v[10:11] op_sel:[1,0,0] op_sel_hi:[0,1,1]
	v_pk_fma_f32 v[4:5], v[4:5], v[66:67], v[10:11] op_sel:[1,0,0] op_sel_hi:[0,0,1] neg_lo:[0,0,1] neg_hi:[0,0,1]
	v_pk_mul_f32 v[10:11], v[6:7], v[70:71] op_sel:[0,1]
	v_mov_b32_e32 v9, v5
	v_pk_fma_f32 v[4:5], v[6:7], v[66:67], v[10:11] op_sel:[1,1,0] op_sel_hi:[0,1,1]
	v_pk_fma_f32 v[6:7], v[6:7], v[66:67], v[10:11] op_sel:[1,1,0] op_sel_hi:[0,1,1] neg_lo:[0,0,1] neg_hi:[0,0,1]
	v_pk_mul_f32 v[10:11], v[0:1], v[72:73] op_sel_hi:[1,0]
	v_mov_b32_e32 v5, v7
	v_pk_fma_f32 v[6:7], v[0:1], v[68:69], v[10:11] op_sel:[1,0,0] op_sel_hi:[0,1,1]
	v_pk_fma_f32 v[0:1], v[0:1], v[68:69], v[10:11] op_sel:[1,0,0] op_sel_hi:[0,0,1] neg_lo:[0,0,1] neg_hi:[0,0,1]
	v_mov_b32_e32 v0, v73
	v_pk_mul_f32 v[10:11], v[2:3], v[0:1] op_sel_hi:[1,0]
	v_mov_b32_e32 v7, v1
	v_pk_fma_f32 v[0:1], v[2:3], v[12:13], v[10:11] op_sel:[1,0,0] op_sel_hi:[0,0,1]
	v_pk_fma_f32 v[2:3], v[2:3], v[12:13], v[10:11] op_sel:[1,0,0] op_sel_hi:[0,0,1] neg_lo:[0,0,1] neg_hi:[0,0,1]
	v_mov_b32_e32 v1, v3
	s_and_saveexec_b64 s[6:7], s[4:5]
	v_pk_add_f32 v[60:61], v[8:9], v[60:61]
	v_pk_add_f32 v[58:59], v[4:5], v[58:59]
	v_pk_add_f32 v[56:57], v[6:7], v[56:57]
	v_pk_add_f32 v[62:63], v[0:1], v[62:63]
	s_or_b64 exec, exec, s[6:7]
	v_pk_mul_f32 v[2:3], v[122:123], v[8:9]
	v_pk_mul_f32 v[4:5], v[122:123], v[4:5]
	v_pk_mov_b32 v[2:3], v[2:3], v[2:3] op_sel:[1,0]
	v_pk_mov_b32 v[4:5], v[4:5], v[4:5] op_sel:[1,0]
	v_cvt_pk_bf16_f32 v2, v2, v3
	v_cvt_pk_bf16_f32 v3, v4, v5
	v_pk_mul_f32 v[4:5], v[122:123], v[6:7]
	v_pk_mul_f32 v[0:1], v[122:123], v[0:1]
	v_pk_mov_b32 v[4:5], v[4:5], v[4:5] op_sel:[1,0]
	v_pk_mov_b32 v[0:1], v[0:1], v[0:1] op_sel:[1,0]
	v_add_u32_e32 v64, v34, v26
	v_cvt_pk_bf16_f32 v4, v4, v5
	v_cvt_pk_bf16_f32 v5, v0, v1
	v_lshl_add_u64 v[0:1], v[64:65], 1, s[84:85]
	global_store_dwordx4 v[0:1], v[2:5], off nt
	s_and_saveexec_b64 s[6:7], s[4:5]
	s_cbranch_execz .LBB0_564
	ds_swizzle_b32 v1, v60 offset:swizzle(SWAP,1)
	ds_swizzle_b32 v2, v59 offset:swizzle(SWAP,1)
	ds_swizzle_b32 v6, v58 offset:swizzle(SWAP,1)
	ds_swizzle_b32 v0, v61 offset:swizzle(SWAP,1)
	ds_swizzle_b32 v7, v57 offset:swizzle(SWAP,1)
	s_waitcnt lgkmcnt(0)
	v_add_f32_e32 v1, v60, v1
	ds_swizzle_b32 v4, v1 offset:swizzle(SWAP,2)
	v_add_f32_e32 v2, v59, v2
	ds_swizzle_b32 v5, v2 offset:swizzle(SWAP,2)
	ds_swizzle_b32 v11, v63 offset:swizzle(SWAP,1)
	ds_swizzle_b32 v12, v62 offset:swizzle(SWAP,1)
	s_waitcnt lgkmcnt(0)
	v_add_f32_e32 v1, v1, v4
	ds_swizzle_b32 v4, v1 offset:swizzle(SWAP,4)
	v_add_f32_e32 v5, v2, v5
	v_add_f32_e32 v0, v61, v0
	v_add_f32_e32 v7, v57, v7
	v_add_f32_e32 v11, v63, v11
	s_waitcnt lgkmcnt(0)
	v_add_f32_e32 v2, v1, v4
	v_add_f32_e32 v4, v58, v6
	ds_swizzle_b32 v6, v4 offset:swizzle(SWAP,2)
	v_add_f32_e32 v12, v62, v12
	ds_swizzle_b32 v3, v0 offset:swizzle(SWAP,2)
	ds_swizzle_b32 v8, v5 offset:swizzle(SWAP,4)
	ds_swizzle_b32 v9, v7 offset:swizzle(SWAP,2)
	s_waitcnt lgkmcnt(0)
	v_add_f32_e32 v6, v4, v6
	ds_swizzle_b32 v10, v6 offset:swizzle(SWAP,4)
	ds_swizzle_b32 v14, v11 offset:swizzle(SWAP,2)
	ds_swizzle_b32 v15, v12 offset:swizzle(SWAP,2)
	v_add_f32_e32 v0, v0, v3
	v_add_f32_e32 v4, v5, v8
	s_waitcnt lgkmcnt(0)
	v_add_f32_e32 v6, v6, v10
	ds_swizzle_b32 v10, v56 offset:swizzle(SWAP,1)
	v_add_f32_e32 v8, v7, v9
	v_add_f32_e32 v14, v11, v14
	v_add_f32_e32 v15, v12, v15
	ds_swizzle_b32 v3, v0 offset:swizzle(SWAP,4)
	s_waitcnt lgkmcnt(0)
	v_add_f32_e32 v10, v56, v10
	ds_swizzle_b32 v13, v10 offset:swizzle(SWAP,2)
	ds_swizzle_b32 v9, v8 offset:swizzle(SWAP,4)
	ds_swizzle_b32 v16, v14 offset:swizzle(SWAP,4)
	ds_swizzle_b32 v17, v15 offset:swizzle(SWAP,4)
	v_add_f32_e32 v0, v0, v3
	s_waitcnt lgkmcnt(0)
	v_add_f32_e32 v10, v10, v13
	ds_swizzle_b32 v13, v10 offset:swizzle(SWAP,4)
	v_add_f32_e32 v8, v8, v9
	v_add_f32_e32 v12, v14, v16
	v_add_f32_e32 v14, v15, v17
	ds_swizzle_b32 v1, v0 offset:swizzle(SWAP,8)
	s_waitcnt lgkmcnt(0)
	v_add_f32_e32 v10, v10, v13
	ds_swizzle_b32 v3, v2 offset:swizzle(SWAP,8)
	ds_swizzle_b32 v5, v4 offset:swizzle(SWAP,8)
	ds_swizzle_b32 v7, v6 offset:swizzle(SWAP,8)
	ds_swizzle_b32 v9, v8 offset:swizzle(SWAP,8)
	ds_swizzle_b32 v11, v10 offset:swizzle(SWAP,8)
	ds_swizzle_b32 v13, v12 offset:swizzle(SWAP,8)
	ds_swizzle_b32 v15, v14 offset:swizzle(SWAP,8)
	s_and_b64 exec, exec, s[0:1]
	s_cbranch_execz .LBB0_564
	s_lshr_b32 s0, s12, 3
	s_waitcnt lgkmcnt(0)
	v_add_f32_e32 v2, v2, v3
	v_add_f32_e32 v3, v0, v1
	v_mad_u64_u32 v[0:1], s[0:1], s0, 6, v[124:125]
	s_and_b32 s0, s11, 0x700
	s_nop 0
	v_lshl_or_b32 v64, v0, 11, s0
	v_lshl_add_u64 v[0:1], s[48:49], 0, v[64:65]
	v_lshlrev_b32_e32 v64, 2, v191
	v_lshl_add_u64 v[0:1], v[0:1], 0, v[64:65]
	v_add_f32_e32 v14, v14, v15
	v_add_f32_e32 v12, v12, v13
	v_add_f32_e32 v10, v10, v11
	v_add_f32_e32 v8, v8, v9
	v_add_f32_e32 v6, v6, v7
	v_add_f32_e32 v4, v4, v5
	flat_atomic_add_f32 v[0:1], v3
	flat_atomic_add_f32 v[0:1], v2 offset:4
	flat_atomic_add_f32 v[0:1], v4 offset:8
	flat_atomic_add_f32 v[0:1], v6 offset:12
	flat_atomic_add_f32 v[0:1], v8 offset:16
	flat_atomic_add_f32 v[0:1], v10 offset:20
	flat_atomic_add_f32 v[0:1], v12 offset:24
	flat_atomic_add_f32 v[0:1], v14 offset:28

; __device__ __forceinline__ unsigned pk2(float lo, float hi) { f32x2_t v = {lo, hi}; bf16x2_t b = __builtin_convertvector(v, bf16x2_t); return __builtin_bit_cast(unsigned, b); }
; __device__ __forceinline__ void store_o(const f32x16 (&o)[2], float inv, bf16_t* orow, const WaveCtx& c) {
; #pragma unroll
;     for (int dt = 0; dt < 2; ++dt)
; #pragma unroll
;         for (int r4 = 0; r4 < 4; ++r4) {
;             u32x2 w; w.x = pk2(o[dt][4 * r4] * inv, o[dt][4 * r4 + 1] * inv); w.y = pk2(o[dt][4 * r4 + 2] * inv, o[dt][4 * r4 + 3] * inv);
;             *(u32x2*)(orow + 32 * dt + 8 * r4 + 4 * c.h) = w;
;         }
; }
.LBB0_585:
	v_rcp_f32_e32 v34, v197
	v_lshl_or_b32 v32, s12, 11, v165
	v_mul_lo_u32 v64, v32, s96
	v_lshl_add_u64 v[32:33], s[44:45], 0, v[64:65]
	s_lshl_b32 s80, s11, 1
	v_lshl_add_u64 v[32:33], v[32:33], 0, s[80:81]
	v_pk_mul_f32 v[16:17], v[16:17], v[34:35] op_sel_hi:[1,0]
	v_pk_mul_f32 v[18:19], v[18:19], v[34:35] op_sel_hi:[1,0]
	v_lshlrev_b32_e32 v64, 1, v164
	v_pk_mul_f32 v[0:1], v[0:1], v[34:35] op_sel_hi:[1,0]
	v_pk_mul_f32 v[2:3], v[2:3], v[34:35] op_sel_hi:[1,0]
	v_cvt_pk_bf16_f32 v16, v16, v17
	v_cvt_pk_bf16_f32 v17, v18, v19
	v_lshl_add_u64 v[18:19], v[32:33], 0, v[64:65]
	v_cvt_pk_bf16_f32 v0, v0, v1
	v_cvt_pk_bf16_f32 v1, v2, v3
	global_store_dwordx2 v[18:19], v[16:17], off
	v_pk_mul_f32 v[16:17], v[20:21], v[34:35] op_sel_hi:[1,0]
	v_pk_mul_f32 v[20:21], v[22:23], v[34:35] op_sel_hi:[1,0]
	global_store_dwordx2 v[18:19], v[0:1], off offset:64
	v_pk_mul_f32 v[0:1], v[4:5], v[34:35] op_sel_hi:[1,0]
	v_pk_mul_f32 v[2:3], v[6:7], v[34:35] op_sel_hi:[1,0]
	v_cvt_pk_bf16_f32 v16, v16, v17
	v_cvt_pk_bf16_f32 v17, v20, v21
	v_cvt_pk_bf16_f32 v0, v0, v1
	v_cvt_pk_bf16_f32 v1, v2, v3
	global_store_dwordx2 v[18:19], v[16:17], off offset:16
	v_pk_mul_f32 v[16:17], v[24:25], v[34:35] op_sel_hi:[1,0]
	v_pk_mul_f32 v[20:21], v[26:27], v[34:35] op_sel_hi:[1,0]
	global_store_dwordx2 v[18:19], v[0:1], off offset:80
	v_pk_mul_f32 v[0:1], v[8:9], v[34:35] op_sel_hi:[1,0]
	v_pk_mul_f32 v[2:3], v[10:11], v[34:35] op_sel_hi:[1,0]
	v_cvt_pk_bf16_f32 v16, v16, v17
	v_cvt_pk_bf16_f32 v17, v20, v21
	v_cvt_pk_bf16_f32 v0, v0, v1
	v_cvt_pk_bf16_f32 v1, v2, v3
	global_store_dwordx2 v[18:19], v[16:17], off offset:32
	v_pk_mul_f32 v[16:17], v[28:29], v[34:35] op_sel_hi:[1,0]
	v_pk_mul_f32 v[20:21], v[30:31], v[34:35] op_sel_hi:[1,0]
	global_store_dwordx2 v[18:19], v[0:1], off offset:96
	v_pk_mul_f32 v[0:1], v[12:13], v[34:35] op_sel_hi:[1,0]
	v_mov_b32_e32 v165, v65
	v_cvt_pk_bf16_f32 v16, v16, v17
	v_cvt_pk_bf16_f32 v17, v20, v21
	v_cvt_pk_bf16_f32 v0, v0, v1
	v_pk_mul_f32 v[30:31], v[14:15], v[34:35] op_sel_hi:[1,0]
	global_store_dwordx2 v[18:19], v[16:17], off offset:48
.LBB0_586:
	v_cvt_pk_bf16_f32 v1, v30, v31
	v_lshl_add_u64 v[2:3], v[164:165], 1, v[32:33]
	s_mov_b64 s[0:1], 0
	global_store_dwordx2 v[2:3], v[0:1], off offset:112

; __device__ __forceinline__ unsigned pk2(float lo, float hi) { f32x2_t v = {lo, hi}; bf16x2_t b = __builtin_convertvector(v, bf16x2_t); return __builtin_bit_cast(unsigned, b); }
; __device__ __forceinline__ void store_o(const f32x16 (&o)[2], float inv, bf16_t* orow, const WaveCtx& c) {
; #pragma unroll
;     for (int dt = 0; dt < 2; ++dt)
; #pragma unroll
;         for (int r4 = 0; r4 < 4; ++r4) {
;             u32x2 w; w.x = pk2(o[dt][4 * r4] * inv, o[dt][4 * r4 + 1] * inv); w.y = pk2(o[dt][4 * r4 + 2] * inv, o[dt][4 * r4 + 3] * inv);
;             *(u32x2*)(orow + 32 * dt + 8 * r4 + 4 * c.h) = w;
;         }
; }
.LBB0_602:
	v_lshl_add_u32 v34, s12, 11, v165
	v_mov_b64_e32 v[32:33], s[2:3]
	v_mad_u64_u32 v[32:33], s[0:1], v34, s96, v[32:33]
	s_lshl_b32 s80, s13, 1
	v_lshl_add_u64 v[32:33], v[32:33], 0, s[80:81]
	v_lshlrev_b32_e32 v64, 1, v164
	v_cvt_pk_bf16_f32 v0, v0, v1
	v_cvt_pk_bf16_f32 v1, v2, v3
	v_lshl_add_u64 v[2:3], v[32:33], 0, v[64:65]
	global_store_dwordx2 v[2:3], v[0:1], off
	v_cvt_pk_bf16_f32 v0, v4, v5
	v_cvt_pk_bf16_f32 v1, v6, v7
	global_store_dwordx2 v[2:3], v[0:1], off offset:16
	v_cvt_pk_bf16_f32 v0, v8, v9
	v_cvt_pk_bf16_f32 v1, v10, v11
	global_store_dwordx2 v[2:3], v[0:1], off offset:32
	v_cvt_pk_bf16_f32 v0, v12, v13
	v_cvt_pk_bf16_f32 v1, v14, v15
	global_store_dwordx2 v[2:3], v[0:1], off offset:48
	v_cvt_pk_bf16_f32 v0, v16, v17
	v_cvt_pk_bf16_f32 v1, v18, v19
	global_store_dwordx2 v[2:3], v[0:1], off offset:64
	v_cvt_pk_bf16_f32 v0, v20, v21
	v_cvt_pk_bf16_f32 v1, v22, v23
	global_store_dwordx2 v[2:3], v[0:1], off offset:80
	v_cvt_pk_bf16_f32 v0, v24, v25
	v_cvt_pk_bf16_f32 v1, v26, v27
	v_mov_b32_e32 v165, v65
	global_store_dwordx2 v[2:3], v[0:1], off offset:96
	v_cvt_pk_bf16_f32 v0, v28, v29
	s_mov_b64 s[0:1], 0

; __global__ void __launch_bounds__(NTHR, 2) fwd_kernel(Params p) {
;     ...
;                 if (blockIdx.x == 0) { for (int i = tid; i < NB * 6 * 8 * 64; i += NTHR) km[i] = 0.f; }
.LBB0_631:
	v_add_u32_e32 v4, -2, v4
	v_ashrrev_i32_e32 v7, 31, v1
	v_mov_b32_e32 v6, v1
	v_ashrrev_i32_e32 v9, 31, v0
	v_mov_b32_e32 v8, v0
	v_cmp_eq_u32_e32 vcc, 0, v4
	v_add_u32_e32 v1, 0x400, v1
	v_add_u32_e32 v0, 0x400, v0
	v_lshl_add_u64 v[8:9], v[8:9], 2, s[2:3]
	v_lshl_add_u64 v[6:7], v[6:7], 2, s[2:3]
	s_or_b64 s[6:7], vcc, s[6:7]
	global_store_dword v[8:9], v65, off
	global_store_dword v[6:7], v65, off
	s_andn2_b64 exec, exec, s[6:7]
	s_cbranch_execnz .LBB0_631
	s_or_b64 exec, exec, s[6:7]
	v_cmp_ne_u32_e32 vcc, v2, v3
	v_lshl_add_u32 v0, v3, 9, v236
	s_orn2_b64 s[6:7], vcc, exec

; __global__ void __launch_bounds__(NTHR, 2) fwd_kernel(Params p) {
;     ...
;                 if (blockIdx.x == 0) { for (int i = tid; i < NB * 6 * 8 * 64; i += NTHR) km[i] = 0.f; }
.LBB0_635:
	v_add_u32_e32 v2, 0x200, v2
	s_movk_i32 s4, 0x5dff
	v_cmp_lt_i32_e32 vcc, s4, v2
	global_store_dword v[0:1], v65, off
	s_or_b64 s[2:3], vcc, s[2:3]
	v_lshl_add_u64 v[0:1], v[0:1], 0, s[6:7]
	s_andn2_b64 exec, exec, s[2:3]
	s_cbranch_execnz .LBB0_635

; __device__ __forceinline__ void transpose_item(const float* W, int K, int N, bf16_t* WT, int ldk, int row_off, int kind, LAS float* scr, int item, int lane) {
;     const int nblk = N / 32, kb = item / nblk, nb = item % nblk, k0 = 64 * kb, n0 = 32 * nb;
; #pragma unroll 8
;     for (int i = 0; i < 32; ++i) { const int kk = 2 * i + (lane >> 5); scr[kk * 33 + (lane & 31)] = W[(size_t)(k0 + kk) * N + n0 + (lane & 31)]; }
;     asm volatile("s_waitcnt lgkmcnt(0)" ::: "memory");
.LBB0_647:
	s_lshl_b32 s8, s5, 1
	s_lshl_b32 s7, s1, 1
	v_or_b32_e32 v64, s8, v38
	s_add_i32 s11, s8, 4
	s_add_i32 s10, s7, 4
	s_add_i32 s12, s7, 8
	s_add_i32 s13, s8, 8
	v_lshlrev_b64 v[66:67], 12, v[64:65]
	v_or_b32_e32 v64, s11, v38
	v_mov_b32_e32 v49, v65
	v_mov_b32_e32 v51, v65
	v_mov_b32_e32 v53, v65
	v_or_b32_e32 v48, s7, v3
	s_add_i32 s14, s7, 12
	s_add_i32 s15, s8, 12
	s_add_i32 s16, s7, 16
	s_add_i32 s18, s7, 20
	s_add_i32 s20, s7, 24
	s_add_i32 s22, s7, 28
	v_or_b32_e32 v50, s10, v3
	v_or_b32_e32 v52, s12, v3
	v_lshlrev_b64 v[68:69], 12, v[64:65]
	v_or_b32_e32 v64, s13, v38
	v_mov_b32_e32 v55, v65
	v_mov_b32_e32 v57, v65
	v_mov_b32_e32 v59, v65
	v_mov_b32_e32 v61, v65
	v_mov_b32_e32 v63, v65
	s_add_i32 s17, s8, 16
	v_lshlrev_b64 v[48:49], 12, v[48:49]
	v_or_b32_e32 v54, s14, v3
	v_or_b32_e32 v56, s16, v3
	v_or_b32_e32 v58, s18, v3
	v_or_b32_e32 v60, s20, v3
	v_or_b32_e32 v62, s22, v3
	v_lshl_add_u64 v[66:67], v[36:37], 0, v[66:67]
	v_lshlrev_b64 v[50:51], 12, v[50:51]
	v_lshlrev_b64 v[52:53], 12, v[52:53]
	v_lshlrev_b64 v[70:71], 12, v[64:65]
	v_or_b32_e32 v64, s15, v38
	s_add_i32 s19, s8, 20
	v_lshl_add_u64 v[48:49], v[36:37], 0, v[48:49]
	v_lshlrev_b64 v[54:55], 12, v[54:55]
	v_lshlrev_b64 v[56:57], 12, v[56:57]
	v_lshlrev_b64 v[58:59], 12, v[58:59]
	v_lshlrev_b64 v[60:61], 12, v[60:61]
	v_lshlrev_b64 v[62:63], 12, v[62:63]
	v_lshl_add_u64 v[68:69], v[36:37], 0, v[68:69]
	v_lshl_add_u64 v[50:51], v[36:37], 0, v[50:51]
	v_lshl_add_u64 v[52:53], v[36:37], 0, v[52:53]
	global_load_dword v47, v[66:67], off
	global_load_dword v82, v[48:49], off
	v_lshlrev_b64 v[66:67], 12, v[64:65]
	v_or_b32_e32 v64, s17, v38
	s_add_i32 s21, s8, 24
	v_lshl_add_u64 v[54:55], v[36:37], 0, v[54:55]
	v_lshl_add_u64 v[56:57], v[36:37], 0, v[56:57]
	v_lshl_add_u64 v[58:59], v[36:37], 0, v[58:59]
	v_lshl_add_u64 v[60:61], v[36:37], 0, v[60:61]
	v_lshl_add_u64 v[62:63], v[36:37], 0, v[62:63]
	global_load_dword v83, v[68:69], off
	global_load_dword v84, v[50:51], off
	global_load_dword v85, v[52:53], off
	global_load_dword v86, v[54:55], off
	global_load_dword v87, v[56:57], off
	global_load_dword v88, v[58:59], off
	global_load_dword v89, v[60:61], off
	global_load_dword v90, v[62:63], off
	v_lshl_add_u64 v[50:51], v[36:37], 0, v[66:67]
	v_lshlrev_b64 v[52:53], 12, v[64:65]
	v_or_b32_e32 v64, s19, v38
	s_add_i32 s23, s8, 28
	v_lshl_add_u64 v[48:49], v[36:37], 0, v[70:71]
	global_load_dword v91, v[50:51], off
	global_load_dword v92, v[48:49], off
	v_lshlrev_b64 v[50:51], 12, v[64:65]
	v_or_b32_e32 v64, s21, v38
	v_lshl_add_u64 v[48:49], v[36:37], 0, v[52:53]
	v_lshlrev_b64 v[52:53], 12, v[64:65]
	v_or_b32_e32 v64, s23, v38
	v_lshlrev_b64 v[54:55], 12, v[64:65]
	v_lshl_add_u64 v[54:55], v[36:37], 0, v[54:55]
	v_lshl_add_u64 v[50:51], v[36:37], 0, v[50:51]
	v_lshl_add_u64 v[52:53], v[36:37], 0, v[52:53]
	global_load_dword v64, v[54:55], off
	global_load_dword v93, v[52:53], off
	global_load_dword v94, v[50:51], off
	global_load_dword v95, v[48:49], off
	v_or_b32_e32 v50, s7, v1
	v_or_b32_e32 v48, s8, v0
	s_add_i32 s5, s5, 16
	s_add_i32 s1, s1, 16
	s_add_i32 s6, s6, -16
	v_mad_u64_u32 v[48:49], s[8:9], v48, s92, v[2:3]
	v_mad_u64_u32 v[50:51], s[8:9], v50, s92, v[2:3]
	v_or_b32_e32 v49, s10, v1
	v_or_b32_e32 v51, s11, v0
	v_or_b32_e32 v58, s12, v1
	v_or_b32_e32 v56, s13, v0
	v_or_b32_e32 v62, s14, v1
	v_or_b32_e32 v60, s15, v0
	v_or_b32_e32 v68, s16, v1
	v_or_b32_e32 v66, s17, v0
	v_or_b32_e32 v72, s18, v1
	v_or_b32_e32 v70, s19, v0
	v_or_b32_e32 v76, s20, v1
	v_or_b32_e32 v74, s21, v0
	v_or_b32_e32 v80, s22, v1
	v_or_b32_e32 v78, s23, v0
	s_cmp_lg_u32 s6, 0
	v_mad_u64_u32 v[52:53], s[8:9], v51, s92, v[2:3]
	v_mad_u64_u32 v[54:55], s[8:9], v49, s92, v[2:3]
	v_mad_u64_u32 v[56:57], s[8:9], v56, s92, v[2:3]
	v_mad_u64_u32 v[58:59], s[8:9], v58, s92, v[2:3]
	v_mad_u64_u32 v[60:61], s[8:9], v60, s92, v[2:3]
	v_mad_u64_u32 v[62:63], s[8:9], v62, s92, v[2:3]
	v_mad_u64_u32 v[66:67], s[8:9], v66, s92, v[2:3]
	v_mad_u64_u32 v[68:69], s[8:9], v68, s92, v[2:3]
	v_mad_u64_u32 v[70:71], s[8:9], v70, s92, v[2:3]
	v_mad_u64_u32 v[72:73], s[8:9], v72, s92, v[2:3]
	v_mad_u64_u32 v[74:75], s[8:9], v74, s92, v[2:3]
	v_mad_u64_u32 v[76:77], s[8:9], v76, s92, v[2:3]
	v_mad_u64_u32 v[78:79], s[8:9], v78, s92, v[2:3]
	v_mad_u64_u32 v[80:81], s[8:9], v80, s92, v[2:3]
	s_waitcnt vmcnt(0)
	ds_write_b32 v48, v47
	ds_write_b32 v50, v82
	ds_write_b32 v52, v83
	ds_write_b32 v54, v84
	ds_write_b32 v56, v92
	ds_write_b32 v58, v85
	ds_write_b32 v60, v91
	ds_write_b32 v62, v86
	ds_write_b32 v66, v95
	ds_write_b32 v68, v87
	ds_write_b32 v70, v94
	ds_write_b32 v72, v88
	ds_write_b32 v74, v93
	ds_write_b32 v76, v89
	ds_write_b32 v78, v64
	ds_write_b32 v80, v90
	s_cbranch_scc1 .LBB0_647
; #define LAS __attribute__((address_space(3)))
; __device__ __forceinline__ unsigned pk2(float lo, float hi) { f32x2_t v = {lo, hi}; bf16x2_t b = __builtin_convertvector(v, bf16x2_t); return __builtin_bit_cast(unsigned, b); }
; __device__ __forceinline__ void transpose_item(const float* W, int K, int N, bf16_t* WT, int ldk, int row_off, int kind, LAS float* scr, int item, int lane) {
;     ...
;     const int c = lane & 7;
; #pragma unroll
;     for (int j = 0; j < 4; ++j) { const int n = (lane >> 3) + 8 * j; const LAS float* s = scr + (8 * c) * 33 + n;
;         u32x4 o; o.x = pk2(s[0 * 33], s[1 * 33]); o.y = pk2(s[2 * 33], s[3 * 33]); o.z = pk2(s[4 * 33], s[5 * 33]); o.w = pk2(s[6 * 33], s[7 * 33]);
;         *(u32x4*)(WT + (size_t)(row_off + rowmap(kind, n0 + n)) * ldk + k0 + 8 * c) = o; }
;     asm volatile("s_waitcnt lgkmcnt(0)" ::: "memory");
	s_waitcnt lgkmcnt(0)
	ds_read_b32 v3, v39
	ds_read_b32 v38, v39 offset:132
	ds_read_b32 v47, v39 offset:264
	ds_read_b32 v49, v39 offset:396
	ds_read_b32 v50, v39 offset:528
	ds_read_b32 v51, v39 offset:660
	ds_read_b32 v52, v39 offset:792
	ds_read_b32 v53, v39 offset:924
	s_waitcnt lgkmcnt(0)
	v_cvt_pk_bf16_f32 v48, v3, v38
	v_or_b32_e32 v3, s0, v17
	s_lshl_b32 s80, s4, 1
	v_mul_u32_u24_e32 v3, 0xb00, v3
	v_lshl_add_u64 v[36:37], v[4:5], 0, s[80:81]
	v_lshlrev_b32_e32 v64, 1, v3
	v_cvt_pk_bf16_f32 v49, v47, v49
	v_cvt_pk_bf16_f32 v50, v50, v51
	v_cvt_pk_bf16_f32 v51, v52, v53
	v_lshl_add_u64 v[52:53], v[36:37], 0, v[64:65]
	global_store_dwordx4 v[52:53], v[48:51], off
	ds_read_b32 v3, v39 offset:32
	ds_read_b32 v38, v39 offset:164
	ds_read_b32 v47, v39 offset:296
	ds_read_b32 v49, v39 offset:428
	ds_read_b32 v50, v39 offset:560
	ds_read_b32 v51, v39 offset:692
	ds_read_b32 v52, v39 offset:824
	ds_read_b32 v53, v39 offset:956
	s_waitcnt lgkmcnt(0)
	v_cvt_pk_bf16_f32 v48, v3, v38
	v_or_b32_e32 v3, s0, v40
	v_mul_u32_u24_e32 v3, 0xb00, v3
	v_lshlrev_b32_e32 v64, 1, v3
	v_cvt_pk_bf16_f32 v49, v47, v49
	v_cvt_pk_bf16_f32 v50, v50, v51
	v_cvt_pk_bf16_f32 v51, v52, v53
	v_lshl_add_u64 v[52:53], v[36:37], 0, v[64:65]
	global_store_dwordx4 v[52:53], v[48:51], off
	ds_read_b32 v3, v39 offset:64
	ds_read_b32 v38, v39 offset:196
	ds_read_b32 v47, v39 offset:328
	ds_read_b32 v49, v39 offset:460
	ds_read_b32 v50, v39 offset:592
	ds_read_b32 v51, v39 offset:724
	ds_read_b32 v52, v39 offset:856
	ds_read_b32 v53, v39 offset:988
	s_waitcnt lgkmcnt(0)
	v_cvt_pk_bf16_f32 v48, v3, v38
	v_or_b32_e32 v3, s0, v41
	v_mul_u32_u24_e32 v3, 0xb00, v3
	v_lshlrev_b32_e32 v64, 1, v3
	v_cvt_pk_bf16_f32 v49, v47, v49
	v_cvt_pk_bf16_f32 v50, v50, v51
	v_cvt_pk_bf16_f32 v51, v52, v53
	v_lshl_add_u64 v[52:53], v[36:37], 0, v[64:65]
	global_store_dwordx4 v[52:53], v[48:51], off
	ds_read_b32 v3, v39 offset:96
	ds_read_b32 v38, v39 offset:228
	ds_read_b32 v47, v39 offset:360
	ds_read_b32 v49, v39 offset:492
	ds_read_b32 v50, v39 offset:624
	ds_read_b32 v51, v39 offset:756
	ds_read_b32 v52, v39 offset:888
	ds_read_b32 v53, v39 offset:1020
	v_or_b32_e32 v54, s0, v42
	s_waitcnt lgkmcnt(0)
	v_cvt_pk_bf16_f32 v48, v3, v38
	v_mul_u32_u24_e32 v3, 0xb00, v54
	v_lshlrev_b32_e32 v64, 1, v3
	v_cvt_pk_bf16_f32 v49, v47, v49
	v_cvt_pk_bf16_f32 v50, v50, v51
	v_cvt_pk_bf16_f32 v51, v52, v53
	v_lshl_add_u64 v[36:37], v[36:37], 0, v[64:65]
	global_store_dwordx4 v[36:37], v[48:51], off
	s_waitcnt lgkmcnt(0)
	s_mov_b64 s[0:1], 0

; __device__ __forceinline__ void transpose_item(const float* W, int K, int N, bf16_t* WT, int ldk, int row_off, int kind, LAS float* scr, int item, int lane) {
;     const int nblk = N / 32, kb = item / nblk, nb = item % nblk, k0 = 64 * kb, n0 = 32 * nb;
; #pragma unroll 8
;     for (int i = 0; i < 32; ++i) { const int kk = 2 * i + (lane >> 5); scr[kk * 33 + (lane & 31)] = W[(size_t)(k0 + kk) * N + n0 + (lane & 31)]; }
;     asm volatile("s_waitcnt lgkmcnt(0)" ::: "memory");
.LBB0_651:
	s_lshl_b32 s10, s5, 1
	s_lshl_b32 s11, s6, 1
	v_or_b32_e32 v47, s10, v3
	v_or_b32_e32 v48, s11, v38
	s_add_i32 s12, s10, 4
	s_add_i32 s13, s11, 4
	s_add_i32 s14, s10, 8
	s_add_i32 s15, s11, 8
	s_add_i32 s16, s10, 12
	s_add_i32 s17, s11, 12
	s_add_i32 s18, s10, 16
	s_add_i32 s19, s11, 16
	s_add_i32 s20, s10, 20
	s_add_i32 s21, s11, 20
	s_add_i32 s22, s10, 24
	s_add_i32 s23, s11, 24
	s_add_i32 s24, s10, 28
	s_add_i32 s25, s11, 28
	v_mad_u64_u32 v[48:49], s[8:9], v48, s26, v[36:37]
	v_mad_u64_u32 v[50:51], s[8:9], v47, s26, v[36:37]
	v_or_b32_e32 v47, s12, v3
	v_or_b32_e32 v52, s13, v38
	v_or_b32_e32 v58, s14, v3
	v_or_b32_e32 v56, s15, v38
	v_or_b32_e32 v62, s16, v3
	v_or_b32_e32 v60, s17, v38
	v_or_b32_e32 v64, s18, v3
	v_or_b32_e32 v66, s19, v38
	v_or_b32_e32 v72, s20, v3
	v_or_b32_e32 v70, s21, v38
	v_or_b32_e32 v76, s22, v3
	v_or_b32_e32 v74, s23, v38
	v_or_b32_e32 v80, s24, v3
	v_or_b32_e32 v78, s25, v38
	v_mad_u64_u32 v[52:53], s[8:9], v52, s26, v[36:37]
	v_mad_u64_u32 v[54:55], s[8:9], v47, s26, v[36:37]
	v_mad_u64_u32 v[56:57], s[8:9], v56, s26, v[36:37]
	v_mad_u64_u32 v[58:59], s[8:9], v58, s26, v[36:37]
	v_mad_u64_u32 v[60:61], s[8:9], v60, s26, v[36:37]
	v_mad_u64_u32 v[62:63], s[8:9], v62, s26, v[36:37]
	v_mad_u64_u32 v[66:67], s[8:9], v66, s26, v[36:37]
	v_mad_u64_u32 v[68:69], s[8:9], v64, s26, v[36:37]
	v_mad_u64_u32 v[70:71], s[8:9], v70, s26, v[36:37]
	v_mad_u64_u32 v[72:73], s[8:9], v72, s26, v[36:37]
	v_mad_u64_u32 v[74:75], s[8:9], v74, s26, v[36:37]
	v_mad_u64_u32 v[76:77], s[8:9], v76, s26, v[36:37]
	v_mad_u64_u32 v[78:79], s[8:9], v78, s26, v[36:37]
	v_mad_u64_u32 v[80:81], s[8:9], v80, s26, v[36:37]
	global_load_dword v47, v[48:49], off
	global_load_dword v64, v[50:51], off
	global_load_dword v82, v[52:53], off
	global_load_dword v83, v[54:55], off
	global_load_dword v84, v[56:57], off
	global_load_dword v85, v[58:59], off
	global_load_dword v86, v[60:61], off
	global_load_dword v87, v[62:63], off
	global_load_dword v88, v[66:67], off
	global_load_dword v89, v[68:69], off
	global_load_dword v90, v[70:71], off
	global_load_dword v91, v[72:73], off
	global_load_dword v92, v[74:75], off
	global_load_dword v93, v[76:77], off
	global_load_dword v94, v[78:79], off
	global_load_dword v95, v[80:81], off
	v_or_b32_e32 v50, s10, v1
	v_or_b32_e32 v48, s11, v0
	s_add_i32 s6, s6, 16
	s_add_i32 s5, s5, 16
	s_add_i32 s7, s7, -16
	v_mad_u64_u32 v[48:49], s[8:9], v48, s92, v[2:3]
	v_mad_u64_u32 v[50:51], s[8:9], v50, s92, v[2:3]
	v_or_b32_e32 v49, s12, v1
	v_or_b32_e32 v51, s13, v0
	v_or_b32_e32 v58, s14, v1
	v_or_b32_e32 v56, s15, v0
	v_or_b32_e32 v62, s16, v1
	v_or_b32_e32 v60, s17, v0
	v_or_b32_e32 v68, s18, v1
	v_or_b32_e32 v66, s19, v0
	v_or_b32_e32 v72, s20, v1
	v_or_b32_e32 v70, s21, v0
	v_or_b32_e32 v76, s22, v1
	v_or_b32_e32 v74, s23, v0
	v_or_b32_e32 v80, s24, v1
	v_or_b32_e32 v78, s25, v0
	s_cmp_lg_u32 s7, 0
	v_mad_u64_u32 v[52:53], s[8:9], v51, s92, v[2:3]
	v_mad_u64_u32 v[54:55], s[8:9], v49, s92, v[2:3]
	v_mad_u64_u32 v[56:57], s[8:9], v56, s92, v[2:3]
	v_mad_u64_u32 v[58:59], s[8:9], v58, s92, v[2:3]
	v_mad_u64_u32 v[60:61], s[8:9], v60, s92, v[2:3]
	v_mad_u64_u32 v[62:63], s[8:9], v62, s92, v[2:3]
	v_mad_u64_u32 v[66:67], s[8:9], v66, s92, v[2:3]
	v_mad_u64_u32 v[68:69], s[8:9], v68, s92, v[2:3]
	v_mad_u64_u32 v[70:71], s[8:9], v70, s92, v[2:3]
	v_mad_u64_u32 v[72:73], s[8:9], v72, s92, v[2:3]
	v_mad_u64_u32 v[74:75], s[8:9], v74, s92, v[2:3]
	v_mad_u64_u32 v[76:77], s[8:9], v76, s92, v[2:3]
	v_mad_u64_u32 v[78:79], s[8:9], v78, s92, v[2:3]
	v_mad_u64_u32 v[80:81], s[8:9], v80, s92, v[2:3]
	s_waitcnt vmcnt(0)
	ds_write_b32 v48, v47
	ds_write_b32 v50, v64
	ds_write_b32 v52, v82
	ds_write_b32 v54, v83
	ds_write_b32 v56, v84
	ds_write_b32 v58, v85
	ds_write_b32 v60, v86
	ds_write_b32 v62, v87
	ds_write_b32 v66, v88
	ds_write_b32 v68, v89
	ds_write_b32 v70, v90
	ds_write_b32 v72, v91
	ds_write_b32 v74, v92
	ds_write_b32 v76, v93
	ds_write_b32 v78, v94
	ds_write_b32 v80, v95
	s_cbranch_scc1 .LBB0_651
; #define LAS __attribute__((address_space(3)))
; __device__ __forceinline__ unsigned pk2(float lo, float hi) { f32x2_t v = {lo, hi}; bf16x2_t b = __builtin_convertvector(v, bf16x2_t); return __builtin_bit_cast(unsigned, b); }
; __device__ __forceinline__ int rowmap(int kind, int n) {
;     ...
;     if (kind == 2) { const int up = n >= DFF, j = up ? n - DFF : n; return (j >> 7) * 256 + up * 128 + (j & 127); }
; __device__ __forceinline__ void transpose_item(const float* W, int K, int N, bf16_t* WT, int ldk, int row_off, int kind, LAS float* scr, int item, int lane) {
;     ...
;     const int c = lane & 7;
; #pragma unroll
;     for (int j = 0; j < 4; ++j) { const int n = (lane >> 3) + 8 * j; const LAS float* s = scr + (8 * c) * 33 + n;
;         u32x4 o; o.x = pk2(s[0 * 33], s[1 * 33]); o.y = pk2(s[2 * 33], s[3 * 33]); o.z = pk2(s[4 * 33], s[5 * 33]); o.w = pk2(s[6 * 33], s[7 * 33]);
;         *(u32x4*)(WT + (size_t)(row_off + rowmap(kind, n0 + n)) * ldk + k0 + 8 * c) = o; }
;     asm volatile("s_waitcnt lgkmcnt(0)" ::: "memory");
	s_waitcnt lgkmcnt(0)
	s_and_b32 s1, 0xffff, s1
	s_and_b32 s4, 0xffff, s4
	s_lshl_b32 s80, s1, 1
	ds_read_b32 v3, v39
	ds_read_b32 v38, v39 offset:132
	ds_read_b32 v47, v39 offset:264
	ds_read_b32 v49, v39 offset:396
	ds_read_b32 v50, v39 offset:528
	ds_read_b32 v51, v39 offset:660
	ds_read_b32 v52, v39 offset:792
	ds_read_b32 v53, v39 offset:924
	s_and_b32 s0, 0xffff, s0
	s_waitcnt lgkmcnt(0)
	v_cvt_pk_bf16_f32 v48, v3, v38
	v_or_b32_e32 v3, s4, v17
	s_cmpk_gt_u32 s0, 0x57
	v_add_u32_e32 v38, 0xfffff500, v3
	s_cselect_b64 vcc, -1, 0
	v_cndmask_b32_e32 v3, v3, v38, vcc
	v_lshlrev_b32_e32 v38, 1, v3
	s_and_b64 s[0:1], vcc, exec
	v_and_b32_e32 v38, 0xffffff00, v38
	s_cselect_b32 s0, 0x80, 0
	v_and_b32_e32 v3, 0x67, v3
	v_cvt_pk_bf16_f32 v50, v50, v51
	v_cvt_pk_bf16_f32 v51, v52, v53
	v_or3_b32 v52, v3, v38, s0
	v_ashrrev_i32_e32 v53, 31, v52
	v_lshl_add_u64 v[36:37], v[6:7], 0, s[80:81]
	v_lshlrev_b64 v[52:53], 11, v[52:53]
	v_cvt_pk_bf16_f32 v49, v47, v49
	v_lshl_add_u64 v[52:53], v[36:37], 0, v[52:53]
	global_store_dwordx4 v[52:53], v[48:51], off
	ds_read_b32 v3, v39 offset:32
	ds_read_b32 v38, v39 offset:164
	ds_read_b32 v47, v39 offset:296
	ds_read_b32 v49, v39 offset:428
	ds_read_b32 v50, v39 offset:560
	ds_read_b32 v51, v39 offset:692
	ds_read_b32 v52, v39 offset:824
	ds_read_b32 v53, v39 offset:956
	s_waitcnt lgkmcnt(0)
	v_cvt_pk_bf16_f32 v48, v3, v38
	v_or_b32_e32 v3, s4, v40
	v_add_u32_e32 v38, 0xfffff500, v3
	v_cndmask_b32_e32 v3, v3, v38, vcc
	v_lshlrev_b32_e32 v38, 1, v3
	v_and_b32_e32 v38, 0xffffff00, v38
	v_and_b32_e32 v3, 0x6f, v3
	v_cvt_pk_bf16_f32 v50, v50, v51
	v_cvt_pk_bf16_f32 v51, v52, v53
	v_or3_b32 v52, v3, v38, s0
	v_ashrrev_i32_e32 v53, 31, v52
	v_lshlrev_b64 v[52:53], 11, v[52:53]
	v_cvt_pk_bf16_f32 v49, v47, v49
	v_lshl_add_u64 v[52:53], v[36:37], 0, v[52:53]
	global_store_dwordx4 v[52:53], v[48:51], off
	ds_read_b32 v3, v39 offset:64
	ds_read_b32 v38, v39 offset:196
	ds_read_b32 v47, v39 offset:328
	ds_read_b32 v49, v39 offset:460
	ds_read_b32 v50, v39 offset:592
	ds_read_b32 v51, v39 offset:724
	ds_read_b32 v52, v39 offset:856
	ds_read_b32 v53, v39 offset:988
	s_waitcnt lgkmcnt(0)
	v_cvt_pk_bf16_f32 v48, v3, v38
	v_or_b32_e32 v3, s4, v41
	v_add_u32_e32 v38, 0xfffff500, v3
	v_cndmask_b32_e32 v3, v3, v38, vcc
	v_lshlrev_b32_e32 v38, 1, v3
	v_and_b32_e32 v38, 0xffffff00, v38
	v_and_b32_e32 v3, 0x77, v3
	v_cvt_pk_bf16_f32 v50, v50, v51
	v_cvt_pk_bf16_f32 v51, v52, v53
	v_or3_b32 v52, v3, v38, s0
	v_ashrrev_i32_e32 v53, 31, v52
	v_lshlrev_b64 v[52:53], 11, v[52:53]
	v_cvt_pk_bf16_f32 v49, v47, v49
	v_lshl_add_u64 v[52:53], v[36:37], 0, v[52:53]
	global_store_dwordx4 v[52:53], v[48:51], off
	ds_read_b32 v3, v39 offset:96
	ds_read_b32 v38, v39 offset:228
	ds_read_b32 v47, v39 offset:360
	ds_read_b32 v49, v39 offset:492
	ds_read_b32 v50, v39 offset:624
	ds_read_b32 v51, v39 offset:756
	ds_read_b32 v53, v39 offset:888
	ds_read_b32 v54, v39 offset:1020
	v_or_b32_e32 v48, s4, v42
	v_add_u32_e32 v52, 0xfffff500, v48
	v_cndmask_b32_e32 v48, v48, v52, vcc
	v_lshlrev_b32_e32 v52, 1, v48
	v_and_b32_e32 v52, 0xffffff00, v52
	v_and_b32_e32 v48, 0x7f, v48
	v_or3_b32 v52, v48, v52, s0
	s_waitcnt lgkmcnt(0)
	v_cvt_pk_bf16_f32 v50, v50, v51
	v_cvt_pk_bf16_f32 v51, v53, v54
	v_ashrrev_i32_e32 v53, 31, v52
	v_lshlrev_b64 v[52:53], 11, v[52:53]
	v_cvt_pk_bf16_f32 v48, v3, v38
	v_cvt_pk_bf16_f32 v49, v47, v49
	v_lshl_add_u64 v[36:37], v[36:37], 0, v[52:53]
	global_store_dwordx4 v[36:37], v[48:51], off
	s_waitcnt lgkmcnt(0)

; __device__ __forceinline__ void transpose_item(const float* W, int K, int N, bf16_t* WT, int ldk, int row_off, int kind, LAS float* scr, int item, int lane) {
;     const int nblk = N / 32, kb = item / nblk, nb = item % nblk, k0 = 64 * kb, n0 = 32 * nb;
; #pragma unroll 8
;     for (int i = 0; i < 32; ++i) { const int kk = 2 * i + (lane >> 5); scr[kk * 33 + (lane & 31)] = W[(size_t)(k0 + kk) * N + n0 + (lane & 31)]; }
;     asm volatile("s_waitcnt lgkmcnt(0)" ::: "memory");
.LBB0_656:
	s_lshl_b32 s8, s5, 1
	s_lshl_b32 s7, s1, 1
	v_or_b32_e32 v64, s8, v38
	s_add_i32 s11, s8, 4
	s_add_i32 s10, s7, 4
	s_add_i32 s12, s7, 8
	s_add_i32 s13, s8, 8
	v_lshlrev_b64 v[66:67], 12, v[64:65]
	v_or_b32_e32 v64, s11, v38
	v_mov_b32_e32 v49, v65
	v_mov_b32_e32 v51, v65
	v_mov_b32_e32 v53, v65
	v_or_b32_e32 v48, s7, v3
	s_add_i32 s14, s7, 12
	s_add_i32 s15, s8, 12
	s_add_i32 s16, s7, 16
	s_add_i32 s18, s7, 20
	s_add_i32 s20, s7, 24
	s_add_i32 s22, s7, 28
	v_or_b32_e32 v50, s10, v3
	v_or_b32_e32 v52, s12, v3
	v_lshlrev_b64 v[68:69], 12, v[64:65]
	v_or_b32_e32 v64, s13, v38
	v_mov_b32_e32 v55, v65
	v_mov_b32_e32 v57, v65
	v_mov_b32_e32 v59, v65
	v_mov_b32_e32 v61, v65
	v_mov_b32_e32 v63, v65
	s_add_i32 s17, s8, 16
	v_lshlrev_b64 v[48:49], 12, v[48:49]
	v_or_b32_e32 v54, s14, v3
	v_or_b32_e32 v56, s16, v3
	v_or_b32_e32 v58, s18, v3
	v_or_b32_e32 v60, s20, v3
	v_or_b32_e32 v62, s22, v3
	v_lshl_add_u64 v[66:67], v[36:37], 0, v[66:67]
	v_lshlrev_b64 v[50:51], 12, v[50:51]
	v_lshlrev_b64 v[52:53], 12, v[52:53]
	v_lshlrev_b64 v[70:71], 12, v[64:65]
	v_or_b32_e32 v64, s15, v38
	s_add_i32 s19, s8, 20
	v_lshl_add_u64 v[48:49], v[36:37], 0, v[48:49]
	v_lshlrev_b64 v[54:55], 12, v[54:55]
	v_lshlrev_b64 v[56:57], 12, v[56:57]
	v_lshlrev_b64 v[58:59], 12, v[58:59]
	v_lshlrev_b64 v[60:61], 12, v[60:61]
	v_lshlrev_b64 v[62:63], 12, v[62:63]
	v_lshl_add_u64 v[68:69], v[36:37], 0, v[68:69]
	v_lshl_add_u64 v[50:51], v[36:37], 0, v[50:51]
	v_lshl_add_u64 v[52:53], v[36:37], 0, v[52:53]
	global_load_dword v47, v[66:67], off
	global_load_dword v82, v[48:49], off
	v_lshlrev_b64 v[66:67], 12, v[64:65]
	v_or_b32_e32 v64, s17, v38
	s_add_i32 s21, s8, 24
	v_lshl_add_u64 v[54:55], v[36:37], 0, v[54:55]
	v_lshl_add_u64 v[56:57], v[36:37], 0, v[56:57]
	v_lshl_add_u64 v[58:59], v[36:37], 0, v[58:59]
	v_lshl_add_u64 v[60:61], v[36:37], 0, v[60:61]
	v_lshl_add_u64 v[62:63], v[36:37], 0, v[62:63]
	global_load_dword v83, v[68:69], off
	global_load_dword v84, v[50:51], off
	global_load_dword v85, v[52:53], off
	global_load_dword v86, v[54:55], off
	global_load_dword v87, v[56:57], off
	global_load_dword v88, v[58:59], off
	global_load_dword v89, v[60:61], off
	global_load_dword v90, v[62:63], off
	v_lshl_add_u64 v[50:51], v[36:37], 0, v[66:67]
	v_lshlrev_b64 v[52:53], 12, v[64:65]
	v_or_b32_e32 v64, s19, v38
	s_add_i32 s23, s8, 28
	v_lshl_add_u64 v[48:49], v[36:37], 0, v[70:71]
	global_load_dword v91, v[50:51], off
	global_load_dword v92, v[48:49], off
	v_lshlrev_b64 v[50:51], 12, v[64:65]
	v_or_b32_e32 v64, s21, v38
	v_lshl_add_u64 v[48:49], v[36:37], 0, v[52:53]
	v_lshlrev_b64 v[52:53], 12, v[64:65]
	v_or_b32_e32 v64, s23, v38
	v_lshlrev_b64 v[54:55], 12, v[64:65]
	v_lshl_add_u64 v[54:55], v[36:37], 0, v[54:55]
	v_lshl_add_u64 v[50:51], v[36:37], 0, v[50:51]
	v_lshl_add_u64 v[52:53], v[36:37], 0, v[52:53]
	global_load_dword v64, v[54:55], off
	global_load_dword v93, v[52:53], off
	global_load_dword v94, v[50:51], off
	global_load_dword v95, v[48:49], off
	v_or_b32_e32 v50, s7, v1
	v_or_b32_e32 v48, s8, v0
	s_add_i32 s5, s5, 16
	s_add_i32 s1, s1, 16
	s_add_i32 s6, s6, -16
	v_mad_u64_u32 v[48:49], s[8:9], v48, s92, v[2:3]
	v_mad_u64_u32 v[50:51], s[8:9], v50, s92, v[2:3]
	v_or_b32_e32 v49, s10, v1
	v_or_b32_e32 v51, s11, v0
	v_or_b32_e32 v58, s12, v1
	v_or_b32_e32 v56, s13, v0
	v_or_b32_e32 v62, s14, v1
	v_or_b32_e32 v60, s15, v0
	v_or_b32_e32 v68, s16, v1
	v_or_b32_e32 v66, s17, v0
	v_or_b32_e32 v72, s18, v1
	v_or_b32_e32 v70, s19, v0
	v_or_b32_e32 v76, s20, v1
	v_or_b32_e32 v74, s21, v0
	v_or_b32_e32 v80, s22, v1
	v_or_b32_e32 v78, s23, v0
	s_cmp_lg_u32 s6, 0
	v_mad_u64_u32 v[52:53], s[8:9], v51, s92, v[2:3]
	v_mad_u64_u32 v[54:55], s[8:9], v49, s92, v[2:3]
	v_mad_u64_u32 v[56:57], s[8:9], v56, s92, v[2:3]
	v_mad_u64_u32 v[58:59], s[8:9], v58, s92, v[2:3]
	v_mad_u64_u32 v[60:61], s[8:9], v60, s92, v[2:3]
	v_mad_u64_u32 v[62:63], s[8:9], v62, s92, v[2:3]
	v_mad_u64_u32 v[66:67], s[8:9], v66, s92, v[2:3]
	v_mad_u64_u32 v[68:69], s[8:9], v68, s92, v[2:3]
	v_mad_u64_u32 v[70:71], s[8:9], v70, s92, v[2:3]
	v_mad_u64_u32 v[72:73], s[8:9], v72, s92, v[2:3]
	v_mad_u64_u32 v[74:75], s[8:9], v74, s92, v[2:3]
	v_mad_u64_u32 v[76:77], s[8:9], v76, s92, v[2:3]
	v_mad_u64_u32 v[78:79], s[8:9], v78, s92, v[2:3]
	v_mad_u64_u32 v[80:81], s[8:9], v80, s92, v[2:3]
	s_waitcnt vmcnt(0)
	ds_write_b32 v48, v47
	ds_write_b32 v50, v82
	ds_write_b32 v52, v83
	ds_write_b32 v54, v84
	ds_write_b32 v56, v92
	ds_write_b32 v58, v85
	ds_write_b32 v60, v91
	ds_write_b32 v62, v86
	ds_write_b32 v66, v95
	ds_write_b32 v68, v87
	ds_write_b32 v70, v94
	ds_write_b32 v72, v88
	ds_write_b32 v74, v93
	ds_write_b32 v76, v89
	ds_write_b32 v78, v64
	ds_write_b32 v80, v90
	s_cbranch_scc1 .LBB0_656
; #define LAS __attribute__((address_space(3)))
; __device__ __forceinline__ unsigned pk2(float lo, float hi) { f32x2_t v = {lo, hi}; bf16x2_t b = __builtin_convertvector(v, bf16x2_t); return __builtin_bit_cast(unsigned, b); }
; __device__ __forceinline__ void transpose_item(const float* W, int K, int N, bf16_t* WT, int ldk, int row_off, int kind, LAS float* scr, int item, int lane) {
;     ...
;     const int c = lane & 7;
; #pragma unroll
;     for (int j = 0; j < 4; ++j) { const int n = (lane >> 3) + 8 * j; const LAS float* s = scr + (8 * c) * 33 + n;
;         u32x4 o; o.x = pk2(s[0 * 33], s[1 * 33]); o.y = pk2(s[2 * 33], s[3 * 33]); o.z = pk2(s[4 * 33], s[5 * 33]); o.w = pk2(s[6 * 33], s[7 * 33]);
;         *(u32x4*)(WT + (size_t)(row_off + rowmap(kind, n0 + n)) * ldk + k0 + 8 * c) = o; }
;     asm volatile("s_waitcnt lgkmcnt(0)" ::: "memory");
	s_waitcnt lgkmcnt(0)
	ds_read_b32 v3, v39
	ds_read_b32 v38, v39 offset:132
	ds_read_b32 v47, v39 offset:264
	ds_read_b32 v49, v39 offset:396
	ds_read_b32 v50, v39 offset:528
	ds_read_b32 v51, v39 offset:660
	ds_read_b32 v52, v39 offset:792
	ds_read_b32 v53, v39 offset:924
	s_lshl_b32 s80, s4, 1
	s_waitcnt lgkmcnt(0)
	v_cvt_pk_bf16_f32 v48, v3, v38
	v_or_b32_e32 v3, s0, v17
	v_lshl_add_u64 v[36:37], v[8:9], 0, s[80:81]
	v_lshlrev_b32_e32 v64, 11, v3
	v_cvt_pk_bf16_f32 v49, v47, v49
	v_cvt_pk_bf16_f32 v50, v50, v51
	v_cvt_pk_bf16_f32 v51, v52, v53
	v_lshl_add_u64 v[52:53], v[36:37], 0, v[64:65]
	global_store_dwordx4 v[52:53], v[48:51], off
	ds_read_b32 v3, v39 offset:32
	ds_read_b32 v38, v39 offset:164
	ds_read_b32 v47, v39 offset:296
	ds_read_b32 v49, v39 offset:428
	ds_read_b32 v50, v39 offset:560
	ds_read_b32 v51, v39 offset:692
	ds_read_b32 v52, v39 offset:824
	ds_read_b32 v53, v39 offset:956
	s_waitcnt lgkmcnt(0)
	v_cvt_pk_bf16_f32 v48, v3, v38
	v_or_b32_e32 v3, s0, v40
	v_lshlrev_b32_e32 v64, 11, v3
	v_cvt_pk_bf16_f32 v49, v47, v49
	v_cvt_pk_bf16_f32 v50, v50, v51
	v_cvt_pk_bf16_f32 v51, v52, v53
	v_lshl_add_u64 v[52:53], v[36:37], 0, v[64:65]
	global_store_dwordx4 v[52:53], v[48:51], off
	ds_read_b32 v3, v39 offset:64
	ds_read_b32 v38, v39 offset:196
	ds_read_b32 v47, v39 offset:328
	ds_read_b32 v49, v39 offset:460
	ds_read_b32 v50, v39 offset:592
	ds_read_b32 v51, v39 offset:724
	ds_read_b32 v52, v39 offset:856
	ds_read_b32 v53, v39 offset:988
	s_waitcnt lgkmcnt(0)
	v_cvt_pk_bf16_f32 v48, v3, v38
	v_or_b32_e32 v3, s0, v41
	v_lshlrev_b32_e32 v64, 11, v3
	v_cvt_pk_bf16_f32 v49, v47, v49
	v_cvt_pk_bf16_f32 v50, v50, v51
	v_cvt_pk_bf16_f32 v51, v52, v53
	v_lshl_add_u64 v[52:53], v[36:37], 0, v[64:65]
	global_store_dwordx4 v[52:53], v[48:51], off
	ds_read_b32 v3, v39 offset:96
	ds_read_b32 v38, v39 offset:228
	ds_read_b32 v47, v39 offset:360
	ds_read_b32 v49, v39 offset:492
	ds_read_b32 v50, v39 offset:624
	ds_read_b32 v51, v39 offset:756
	ds_read_b32 v52, v39 offset:888
	ds_read_b32 v53, v39 offset:1020
	v_or_b32_e32 v54, s0, v42
	v_lshlrev_b32_e32 v64, 11, v54
	s_waitcnt lgkmcnt(0)
	v_cvt_pk_bf16_f32 v48, v3, v38
	v_cvt_pk_bf16_f32 v49, v47, v49
	v_cvt_pk_bf16_f32 v50, v50, v51
	v_cvt_pk_bf16_f32 v51, v52, v53
	v_lshl_add_u64 v[36:37], v[36:37], 0, v[64:65]
	global_store_dwordx4 v[36:37], v[48:51], off
	s_waitcnt lgkmcnt(0)

; __device__ __forceinline__ void transpose_item(const float* W, int K, int N, bf16_t* WT, int ldk, int row_off, int kind, LAS float* scr, int item, int lane) {
;     const int nblk = N / 32, kb = item / nblk, nb = item % nblk, k0 = 64 * kb, n0 = 32 * nb;
; #pragma unroll 8
;     for (int i = 0; i < 32; ++i) { const int kk = 2 * i + (lane >> 5); scr[kk * 33 + (lane & 31)] = W[(size_t)(k0 + kk) * N + n0 + (lane & 31)]; }
;     asm volatile("s_waitcnt lgkmcnt(0)" ::: "memory");
.LBB0_661:
	s_lshl_b32 s8, s5, 1
	s_lshl_b32 s7, s1, 1
	v_or_b32_e32 v64, s8, v38
	s_add_i32 s11, s8, 4
	s_add_i32 s10, s7, 4
	s_add_i32 s12, s7, 8
	s_add_i32 s13, s8, 8
	v_lshlrev_b64 v[66:67], 12, v[64:65]
	v_or_b32_e32 v64, s11, v38
	v_mov_b32_e32 v49, v65
	v_mov_b32_e32 v51, v65
	v_mov_b32_e32 v53, v65
	v_or_b32_e32 v48, s7, v3
	s_add_i32 s14, s7, 12
	s_add_i32 s15, s8, 12
	s_add_i32 s16, s7, 16
	s_add_i32 s18, s7, 20
	s_add_i32 s20, s7, 24
	s_add_i32 s22, s7, 28
	v_or_b32_e32 v50, s10, v3
	v_or_b32_e32 v52, s12, v3
	v_lshlrev_b64 v[68:69], 12, v[64:65]
	v_or_b32_e32 v64, s13, v38
	v_mov_b32_e32 v55, v65
	v_mov_b32_e32 v57, v65
	v_mov_b32_e32 v59, v65
	v_mov_b32_e32 v61, v65
	v_mov_b32_e32 v63, v65
	s_add_i32 s17, s8, 16
	v_lshlrev_b64 v[48:49], 12, v[48:49]
	v_or_b32_e32 v54, s14, v3
	v_or_b32_e32 v56, s16, v3
	v_or_b32_e32 v58, s18, v3
	v_or_b32_e32 v60, s20, v3
	v_or_b32_e32 v62, s22, v3
	v_lshl_add_u64 v[66:67], v[36:37], 0, v[66:67]
	v_lshlrev_b64 v[50:51], 12, v[50:51]
	v_lshlrev_b64 v[52:53], 12, v[52:53]
	v_lshlrev_b64 v[70:71], 12, v[64:65]
	v_or_b32_e32 v64, s15, v38
	s_add_i32 s19, s8, 20
	v_lshl_add_u64 v[48:49], v[36:37], 0, v[48:49]
	v_lshlrev_b64 v[54:55], 12, v[54:55]
	v_lshlrev_b64 v[56:57], 12, v[56:57]
	v_lshlrev_b64 v[58:59], 12, v[58:59]
	v_lshlrev_b64 v[60:61], 12, v[60:61]
	v_lshlrev_b64 v[62:63], 12, v[62:63]
	v_lshl_add_u64 v[68:69], v[36:37], 0, v[68:69]
	v_lshl_add_u64 v[50:51], v[36:37], 0, v[50:51]
	v_lshl_add_u64 v[52:53], v[36:37], 0, v[52:53]
	global_load_dword v47, v[66:67], off
	global_load_dword v82, v[48:49], off
	v_lshlrev_b64 v[66:67], 12, v[64:65]
	v_or_b32_e32 v64, s17, v38
	s_add_i32 s21, s8, 24
	v_lshl_add_u64 v[54:55], v[36:37], 0, v[54:55]
	v_lshl_add_u64 v[56:57], v[36:37], 0, v[56:57]
	v_lshl_add_u64 v[58:59], v[36:37], 0, v[58:59]
	v_lshl_add_u64 v[60:61], v[36:37], 0, v[60:61]
	v_lshl_add_u64 v[62:63], v[36:37], 0, v[62:63]
	global_load_dword v83, v[68:69], off
	global_load_dword v84, v[50:51], off
	global_load_dword v85, v[52:53], off
	global_load_dword v86, v[54:55], off
	global_load_dword v87, v[56:57], off
	global_load_dword v88, v[58:59], off
	global_load_dword v89, v[60:61], off
	global_load_dword v90, v[62:63], off
	v_lshl_add_u64 v[50:51], v[36:37], 0, v[66:67]
	v_lshlrev_b64 v[52:53], 12, v[64:65]
	v_or_b32_e32 v64, s19, v38
	s_add_i32 s23, s8, 28
	v_lshl_add_u64 v[48:49], v[36:37], 0, v[70:71]
	global_load_dword v91, v[50:51], off
	global_load_dword v92, v[48:49], off
	v_lshlrev_b64 v[50:51], 12, v[64:65]
	v_or_b32_e32 v64, s21, v38
	v_lshl_add_u64 v[48:49], v[36:37], 0, v[52:53]
	v_lshlrev_b64 v[52:53], 12, v[64:65]
	v_or_b32_e32 v64, s23, v38
	v_lshlrev_b64 v[54:55], 12, v[64:65]
	v_lshl_add_u64 v[54:55], v[36:37], 0, v[54:55]
	v_lshl_add_u64 v[50:51], v[36:37], 0, v[50:51]
	v_lshl_add_u64 v[52:53], v[36:37], 0, v[52:53]
	global_load_dword v64, v[54:55], off
	global_load_dword v93, v[52:53], off
	global_load_dword v94, v[50:51], off
	global_load_dword v95, v[48:49], off
	v_or_b32_e32 v50, s7, v1
	v_or_b32_e32 v48, s8, v0
	s_add_i32 s5, s5, 16
	s_add_i32 s1, s1, 16
	s_add_i32 s6, s6, -16
	v_mad_u64_u32 v[48:49], s[8:9], v48, s92, v[2:3]
	v_mad_u64_u32 v[50:51], s[8:9], v50, s92, v[2:3]
	v_or_b32_e32 v49, s10, v1
	v_or_b32_e32 v51, s11, v0
	v_or_b32_e32 v58, s12, v1
	v_or_b32_e32 v56, s13, v0
	v_or_b32_e32 v62, s14, v1
	v_or_b32_e32 v60, s15, v0
	v_or_b32_e32 v68, s16, v1
	v_or_b32_e32 v66, s17, v0
	v_or_b32_e32 v72, s18, v1
	v_or_b32_e32 v70, s19, v0
	v_or_b32_e32 v76, s20, v1
	v_or_b32_e32 v74, s21, v0
	v_or_b32_e32 v80, s22, v1
	v_or_b32_e32 v78, s23, v0
	s_cmp_lg_u32 s6, 0
	v_mad_u64_u32 v[52:53], s[8:9], v51, s92, v[2:3]
	v_mad_u64_u32 v[54:55], s[8:9], v49, s92, v[2:3]
	v_mad_u64_u32 v[56:57], s[8:9], v56, s92, v[2:3]
	v_mad_u64_u32 v[58:59], s[8:9], v58, s92, v[2:3]
	v_mad_u64_u32 v[60:61], s[8:9], v60, s92, v[2:3]
	v_mad_u64_u32 v[62:63], s[8:9], v62, s92, v[2:3]
	v_mad_u64_u32 v[66:67], s[8:9], v66, s92, v[2:3]
	v_mad_u64_u32 v[68:69], s[8:9], v68, s92, v[2:3]
	v_mad_u64_u32 v[70:71], s[8:9], v70, s92, v[2:3]
	v_mad_u64_u32 v[72:73], s[8:9], v72, s92, v[2:3]
	v_mad_u64_u32 v[74:75], s[8:9], v74, s92, v[2:3]
	v_mad_u64_u32 v[76:77], s[8:9], v76, s92, v[2:3]
	v_mad_u64_u32 v[78:79], s[8:9], v78, s92, v[2:3]
	v_mad_u64_u32 v[80:81], s[8:9], v80, s92, v[2:3]
	s_waitcnt vmcnt(0)
	ds_write_b32 v48, v47
	ds_write_b32 v50, v82
	ds_write_b32 v52, v83
	ds_write_b32 v54, v84
	ds_write_b32 v56, v92
	ds_write_b32 v58, v85
	ds_write_b32 v60, v91
	ds_write_b32 v62, v86
	ds_write_b32 v66, v95
	ds_write_b32 v68, v87
	ds_write_b32 v70, v94
	ds_write_b32 v72, v88
	ds_write_b32 v74, v93
	ds_write_b32 v76, v89
	ds_write_b32 v78, v64
	ds_write_b32 v80, v90
	s_cbranch_scc1 .LBB0_661
; #define LAS __attribute__((address_space(3)))
; __device__ __forceinline__ unsigned pk2(float lo, float hi) { f32x2_t v = {lo, hi}; bf16x2_t b = __builtin_convertvector(v, bf16x2_t); return __builtin_bit_cast(unsigned, b); }
; __device__ __forceinline__ void transpose_item(const float* W, int K, int N, bf16_t* WT, int ldk, int row_off, int kind, LAS float* scr, int item, int lane) {
;     ...
;     const int c = lane & 7;
; #pragma unroll
;     for (int j = 0; j < 4; ++j) { const int n = (lane >> 3) + 8 * j; const LAS float* s = scr + (8 * c) * 33 + n;
;         u32x4 o; o.x = pk2(s[0 * 33], s[1 * 33]); o.y = pk2(s[2 * 33], s[3 * 33]); o.z = pk2(s[4 * 33], s[5 * 33]); o.w = pk2(s[6 * 33], s[7 * 33]);
;         *(u32x4*)(WT + (size_t)(row_off + rowmap(kind, n0 + n)) * ldk + k0 + 8 * c) = o; }
;     asm volatile("s_waitcnt lgkmcnt(0)" ::: "memory");
	s_waitcnt lgkmcnt(0)
	ds_read_b32 v3, v39
	ds_read_b32 v38, v39 offset:132
	ds_read_b32 v47, v39 offset:264
	ds_read_b32 v49, v39 offset:396
	ds_read_b32 v50, v39 offset:528
	ds_read_b32 v51, v39 offset:660
	ds_read_b32 v52, v39 offset:792
	ds_read_b32 v53, v39 offset:924
	s_waitcnt lgkmcnt(0)
	v_cvt_pk_bf16_f32 v48, v3, v38
	v_or_b32_e32 v3, s0, v17
	s_lshl_b32 s80, s4, 1
	v_mul_u32_u24_e32 v3, 0x180, v3
	v_lshl_add_u64 v[36:37], v[10:11], 0, s[80:81]
	v_lshlrev_b32_e32 v64, 1, v3
	v_cvt_pk_bf16_f32 v49, v47, v49
	v_cvt_pk_bf16_f32 v50, v50, v51
	v_cvt_pk_bf16_f32 v51, v52, v53
	v_lshl_add_u64 v[52:53], v[36:37], 0, v[64:65]
	global_store_dwordx4 v[52:53], v[48:51], off
	ds_read_b32 v3, v39 offset:32
	ds_read_b32 v38, v39 offset:164
	ds_read_b32 v47, v39 offset:296
	ds_read_b32 v49, v39 offset:428
	ds_read_b32 v50, v39 offset:560
	ds_read_b32 v51, v39 offset:692
	ds_read_b32 v52, v39 offset:824
	ds_read_b32 v53, v39 offset:956
	s_waitcnt lgkmcnt(0)
	v_cvt_pk_bf16_f32 v48, v3, v38
	v_or_b32_e32 v3, s0, v40
	v_mul_u32_u24_e32 v3, 0x180, v3
	v_lshlrev_b32_e32 v64, 1, v3
	v_cvt_pk_bf16_f32 v49, v47, v49
	v_cvt_pk_bf16_f32 v50, v50, v51
	v_cvt_pk_bf16_f32 v51, v52, v53
	v_lshl_add_u64 v[52:53], v[36:37], 0, v[64:65]
	global_store_dwordx4 v[52:53], v[48:51], off
	ds_read_b32 v3, v39 offset:64
	ds_read_b32 v38, v39 offset:196
	ds_read_b32 v47, v39 offset:328
	ds_read_b32 v49, v39 offset:460
	ds_read_b32 v50, v39 offset:592
	ds_read_b32 v51, v39 offset:724
	ds_read_b32 v52, v39 offset:856
	ds_read_b32 v53, v39 offset:988
	s_waitcnt lgkmcnt(0)
	v_cvt_pk_bf16_f32 v48, v3, v38
	v_or_b32_e32 v3, s0, v41
	v_mul_u32_u24_e32 v3, 0x180, v3
	v_lshlrev_b32_e32 v64, 1, v3
	v_cvt_pk_bf16_f32 v49, v47, v49
	v_cvt_pk_bf16_f32 v50, v50, v51
	v_cvt_pk_bf16_f32 v51, v52, v53
	v_lshl_add_u64 v[52:53], v[36:37], 0, v[64:65]
	global_store_dwordx4 v[52:53], v[48:51], off
	ds_read_b32 v3, v39 offset:96
	ds_read_b32 v38, v39 offset:228
	ds_read_b32 v47, v39 offset:360
	ds_read_b32 v49, v39 offset:492
	ds_read_b32 v50, v39 offset:624
	ds_read_b32 v51, v39 offset:756
	ds_read_b32 v52, v39 offset:888
	ds_read_b32 v53, v39 offset:1020
	v_or_b32_e32 v54, s0, v42
	s_waitcnt lgkmcnt(0)
	v_cvt_pk_bf16_f32 v48, v3, v38
	v_mul_u32_u24_e32 v3, 0x180, v54
	v_lshlrev_b32_e32 v64, 1, v3
	v_cvt_pk_bf16_f32 v49, v47, v49
	v_cvt_pk_bf16_f32 v50, v50, v51
	v_cvt_pk_bf16_f32 v51, v52, v53
	v_lshl_add_u64 v[36:37], v[36:37], 0, v[64:65]
	global_store_dwordx4 v[36:37], v[48:51], off
	s_waitcnt lgkmcnt(0)

; __device__ __forceinline__ void transpose_item(const float* W, int K, int N, bf16_t* WT, int ldk, int row_off, int kind, LAS float* scr, int item, int lane) {
;     const int nblk = N / 32, kb = item / nblk, nb = item % nblk, k0 = 64 * kb, n0 = 32 * nb;
; #pragma unroll 8
;     for (int i = 0; i < 32; ++i) { const int kk = 2 * i + (lane >> 5); scr[kk * 33 + (lane & 31)] = W[(size_t)(k0 + kk) * N + n0 + (lane & 31)]; }
;     asm volatile("s_waitcnt lgkmcnt(0)" ::: "memory");
.LBB0_666:
	s_lshl_b32 s8, s5, 1
	s_lshl_b32 s7, s1, 1
	v_or_b32_e32 v64, s8, v38
	s_add_i32 s11, s8, 4
	s_add_i32 s10, s7, 4
	s_add_i32 s12, s7, 8
	s_add_i32 s13, s8, 8
	v_lshlrev_b64 v[66:67], 12, v[64:65]
	v_or_b32_e32 v64, s11, v38
	v_mov_b32_e32 v49, v65
	v_mov_b32_e32 v51, v65
	v_mov_b32_e32 v53, v65
	v_or_b32_e32 v48, s7, v3
	s_add_i32 s14, s7, 12
	s_add_i32 s15, s8, 12
	s_add_i32 s16, s7, 16
	s_add_i32 s18, s7, 20
	s_add_i32 s20, s7, 24
	s_add_i32 s22, s7, 28
	v_or_b32_e32 v50, s10, v3
	v_or_b32_e32 v52, s12, v3
	v_lshlrev_b64 v[68:69], 12, v[64:65]
	v_or_b32_e32 v64, s13, v38
	v_mov_b32_e32 v55, v65
	v_mov_b32_e32 v57, v65
	v_mov_b32_e32 v59, v65
	v_mov_b32_e32 v61, v65
	v_mov_b32_e32 v63, v65
	s_add_i32 s17, s8, 16
	v_lshlrev_b64 v[48:49], 12, v[48:49]
	v_or_b32_e32 v54, s14, v3
	v_or_b32_e32 v56, s16, v3
	v_or_b32_e32 v58, s18, v3
	v_or_b32_e32 v60, s20, v3
	v_or_b32_e32 v62, s22, v3
	v_lshl_add_u64 v[66:67], v[36:37], 0, v[66:67]
	v_lshlrev_b64 v[50:51], 12, v[50:51]
	v_lshlrev_b64 v[52:53], 12, v[52:53]
	v_lshlrev_b64 v[70:71], 12, v[64:65]
	v_or_b32_e32 v64, s15, v38
	s_add_i32 s19, s8, 20
	v_lshl_add_u64 v[48:49], v[36:37], 0, v[48:49]
	v_lshlrev_b64 v[54:55], 12, v[54:55]
	v_lshlrev_b64 v[56:57], 12, v[56:57]
	v_lshlrev_b64 v[58:59], 12, v[58:59]
	v_lshlrev_b64 v[60:61], 12, v[60:61]
	v_lshlrev_b64 v[62:63], 12, v[62:63]
	v_lshl_add_u64 v[68:69], v[36:37], 0, v[68:69]
	v_lshl_add_u64 v[50:51], v[36:37], 0, v[50:51]
	v_lshl_add_u64 v[52:53], v[36:37], 0, v[52:53]
	global_load_dword v47, v[66:67], off
	global_load_dword v82, v[48:49], off
	v_lshlrev_b64 v[66:67], 12, v[64:65]
	v_or_b32_e32 v64, s17, v38
	s_add_i32 s21, s8, 24
	v_lshl_add_u64 v[54:55], v[36:37], 0, v[54:55]
	v_lshl_add_u64 v[56:57], v[36:37], 0, v[56:57]
	v_lshl_add_u64 v[58:59], v[36:37], 0, v[58:59]
	v_lshl_add_u64 v[60:61], v[36:37], 0, v[60:61]
	v_lshl_add_u64 v[62:63], v[36:37], 0, v[62:63]
	global_load_dword v83, v[68:69], off
	global_load_dword v84, v[50:51], off
	global_load_dword v85, v[52:53], off
	global_load_dword v86, v[54:55], off
	global_load_dword v87, v[56:57], off
	global_load_dword v88, v[58:59], off
	global_load_dword v89, v[60:61], off
	global_load_dword v90, v[62:63], off
	v_lshl_add_u64 v[50:51], v[36:37], 0, v[66:67]
	v_lshlrev_b64 v[52:53], 12, v[64:65]
	v_or_b32_e32 v64, s19, v38
	s_add_i32 s23, s8, 28
	v_lshl_add_u64 v[48:49], v[36:37], 0, v[70:71]
	global_load_dword v91, v[50:51], off
	global_load_dword v92, v[48:49], off
	v_lshlrev_b64 v[50:51], 12, v[64:65]
	v_or_b32_e32 v64, s21, v38
	v_lshl_add_u64 v[48:49], v[36:37], 0, v[52:53]
	v_lshlrev_b64 v[52:53], 12, v[64:65]
	v_or_b32_e32 v64, s23, v38
	v_lshlrev_b64 v[54:55], 12, v[64:65]
	v_lshl_add_u64 v[54:55], v[36:37], 0, v[54:55]
	v_lshl_add_u64 v[50:51], v[36:37], 0, v[50:51]
	v_lshl_add_u64 v[52:53], v[36:37], 0, v[52:53]
	global_load_dword v64, v[54:55], off
	global_load_dword v93, v[52:53], off
	global_load_dword v94, v[50:51], off
	global_load_dword v95, v[48:49], off
	v_or_b32_e32 v50, s7, v1
	v_or_b32_e32 v48, s8, v0
	s_add_i32 s5, s5, 16
	s_add_i32 s1, s1, 16
	s_add_i32 s6, s6, -16
	v_mad_u64_u32 v[48:49], s[8:9], v48, s92, v[2:3]
	v_mad_u64_u32 v[50:51], s[8:9], v50, s92, v[2:3]
	v_or_b32_e32 v49, s10, v1
	v_or_b32_e32 v51, s11, v0
	v_or_b32_e32 v58, s12, v1
	v_or_b32_e32 v56, s13, v0
	v_or_b32_e32 v62, s14, v1
	v_or_b32_e32 v60, s15, v0
	v_or_b32_e32 v68, s16, v1
	v_or_b32_e32 v66, s17, v0
	v_or_b32_e32 v72, s18, v1
	v_or_b32_e32 v70, s19, v0
	v_or_b32_e32 v76, s20, v1
	v_or_b32_e32 v74, s21, v0
	v_or_b32_e32 v80, s22, v1
	v_or_b32_e32 v78, s23, v0
	s_cmp_lg_u32 s6, 0
	v_mad_u64_u32 v[52:53], s[8:9], v51, s92, v[2:3]
	v_mad_u64_u32 v[54:55], s[8:9], v49, s92, v[2:3]
	v_mad_u64_u32 v[56:57], s[8:9], v56, s92, v[2:3]
	v_mad_u64_u32 v[58:59], s[8:9], v58, s92, v[2:3]
	v_mad_u64_u32 v[60:61], s[8:9], v60, s92, v[2:3]
	v_mad_u64_u32 v[62:63], s[8:9], v62, s92, v[2:3]
	v_mad_u64_u32 v[66:67], s[8:9], v66, s92, v[2:3]
	v_mad_u64_u32 v[68:69], s[8:9], v68, s92, v[2:3]
	v_mad_u64_u32 v[70:71], s[8:9], v70, s92, v[2:3]
	v_mad_u64_u32 v[72:73], s[8:9], v72, s92, v[2:3]
	v_mad_u64_u32 v[74:75], s[8:9], v74, s92, v[2:3]
	v_mad_u64_u32 v[76:77], s[8:9], v76, s92, v[2:3]
	v_mad_u64_u32 v[78:79], s[8:9], v78, s92, v[2:3]
	v_mad_u64_u32 v[80:81], s[8:9], v80, s92, v[2:3]
	s_waitcnt vmcnt(0)
	ds_write_b32 v48, v47
	ds_write_b32 v50, v82
	ds_write_b32 v52, v83
	ds_write_b32 v54, v84
	ds_write_b32 v56, v92
	ds_write_b32 v58, v85
	ds_write_b32 v60, v91
	ds_write_b32 v62, v86
	ds_write_b32 v66, v95
	ds_write_b32 v68, v87
	ds_write_b32 v70, v94
	ds_write_b32 v72, v88
	ds_write_b32 v74, v93
	ds_write_b32 v76, v89
	ds_write_b32 v78, v64
	ds_write_b32 v80, v90
	s_cbranch_scc1 .LBB0_666
; #define LAS __attribute__((address_space(3)))
; __device__ __forceinline__ unsigned pk2(float lo, float hi) { f32x2_t v = {lo, hi}; bf16x2_t b = __builtin_convertvector(v, bf16x2_t); return __builtin_bit_cast(unsigned, b); }
; __device__ __forceinline__ void transpose_item(const float* W, int K, int N, bf16_t* WT, int ldk, int row_off, int kind, LAS float* scr, int item, int lane) {
;     ...
;     const int c = lane & 7;
; #pragma unroll
;     for (int j = 0; j < 4; ++j) { const int n = (lane >> 3) + 8 * j; const LAS float* s = scr + (8 * c) * 33 + n;
;         u32x4 o; o.x = pk2(s[0 * 33], s[1 * 33]); o.y = pk2(s[2 * 33], s[3 * 33]); o.z = pk2(s[4 * 33], s[5 * 33]); o.w = pk2(s[6 * 33], s[7 * 33]);
;         *(u32x4*)(WT + (size_t)(row_off + rowmap(kind, n0 + n)) * ldk + k0 + 8 * c) = o; }
;     asm volatile("s_waitcnt lgkmcnt(0)" ::: "memory");
	s_waitcnt lgkmcnt(0)
	ds_read_b32 v3, v39
	ds_read_b32 v38, v39 offset:132
	ds_read_b32 v47, v39 offset:264
	ds_read_b32 v49, v39 offset:396
	ds_read_b32 v50, v39 offset:528
	ds_read_b32 v51, v39 offset:660
	ds_read_b32 v52, v39 offset:792
	ds_read_b32 v53, v39 offset:924
	s_waitcnt lgkmcnt(0)
	v_cvt_pk_bf16_f32 v48, v3, v38
	v_or_b32_e32 v3, s0, v17
	s_lshl_b32 s80, s4, 1
	v_mul_u32_u24_e32 v3, 0x180, v3
	v_lshl_add_u64 v[36:37], v[12:13], 0, s[80:81]
	v_lshlrev_b32_e32 v64, 1, v3
	v_cvt_pk_bf16_f32 v49, v47, v49
	v_cvt_pk_bf16_f32 v50, v50, v51
	v_cvt_pk_bf16_f32 v51, v52, v53
	v_lshl_add_u64 v[52:53], v[36:37], 0, v[64:65]
	global_store_dwordx4 v[52:53], v[48:51], off
	ds_read_b32 v3, v39 offset:32
	ds_read_b32 v38, v39 offset:164
	ds_read_b32 v47, v39 offset:296
	ds_read_b32 v49, v39 offset:428
	ds_read_b32 v50, v39 offset:560
	ds_read_b32 v51, v39 offset:692
	ds_read_b32 v52, v39 offset:824
	ds_read_b32 v53, v39 offset:956
	s_waitcnt lgkmcnt(0)
	v_cvt_pk_bf16_f32 v48, v3, v38
	v_or_b32_e32 v3, s0, v40
	v_mul_u32_u24_e32 v3, 0x180, v3
	v_lshlrev_b32_e32 v64, 1, v3
	v_cvt_pk_bf16_f32 v49, v47, v49
	v_cvt_pk_bf16_f32 v50, v50, v51
	v_cvt_pk_bf16_f32 v51, v52, v53
	v_lshl_add_u64 v[52:53], v[36:37], 0, v[64:65]
	global_store_dwordx4 v[52:53], v[48:51], off
	ds_read_b32 v3, v39 offset:64
	ds_read_b32 v38, v39 offset:196
	ds_read_b32 v47, v39 offset:328
	ds_read_b32 v49, v39 offset:460
	ds_read_b32 v50, v39 offset:592
	ds_read_b32 v51, v39 offset:724
	ds_read_b32 v52, v39 offset:856
	ds_read_b32 v53, v39 offset:988
	s_waitcnt lgkmcnt(0)
	v_cvt_pk_bf16_f32 v48, v3, v38
	v_or_b32_e32 v3, s0, v41
	v_mul_u32_u24_e32 v3, 0x180, v3
	v_lshlrev_b32_e32 v64, 1, v3
	v_cvt_pk_bf16_f32 v49, v47, v49
	v_cvt_pk_bf16_f32 v50, v50, v51
	v_cvt_pk_bf16_f32 v51, v52, v53
	v_lshl_add_u64 v[52:53], v[36:37], 0, v[64:65]
	global_store_dwordx4 v[52:53], v[48:51], off
	ds_read_b32 v3, v39 offset:96
	ds_read_b32 v38, v39 offset:228
	ds_read_b32 v47, v39 offset:360
	ds_read_b32 v49, v39 offset:492
	ds_read_b32 v50, v39 offset:624
	ds_read_b32 v51, v39 offset:756
	ds_read_b32 v52, v39 offset:888
	ds_read_b32 v53, v39 offset:1020
	v_or_b32_e32 v54, s0, v42
	s_waitcnt lgkmcnt(0)
	v_cvt_pk_bf16_f32 v48, v3, v38
	v_mul_u32_u24_e32 v3, 0x180, v54
	v_lshlrev_b32_e32 v64, 1, v3
	v_cvt_pk_bf16_f32 v49, v47, v49
	v_cvt_pk_bf16_f32 v50, v50, v51
	v_cvt_pk_bf16_f32 v51, v52, v53
	v_lshl_add_u64 v[36:37], v[36:37], 0, v[64:65]
	global_store_dwordx4 v[36:37], v[48:51], off
	s_waitcnt lgkmcnt(0)

; __device__ __forceinline__ void transpose_item(const float* W, int K, int N, bf16_t* WT, int ldk, int row_off, int kind, LAS float* scr, int item, int lane) {
;     const int nblk = N / 32, kb = item / nblk, nb = item % nblk, k0 = 64 * kb, n0 = 32 * nb;
; #pragma unroll 8
;     for (int i = 0; i < 32; ++i) { const int kk = 2 * i + (lane >> 5); scr[kk * 33 + (lane & 31)] = W[(size_t)(k0 + kk) * N + n0 + (lane & 31)]; }
;     asm volatile("s_waitcnt lgkmcnt(0)" ::: "memory");
.LBB0_671:
	s_lshl_b32 s8, s5, 1
	s_lshl_b32 s7, s4, 1
	v_or_b32_e32 v64, s8, v38
	s_add_i32 s11, s8, 4
	s_add_i32 s10, s7, 4
	s_add_i32 s12, s7, 8
	s_add_i32 s13, s8, 8
	v_lshlrev_b64 v[66:67], 12, v[64:65]
	v_or_b32_e32 v64, s11, v38
	v_mov_b32_e32 v49, v65
	v_mov_b32_e32 v51, v65
	v_mov_b32_e32 v53, v65
	v_or_b32_e32 v48, s7, v3
	s_add_i32 s14, s7, 12
	s_add_i32 s15, s8, 12
	s_add_i32 s16, s7, 16
	s_add_i32 s18, s7, 20
	s_add_i32 s20, s7, 24
	s_add_i32 s22, s7, 28
	v_or_b32_e32 v50, s10, v3
	v_or_b32_e32 v52, s12, v3
	v_lshlrev_b64 v[68:69], 12, v[64:65]
	v_or_b32_e32 v64, s13, v38
	v_mov_b32_e32 v55, v65
	v_mov_b32_e32 v57, v65
	v_mov_b32_e32 v59, v65
	v_mov_b32_e32 v61, v65
	v_mov_b32_e32 v63, v65
	s_add_i32 s17, s8, 16
	v_lshlrev_b64 v[48:49], 12, v[48:49]
	v_or_b32_e32 v54, s14, v3
	v_or_b32_e32 v56, s16, v3
	v_or_b32_e32 v58, s18, v3
	v_or_b32_e32 v60, s20, v3
	v_or_b32_e32 v62, s22, v3
	v_lshl_add_u64 v[66:67], v[36:37], 0, v[66:67]
	v_lshlrev_b64 v[50:51], 12, v[50:51]
	v_lshlrev_b64 v[52:53], 12, v[52:53]
	v_lshlrev_b64 v[70:71], 12, v[64:65]
	v_or_b32_e32 v64, s15, v38
	s_add_i32 s19, s8, 20
	v_lshl_add_u64 v[48:49], v[36:37], 0, v[48:49]
	v_lshlrev_b64 v[54:55], 12, v[54:55]
	v_lshlrev_b64 v[56:57], 12, v[56:57]
	v_lshlrev_b64 v[58:59], 12, v[58:59]
	v_lshlrev_b64 v[60:61], 12, v[60:61]
	v_lshlrev_b64 v[62:63], 12, v[62:63]
	v_lshl_add_u64 v[68:69], v[36:37], 0, v[68:69]
	v_lshl_add_u64 v[50:51], v[36:37], 0, v[50:51]
	v_lshl_add_u64 v[52:53], v[36:37], 0, v[52:53]
	global_load_dword v47, v[66:67], off
	global_load_dword v82, v[48:49], off
	v_lshlrev_b64 v[66:67], 12, v[64:65]
	v_or_b32_e32 v64, s17, v38
	s_add_i32 s21, s8, 24
	v_lshl_add_u64 v[54:55], v[36:37], 0, v[54:55]
	v_lshl_add_u64 v[56:57], v[36:37], 0, v[56:57]
	v_lshl_add_u64 v[58:59], v[36:37], 0, v[58:59]
	v_lshl_add_u64 v[60:61], v[36:37], 0, v[60:61]
	v_lshl_add_u64 v[62:63], v[36:37], 0, v[62:63]
	global_load_dword v83, v[68:69], off
	global_load_dword v84, v[50:51], off
	global_load_dword v85, v[52:53], off
	global_load_dword v86, v[54:55], off
	global_load_dword v87, v[56:57], off
	global_load_dword v88, v[58:59], off
	global_load_dword v89, v[60:61], off
	global_load_dword v90, v[62:63], off
	v_lshl_add_u64 v[50:51], v[36:37], 0, v[66:67]
	v_lshlrev_b64 v[52:53], 12, v[64:65]
	v_or_b32_e32 v64, s19, v38
	s_add_i32 s23, s8, 28
	v_lshl_add_u64 v[48:49], v[36:37], 0, v[70:71]
	global_load_dword v91, v[50:51], off
	global_load_dword v92, v[48:49], off
	v_lshlrev_b64 v[50:51], 12, v[64:65]
	v_or_b32_e32 v64, s21, v38
	v_lshl_add_u64 v[48:49], v[36:37], 0, v[52:53]
	v_lshlrev_b64 v[52:53], 12, v[64:65]
	v_or_b32_e32 v64, s23, v38
	v_lshlrev_b64 v[54:55], 12, v[64:65]
	v_lshl_add_u64 v[54:55], v[36:37], 0, v[54:55]
	v_lshl_add_u64 v[50:51], v[36:37], 0, v[50:51]
	v_lshl_add_u64 v[52:53], v[36:37], 0, v[52:53]
	global_load_dword v64, v[54:55], off
	global_load_dword v93, v[52:53], off
	global_load_dword v94, v[50:51], off
	global_load_dword v95, v[48:49], off
	v_or_b32_e32 v50, s7, v1
	v_or_b32_e32 v48, s8, v0
	s_add_i32 s5, s5, 16
	s_add_i32 s4, s4, 16
	s_add_i32 s6, s6, -16
	v_mad_u64_u32 v[48:49], s[8:9], v48, s92, v[2:3]
	v_mad_u64_u32 v[50:51], s[8:9], v50, s92, v[2:3]
	v_or_b32_e32 v49, s10, v1
	v_or_b32_e32 v51, s11, v0
	v_or_b32_e32 v58, s12, v1
	v_or_b32_e32 v56, s13, v0
	v_or_b32_e32 v62, s14, v1
	v_or_b32_e32 v60, s15, v0
	v_or_b32_e32 v68, s16, v1
	v_or_b32_e32 v66, s17, v0
	v_or_b32_e32 v72, s18, v1
	v_or_b32_e32 v70, s19, v0
	v_or_b32_e32 v76, s20, v1
	v_or_b32_e32 v74, s21, v0
	v_or_b32_e32 v80, s22, v1
	v_or_b32_e32 v78, s23, v0
	s_cmp_lg_u32 s6, 0
	v_mad_u64_u32 v[52:53], s[8:9], v51, s92, v[2:3]
	v_mad_u64_u32 v[54:55], s[8:9], v49, s92, v[2:3]
	v_mad_u64_u32 v[56:57], s[8:9], v56, s92, v[2:3]
	v_mad_u64_u32 v[58:59], s[8:9], v58, s92, v[2:3]
	v_mad_u64_u32 v[60:61], s[8:9], v60, s92, v[2:3]
	v_mad_u64_u32 v[62:63], s[8:9], v62, s92, v[2:3]
	v_mad_u64_u32 v[66:67], s[8:9], v66, s92, v[2:3]
	v_mad_u64_u32 v[68:69], s[8:9], v68, s92, v[2:3]
	v_mad_u64_u32 v[70:71], s[8:9], v70, s92, v[2:3]
	v_mad_u64_u32 v[72:73], s[8:9], v72, s92, v[2:3]
	v_mad_u64_u32 v[74:75], s[8:9], v74, s92, v[2:3]
	v_mad_u64_u32 v[76:77], s[8:9], v76, s92, v[2:3]
	v_mad_u64_u32 v[78:79], s[8:9], v78, s92, v[2:3]
	v_mad_u64_u32 v[80:81], s[8:9], v80, s92, v[2:3]
	s_waitcnt vmcnt(0)
	ds_write_b32 v48, v47
	ds_write_b32 v50, v82
	ds_write_b32 v52, v83
	ds_write_b32 v54, v84
	ds_write_b32 v56, v92
	ds_write_b32 v58, v85
	ds_write_b32 v60, v91
	ds_write_b32 v62, v86
	ds_write_b32 v66, v95
	ds_write_b32 v68, v87
	ds_write_b32 v70, v94
	ds_write_b32 v72, v88
	ds_write_b32 v74, v93
	ds_write_b32 v76, v89
	ds_write_b32 v78, v64
	ds_write_b32 v80, v90
	s_cbranch_scc1 .LBB0_671
; #define LAS __attribute__((address_space(3)))
; __device__ __forceinline__ unsigned pk2(float lo, float hi) { f32x2_t v = {lo, hi}; bf16x2_t b = __builtin_convertvector(v, bf16x2_t); return __builtin_bit_cast(unsigned, b); }
; __device__ __forceinline__ void transpose_item(const float* W, int K, int N, bf16_t* WT, int ldk, int row_off, int kind, LAS float* scr, int item, int lane) {
;     ...
;     const int c = lane & 7;
; #pragma unroll
;     for (int j = 0; j < 4; ++j) { const int n = (lane >> 3) + 8 * j; const LAS float* s = scr + (8 * c) * 33 + n;
;         u32x4 o; o.x = pk2(s[0 * 33], s[1 * 33]); o.y = pk2(s[2 * 33], s[3 * 33]); o.z = pk2(s[4 * 33], s[5 * 33]); o.w = pk2(s[6 * 33], s[7 * 33]);
;         *(u32x4*)(WT + (size_t)(row_off + rowmap(kind, n0 + n)) * ldk + k0 + 8 * c) = o; }
;     asm volatile("s_waitcnt lgkmcnt(0)" ::: "memory");
	s_waitcnt lgkmcnt(0)
	ds_read_b32 v3, v39
	ds_read_b32 v38, v39 offset:132
	ds_read_b32 v47, v39 offset:264
	ds_read_b32 v49, v39 offset:396
	ds_read_b32 v50, v39 offset:528
	ds_read_b32 v51, v39 offset:660
	ds_read_b32 v52, v39 offset:792
	ds_read_b32 v53, v39 offset:924
	s_waitcnt lgkmcnt(0)
	v_cvt_pk_bf16_f32 v48, v3, v38
	v_or_b32_e32 v3, s0, v17
	s_lshl_b32 s80, s1, 1
	v_mul_u32_u24_e32 v3, 0x180, v3
	v_lshl_add_u64 v[36:37], v[14:15], 0, s[80:81]
	v_lshlrev_b32_e32 v64, 1, v3
	v_cvt_pk_bf16_f32 v49, v47, v49
	v_cvt_pk_bf16_f32 v50, v50, v51
	v_cvt_pk_bf16_f32 v51, v52, v53
	v_lshl_add_u64 v[52:53], v[36:37], 0, v[64:65]
	global_store_dwordx4 v[52:53], v[48:51], off
	ds_read_b32 v3, v39 offset:32
	ds_read_b32 v38, v39 offset:164
	ds_read_b32 v47, v39 offset:296
	ds_read_b32 v49, v39 offset:428
	ds_read_b32 v50, v39 offset:560
	ds_read_b32 v51, v39 offset:692
	ds_read_b32 v52, v39 offset:824
	ds_read_b32 v53, v39 offset:956
	s_waitcnt lgkmcnt(0)
	v_cvt_pk_bf16_f32 v48, v3, v38
	v_or_b32_e32 v3, s0, v40
	v_mul_u32_u24_e32 v3, 0x180, v3
	v_lshlrev_b32_e32 v64, 1, v3
	v_cvt_pk_bf16_f32 v49, v47, v49
	v_cvt_pk_bf16_f32 v50, v50, v51
	v_cvt_pk_bf16_f32 v51, v52, v53
	v_lshl_add_u64 v[52:53], v[36:37], 0, v[64:65]
	global_store_dwordx4 v[52:53], v[48:51], off
	ds_read_b32 v3, v39 offset:64
	ds_read_b32 v38, v39 offset:196
	ds_read_b32 v47, v39 offset:328
	ds_read_b32 v49, v39 offset:460
	ds_read_b32 v50, v39 offset:592
	ds_read_b32 v51, v39 offset:724
	ds_read_b32 v52, v39 offset:856
	ds_read_b32 v53, v39 offset:988
	s_waitcnt lgkmcnt(0)
	v_cvt_pk_bf16_f32 v48, v3, v38
	v_or_b32_e32 v3, s0, v41
	v_mul_u32_u24_e32 v3, 0x180, v3
	v_lshlrev_b32_e32 v64, 1, v3
	v_cvt_pk_bf16_f32 v49, v47, v49
	v_cvt_pk_bf16_f32 v50, v50, v51
	v_cvt_pk_bf16_f32 v51, v52, v53
	v_lshl_add_u64 v[52:53], v[36:37], 0, v[64:65]
	global_store_dwordx4 v[52:53], v[48:51], off
	ds_read_b32 v3, v39 offset:96
	ds_read_b32 v38, v39 offset:228
	ds_read_b32 v47, v39 offset:360
	ds_read_b32 v49, v39 offset:492
	ds_read_b32 v50, v39 offset:624
	ds_read_b32 v51, v39 offset:756
	ds_read_b32 v52, v39 offset:888
	ds_read_b32 v53, v39 offset:1020
	v_or_b32_e32 v54, s0, v42
	s_waitcnt lgkmcnt(0)
	v_cvt_pk_bf16_f32 v48, v3, v38
	v_mul_u32_u24_e32 v3, 0x180, v54
	v_lshlrev_b32_e32 v64, 1, v3
	v_cvt_pk_bf16_f32 v49, v47, v49
	v_cvt_pk_bf16_f32 v50, v50, v51
	v_cvt_pk_bf16_f32 v51, v52, v53
	v_lshl_add_u64 v[36:37], v[36:37], 0, v[64:65]
	global_store_dwordx4 v[36:37], v[48:51], off
	s_waitcnt lgkmcnt(0)

; #define LAS __attribute__((address_space(3)))
; __device__ __forceinline__ unsigned pk2(float lo, float hi) { f32x2_t v = {lo, hi}; bf16x2_t b = __builtin_convertvector(v, bf16x2_t); return __builtin_bit_cast(unsigned, b); }
; __device__ __forceinline__ void transpose_item(const float* W, int K, int N, bf16_t* WT, int ldk, int row_off, int kind, LAS float* scr, int item, int lane) {
;     ...
;     for (int i = 0; i < 32; ++i) { const int kk = 2 * i + (lane >> 5); scr[kk * 33 + (lane & 31)] = W[(size_t)(k0 + kk) * N + n0 + (lane & 31)]; }
;     asm volatile("s_waitcnt lgkmcnt(0)" ::: "memory");
;     const int c = lane & 7;
; #pragma unroll
;     for (int j = 0; j < 4; ++j) { const int n = (lane >> 3) + 8 * j; const LAS float* s = scr + (8 * c) * 33 + n;
;         u32x4 o; o.x = pk2(s[0 * 33], s[1 * 33]); o.y = pk2(s[2 * 33], s[3 * 33]); o.z = pk2(s[4 * 33], s[5 * 33]); o.w = pk2(s[6 * 33], s[7 * 33]);
;         *(u32x4*)(WT + (size_t)(row_off + rowmap(kind, n0 + n)) * ldk + k0 + 8 * c) = o; }
;     asm volatile("s_waitcnt lgkmcnt(0)" ::: "memory");
.LBB0_676:
	s_lshl_b32 s7, s4, 1
	s_lshl_b32 s10, s5, 1
	v_or_b32_e32 v47, s7, v3
	v_or_b32_e32 v48, s10, v38
	s_add_i32 s11, s7, 4
	s_add_i32 s12, s10, 4
	s_add_i32 s13, s7, 8
	s_add_i32 s14, s10, 8
	s_add_i32 s15, s7, 12
	s_add_i32 s16, s10, 12
	s_add_i32 s17, s7, 16
	s_add_i32 s18, s10, 16
	s_add_i32 s19, s7, 20
	s_add_i32 s20, s10, 20
	s_add_i32 s21, s7, 24
	s_add_i32 s22, s10, 24
	s_add_i32 s23, s7, 28
	s_add_i32 s24, s10, 28
	v_mad_u64_u32 v[48:49], s[8:9], v48, s88, v[36:37]
	v_mad_u64_u32 v[50:51], s[8:9], v47, s88, v[36:37]
	v_or_b32_e32 v47, s11, v3
	v_or_b32_e32 v52, s12, v38
	v_or_b32_e32 v58, s13, v3
	v_or_b32_e32 v56, s14, v38
	v_or_b32_e32 v62, s15, v3
	v_or_b32_e32 v60, s16, v38
	v_or_b32_e32 v64, s17, v3
	v_or_b32_e32 v66, s18, v38
	v_or_b32_e32 v72, s19, v3
	v_or_b32_e32 v70, s20, v38
	v_or_b32_e32 v76, s21, v3
	v_or_b32_e32 v74, s22, v38
	v_or_b32_e32 v80, s23, v3
	v_or_b32_e32 v78, s24, v38
	v_mad_u64_u32 v[52:53], s[8:9], v52, s88, v[36:37]
	v_mad_u64_u32 v[54:55], s[8:9], v47, s88, v[36:37]
	v_mad_u64_u32 v[56:57], s[8:9], v56, s88, v[36:37]
	v_mad_u64_u32 v[58:59], s[8:9], v58, s88, v[36:37]
	v_mad_u64_u32 v[60:61], s[8:9], v60, s88, v[36:37]
	v_mad_u64_u32 v[62:63], s[8:9], v62, s88, v[36:37]
	v_mad_u64_u32 v[66:67], s[8:9], v66, s88, v[36:37]
	v_mad_u64_u32 v[68:69], s[8:9], v64, s88, v[36:37]
	v_mad_u64_u32 v[70:71], s[8:9], v70, s88, v[36:37]
	v_mad_u64_u32 v[72:73], s[8:9], v72, s88, v[36:37]
	v_mad_u64_u32 v[74:75], s[8:9], v74, s88, v[36:37]
	v_mad_u64_u32 v[76:77], s[8:9], v76, s88, v[36:37]
	v_mad_u64_u32 v[78:79], s[8:9], v78, s88, v[36:37]
	v_mad_u64_u32 v[80:81], s[8:9], v80, s88, v[36:37]
	global_load_dword v47, v[48:49], off
	global_load_dword v64, v[50:51], off
	global_load_dword v82, v[52:53], off
	global_load_dword v83, v[54:55], off
	global_load_dword v84, v[56:57], off
	global_load_dword v85, v[58:59], off
	global_load_dword v86, v[60:61], off
	global_load_dword v87, v[62:63], off
	global_load_dword v88, v[66:67], off
	global_load_dword v89, v[68:69], off
	global_load_dword v90, v[70:71], off
	global_load_dword v91, v[72:73], off
	global_load_dword v92, v[74:75], off
	global_load_dword v93, v[76:77], off
	global_load_dword v94, v[78:79], off
	global_load_dword v95, v[80:81], off
	v_or_b32_e32 v50, s7, v1
	v_or_b32_e32 v48, s10, v0
	s_add_i32 s5, s5, 16
	s_add_i32 s4, s4, 16
	s_add_i32 s6, s6, -16
	v_mad_u64_u32 v[48:49], s[8:9], v48, s92, v[2:3]
	v_mad_u64_u32 v[50:51], s[8:9], v50, s92, v[2:3]
	v_or_b32_e32 v49, s11, v1
	v_or_b32_e32 v51, s12, v0
	v_or_b32_e32 v58, s13, v1
	v_or_b32_e32 v56, s14, v0
	v_or_b32_e32 v62, s15, v1
	v_or_b32_e32 v60, s16, v0
	v_or_b32_e32 v68, s17, v1
	v_or_b32_e32 v66, s18, v0
	v_or_b32_e32 v72, s19, v1
	v_or_b32_e32 v70, s20, v0
	v_or_b32_e32 v76, s21, v1
	v_or_b32_e32 v74, s22, v0
	v_or_b32_e32 v80, s23, v1
	v_or_b32_e32 v78, s24, v0
	s_cmp_lg_u32 s6, 0
	v_mad_u64_u32 v[52:53], s[8:9], v51, s92, v[2:3]
	v_mad_u64_u32 v[54:55], s[8:9], v49, s92, v[2:3]
	v_mad_u64_u32 v[56:57], s[8:9], v56, s92, v[2:3]
	v_mad_u64_u32 v[58:59], s[8:9], v58, s92, v[2:3]
	v_mad_u64_u32 v[60:61], s[8:9], v60, s92, v[2:3]
	v_mad_u64_u32 v[62:63], s[8:9], v62, s92, v[2:3]
	v_mad_u64_u32 v[66:67], s[8:9], v66, s92, v[2:3]
	v_mad_u64_u32 v[68:69], s[8:9], v68, s92, v[2:3]
	v_mad_u64_u32 v[70:71], s[8:9], v70, s92, v[2:3]
	v_mad_u64_u32 v[72:73], s[8:9], v72, s92, v[2:3]
	v_mad_u64_u32 v[74:75], s[8:9], v74, s92, v[2:3]
	v_mad_u64_u32 v[76:77], s[8:9], v76, s92, v[2:3]
	v_mad_u64_u32 v[78:79], s[8:9], v78, s92, v[2:3]
	v_mad_u64_u32 v[80:81], s[8:9], v80, s92, v[2:3]
	s_waitcnt vmcnt(0)
	ds_write_b32 v48, v47
	ds_write_b32 v50, v64
	ds_write_b32 v52, v82
	ds_write_b32 v54, v83
	ds_write_b32 v56, v84
	ds_write_b32 v58, v85
	ds_write_b32 v60, v86
	ds_write_b32 v62, v87
	ds_write_b32 v66, v88
	ds_write_b32 v68, v89
	ds_write_b32 v70, v90
	ds_write_b32 v72, v91
	ds_write_b32 v74, v92
	ds_write_b32 v76, v93
	ds_write_b32 v78, v94
	ds_write_b32 v80, v95
	s_cbranch_scc1 .LBB0_676
	s_waitcnt lgkmcnt(0)
	ds_read_b32 v3, v39
	ds_read_b32 v38, v39 offset:132
	ds_read_b32 v47, v39 offset:264
	ds_read_b32 v49, v39 offset:396
	ds_read_b32 v50, v39 offset:528
	ds_read_b32 v51, v39 offset:660
	ds_read_b32 v52, v39 offset:792
	ds_read_b32 v53, v39 offset:924
	s_and_b32 s1, 0xffff, s1
	s_and_b32 s0, 0xffff, s0
	s_lshl_b32 s80, s0, 1
	s_waitcnt lgkmcnt(0)
	v_cvt_pk_bf16_f32 v48, v3, v38
	v_or_b32_e32 v3, s1, v17
	v_lshl_add_u64 v[36:37], v[18:19], 0, s[80:81]
	v_lshlrev_b32_e32 v64, 11, v3
	v_cvt_pk_bf16_f32 v50, v50, v51
	v_cvt_pk_bf16_f32 v51, v52, v53
	v_lshl_add_u64 v[52:53], v[36:37], 0, v[64:65]
	v_add_co_u32_e32 v52, vcc, s60, v52
	v_cvt_pk_bf16_f32 v49, v47, v49
	s_nop 0
	v_addc_co_u32_e32 v53, vcc, 0, v53, vcc
	global_store_dwordx4 v[52:53], v[48:51], off
	ds_read_b32 v3, v39 offset:32
	ds_read_b32 v38, v39 offset:164
	ds_read_b32 v47, v39 offset:296
	ds_read_b32 v49, v39 offset:428
	ds_read_b32 v50, v39 offset:560
	ds_read_b32 v51, v39 offset:692
	ds_read_b32 v52, v39 offset:824
	ds_read_b32 v53, v39 offset:956
	s_waitcnt lgkmcnt(0)
	v_cvt_pk_bf16_f32 v48, v3, v38
	v_or_b32_e32 v3, s1, v40
	v_lshlrev_b32_e32 v64, 11, v3
	v_cvt_pk_bf16_f32 v50, v50, v51
	v_cvt_pk_bf16_f32 v51, v52, v53
	v_lshl_add_u64 v[52:53], v[36:37], 0, v[64:65]
	v_add_co_u32_e32 v52, vcc, s60, v52
	v_cvt_pk_bf16_f32 v49, v47, v49
	s_nop 0
	v_addc_co_u32_e32 v53, vcc, 0, v53, vcc
	global_store_dwordx4 v[52:53], v[48:51], off
	ds_read_b32 v3, v39 offset:64
	ds_read_b32 v38, v39 offset:196
	ds_read_b32 v47, v39 offset:328
	ds_read_b32 v49, v39 offset:460
	ds_read_b32 v50, v39 offset:592
	ds_read_b32 v51, v39 offset:724
	ds_read_b32 v52, v39 offset:856
	ds_read_b32 v53, v39 offset:988
	s_waitcnt lgkmcnt(0)
	v_cvt_pk_bf16_f32 v48, v3, v38
	v_or_b32_e32 v3, s1, v41
	v_lshlrev_b32_e32 v64, 11, v3
	v_cvt_pk_bf16_f32 v50, v50, v51
	v_cvt_pk_bf16_f32 v51, v52, v53
	v_lshl_add_u64 v[52:53], v[36:37], 0, v[64:65]
	v_add_co_u32_e32 v52, vcc, s60, v52
	v_cvt_pk_bf16_f32 v49, v47, v49
	s_nop 0
	v_addc_co_u32_e32 v53, vcc, 0, v53, vcc
	global_store_dwordx4 v[52:53], v[48:51], off
	ds_read_b32 v3, v39 offset:96
	ds_read_b32 v38, v39 offset:228
	ds_read_b32 v47, v39 offset:360
	ds_read_b32 v49, v39 offset:492
	ds_read_b32 v50, v39 offset:624
	ds_read_b32 v51, v39 offset:756
	ds_read_b32 v52, v39 offset:888
	ds_read_b32 v53, v39 offset:1020
	v_or_b32_e32 v54, s1, v42
	v_lshlrev_b32_e32 v64, 11, v54
	v_lshl_add_u64 v[36:37], v[36:37], 0, v[64:65]
	v_add_co_u32_e32 v36, vcc, 0x900000, v36
	s_waitcnt lgkmcnt(0)
	v_cvt_pk_bf16_f32 v48, v3, v38
	v_cvt_pk_bf16_f32 v49, v47, v49
	v_cvt_pk_bf16_f32 v50, v50, v51
	v_cvt_pk_bf16_f32 v51, v52, v53
	v_addc_co_u32_e32 v37, vcc, 0, v37, vcc
	global_store_dwordx4 v[36:37], v[48:51], off
	s_waitcnt lgkmcnt(0)

; __device__ __forceinline__ void transpose_item(const float* W, int K, int N, bf16_t* WT, int ldk, int row_off, int kind, LAS float* scr, int item, int lane) {
;     ...
; #pragma unroll 8
;     for (int i = 0; i < 32; ++i) { const int kk = 2 * i + (lane >> 5); scr[kk * 33 + (lane & 31)] = W[(size_t)(k0 + kk) * N + n0 + (lane & 31)]; }
.LBB0_681:
	s_lshl_b32 s7, s1, 1
	s_lshl_b32 s10, s5, 1
	v_or_b32_e32 v47, s7, v3
	v_or_b32_e32 v48, s10, v38
	s_add_i32 s11, s7, 4
	s_add_i32 s12, s10, 4
	s_add_i32 s13, s7, 8
	s_add_i32 s14, s10, 8
	s_add_i32 s15, s7, 12
	s_add_i32 s16, s10, 12
	s_add_i32 s17, s7, 16
	s_add_i32 s18, s10, 16
	s_add_i32 s19, s7, 20
	s_add_i32 s20, s10, 20
	s_add_i32 s21, s7, 24
	s_add_i32 s22, s10, 24
	s_add_i32 s23, s7, 28
	s_add_i32 s24, s10, 28
	v_mad_i64_i32 v[48:49], s[8:9], v48, s74, v[36:37]
	v_mad_i64_i32 v[50:51], s[8:9], v47, s74, v[36:37]
	v_or_b32_e32 v47, s11, v3
	v_or_b32_e32 v52, s12, v38
	v_or_b32_e32 v58, s13, v3
	v_or_b32_e32 v56, s14, v38
	v_or_b32_e32 v62, s15, v3
	v_or_b32_e32 v60, s16, v38
	v_or_b32_e32 v64, s17, v3
	v_or_b32_e32 v66, s18, v38
	v_or_b32_e32 v72, s19, v3
	v_or_b32_e32 v70, s20, v38
	v_or_b32_e32 v76, s21, v3
	v_or_b32_e32 v74, s22, v38
	v_or_b32_e32 v80, s23, v3
	v_or_b32_e32 v78, s24, v38
	v_mad_i64_i32 v[52:53], s[8:9], v52, s74, v[36:37]
	v_mad_i64_i32 v[54:55], s[8:9], v47, s74, v[36:37]
	v_mad_i64_i32 v[56:57], s[8:9], v56, s74, v[36:37]
	v_mad_i64_i32 v[58:59], s[8:9], v58, s74, v[36:37]
	v_mad_i64_i32 v[60:61], s[8:9], v60, s74, v[36:37]
	v_mad_i64_i32 v[62:63], s[8:9], v62, s74, v[36:37]
	v_mad_i64_i32 v[66:67], s[8:9], v66, s74, v[36:37]
	v_mad_i64_i32 v[68:69], s[8:9], v64, s74, v[36:37]
	v_mad_i64_i32 v[70:71], s[8:9], v70, s74, v[36:37]
	v_mad_i64_i32 v[72:73], s[8:9], v72, s74, v[36:37]
	v_mad_i64_i32 v[74:75], s[8:9], v74, s74, v[36:37]
	v_mad_i64_i32 v[76:77], s[8:9], v76, s74, v[36:37]
	v_mad_i64_i32 v[78:79], s[8:9], v78, s74, v[36:37]
	v_mad_i64_i32 v[80:81], s[8:9], v80, s74, v[36:37]
	global_load_dword v47, v[48:49], off
	global_load_dword v64, v[50:51], off
	global_load_dword v82, v[52:53], off
	global_load_dword v83, v[54:55], off
	global_load_dword v84, v[56:57], off
	global_load_dword v85, v[58:59], off
	global_load_dword v86, v[60:61], off
	global_load_dword v87, v[62:63], off
	global_load_dword v88, v[66:67], off
	global_load_dword v89, v[68:69], off
	global_load_dword v90, v[70:71], off
	global_load_dword v91, v[72:73], off
	global_load_dword v92, v[74:75], off
	global_load_dword v93, v[76:77], off
	global_load_dword v94, v[78:79], off
	global_load_dword v95, v[80:81], off
	v_or_b32_e32 v50, s7, v1
	v_or_b32_e32 v48, s10, v0
	s_add_i32 s5, s5, 16
	s_add_i32 s1, s1, 16
	s_add_i32 s6, s6, -16
	v_mad_u64_u32 v[48:49], s[8:9], v48, s92, v[2:3]
	v_mad_u64_u32 v[50:51], s[8:9], v50, s92, v[2:3]
	v_or_b32_e32 v49, s11, v1
	v_or_b32_e32 v51, s12, v0
	v_or_b32_e32 v58, s13, v1
	v_or_b32_e32 v56, s14, v0
	v_or_b32_e32 v62, s15, v1
	v_or_b32_e32 v60, s16, v0
	v_or_b32_e32 v68, s17, v1
	v_or_b32_e32 v66, s18, v0
	v_or_b32_e32 v72, s19, v1
	v_or_b32_e32 v70, s20, v0
	v_or_b32_e32 v76, s21, v1
	v_or_b32_e32 v74, s22, v0
	v_or_b32_e32 v80, s23, v1
	v_or_b32_e32 v78, s24, v0
	s_cmp_lg_u32 s6, 0
	v_mad_u64_u32 v[52:53], s[8:9], v51, s92, v[2:3]
	v_mad_u64_u32 v[54:55], s[8:9], v49, s92, v[2:3]
	v_mad_u64_u32 v[56:57], s[8:9], v56, s92, v[2:3]
	v_mad_u64_u32 v[58:59], s[8:9], v58, s92, v[2:3]
	v_mad_u64_u32 v[60:61], s[8:9], v60, s92, v[2:3]
	v_mad_u64_u32 v[62:63], s[8:9], v62, s92, v[2:3]
	v_mad_u64_u32 v[66:67], s[8:9], v66, s92, v[2:3]
	v_mad_u64_u32 v[68:69], s[8:9], v68, s92, v[2:3]
	v_mad_u64_u32 v[70:71], s[8:9], v70, s92, v[2:3]
	v_mad_u64_u32 v[72:73], s[8:9], v72, s92, v[2:3]
	v_mad_u64_u32 v[74:75], s[8:9], v74, s92, v[2:3]
	v_mad_u64_u32 v[76:77], s[8:9], v76, s92, v[2:3]
	v_mad_u64_u32 v[78:79], s[8:9], v78, s92, v[2:3]
	v_mad_u64_u32 v[80:81], s[8:9], v80, s92, v[2:3]
	s_waitcnt vmcnt(0)
	ds_write_b32 v48, v47
	ds_write_b32 v50, v64
	ds_write_b32 v52, v82
	ds_write_b32 v54, v83
	ds_write_b32 v56, v84
	ds_write_b32 v58, v85
	ds_write_b32 v60, v86
	ds_write_b32 v62, v87
	ds_write_b32 v66, v88
	ds_write_b32 v68, v89
	ds_write_b32 v70, v90
	ds_write_b32 v72, v91
	ds_write_b32 v74, v92
	ds_write_b32 v76, v93
	ds_write_b32 v78, v94
	ds_write_b32 v80, v95
	s_cbranch_scc1 .LBB0_681
; #define LAS __attribute__((address_space(3)))
; __device__ __forceinline__ unsigned pk2(float lo, float hi) { f32x2_t v = {lo, hi}; bf16x2_t b = __builtin_convertvector(v, bf16x2_t); return __builtin_bit_cast(unsigned, b); }
; __device__ __forceinline__ int rowmap(int kind, int n) {
;     if (kind == 1) { const int which = n / MIXW, rem = n - which * MIXW, head = rem >> 6, d = rem & 63;
;         const int dd = (which < 2 && head < 18) ? (2 * (d & 31) + (d >> 5)) : d; return which * MIXW + head * 64 + dd; }
;     if (kind == 2) { const int up = n >= DFF, j = up ? n - DFF : n; return (j >> 7) * 256 + up * 128 + (j & 127); }
;     return n;
; __device__ __forceinline__ void transpose_item(const float* W, int K, int N, bf16_t* WT, int ldk, int row_off, int kind, LAS float* scr, int item, int lane) {
;     ...
;     const int c = lane & 7;
; #pragma unroll
;     for (int j = 0; j < 4; ++j) { const int n = (lane >> 3) + 8 * j; const LAS float* s = scr + (8 * c) * 33 + n;
;         u32x4 o; o.x = pk2(s[0 * 33], s[1 * 33]); o.y = pk2(s[2 * 33], s[3 * 33]); o.z = pk2(s[4 * 33], s[5 * 33]); o.w = pk2(s[6 * 33], s[7 * 33]);
;         *(u32x4*)(WT + (size_t)(row_off + rowmap(kind, n0 + n)) * ldk + k0 + 8 * c) = o; }
;     asm volatile("s_waitcnt lgkmcnt(0)" ::: "memory");
	s_waitcnt lgkmcnt(0)
	ds_read_b32 v3, v39
	ds_read_b32 v38, v39 offset:132
	ds_read_b32 v47, v39 offset:264
	ds_read_b32 v49, v39 offset:396
	ds_read_b32 v50, v39 offset:528
	ds_read_b32 v51, v39 offset:660
	ds_read_b32 v52, v39 offset:792
	ds_read_b32 v53, v39 offset:924
	s_waitcnt lgkmcnt(0)
	v_cvt_pk_bf16_f32 v48, v3, v38
	v_or_b32_e32 v3, s4, v17
	s_mov_b32 s8, 0x2aaaaaab
	v_mul_hi_i32 v38, v3, s8
	v_cvt_pk_bf16_f32 v49, v47, v49
	v_lshrrev_b32_e32 v47, 31, v38
	v_lshrrev_b32_e32 v38, 8, v38
	v_add_u32_e32 v38, v38, v47
	s_movk_i32 s7, 0x600
	v_mul_lo_u32 v38, v38, s7
	s_ashr_i32 s1, s0, 31
	v_sub_u32_e32 v47, v3, v38
	s_movk_i32 s5, 0xc00
	s_movk_i32 s6, 0x480
	v_lshl_add_u64 v[36:37], s[0:1], 1, v[18:19]
	v_cmp_gt_i32_e32 vcc, s5, v3
	v_cmp_gt_i32_e64 s[0:1], s6, v47
	v_bfe_u32 v3, v3, 5, 1
	v_cvt_pk_bf16_f32 v50, v50, v51
	v_cvt_pk_bf16_f32 v51, v52, v53
	v_bitop3_b32 v52, s4, 39, v17 bitop3:0xc8
	v_or_b32_e32 v3, v3, v43
	s_and_b64 vcc, vcc, s[0:1]
	v_and_b32_e32 v47, 0xffffffc0, v47
	v_cndmask_b32_e32 v3, v52, v3, vcc
	v_add_u32_e32 v38, v38, v47
	v_or_b32_e32 v52, v38, v3
	v_ashrrev_i32_e32 v53, 31, v52
	v_lshlrev_b64 v[52:53], 11, v[52:53]
	v_lshl_add_u64 v[52:53], v[36:37], 0, v[52:53]
	global_store_dwordx4 v[52:53], v[48:51], off
	ds_read_b32 v3, v39 offset:32
	ds_read_b32 v38, v39 offset:164
	ds_read_b32 v47, v39 offset:296
	ds_read_b32 v49, v39 offset:428
	ds_read_b32 v50, v39 offset:560
	ds_read_b32 v51, v39 offset:692
	ds_read_b32 v52, v39 offset:824
	ds_read_b32 v53, v39 offset:956
	s_waitcnt lgkmcnt(0)
	v_cvt_pk_bf16_f32 v48, v3, v38
	v_or_b32_e32 v3, s4, v40
	v_mul_hi_i32 v38, v3, s8
	v_cvt_pk_bf16_f32 v49, v47, v49
	v_lshrrev_b32_e32 v47, 31, v38
	v_lshrrev_b32_e32 v38, 8, v38
	v_add_u32_e32 v38, v38, v47
	v_mul_lo_u32 v38, v38, s7
	v_sub_u32_e32 v47, v3, v38
	v_cmp_gt_i32_e32 vcc, s5, v3
	v_cmp_gt_i32_e64 s[0:1], s6, v47
	v_bfe_u32 v3, v3, 5, 1
	v_cvt_pk_bf16_f32 v50, v50, v51
	v_cvt_pk_bf16_f32 v51, v52, v53
	v_bitop3_b32 v52, s4, 47, v40 bitop3:0xc8
	v_or_b32_e32 v3, v3, v44
	s_and_b64 vcc, vcc, s[0:1]
	v_and_b32_e32 v47, 0xffffffc0, v47
	v_cndmask_b32_e32 v3, v52, v3, vcc
	v_add_u32_e32 v38, v38, v47
	v_or_b32_e32 v52, v38, v3
	v_ashrrev_i32_e32 v53, 31, v52
	v_lshlrev_b64 v[52:53], 11, v[52:53]
	v_lshl_add_u64 v[52:53], v[36:37], 0, v[52:53]
	global_store_dwordx4 v[52:53], v[48:51], off
	ds_read_b32 v3, v39 offset:64
	ds_read_b32 v38, v39 offset:196
	ds_read_b32 v47, v39 offset:328
	ds_read_b32 v49, v39 offset:460
	ds_read_b32 v50, v39 offset:592
	ds_read_b32 v51, v39 offset:724
	ds_read_b32 v52, v39 offset:856
	ds_read_b32 v53, v39 offset:988
	s_waitcnt lgkmcnt(0)
	v_cvt_pk_bf16_f32 v48, v3, v38
	v_or_b32_e32 v3, s4, v41
	v_mul_hi_i32 v38, v3, s8
	v_cvt_pk_bf16_f32 v49, v47, v49
	v_lshrrev_b32_e32 v47, 31, v38
	v_lshrrev_b32_e32 v38, 8, v38
	v_add_u32_e32 v38, v38, v47
	v_mul_lo_u32 v38, v38, s7
	v_sub_u32_e32 v47, v3, v38
	v_cmp_gt_i32_e32 vcc, s5, v3
	v_cmp_gt_i32_e64 s[0:1], s6, v47
	v_bfe_u32 v3, v3, 5, 1
	v_cvt_pk_bf16_f32 v50, v50, v51
	v_cvt_pk_bf16_f32 v51, v52, v53
	v_bitop3_b32 v52, s4, 55, v41 bitop3:0xc8
	v_or_b32_e32 v3, v3, v45
	s_and_b64 vcc, vcc, s[0:1]
	v_and_b32_e32 v47, 0xffffffc0, v47
	v_cndmask_b32_e32 v3, v52, v3, vcc
	v_add_u32_e32 v38, v38, v47
	v_or_b32_e32 v52, v38, v3
	v_ashrrev_i32_e32 v53, 31, v52
	v_lshlrev_b64 v[52:53], 11, v[52:53]
	v_lshl_add_u64 v[52:53], v[36:37], 0, v[52:53]
	global_store_dwordx4 v[52:53], v[48:51], off
	ds_read_b32 v3, v39 offset:96
	ds_read_b32 v38, v39 offset:228
	ds_read_b32 v47, v39 offset:360
	ds_read_b32 v49, v39 offset:492
	ds_read_b32 v50, v39 offset:624
	ds_read_b32 v51, v39 offset:756
	ds_read_b32 v53, v39 offset:888
	ds_read_b32 v54, v39 offset:1020
	v_or_b32_e32 v48, s4, v42
	v_mul_hi_i32 v52, v48, s8
	v_lshrrev_b32_e32 v55, 31, v52
	v_lshrrev_b32_e32 v52, 8, v52
	v_add_u32_e32 v52, v52, v55
	v_mul_lo_u32 v52, v52, s7
	v_sub_u32_e32 v55, v48, v52
	v_cmp_gt_i32_e32 vcc, s5, v48
	v_cmp_gt_i32_e64 s[0:1], s6, v55
	v_bfe_u32 v48, v48, 5, 1
	v_bitop3_b32 v56, s4, 63, v42 bitop3:0xc8
	v_or_b32_e32 v48, v48, v46
	s_and_b64 vcc, vcc, s[0:1]
	v_and_b32_e32 v55, 0xffffffc0, v55
	v_cndmask_b32_e32 v48, v56, v48, vcc
	v_add_u32_e32 v52, v52, v55
	v_or_b32_e32 v52, v52, v48
	s_waitcnt lgkmcnt(0)
	v_cvt_pk_bf16_f32 v50, v50, v51
	v_cvt_pk_bf16_f32 v51, v53, v54
	v_ashrrev_i32_e32 v53, 31, v52
	v_lshlrev_b64 v[52:53], 11, v[52:53]
	v_cvt_pk_bf16_f32 v48, v3, v38
	v_cvt_pk_bf16_f32 v49, v47, v49
	v_lshl_add_u64 v[36:37], v[36:37], 0, v[52:53]
	global_store_dwordx4 v[36:37], v[48:51], off
	s_waitcnt lgkmcnt(0)
	s_movk_i32 s76, 0xc00
	s_branch .LBB0_638

; __device__ __forceinline__ void convert_weights(const Params& p, unsigned char* ws, int l, LAS unsigned char* lds, int gw, int ngw, int wid, int lane) {
;     ...
;     { unsigned z = 0u; asm volatile("" : "+v"(z));
;       for (int r = gw; r < DM; r += ngw) { if (lane < 16) *(u32x4*)((bf16_t*)(wb + W_A) + (size_t)r * 384 + 256 + lane * 8) = (u32x4){z, z, z, z}; } }
.LBB0_686:
	s_and_saveexec_b64 s[0:1], vcc
	s_cbranch_execz .LBB0_685
	global_store_dwordx4 v[4:5], v[0:3], off
	s_branch .LBB0_685

; __device__ __forceinline__ unsigned pk2(float lo, float hi) { f32x2_t v = {lo, hi}; bf16x2_t b = __builtin_convertvector(v, bf16x2_t); return __builtin_bit_cast(unsigned, b); }
; __device__ __forceinline__ void norm_rows(const float* x, const float* g, const float* modl  , int sh_off, int sc_off, bf16_t* h, int gw, int ngw, int lane) {
;     ...
;     for (int row = gw; row < M; row += ngw) {
;         const f32x4* xr = (const f32x4*)(x + (size_t)row * DM) + lane;
;         f32x4 v[4]; float ss = 0.f;
; #pragma unroll
;         for (int j = 0; j < 4; ++j) { v[j] = xr[64 * j]; ss += (v[j].x * v[j].x + v[j].y * v[j].y) + (v[j].z * v[j].z + v[j].w * v[j].w); }
;         const float rstd = 1.0f / sqrtf(wave_sum(ss) * (1.0f / DM) + NORM_EPS);
;         const float* mb = modl + (size_t)(row >> 11) * 6 * DM;
;         unsigned long long* o8 = (unsigned long long*)(h + (size_t)row * DM) + lane;
; #pragma unroll
;         for (int j = 0; j < 4; ++j) {
;             const f32x4 sc = *((const f32x4*)(mb + sc_off) + lane + 64 * j), sh = *((const f32x4*)(mb + sh_off) + lane + 64 * j);
;             const f32x4 y = v[j] * rstd * gv[j] * (sc + 1.0f) + sh;
;             o8[64 * j] = (unsigned long long)pk2(y.x, y.y) | ((unsigned long long)pk2(y.z, y.w) << 32);
;         }
;     }
.LBB0_691:
	global_load_dwordx4 v[24:27], v[22:23], off offset:-3072
	global_load_dwordx4 v[28:31], v[22:23], off offset:-2048
	global_load_dwordx4 v[32:35], v[22:23], off offset:-1024
	global_load_dwordx4 v[16:19], v[22:23], off
	s_ashr_i32 s0, s2, 11
	s_mul_i32 s0, s0, 6
	s_ashr_i32 s1, s0, 31
	s_lshl_b64 s[0:1], s[0:1], 12
	s_add_u32 s0, s7, s0
	s_addc_u32 s1, s35, s1
	v_lshl_add_u64 v[44:45], s[0:1], 0, v[64:65]
	s_mov_b64 s[0:1], 0x1000
	v_lshl_add_u64 v[46:47], v[44:45], 0, s[0:1]
	s_movk_i32 s0, 0x1000
	v_add_co_u32_e32 v40, vcc, s0, v44
	s_add_i32 s2, s2, s6
	s_nop 0
	v_addc_co_u32_e32 v41, vcc, 0, v45, vcc
	flat_load_dwordx4 v[36:39], v[44:45]
	s_nop 0
	flat_load_dwordx4 v[40:43], v[40:41]
	v_lshl_add_u64 v[22:23], v[22:23], 0, s[8:9]
	s_cmpk_gt_i32 s2, 0x3fff
	s_waitcnt vmcnt(0)
	v_mul_f32_e32 v48, v25, v25
	v_mul_f32_e32 v49, v27, v27
	v_mul_f32_e32 v50, v29, v29
	v_mul_f32_e32 v51, v31, v31
	v_mul_f32_e32 v52, v33, v33
	v_mul_f32_e32 v53, v35, v35
	v_fmac_f32_e32 v48, v24, v24
	v_fmac_f32_e32 v49, v26, v26
	v_fmac_f32_e32 v50, v28, v28
	v_fmac_f32_e32 v51, v30, v30
	v_mul_f32_e32 v54, v17, v17
	v_mul_f32_e32 v55, v19, v19
	v_fmac_f32_e32 v52, v32, v32
	v_fmac_f32_e32 v53, v34, v34
	v_add_f32_e32 v48, v48, v49
	v_add_f32_e32 v49, v50, v51
	v_fmac_f32_e32 v54, v16, v16
	v_fmac_f32_e32 v55, v18, v18
	v_add_f32_e32 v50, v52, v53
	v_add_f32_e32 v48, v48, v49
	v_add_f32_e32 v51, v54, v55
	v_add_f32_e32 v48, v48, v50
	v_add_f32_e32 v48, v48, v51
	ds_swizzle_b32 v49, v48 offset:swizzle(SWAP,1)
	s_waitcnt lgkmcnt(0)
	v_pk_add_f32 v[42:43], v[42:43], 1.0 op_sel_hi:[1,0]
	v_pk_add_f32 v[40:41], v[40:41], 1.0 op_sel_hi:[1,0]
	v_add_f32_e32 v48, v48, v49
	ds_swizzle_b32 v49, v48 offset:swizzle(SWAP,2)
	s_waitcnt lgkmcnt(0)
	v_add_f32_e32 v48, v48, v49
	ds_swizzle_b32 v49, v48 offset:swizzle(SWAP,4)
	s_waitcnt lgkmcnt(0)
	v_add_f32_e32 v48, v48, v49
	ds_swizzle_b32 v49, v48 offset:swizzle(SWAP,8)
	s_waitcnt lgkmcnt(0)
	v_add_f32_e32 v48, v48, v49
	ds_swizzle_b32 v49, v48 offset:swizzle(SWAP,16)
	s_waitcnt lgkmcnt(0)
	v_add_f32_e32 v48, v48, v49
	v_mov_b32_e32 v49, v48
	s_nop 1
	v_permlane32_swap_b32_e32 v48, v49
	v_add_f32_e32 v48, v48, v49
	v_fmamk_f32 v48, v48, 0x3a800000, v242
	v_mul_f32_e32 v49, 0x4f800000, v48
	v_cmp_gt_f32_e32 vcc, s3, v48
	s_nop 1
	v_cndmask_b32_e32 v48, v48, v49, vcc
	v_sqrt_f32_e32 v49, v48
	s_nop 0
	v_add_u32_e32 v50, -1, v49
	v_add_u32_e32 v51, 1, v49
	v_fma_f32 v52, -v50, v49, v48
	v_fma_f32 v53, -v51, v49, v48
	v_cmp_ge_f32_e64 s[0:1], 0, v52
	s_nop 1
	v_cndmask_b32_e64 v49, v49, v50, s[0:1]
	v_cmp_lt_f32_e64 s[0:1], 0, v53
	s_nop 1
	v_cndmask_b32_e64 v49, v49, v51, s[0:1]
	v_mul_f32_e32 v50, 0x37800000, v49
	v_cndmask_b32_e32 v49, v49, v50, vcc
	v_cmp_class_f32_e32 vcc, v48, v245
	s_nop 1
	v_cndmask_b32_e32 v48, v49, v48, vcc
	v_div_scale_f32 v49, s[0:1], v48, v48, 1.0
	v_rcp_f32_e32 v51, v49
	v_div_scale_f32 v50, vcc, 1.0, v48, 1.0
	v_fma_f32 v52, -v49, v51, 1.0
	v_fmac_f32_e32 v51, v52, v51
	v_mul_f32_e32 v52, v50, v51
	v_fma_f32 v53, -v49, v52, v50
	v_fmac_f32_e32 v52, v53, v51
	v_fma_f32 v49, -v49, v52, v50
	v_div_fmas_f32 v49, v49, v51, v52
	v_div_fixup_f32 v48, v49, v48, 1.0
	v_pk_mul_f32 v[26:27], v[26:27], v[48:49] op_sel_hi:[1,0]
	v_pk_mul_f32 v[24:25], v[24:25], v[48:49] op_sel_hi:[1,0]
	v_pk_mul_f32 v[26:27], v[2:3], v[26:27]
	v_pk_mul_f32 v[24:25], v[0:1], v[24:25]
	v_pk_fma_f32 v[26:27], v[42:43], v[26:27], v[38:39]
	v_pk_fma_f32 v[24:25], v[40:41], v[24:25], v[36:37]
	v_pk_mul_f32 v[30:31], v[30:31], v[48:49] op_sel_hi:[1,0]
	v_cvt_pk_bf16_f32 v24, v24, v25
	v_cvt_pk_bf16_f32 v25, v26, v27
	global_store_dwordx2 v[20:21], v[24:25], off
	flat_load_dwordx4 v[24:27], v[46:47] offset:1024
	s_nop 0
	flat_load_dwordx4 v[36:39], v[44:45] offset:1024
	v_pk_mul_f32 v[28:29], v[28:29], v[48:49] op_sel_hi:[1,0]
	v_pk_mul_f32 v[30:31], v[6:7], v[30:31]
	v_pk_mul_f32 v[28:29], v[4:5], v[28:29]
	v_pk_mul_f32 v[34:35], v[34:35], v[48:49] op_sel_hi:[1,0]
	v_pk_mul_f32 v[32:33], v[32:33], v[48:49] op_sel_hi:[1,0]
	v_pk_mul_f32 v[34:35], v[10:11], v[34:35]
	v_pk_mul_f32 v[32:33], v[8:9], v[32:33]
	v_pk_mul_f32 v[18:19], v[18:19], v[48:49] op_sel_hi:[1,0]
	v_pk_mul_f32 v[16:17], v[16:17], v[48:49] op_sel_hi:[1,0]
	v_pk_mul_f32 v[18:19], v[14:15], v[18:19]
	v_pk_mul_f32 v[16:17], v[12:13], v[16:17]
	s_waitcnt vmcnt(0) lgkmcnt(0)
	v_pk_add_f32 v[26:27], v[26:27], 1.0 op_sel_hi:[1,0]
	v_pk_add_f32 v[24:25], v[24:25], 1.0 op_sel_hi:[1,0]
	v_pk_fma_f32 v[26:27], v[26:27], v[30:31], v[38:39]
	v_pk_fma_f32 v[24:25], v[24:25], v[28:29], v[36:37]
	s_nop 0
	v_cvt_pk_bf16_f32 v24, v24, v25
	v_cvt_pk_bf16_f32 v25, v26, v27
	global_store_dwordx2 v[20:21], v[24:25], off offset:512
	flat_load_dwordx4 v[24:27], v[46:47] offset:2048
	s_nop 0
	flat_load_dwordx4 v[28:31], v[44:45] offset:2048
	s_waitcnt vmcnt(0) lgkmcnt(0)
	v_pk_add_f32 v[26:27], v[26:27], 1.0 op_sel_hi:[1,0]
	v_pk_add_f32 v[24:25], v[24:25], 1.0 op_sel_hi:[1,0]
	v_pk_fma_f32 v[26:27], v[26:27], v[34:35], v[30:31]
	v_pk_fma_f32 v[24:25], v[24:25], v[32:33], v[28:29]
	s_nop 0
	v_cvt_pk_bf16_f32 v24, v24, v25
	v_cvt_pk_bf16_f32 v25, v26, v27
	global_store_dwordx2 v[20:21], v[24:25], off offset:1024
	flat_load_dwordx4 v[24:27], v[46:47] offset:3072
	s_nop 0
	flat_load_dwordx4 v[28:31], v[44:45] offset:3072
	s_waitcnt vmcnt(0) lgkmcnt(0)
	v_pk_add_f32 v[26:27], v[26:27], 1.0 op_sel_hi:[1,0]
	v_pk_add_f32 v[24:25], v[24:25], 1.0 op_sel_hi:[1,0]
	v_pk_fma_f32 v[18:19], v[18:19], v[26:27], v[30:31]
	v_pk_fma_f32 v[16:17], v[16:17], v[24:25], v[28:29]
	s_nop 0
	v_cvt_pk_bf16_f32 v16, v16, v17
	v_cvt_pk_bf16_f32 v17, v18, v19
	global_store_dwordx2 v[20:21], v[16:17], off offset:1536
	v_lshl_add_u64 v[20:21], v[20:21], 0, s[4:5]
	s_cbranch_scc0 .LBB0_691

; __device__ __forceinline__ unsigned pk2(float lo, float hi) { f32x2_t v = {lo, hi}; bf16x2_t b = __builtin_convertvector(v, bf16x2_t); return __builtin_bit_cast(unsigned, b); }
; __device__ __forceinline__ float sigmoidf_(float x) { return __builtin_amdgcn_rcpf(1.0f + __expf(-x)); }
;     __device__ __forceinline__ void operator()(const f32x4 (&acc)[2][2][4][2], const Unit& u, int wr, int wc, int fr, int fq) const {
;     ...
;             } else {
;                 const int gcol = col - LDQ;
;                 const f32x4 b0 = *(const f32x4*)(bgate + gcol), b1 = *(const f32x4*)(bgate + gcol + 4);
; #pragma unroll
;                 for (int ai = 0; ai < 2; ++ai)
; #pragma unroll
;                     for (int m = 0; m < 4; ++m) {
;                         const int row = row0 + ai * 128 + m * 16;
;                         const f32x4 v0 = acc[ai][bj][m][0] + b0, v1 = acc[ai][bj][m][1] + b1;
;                         u32x4 w; w.x = pk2(sigmoidf_(v0[0]), sigmoidf_(v0[1])); w.y = pk2(sigmoidf_(v0[2]), sigmoidf_(v0[3]));
;                         w.z = pk2(sigmoidf_(v1[0]), sigmoidf_(v1[1])); w.w = pk2(sigmoidf_(v1[2]), sigmoidf_(v1[3]));
;                         __builtin_nontemporal_store(w, (u32x4*)(gates + (unsigned)(row * NG + gcol)));
;                     }
.LBB0_707:
	s_lshl_b32 s15, s28, 8
	s_cmp_gt_i32 s28, 17
	s_cselect_b64 s[24:25], -1, 0
	v_lshl_add_u32 v228, s46, 8, v201
	v_or_b32_e32 v200, s15, v217
	s_mov_b64 s[2:3], -1
	s_and_b64 vcc, exec, s[24:25]
	s_cbranch_vccz .LBB0_709
	v_add_u32_e32 v138, 0xffffee00, v200
	v_ashrrev_i32_e32 v139, 31, v138
	v_lshl_add_u64 v[134:135], v[138:139], 2, s[6:7]
	global_load_dwordx4 v[130:133], v[134:135], off offset:16
	s_nop 0
	global_load_dwordx4 v[134:137], v[134:135], off
	s_waitcnt vmcnt(0)
	v_pk_add_f32 v[146:147], v[122:123], v[130:131]
	v_pk_add_f32 v[140:141], v[126:127], v[134:135]
	v_pk_add_f32 v[142:143], v[128:129], v[136:137]
	v_mul_f32_e32 v64, 0xbfb8aa3b, v140
	v_mul_f32_e32 v139, 0xbfb8aa3b, v141
	v_exp_f32_e32 v64, v64
	v_exp_f32_e32 v139, v139
	v_pk_add_f32 v[144:145], v[124:125], v[132:133]
	v_add_f32_e32 v64, 1.0, v64
	v_add_f32_e32 v139, 1.0, v139
	v_rcp_f32_e32 v64, v64
	v_rcp_f32_e32 v139, v139
	s_nop 0
	v_cvt_pk_bf16_f32 v140, v64, v139
	v_mul_f32_e32 v64, 0xbfb8aa3b, v142
	v_mul_f32_e32 v139, 0xbfb8aa3b, v143
	v_exp_f32_e32 v64, v64
	v_exp_f32_e32 v139, v139
	v_add_f32_e32 v64, 1.0, v64
	v_add_f32_e32 v139, 1.0, v139
	v_rcp_f32_e32 v64, v64
	v_rcp_f32_e32 v139, v139
	s_nop 0
	v_cvt_pk_bf16_f32 v141, v64, v139
	v_mul_f32_e32 v64, 0xbfb8aa3b, v146
	v_mul_f32_e32 v139, 0xbfb8aa3b, v147
	v_exp_f32_e32 v64, v64
	v_exp_f32_e32 v139, v139
	v_pk_add_f32 v[146:147], v[114:115], v[130:131]
	v_add_f32_e32 v64, 1.0, v64
	v_add_f32_e32 v139, 1.0, v139
	v_rcp_f32_e32 v64, v64
	v_rcp_f32_e32 v139, v139
	s_nop 0
	v_cvt_pk_bf16_f32 v142, v64, v139
	v_mul_f32_e32 v64, 0xbfb8aa3b, v144
	v_mul_f32_e32 v139, 0xbfb8aa3b, v145
	v_exp_f32_e32 v64, v64
	v_exp_f32_e32 v139, v139
	v_add_f32_e32 v64, 1.0, v64
	v_add_f32_e32 v139, 1.0, v139
	v_rcp_f32_e32 v64, v64
	v_rcp_f32_e32 v139, v139
	s_nop 0
	v_cvt_pk_bf16_f32 v143, v64, v139
	v_mad_u64_u32 v[138:139], s[2:3], v228, s76, v[138:139]
	v_mov_b32_e32 v139, v65
	v_lshl_add_u64 v[144:145], v[138:139], 1, s[36:37]
	global_store_dwordx4 v[144:145], v[140:143], off nt
	v_pk_add_f32 v[144:145], v[116:117], v[132:133]
	s_mov_b64 s[2:3], 0
	v_pk_add_f32 v[140:141], v[118:119], v[134:135]
	v_pk_add_f32 v[142:143], v[120:121], v[136:137]
	v_mul_f32_e32 v64, 0xbfb8aa3b, v140
	v_mul_f32_e32 v139, 0xbfb8aa3b, v141
	v_exp_f32_e32 v64, v64
	v_exp_f32_e32 v139, v139
	v_add_f32_e32 v64, 1.0, v64
	v_add_f32_e32 v139, 1.0, v139
	v_rcp_f32_e32 v64, v64
	v_rcp_f32_e32 v139, v139
	s_nop 0
	v_cvt_pk_bf16_f32 v140, v64, v139
	v_mul_f32_e32 v64, 0xbfb8aa3b, v142
	v_mul_f32_e32 v139, 0xbfb8aa3b, v143
	v_exp_f32_e32 v64, v64
	v_exp_f32_e32 v139, v139
	v_add_f32_e32 v64, 1.0, v64
	v_add_f32_e32 v139, 1.0, v139
	v_rcp_f32_e32 v64, v64
	v_rcp_f32_e32 v139, v139
	s_nop 0
	v_cvt_pk_bf16_f32 v141, v64, v139
	v_mul_f32_e32 v64, 0xbfb8aa3b, v146
	v_mul_f32_e32 v139, 0xbfb8aa3b, v147
	v_exp_f32_e32 v64, v64
	v_exp_f32_e32 v139, v139
	v_pk_add_f32 v[146:147], v[110:111], v[134:135]
	v_add_f32_e32 v64, 1.0, v64
	v_add_f32_e32 v139, 1.0, v139
	v_rcp_f32_e32 v64, v64
	v_rcp_f32_e32 v139, v139
	s_nop 0
	v_cvt_pk_bf16_f32 v142, v64, v139
	v_mul_f32_e32 v64, 0xbfb8aa3b, v144
	v_mul_f32_e32 v139, 0xbfb8aa3b, v145
	v_exp_f32_e32 v64, v64
	v_exp_f32_e32 v139, v139
	v_add_f32_e32 v64, 1.0, v64
	v_add_f32_e32 v139, 1.0, v139
	v_rcp_f32_e32 v64, v64
	v_rcp_f32_e32 v139, v139
	s_nop 0
	v_cvt_pk_bf16_f32 v143, v64, v139
	v_add_u32_e32 v64, 0xc000, v138
	v_lshl_add_u64 v[144:145], v[64:65], 1, s[36:37]
	v_mul_f32_e32 v64, 0xbfb8aa3b, v146
	v_mul_f32_e32 v139, 0xbfb8aa3b, v147
	v_exp_f32_e32 v64, v64
	v_exp_f32_e32 v139, v139
	global_store_dwordx4 v[144:145], v[140:143], off nt
	v_pk_add_f32 v[144:145], v[112:113], v[136:137]
	v_add_f32_e32 v64, 1.0, v64
	v_add_f32_e32 v139, 1.0, v139
	v_rcp_f32_e32 v64, v64
	v_rcp_f32_e32 v139, v139
	v_pk_add_f32 v[142:143], v[106:107], v[130:131]
	v_pk_add_f32 v[140:141], v[108:109], v[132:133]
	v_cvt_pk_bf16_f32 v146, v64, v139
	v_mul_f32_e32 v64, 0xbfb8aa3b, v144
	v_mul_f32_e32 v139, 0xbfb8aa3b, v145
	v_exp_f32_e32 v64, v64
	v_exp_f32_e32 v139, v139
	v_pk_add_f32 v[144:145], v[100:101], v[132:133]
	v_add_f32_e32 v64, 1.0, v64
	v_add_f32_e32 v139, 1.0, v139
	v_rcp_f32_e32 v64, v64
	v_rcp_f32_e32 v139, v139
	s_nop 0
	v_cvt_pk_bf16_f32 v147, v64, v139
	v_mul_f32_e32 v64, 0xbfb8aa3b, v142
	v_mul_f32_e32 v139, 0xbfb8aa3b, v143
	v_exp_f32_e32 v64, v64
	v_exp_f32_e32 v139, v139
	v_pk_add_f32 v[142:143], v[104:105], v[136:137]
	v_add_f32_e32 v64, 1.0, v64
	v_add_f32_e32 v139, 1.0, v139
	v_rcp_f32_e32 v64, v64
	v_rcp_f32_e32 v139, v139
	s_nop 0
	v_cvt_pk_bf16_f32 v148, v64, v139
	v_mul_f32_e32 v64, 0xbfb8aa3b, v140
	v_mul_f32_e32 v139, 0xbfb8aa3b, v141
	v_exp_f32_e32 v64, v64
	v_exp_f32_e32 v139, v139
	v_add_f32_e32 v64, 1.0, v64
	v_add_f32_e32 v139, 1.0, v139
	v_rcp_f32_e32 v64, v64
	v_rcp_f32_e32 v139, v139
	s_nop 0
	v_cvt_pk_bf16_f32 v149, v64, v139
	v_add_u32_e32 v64, 0x18000, v138
	v_lshl_add_u64 v[140:141], v[64:65], 1, s[36:37]
	global_store_dwordx4 v[140:141], v[146:149], off nt
	v_pk_add_f32 v[140:141], v[102:103], v[134:135]
	s_nop 0
	v_mul_f32_e32 v64, 0xbfb8aa3b, v140
	v_mul_f32_e32 v139, 0xbfb8aa3b, v141
	v_exp_f32_e32 v64, v64
	v_exp_f32_e32 v139, v139
	v_pk_add_f32 v[146:147], v[98:99], v[130:131]
	v_add_f32_e32 v64, 1.0, v64
	v_add_f32_e32 v139, 1.0, v139
	v_rcp_f32_e32 v64, v64
	v_rcp_f32_e32 v139, v139
	s_nop 0
	v_cvt_pk_bf16_f32 v140, v64, v139
	v_mul_f32_e32 v64, 0xbfb8aa3b, v142
	v_mul_f32_e32 v139, 0xbfb8aa3b, v143
	v_exp_f32_e32 v64, v64
	v_exp_f32_e32 v139, v139
	v_add_f32_e32 v64, 1.0, v64
	v_add_f32_e32 v139, 1.0, v139
	v_rcp_f32_e32 v64, v64
	v_rcp_f32_e32 v139, v139
	s_nop 0
; __device__ __forceinline__ unsigned pk2(float lo, float hi) { f32x2_t v = {lo, hi}; bf16x2_t b = __builtin_convertvector(v, bf16x2_t); return __builtin_bit_cast(unsigned, b); }
; __device__ __forceinline__ float sigmoidf_(float x) { return __builtin_amdgcn_rcpf(1.0f + __expf(-x)); }
;     __device__ __forceinline__ void operator()(const f32x4 (&acc)[2][2][4][2], const Unit& u, int wr, int wc, int fr, int fq) const {
;     ...
;             } else {
;                 const int gcol = col - LDQ;
;                 const f32x4 b0 = *(const f32x4*)(bgate + gcol), b1 = *(const f32x4*)(bgate + gcol + 4);
; #pragma unroll
;                 for (int ai = 0; ai < 2; ++ai)
; #pragma unroll
;                     for (int m = 0; m < 4; ++m) {
;                         const int row = row0 + ai * 128 + m * 16;
;                         const f32x4 v0 = acc[ai][bj][m][0] + b0, v1 = acc[ai][bj][m][1] + b1;
;                         u32x4 w; w.x = pk2(sigmoidf_(v0[0]), sigmoidf_(v0[1])); w.y = pk2(sigmoidf_(v0[2]), sigmoidf_(v0[3]));
;                         w.z = pk2(sigmoidf_(v1[0]), sigmoidf_(v1[1])); w.w = pk2(sigmoidf_(v1[2]), sigmoidf_(v1[3]));
;                         __builtin_nontemporal_store(w, (u32x4*)(gates + (unsigned)(row * NG + gcol)));
;                     }
	v_cvt_pk_bf16_f32 v141, v64, v139
	v_mul_f32_e32 v64, 0xbfb8aa3b, v146
	v_mul_f32_e32 v139, 0xbfb8aa3b, v147
	v_exp_f32_e32 v64, v64
	v_exp_f32_e32 v139, v139
	v_pk_add_f32 v[146:147], v[90:91], v[130:131]
	v_add_f32_e32 v64, 1.0, v64
	v_add_f32_e32 v139, 1.0, v139
	v_rcp_f32_e32 v64, v64
	v_rcp_f32_e32 v139, v139
	s_nop 0
	v_cvt_pk_bf16_f32 v142, v64, v139
	v_mul_f32_e32 v64, 0xbfb8aa3b, v144
	v_mul_f32_e32 v139, 0xbfb8aa3b, v145
	v_exp_f32_e32 v64, v64
	v_exp_f32_e32 v139, v139
	v_add_f32_e32 v64, 1.0, v64
	v_add_f32_e32 v139, 1.0, v139
	v_rcp_f32_e32 v64, v64
	v_rcp_f32_e32 v139, v139
	s_nop 0
	v_cvt_pk_bf16_f32 v143, v64, v139
	v_add_u32_e32 v64, 0x24000, v138
	v_lshl_add_u64 v[144:145], v[64:65], 1, s[36:37]
	global_store_dwordx4 v[144:145], v[140:143], off nt
	v_pk_add_f32 v[144:145], v[92:93], v[132:133]
	s_nop 0
	v_pk_add_f32 v[140:141], v[94:95], v[134:135]
	v_pk_add_f32 v[142:143], v[96:97], v[136:137]
	v_mul_f32_e32 v64, 0xbfb8aa3b, v140
	v_mul_f32_e32 v139, 0xbfb8aa3b, v141
	v_exp_f32_e32 v64, v64
	v_exp_f32_e32 v139, v139
	v_add_f32_e32 v64, 1.0, v64
	v_add_f32_e32 v139, 1.0, v139
	v_rcp_f32_e32 v64, v64
	v_rcp_f32_e32 v139, v139
	s_nop 0
	v_cvt_pk_bf16_f32 v140, v64, v139
	v_mul_f32_e32 v64, 0xbfb8aa3b, v142
	v_mul_f32_e32 v139, 0xbfb8aa3b, v143
	v_exp_f32_e32 v64, v64
	v_exp_f32_e32 v139, v139
	v_add_f32_e32 v64, 1.0, v64
	v_add_f32_e32 v139, 1.0, v139
	v_rcp_f32_e32 v64, v64
	v_rcp_f32_e32 v139, v139
	s_nop 0
	v_cvt_pk_bf16_f32 v141, v64, v139
	v_mul_f32_e32 v64, 0xbfb8aa3b, v146
	v_mul_f32_e32 v139, 0xbfb8aa3b, v147
	v_exp_f32_e32 v64, v64
	v_exp_f32_e32 v139, v139
	v_pk_add_f32 v[146:147], v[82:83], v[130:131]
	v_add_f32_e32 v64, 1.0, v64
	v_add_f32_e32 v139, 1.0, v139
	v_rcp_f32_e32 v64, v64
	v_rcp_f32_e32 v139, v139
	s_nop 0
	v_cvt_pk_bf16_f32 v142, v64, v139
	v_mul_f32_e32 v64, 0xbfb8aa3b, v144
	v_mul_f32_e32 v139, 0xbfb8aa3b, v145
	v_exp_f32_e32 v64, v64
	v_exp_f32_e32 v139, v139
	v_add_f32_e32 v64, 1.0, v64
	v_add_f32_e32 v139, 1.0, v139
	v_rcp_f32_e32 v64, v64
	v_rcp_f32_e32 v139, v139
	s_nop 0
	v_cvt_pk_bf16_f32 v143, v64, v139
	v_add_u32_e32 v64, 0x60000, v138
	v_lshl_add_u64 v[144:145], v[64:65], 1, s[36:37]
	global_store_dwordx4 v[144:145], v[140:143], off nt
	v_pk_add_f32 v[144:145], v[84:85], v[132:133]
	s_nop 0
	v_pk_add_f32 v[140:141], v[86:87], v[134:135]
	v_pk_add_f32 v[142:143], v[88:89], v[136:137]
	v_mul_f32_e32 v64, 0xbfb8aa3b, v140
	v_mul_f32_e32 v139, 0xbfb8aa3b, v141
	v_exp_f32_e32 v64, v64
	v_exp_f32_e32 v139, v139
	v_add_f32_e32 v64, 1.0, v64
	v_add_f32_e32 v139, 1.0, v139
	v_rcp_f32_e32 v64, v64
	v_rcp_f32_e32 v139, v139
	s_nop 0
	v_cvt_pk_bf16_f32 v140, v64, v139
	v_mul_f32_e32 v64, 0xbfb8aa3b, v142
	v_mul_f32_e32 v139, 0xbfb8aa3b, v143
	v_exp_f32_e32 v64, v64
	v_exp_f32_e32 v139, v139
	v_add_f32_e32 v64, 1.0, v64
	v_add_f32_e32 v139, 1.0, v139
	v_rcp_f32_e32 v64, v64
	v_rcp_f32_e32 v139, v139
	s_nop 0
	v_cvt_pk_bf16_f32 v141, v64, v139
	v_mul_f32_e32 v64, 0xbfb8aa3b, v146
	v_mul_f32_e32 v139, 0xbfb8aa3b, v147
	v_exp_f32_e32 v64, v64
	v_exp_f32_e32 v139, v139
	v_pk_add_f32 v[146:147], v[74:75], v[130:131]
	v_add_f32_e32 v64, 1.0, v64
	v_add_f32_e32 v139, 1.0, v139
	v_rcp_f32_e32 v64, v64
	v_rcp_f32_e32 v139, v139
	s_nop 0
	v_cvt_pk_bf16_f32 v142, v64, v139
	v_mul_f32_e32 v64, 0xbfb8aa3b, v144
	v_mul_f32_e32 v139, 0xbfb8aa3b, v145
	v_exp_f32_e32 v64, v64
	v_exp_f32_e32 v139, v139
	v_add_f32_e32 v64, 1.0, v64
	v_add_f32_e32 v139, 1.0, v139
	v_rcp_f32_e32 v64, v64
	v_rcp_f32_e32 v139, v139
	s_nop 0
	v_cvt_pk_bf16_f32 v143, v64, v139
	v_add_u32_e32 v64, 0x6c000, v138
	v_lshl_add_u64 v[144:145], v[64:65], 1, s[36:37]
	global_store_dwordx4 v[144:145], v[140:143], off nt
	v_pk_add_f32 v[144:145], v[76:77], v[132:133]
	s_nop 0
	v_pk_add_f32 v[140:141], v[78:79], v[134:135]
	v_pk_add_f32 v[142:143], v[80:81], v[136:137]
	v_mul_f32_e32 v64, 0xbfb8aa3b, v140
	v_mul_f32_e32 v139, 0xbfb8aa3b, v141
	v_exp_f32_e32 v64, v64
	v_exp_f32_e32 v139, v139
	v_pk_add_f32 v[134:135], v[70:71], v[134:135]
	v_pk_add_f32 v[136:137], v[72:73], v[136:137]
	v_add_f32_e32 v64, 1.0, v64
	v_add_f32_e32 v139, 1.0, v139
	v_rcp_f32_e32 v64, v64
	v_rcp_f32_e32 v139, v139
	s_nop 0
	v_cvt_pk_bf16_f32 v140, v64, v139
	v_mul_f32_e32 v64, 0xbfb8aa3b, v142
	v_mul_f32_e32 v139, 0xbfb8aa3b, v143
	v_exp_f32_e32 v64, v64
	v_exp_f32_e32 v139, v139
	v_add_f32_e32 v64, 1.0, v64
	v_add_f32_e32 v139, 1.0, v139
	v_rcp_f32_e32 v64, v64
	v_rcp_f32_e32 v139, v139
	s_nop 0
	v_cvt_pk_bf16_f32 v141, v64, v139
	v_mul_f32_e32 v64, 0xbfb8aa3b, v146
	v_mul_f32_e32 v139, 0xbfb8aa3b, v147
	v_exp_f32_e32 v64, v64
	v_exp_f32_e32 v139, v139
	v_add_f32_e32 v64, 1.0, v64
	v_add_f32_e32 v139, 1.0, v139
	v_rcp_f32_e32 v64, v64
	v_rcp_f32_e32 v139, v139
	s_nop 0
	v_cvt_pk_bf16_f32 v142, v64, v139
	v_mul_f32_e32 v64, 0xbfb8aa3b, v144
	v_mul_f32_e32 v139, 0xbfb8aa3b, v145
	v_exp_f32_e32 v64, v64
	v_exp_f32_e32 v139, v139
	v_add_f32_e32 v64, 1.0, v64
	v_add_f32_e32 v139, 1.0, v139
	v_rcp_f32_e32 v64, v64
	v_rcp_f32_e32 v139, v139
	s_nop 0
	v_cvt_pk_bf16_f32 v143, v64, v139
	v_add_u32_e32 v64, 0x78000, v138
	v_lshl_add_u64 v[144:145], v[64:65], 1, s[36:37]
	global_store_dwordx4 v[144:145], v[140:143], off nt
	v_mul_f32_e32 v64, 0xbfb8aa3b, v134
	v_exp_f32_e32 v64, v64
	v_pk_add_f32 v[140:141], v[68:69], v[132:133]
	v_pk_add_f32 v[132:133], v[66:67], v[130:131]
	v_mul_f32_e32 v130, 0xbfb8aa3b, v135
	v_exp_f32_e32 v130, v130
	v_add_f32_e32 v64, 1.0, v64
	v_rcp_f32_e32 v64, v64
	v_mul_f32_e32 v131, 0xbfb8aa3b, v137
	v_add_f32_e32 v130, 1.0, v130
	v_rcp_f32_e32 v130, v130
	v_exp_f32_e32 v131, v131
	v_cvt_pk_bf16_f32 v130, v64, v130
	v_mul_f32_e32 v64, 0xbfb8aa3b, v136
	v_exp_f32_e32 v64, v64
	v_add_f32_e32 v131, 1.0, v131
	v_rcp_f32_e32 v131, v131
	v_add_f32_e32 v64, 1.0, v64
	v_rcp_f32_e32 v64, v64
	s_nop 0
	v_cvt_pk_bf16_f32 v131, v64, v131
	v_mul_f32_e32 v64, 0xbfb8aa3b, v132
	v_mul_f32_e32 v132, 0xbfb8aa3b, v133
	v_exp_f32_e32 v64, v64
	v_exp_f32_e32 v132, v132
	v_mul_f32_e32 v133, 0xbfb8aa3b, v141
	v_exp_f32_e32 v133, v133
	v_add_f32_e32 v64, 1.0, v64
	v_add_f32_e32 v132, 1.0, v132
	v_rcp_f32_e32 v64, v64
	v_rcp_f32_e32 v132, v132
	v_add_f32_e32 v133, 1.0, v133
	v_rcp_f32_e32 v133, v133
	v_cvt_pk_bf16_f32 v132, v64, v132
	v_mul_f32_e32 v64, 0xbfb8aa3b, v140
	v_exp_f32_e32 v64, v64
	s_nop 0
	v_add_f32_e32 v64, 1.0, v64
	v_rcp_f32_e32 v64, v64
	s_nop 0
	v_cvt_pk_bf16_f32 v133, v64, v133
	v_add_u32_e32 v64, 0x84000, v138
	v_lshl_add_u64 v[134:135], v[64:65], 1, s[36:37]
	global_store_dwordx4 v[134:135], v[130:133], off nt
; __device__ __forceinline__ unsigned pk2(float lo, float hi) { f32x2_t v = {lo, hi}; bf16x2_t b = __builtin_convertvector(v, bf16x2_t); return __builtin_bit_cast(unsigned, b); }
;     __device__ __forceinline__ void operator()(const f32x4 (&acc)[2][2][4][2], const Unit& u, int wr, int wc, int fr, int fq) const {
;     ...
;             if (u.pn < 18) {
;                 const int which = col / MIXW, rem = col - which * MIXW, head = rem >> 6, dc = rem & 63;
;                 const bool rope = (which < 2) && (head < 18);
;                 const bool ksum_on = (which == 1) && (head >= 12) && (head < 18);
;                 const float sc = (which == 0) ? 0.125f * 1.4426950408889634f : 1.0f;
;     ...
;                 } else {
; #pragma unroll
;                     for (int i = 0; i < 8; ++i) {
;                         const int ai = i >> 2, m = i & 3, row = row0 + ai * 128 + m * 16;
;                         const f32x4 v0 = acc[ai][bj][m][0] * sc, v1 = acc[ai][bj][m][1] * sc;
;                         u32x4 w; w.x = pk2(v0[0], v0[1]); w.y = pk2(v0[2], v0[3]); w.z = pk2(v1[0], v1[1]); w.w = pk2(v1[2], v1[3]);
;                         __builtin_nontemporal_store(w, (u32x4*)(qkv + (unsigned)(row * LDQ + col)));
;                     }
.LBB0_709:
	s_andn2_b64 vcc, exec, s[2:3]
	s_cbranch_vccnz .LBB0_734
	s_mov_b32 s2, 0x2aaaaaab
	v_mul_hi_i32 v64, v200, s2
	v_lshrrev_b32_e32 v130, 31, v64
	v_lshrrev_b32_e32 v64, 8, v64
	v_add_u32_e32 v64, v64, v130
	s_movk_i32 s2, 0x600
	v_mul_lo_u32 v64, v64, s2
	v_sub_u32_e32 v64, v200, v64
	v_ashrrev_i32_e32 v64, 6, v64
	s_movk_i32 s17, 0xbff
	v_cmp_lt_i32_e32 vcc, s17, v200
	v_cmp_lt_i32_e64 s[2:3], 17, v64
	v_add_u32_e32 v130, 0x5ff, v200
	s_or_b64 s[2:3], vcc, s[2:3]
	v_cmp_gt_u32_e32 vcc, s17, v130
	v_mov_b32_e32 v130, 0x3e38aa3b
	s_nop 0
	v_cndmask_b32_e32 v214, 1.0, v130, vcc
	s_and_saveexec_b64 s[26:27], s[2:3]
	s_xor_b64 s[2:3], exec, s[26:27]
	s_cbranch_execz .LBB0_712
	v_pk_mul_f32 v[132:133], v[214:215], v[128:129] op_sel_hi:[0,1]
	v_pk_mul_f32 v[130:131], v[214:215], v[126:127] op_sel_hi:[0,1]
	v_pk_mul_f32 v[134:135], v[214:215], v[124:125] op_sel_hi:[0,1]
	s_movk_i32 s17, 0x1200
	v_cvt_pk_bf16_f32 v130, v130, v131
	v_cvt_pk_bf16_f32 v131, v132, v133
	v_cvt_pk_bf16_f32 v133, v134, v135
	v_mad_u64_u32 v[134:135], s[26:27], v228, s17, v[200:201]
	v_pk_mul_f32 v[136:137], v[214:215], v[122:123] op_sel_hi:[0,1]
	v_mov_b32_e32 v135, v65
	v_cvt_pk_bf16_f32 v132, v136, v137
	v_lshl_add_u64 v[136:137], v[134:135], 1, s[84:85]
	global_store_dwordx4 v[136:137], v[130:133], off nt
	v_pk_mul_f32 v[136:137], v[214:215], v[116:117] op_sel_hi:[0,1]
	v_pk_mul_f32 v[138:139], v[214:215], v[114:115] op_sel_hi:[0,1]
	v_pk_mul_f32 v[132:133], v[214:215], v[120:121] op_sel_hi:[0,1]
	v_pk_mul_f32 v[130:131], v[214:215], v[118:119] op_sel_hi:[0,1]
	v_add_u32_e32 v64, 0x12000, v134
	v_cvt_pk_bf16_f32 v130, v130, v131
	v_cvt_pk_bf16_f32 v131, v132, v133
	v_cvt_pk_bf16_f32 v132, v138, v139
	v_cvt_pk_bf16_f32 v133, v136, v137
	v_lshl_add_u64 v[136:137], v[64:65], 1, s[84:85]
	global_store_dwordx4 v[136:137], v[130:133], off nt
	v_pk_mul_f32 v[136:137], v[214:215], v[108:109] op_sel_hi:[0,1]
	v_pk_mul_f32 v[138:139], v[214:215], v[106:107] op_sel_hi:[0,1]
	v_pk_mul_f32 v[132:133], v[214:215], v[112:113] op_sel_hi:[0,1]
	v_pk_mul_f32 v[130:131], v[214:215], v[110:111] op_sel_hi:[0,1]
	v_add_u32_e32 v64, 0x24000, v134
	v_cvt_pk_bf16_f32 v130, v130, v131
	v_cvt_pk_bf16_f32 v131, v132, v133
	v_cvt_pk_bf16_f32 v132, v138, v139
	v_cvt_pk_bf16_f32 v133, v136, v137
	v_lshl_add_u64 v[136:137], v[64:65], 1, s[84:85]
	global_store_dwordx4 v[136:137], v[130:133], off nt
	v_pk_mul_f32 v[136:137], v[214:215], v[100:101] op_sel_hi:[0,1]
	v_pk_mul_f32 v[138:139], v[214:215], v[98:99] op_sel_hi:[0,1]
	v_pk_mul_f32 v[132:133], v[214:215], v[104:105] op_sel_hi:[0,1]
	v_pk_mul_f32 v[130:131], v[214:215], v[102:103] op_sel_hi:[0,1]
	v_add_u32_e32 v64, 0x36000, v134
	v_cvt_pk_bf16_f32 v130, v130, v131
	v_cvt_pk_bf16_f32 v131, v132, v133
	v_cvt_pk_bf16_f32 v132, v138, v139
	v_cvt_pk_bf16_f32 v133, v136, v137
	v_lshl_add_u64 v[136:137], v[64:65], 1, s[84:85]
	global_store_dwordx4 v[136:137], v[130:133], off nt
	v_pk_mul_f32 v[136:137], v[214:215], v[92:93] op_sel_hi:[0,1]
	v_pk_mul_f32 v[138:139], v[214:215], v[90:91] op_sel_hi:[0,1]
	v_pk_mul_f32 v[132:133], v[214:215], v[96:97] op_sel_hi:[0,1]
	v_pk_mul_f32 v[130:131], v[214:215], v[94:95] op_sel_hi:[0,1]
	v_add_u32_e32 v64, 0x90000, v134
	v_cvt_pk_bf16_f32 v130, v130, v131
	v_cvt_pk_bf16_f32 v131, v132, v133
	v_cvt_pk_bf16_f32 v132, v138, v139
	v_cvt_pk_bf16_f32 v133, v136, v137
	v_lshl_add_u64 v[136:137], v[64:65], 1, s[84:85]
	global_store_dwordx4 v[136:137], v[130:133], off nt
	v_pk_mul_f32 v[136:137], v[214:215], v[84:85] op_sel_hi:[0,1]
	v_pk_mul_f32 v[138:139], v[214:215], v[82:83] op_sel_hi:[0,1]
	v_pk_mul_f32 v[132:133], v[214:215], v[88:89] op_sel_hi:[0,1]
	v_pk_mul_f32 v[130:131], v[214:215], v[86:87] op_sel_hi:[0,1]
	v_add_u32_e32 v64, 0xa2000, v134
	v_cvt_pk_bf16_f32 v130, v130, v131
	v_cvt_pk_bf16_f32 v131, v132, v133
	v_cvt_pk_bf16_f32 v132, v138, v139
	v_cvt_pk_bf16_f32 v133, v136, v137
	v_lshl_add_u64 v[136:137], v[64:65], 1, s[84:85]
	global_store_dwordx4 v[136:137], v[130:133], off nt
	v_pk_mul_f32 v[136:137], v[214:215], v[76:77] op_sel_hi:[0,1]
	v_pk_mul_f32 v[138:139], v[214:215], v[74:75] op_sel_hi:[0,1]
	v_pk_mul_f32 v[132:133], v[214:215], v[80:81] op_sel_hi:[0,1]
	v_pk_mul_f32 v[130:131], v[214:215], v[78:79] op_sel_hi:[0,1]
	v_add_u32_e32 v64, 0xb4000, v134
	v_cvt_pk_bf16_f32 v130, v130, v131
	v_cvt_pk_bf16_f32 v131, v132, v133
	v_cvt_pk_bf16_f32 v132, v138, v139
	v_cvt_pk_bf16_f32 v133, v136, v137
	v_lshl_add_u64 v[136:137], v[64:65], 1, s[84:85]
	global_store_dwordx4 v[136:137], v[130:133], off nt
	v_pk_mul_f32 v[136:137], v[214:215], v[68:69] op_sel_hi:[0,1]
	v_pk_mul_f32 v[138:139], v[214:215], v[66:67] op_sel_hi:[0,1]
	v_pk_mul_f32 v[132:133], v[214:215], v[72:73] op_sel_hi:[0,1]
	v_pk_mul_f32 v[130:131], v[214:215], v[70:71] op_sel_hi:[0,1]
	v_add_u32_e32 v64, 0xc6000, v134
	v_cvt_pk_bf16_f32 v130, v130, v131
	v_cvt_pk_bf16_f32 v131, v132, v133
	v_cvt_pk_bf16_f32 v132, v138, v139
	v_cvt_pk_bf16_f32 v133, v136, v137
	v_lshl_add_u64 v[134:135], v[64:65], 1, s[84:85]
	global_store_dwordx4 v[134:135], v[130:133], off nt
; __device__ __forceinline__ unsigned pk2(float lo, float hi) { f32x2_t v = {lo, hi}; bf16x2_t b = __builtin_convertvector(v, bf16x2_t); return __builtin_bit_cast(unsigned, b); }
;     __device__ __forceinline__ void operator()(const f32x4 (&acc)[2][2][4][2], const Unit& u, int wr, int wc, int fr, int fq) const {
;     ...
;                 if (rope) {
;                     f32x4 c4[8], s4[8];
; #pragma unroll
;                     for (int i = 0; i < 8; ++i) { const int pos = (row0 + (i >> 2) * 128 + (i & 3) * 16) & (SEQ - 1);
;                         c4[i] = *(const f32x4*)(cosT + (unsigned)(pos * 32 + (dc >> 1))); s4[i] = *(const f32x4*)(sinT + (unsigned)(pos * 32 + (dc >> 1))); }
;                     float ks[8];
; #pragma unroll
;                     for (int j = 0; j < 8; ++j) ks[j] = 0.f;
; #pragma unroll
;                     for (int i = 0; i < 8; ++i) {
;                         const int ai = i >> 2, m = i & 3, row = row0 + ai * 128 + m * 16;
;                         const f32x4 v0 = acc[ai][bj][m][0], v1 = acc[ai][bj][m][1];
;                         float r[8];
;                         r[0] = v0[0] * c4[i][0] - v0[1] * s4[i][0]; r[1] = v0[0] * s4[i][0] + v0[1] * c4[i][0];
;                         r[2] = v0[2] * c4[i][1] - v0[3] * s4[i][1]; r[3] = v0[2] * s4[i][1] + v0[3] * c4[i][1];
;                         r[4] = v1[0] * c4[i][2] - v1[1] * s4[i][2]; r[5] = v1[0] * s4[i][2] + v1[1] * c4[i][2];
;                         r[6] = v1[2] * c4[i][3] - v1[3] * s4[i][3]; r[7] = v1[2] * s4[i][3] + v1[3] * c4[i][3];
;                         if (ksum_on) {
; #pragma unroll
;                             for (int j = 0; j < 8; ++j) ks[j] += r[j];
;                         }
;                         u32x4 w; w.x = pk2(r[0] * sc, r[1] * sc); w.y = pk2(r[2] * sc, r[3] * sc); w.z = pk2(r[4] * sc, r[5] * sc); w.w = pk2(r[6] * sc, r[7] * sc);
;                         __builtin_nontemporal_store(w, (u32x4*)(qkv + (unsigned)(row * LDQ + col)));
.LBB0_712:
	s_andn2_saveexec_b64 s[2:3], s[2:3]
	s_cbranch_execz .LBB0_733
	s_add_i32 s17, s15, 0xfffffa00
	s_cmpk_lt_u32 s17, 0x600
	v_lshlrev_b32_e32 v134, 5, v228
	s_mov_b32 s17, 0xf9e0
	v_add_u32_e32 v216, -12, v64
	v_and_or_b32 v64, v134, s17, v226
	v_lshlrev_b32_e32 v64, 2, v64
	v_lshl_add_u64 v[130:131], s[8:9], 0, v[64:65]
	flat_load_dwordx4 v[222:225], v[130:131]
	v_lshl_add_u64 v[130:131], s[10:11], 0, v[64:65]
	flat_load_dwordx4 v[248:251], v[130:131]
	v_or_b32_e32 v130, 0x800, v64
	v_mov_b32_e32 v131, v65
	v_lshl_add_u64 v[132:133], s[8:9], 0, v[130:131]
	v_lshl_add_u64 v[130:131], s[10:11], 0, v[130:131]
	flat_load_dwordx4 v[178:181], v[132:133]
	flat_load_dwordx4 v[182:185], v[130:131]
	v_or_b32_e32 v130, 0x1000, v64
	v_mov_b32_e32 v131, v65
	v_lshl_add_u64 v[132:133], s[8:9], 0, v[130:131]
	v_lshl_add_u64 v[130:131], s[10:11], 0, v[130:131]
	v_or_b32_e32 v64, 0x1800, v64
	flat_load_dwordx4 v[170:173], v[132:133]
	flat_load_dwordx4 v[174:177], v[130:131]
	v_lshl_add_u64 v[130:131], s[8:9], 0, v[64:65]
	flat_load_dwordx4 v[162:165], v[130:131]
	v_lshl_add_u64 v[130:131], s[10:11], 0, v[64:65]
	v_add_u32_e32 v64, 0x1000, v134
	v_and_or_b32 v64, v64, s17, v226
	v_lshlrev_b32_e32 v64, 2, v64
	flat_load_dwordx4 v[166:169], v[130:131]
	v_lshl_add_u64 v[130:131], s[8:9], 0, v[64:65]
	flat_load_dwordx4 v[154:157], v[130:131]
	v_lshl_add_u64 v[130:131], s[10:11], 0, v[64:65]
	flat_load_dwordx4 v[158:161], v[130:131]
	v_or_b32_e32 v130, 0x800, v64
	v_mov_b32_e32 v131, v65
	v_lshl_add_u64 v[132:133], s[8:9], 0, v[130:131]
	v_lshl_add_u64 v[130:131], s[10:11], 0, v[130:131]
	flat_load_dwordx4 v[146:149], v[132:133]
	flat_load_dwordx4 v[150:153], v[130:131]
	v_or_b32_e32 v130, 0x1000, v64
	v_mov_b32_e32 v131, v65
	v_lshl_add_u64 v[132:133], s[8:9], 0, v[130:131]
	v_lshl_add_u64 v[130:131], s[10:11], 0, v[130:131]
	v_or_b32_e32 v64, 0x1800, v64
	flat_load_dwordx4 v[138:141], v[132:133]
	flat_load_dwordx4 v[142:145], v[130:131]
	v_lshl_add_u64 v[130:131], s[8:9], 0, v[64:65]
	v_lshl_add_u64 v[134:135], s[10:11], 0, v[64:65]
	flat_load_dwordx4 v[130:133], v[130:131]
	s_cselect_b64 s[26:27], -1, 0
	flat_load_dwordx4 v[134:137], v[134:135]
	v_cmp_gt_u32_e32 vcc, 6, v216
	s_and_b64 s[26:27], s[26:27], vcc
	s_waitcnt vmcnt(0) lgkmcnt(0)
	v_pk_mul_f32 v[202:203], v[126:127], v[248:249] op_sel_hi:[1,0]
	s_nop 0
	v_pk_fma_f32 v[218:219], v[126:127], v[222:223], v[202:203] op_sel:[1,0,0] op_sel_hi:[0,1,1]
	v_pk_fma_f32 v[126:127], v[126:127], v[222:223], v[202:203] op_sel:[1,0,0] op_sel_hi:[0,0,1] neg_lo:[0,0,1] neg_hi:[0,0,1]
	v_mov_b32_e32 v219, v127
	v_pk_mul_f32 v[126:127], v[128:129], v[248:249] op_sel:[0,1]
	v_mov_b32_e32 v64, v251
	v_pk_fma_f32 v[220:221], v[128:129], v[222:223], v[126:127] op_sel:[1,1,0] op_sel_hi:[0,1,1]
	v_pk_fma_f32 v[126:127], v[128:129], v[222:223], v[126:127] op_sel:[1,1,0] op_sel_hi:[0,1,1] neg_lo:[0,0,1] neg_hi:[0,0,1]
	v_mov_b32_e32 v221, v127
	v_pk_mul_f32 v[126:127], v[122:123], v[250:251] op_sel_hi:[1,0]
	s_nop 0
	v_pk_fma_f32 v[222:223], v[122:123], v[224:225], v[126:127] op_sel:[1,0,0] op_sel_hi:[0,1,1]
	v_pk_fma_f32 v[122:123], v[122:123], v[224:225], v[126:127] op_sel:[1,0,0] op_sel_hi:[0,0,1] neg_lo:[0,0,1] neg_hi:[0,0,1]
	v_mov_b32_e32 v223, v123
	v_pk_mul_f32 v[122:123], v[124:125], v[64:65] op_sel_hi:[1,0]
	v_mov_b32_e32 v64, v225
	v_pk_fma_f32 v[224:225], v[124:125], v[64:65], v[122:123] op_sel:[1,0,0] op_sel_hi:[0,0,1]
	v_pk_fma_f32 v[122:123], v[124:125], v[64:65], v[122:123] op_sel:[1,0,0] op_sel_hi:[0,0,1] neg_lo:[0,0,1] neg_hi:[0,0,1]
	v_mov_b32_e32 v64, v65
	v_mov_b32_e32 v225, v123
	v_mov_b64_e32 v[126:127], v[64:65]
	v_mov_b64_e32 v[124:125], v[64:65]
	v_mov_b64_e32 v[122:123], v[64:65]
	v_mov_b64_e32 v[128:129], v[64:65]
	s_and_saveexec_b64 s[28:29], s[26:27]
	v_pk_add_f32 v[126:127], v[218:219], 0 op_sel_hi:[1,0]
	v_pk_add_f32 v[124:125], v[220:221], 0 op_sel_hi:[1,0]
	v_pk_add_f32 v[122:123], v[222:223], 0 op_sel_hi:[1,0]
	v_pk_add_f32 v[128:129], v[224:225], 0 op_sel_hi:[1,0]
	s_or_b64 exec, exec, s[28:29]
	v_pk_mul_f32 v[202:203], v[214:215], v[218:219] op_sel_hi:[0,1]
	v_pk_mov_b32 v[202:203], v[202:203], v[202:203] op_sel:[1,0]
	s_movk_i32 s17, 0x1200
	v_cvt_pk_bf16_f32 v218, v202, v203
	v_pk_mul_f32 v[202:203], v[214:215], v[220:221] op_sel_hi:[0,1]
	v_pk_mov_b32 v[202:203], v[202:203], v[202:203] op_sel:[1,0]
	s_nop 0
	v_cvt_pk_bf16_f32 v219, v202, v203
	v_pk_mul_f32 v[202:203], v[214:215], v[222:223] op_sel_hi:[0,1]
	v_pk_mov_b32 v[202:203], v[202:203], v[202:203] op_sel:[1,0]
	v_mul_lo_u32 v222, v228, s17
	v_cvt_pk_bf16_f32 v220, v202, v203
	v_pk_mul_f32 v[202:203], v[214:215], v[224:225] op_sel_hi:[0,1]
	v_pk_mov_b32 v[202:203], v[202:203], v[202:203] op_sel:[1,0]
	v_add_u32_e32 v64, v222, v200
	v_cvt_pk_bf16_f32 v221, v202, v203
	v_lshl_add_u64 v[202:203], v[64:65], 1, s[84:85]
	global_store_dwordx4 v[202:203], v[218:221], off nt
	v_pk_mul_f32 v[202:203], v[118:119], v[182:183] op_sel:[1,0] op_sel_hi:[0,0]
	v_pk_mul_f32 v[182:183], v[120:121], v[182:183] op_sel:[1,1] op_sel_hi:[0,1]
	v_mov_b32_e32 v64, v185
	v_pk_fma_f32 v[218:219], v[118:119], v[178:179], v[202:203] op_sel_hi:[1,0,1] neg_lo:[0,0,1] neg_hi:[0,0,1]
	v_pk_fma_f32 v[220:221], v[118:119], v[178:179], v[202:203] op_sel_hi:[1,0,1]
	v_pk_fma_f32 v[118:119], v[120:121], v[178:179], v[182:183] op_sel:[0,1,0] neg_lo:[0,0,1] neg_hi:[0,0,1]
	v_pk_fma_f32 v[178:179], v[120:121], v[178:179], v[182:183] op_sel:[0,1,0]
	v_pk_mul_f32 v[182:183], v[114:115], v[184:185] op_sel:[1,0] op_sel_hi:[0,0]
	v_pk_mul_f32 v[184:185], v[116:117], v[64:65] op_sel:[1,0] op_sel_hi:[0,0]
	v_mov_b32_e32 v64, v181
; __device__ __forceinline__ unsigned pk2(float lo, float hi) { f32x2_t v = {lo, hi}; bf16x2_t b = __builtin_convertvector(v, bf16x2_t); return __builtin_bit_cast(unsigned, b); }
;     __device__ __forceinline__ void operator()(const f32x4 (&acc)[2][2][4][2], const Unit& u, int wr, int wc, int fr, int fq) const {
;     ...
;                     for (int i = 0; i < 8; ++i) {
;                         const int ai = i >> 2, m = i & 3, row = row0 + ai * 128 + m * 16;
;                         const f32x4 v0 = acc[ai][bj][m][0], v1 = acc[ai][bj][m][1];
;                         float r[8];
;                         r[0] = v0[0] * c4[i][0] - v0[1] * s4[i][0]; r[1] = v0[0] * s4[i][0] + v0[1] * c4[i][0];
;                         r[2] = v0[2] * c4[i][1] - v0[3] * s4[i][1]; r[3] = v0[2] * s4[i][1] + v0[3] * c4[i][1];
;                         r[4] = v1[0] * c4[i][2] - v1[1] * s4[i][2]; r[5] = v1[0] * s4[i][2] + v1[1] * c4[i][2];
;                         r[6] = v1[2] * c4[i][3] - v1[3] * s4[i][3]; r[7] = v1[2] * s4[i][3] + v1[3] * c4[i][3];
;                         if (ksum_on) {
; #pragma unroll
;                             for (int j = 0; j < 8; ++j) ks[j] += r[j];
;                         }
;                         u32x4 w; w.x = pk2(r[0] * sc, r[1] * sc); w.y = pk2(r[2] * sc, r[3] * sc); w.z = pk2(r[4] * sc, r[5] * sc); w.w = pk2(r[6] * sc, r[7] * sc);
;                         __builtin_nontemporal_store(w, (u32x4*)(qkv + (unsigned)(row * LDQ + col)));
	v_pk_fma_f32 v[120:121], v[114:115], v[180:181], v[182:183] op_sel_hi:[1,0,1] neg_lo:[0,0,1] neg_hi:[0,0,1]
	v_pk_fma_f32 v[182:183], v[114:115], v[180:181], v[182:183] op_sel_hi:[1,0,1]
	v_pk_fma_f32 v[114:115], v[116:117], v[64:65], v[184:185] op_sel_hi:[1,0,1] neg_lo:[0,0,1] neg_hi:[0,0,1]
	v_pk_fma_f32 v[116:117], v[116:117], v[64:65], v[184:185] op_sel_hi:[1,0,1]
	s_and_saveexec_b64 s[28:29], s[26:27]
	v_pk_mov_b32 v[180:181], v[220:221], v[218:219] op_sel:[1,0]
	s_nop 0
	v_pk_add_f32 v[126:127], v[180:181], v[126:127]
	v_pk_mov_b32 v[180:181], v[178:179], v[118:119] op_sel:[1,0]
	s_nop 0
	v_pk_add_f32 v[124:125], v[180:181], v[124:125]
	v_pk_mov_b32 v[180:181], v[182:183], v[120:121] op_sel:[1,0]
	s_nop 0
	v_pk_add_f32 v[122:123], v[180:181], v[122:123]
	v_pk_mov_b32 v[180:181], v[116:117], v[114:115] op_sel:[1,0]
	s_nop 0
	v_pk_add_f32 v[128:129], v[180:181], v[128:129]
	s_or_b64 exec, exec, s[28:29]
	v_mov_b32_e32 v215, v214
	v_mov_b32_e32 v219, v221
	v_mov_b32_e32 v119, v179
	v_mov_b32_e32 v121, v183
	v_mov_b32_e32 v115, v117
	v_pk_mul_f32 v[116:117], v[214:215], v[218:219]
	v_pk_mul_f32 v[118:119], v[214:215], v[118:119]
	v_add_u32_e32 v178, 0x12000, v200
	v_cvt_pk_bf16_f32 v116, v116, v117
	v_cvt_pk_bf16_f32 v117, v118, v119
	v_pk_mul_f32 v[118:119], v[214:215], v[120:121]
	v_pk_mul_f32 v[114:115], v[214:215], v[114:115]
	v_add_u32_e32 v64, v178, v222
	v_cvt_pk_bf16_f32 v118, v118, v119
	v_cvt_pk_bf16_f32 v119, v114, v115
	v_lshl_add_u64 v[114:115], v[64:65], 1, s[84:85]
	global_store_dwordx4 v[114:115], v[116:119], off nt
	v_mov_b32_e32 v64, v177
	v_pk_mul_f32 v[120:121], v[106:107], v[176:177] op_sel:[1,0] op_sel_hi:[0,0]
	v_pk_mul_f32 v[116:117], v[110:111], v[174:175] op_sel:[1,0] op_sel_hi:[0,0]
	v_pk_mul_f32 v[118:119], v[112:113], v[174:175] op_sel:[1,1] op_sel_hi:[0,1]
	v_pk_fma_f32 v[114:115], v[110:111], v[170:171], v[116:117] op_sel_hi:[1,0,1] neg_lo:[0,0,1] neg_hi:[0,0,1]
	v_pk_fma_f32 v[116:117], v[110:111], v[170:171], v[116:117] op_sel_hi:[1,0,1]
	v_pk_fma_f32 v[110:111], v[112:113], v[170:171], v[118:119] op_sel:[0,1,0] neg_lo:[0,0,1] neg_hi:[0,0,1]
	v_pk_fma_f32 v[118:119], v[112:113], v[170:171], v[118:119] op_sel:[0,1,0]
	v_pk_mul_f32 v[170:171], v[108:109], v[64:65] op_sel:[1,0] op_sel_hi:[0,0]
	v_mov_b32_e32 v64, v173
	v_pk_fma_f32 v[112:113], v[106:107], v[172:173], v[120:121] op_sel_hi:[1,0,1] neg_lo:[0,0,1] neg_hi:[0,0,1]
	v_pk_fma_f32 v[120:121], v[106:107], v[172:173], v[120:121] op_sel_hi:[1,0,1]
	v_pk_fma_f32 v[106:107], v[108:109], v[64:65], v[170:171] op_sel_hi:[1,0,1] neg_lo:[0,0,1] neg_hi:[0,0,1]
	v_pk_fma_f32 v[108:109], v[108:109], v[64:65], v[170:171] op_sel_hi:[1,0,1]
	s_and_saveexec_b64 s[28:29], s[26:27]
	v_pk_mov_b32 v[170:171], v[116:117], v[114:115] op_sel:[1,0]
	s_nop 0
	v_pk_add_f32 v[126:127], v[170:171], v[126:127]
	v_pk_mov_b32 v[170:171], v[118:119], v[110:111] op_sel:[1,0]
	s_nop 0
	v_pk_add_f32 v[124:125], v[170:171], v[124:125]
	v_pk_mov_b32 v[170:171], v[120:121], v[112:113] op_sel:[1,0]
	s_nop 0
	v_pk_add_f32 v[122:123], v[170:171], v[122:123]
	v_pk_mov_b32 v[170:171], v[108:109], v[106:107] op_sel:[1,0]
	s_nop 0
	v_pk_add_f32 v[128:129], v[170:171], v[128:129]
	s_or_b64 exec, exec, s[28:29]
	v_mov_b32_e32 v115, v117
	v_mov_b32_e32 v111, v119
	v_mov_b32_e32 v107, v109
	v_pk_mul_f32 v[108:109], v[214:215], v[114:115]
	v_mov_b32_e32 v113, v121
	v_cvt_pk_bf16_f32 v114, v108, v109
	v_pk_mul_f32 v[108:109], v[214:215], v[110:111]
	v_pk_mul_f32 v[106:107], v[214:215], v[106:107]
	v_cvt_pk_bf16_f32 v115, v108, v109
	v_pk_mul_f32 v[108:109], v[214:215], v[112:113]
	v_cvt_pk_bf16_f32 v117, v106, v107
	v_cvt_pk_bf16_f32 v116, v108, v109
	v_add_u32_e32 v108, 0x24000, v200
	v_add_u32_e32 v64, v108, v222
	v_lshl_add_u64 v[106:107], v[64:65], 1, s[84:85]
	v_pk_mul_f32 v[110:111], v[102:103], v[166:167] op_sel_hi:[1,0]
	global_store_dwordx4 v[106:107], v[114:117], off nt
	v_pk_fma_f32 v[106:107], v[102:103], v[162:163], v[110:111] op_sel:[1,0,0] op_sel_hi:[0,1,1]
	v_pk_fma_f32 v[102:103], v[102:103], v[162:163], v[110:111] op_sel:[1,0,0] op_sel_hi:[0,0,1] neg_lo:[0,0,1] neg_hi:[0,0,1]
	v_pk_mul_f32 v[110:111], v[104:105], v[166:167] op_sel:[0,1]
	v_mov_b32_e32 v107, v103
	v_pk_fma_f32 v[102:103], v[104:105], v[162:163], v[110:111] op_sel:[1,1,0] op_sel_hi:[0,1,1]
	v_pk_fma_f32 v[104:105], v[104:105], v[162:163], v[110:111] op_sel:[1,1,0] op_sel_hi:[0,1,1] neg_lo:[0,0,1] neg_hi:[0,0,1]
	v_pk_mul_f32 v[110:111], v[98:99], v[168:169] op_sel_hi:[1,0]
	v_mov_b32_e32 v64, v169
	v_mov_b32_e32 v103, v105
	v_pk_fma_f32 v[104:105], v[98:99], v[164:165], v[110:111] op_sel:[1,0,0] op_sel_hi:[0,1,1]
	v_pk_fma_f32 v[98:99], v[98:99], v[164:165], v[110:111] op_sel:[1,0,0] op_sel_hi:[0,0,1] neg_lo:[0,0,1] neg_hi:[0,0,1]
	v_pk_mul_f32 v[110:111], v[100:101], v[64:65] op_sel_hi:[1,0]
	v_mov_b32_e32 v64, v165
	v_mov_b32_e32 v105, v99
	v_pk_fma_f32 v[98:99], v[100:101], v[64:65], v[110:111] op_sel:[1,0,0] op_sel_hi:[0,0,1]
	v_pk_fma_f32 v[100:101], v[100:101], v[64:65], v[110:111] op_sel:[1,0,0] op_sel_hi:[0,0,1] neg_lo:[0,0,1] neg_hi:[0,0,1]
	v_mov_b32_e32 v99, v101
	s_and_saveexec_b64 s[28:29], s[26:27]
	v_pk_add_f32 v[126:127], v[106:107], v[126:127]
	v_pk_add_f32 v[124:125], v[102:103], v[124:125]
	v_pk_add_f32 v[122:123], v[104:105], v[122:123]
	v_pk_add_f32 v[128:129], v[98:99], v[128:129]
	s_or_b64 exec, exec, s[28:29]
	v_pk_mul_f32 v[100:101], v[214:215], v[106:107]
	v_pk_mul_f32 v[98:99], v[214:215], v[98:99]
	v_pk_mov_b32 v[100:101], v[100:101], v[100:101] op_sel:[1,0]
	v_pk_mov_b32 v[98:99], v[98:99], v[98:99] op_sel:[1,0]
	v_cvt_pk_bf16_f32 v110, v100, v101
	v_pk_mul_f32 v[100:101], v[214:215], v[102:103]
; __device__ __forceinline__ unsigned pk2(float lo, float hi) { f32x2_t v = {lo, hi}; bf16x2_t b = __builtin_convertvector(v, bf16x2_t); return __builtin_bit_cast(unsigned, b); }
;     __device__ __forceinline__ void operator()(const f32x4 (&acc)[2][2][4][2], const Unit& u, int wr, int wc, int fr, int fq) const {
;     ...
;                     for (int i = 0; i < 8; ++i) {
;                         const int ai = i >> 2, m = i & 3, row = row0 + ai * 128 + m * 16;
;                         const f32x4 v0 = acc[ai][bj][m][0], v1 = acc[ai][bj][m][1];
;                         float r[8];
;                         r[0] = v0[0] * c4[i][0] - v0[1] * s4[i][0]; r[1] = v0[0] * s4[i][0] + v0[1] * c4[i][0];
;                         r[2] = v0[2] * c4[i][1] - v0[3] * s4[i][1]; r[3] = v0[2] * s4[i][1] + v0[3] * c4[i][1];
;                         r[4] = v1[0] * c4[i][2] - v1[1] * s4[i][2]; r[5] = v1[0] * s4[i][2] + v1[1] * c4[i][2];
;                         r[6] = v1[2] * c4[i][3] - v1[3] * s4[i][3]; r[7] = v1[2] * s4[i][3] + v1[3] * c4[i][3];
;                         if (ksum_on) {
; #pragma unroll
;                             for (int j = 0; j < 8; ++j) ks[j] += r[j];
;                         }
;                         u32x4 w; w.x = pk2(r[0] * sc, r[1] * sc); w.y = pk2(r[2] * sc, r[3] * sc); w.z = pk2(r[4] * sc, r[5] * sc); w.w = pk2(r[6] * sc, r[7] * sc);
;                         __builtin_nontemporal_store(w, (u32x4*)(qkv + (unsigned)(row * LDQ + col)));
	v_cvt_pk_bf16_f32 v113, v98, v99
	v_pk_mov_b32 v[100:101], v[100:101], v[100:101] op_sel:[1,0]
	v_pk_mul_f32 v[102:103], v[94:95], v[158:159] op_sel_hi:[1,0]
	v_cvt_pk_bf16_f32 v111, v100, v101
	v_pk_mul_f32 v[100:101], v[214:215], v[104:105]
	s_nop 0
	v_pk_mov_b32 v[100:101], v[100:101], v[100:101] op_sel:[1,0]
	s_nop 0
	v_cvt_pk_bf16_f32 v112, v100, v101
	v_add_u32_e32 v100, 0x36000, v200
	v_add_u32_e32 v64, v100, v222
	v_lshl_add_u64 v[98:99], v[64:65], 1, s[84:85]
	global_store_dwordx4 v[98:99], v[110:113], off nt
	v_pk_fma_f32 v[98:99], v[94:95], v[154:155], v[102:103] op_sel:[1,0,0] op_sel_hi:[0,1,1]
	v_pk_fma_f32 v[94:95], v[94:95], v[154:155], v[102:103] op_sel:[1,0,0] op_sel_hi:[0,0,1] neg_lo:[0,0,1] neg_hi:[0,0,1]
	v_pk_mul_f32 v[102:103], v[96:97], v[158:159] op_sel:[0,1]
	v_mov_b32_e32 v99, v95
	v_pk_fma_f32 v[94:95], v[96:97], v[154:155], v[102:103] op_sel:[1,1,0] op_sel_hi:[0,1,1]
	v_pk_fma_f32 v[96:97], v[96:97], v[154:155], v[102:103] op_sel:[1,1,0] op_sel_hi:[0,1,1] neg_lo:[0,0,1] neg_hi:[0,0,1]
	v_pk_mul_f32 v[102:103], v[90:91], v[160:161] op_sel_hi:[1,0]
	v_mov_b32_e32 v64, v161
	v_mov_b32_e32 v95, v97
	v_pk_fma_f32 v[96:97], v[90:91], v[156:157], v[102:103] op_sel:[1,0,0] op_sel_hi:[0,1,1]
	v_pk_fma_f32 v[90:91], v[90:91], v[156:157], v[102:103] op_sel:[1,0,0] op_sel_hi:[0,0,1] neg_lo:[0,0,1] neg_hi:[0,0,1]
	v_pk_mul_f32 v[102:103], v[92:93], v[64:65] op_sel_hi:[1,0]
	v_mov_b32_e32 v64, v157
	v_mov_b32_e32 v97, v91
	v_pk_fma_f32 v[90:91], v[92:93], v[64:65], v[102:103] op_sel:[1,0,0] op_sel_hi:[0,0,1]
	v_pk_fma_f32 v[92:93], v[92:93], v[64:65], v[102:103] op_sel:[1,0,0] op_sel_hi:[0,0,1] neg_lo:[0,0,1] neg_hi:[0,0,1]
	v_mov_b32_e32 v91, v93
	s_and_saveexec_b64 s[28:29], s[26:27]
	v_pk_add_f32 v[126:127], v[98:99], v[126:127]
	v_pk_add_f32 v[124:125], v[94:95], v[124:125]
	v_pk_add_f32 v[122:123], v[96:97], v[122:123]
	v_pk_add_f32 v[128:129], v[90:91], v[128:129]
	s_or_b64 exec, exec, s[28:29]
	v_pk_mul_f32 v[92:93], v[214:215], v[98:99]
	v_pk_mul_f32 v[90:91], v[214:215], v[90:91]
	v_pk_mov_b32 v[92:93], v[92:93], v[92:93] op_sel:[1,0]
	v_pk_mov_b32 v[90:91], v[90:91], v[90:91] op_sel:[1,0]
	v_cvt_pk_bf16_f32 v102, v92, v93
	v_pk_mul_f32 v[92:93], v[214:215], v[94:95]
	v_cvt_pk_bf16_f32 v105, v90, v91
	v_pk_mov_b32 v[92:93], v[92:93], v[92:93] op_sel:[1,0]
	v_pk_mul_f32 v[94:95], v[86:87], v[150:151] op_sel_hi:[1,0]
	v_cvt_pk_bf16_f32 v103, v92, v93
	v_pk_mul_f32 v[92:93], v[214:215], v[96:97]
	s_nop 0
	v_pk_mov_b32 v[92:93], v[92:93], v[92:93] op_sel:[1,0]
	s_nop 0
	v_cvt_pk_bf16_f32 v104, v92, v93
	v_add_u32_e32 v92, 0x90000, v222
	v_add_u32_e32 v64, v92, v200
	v_lshl_add_u64 v[90:91], v[64:65], 1, s[84:85]
	global_store_dwordx4 v[90:91], v[102:105], off nt
	v_pk_fma_f32 v[90:91], v[86:87], v[146:147], v[94:95] op_sel:[1,0,0] op_sel_hi:[0,1,1]
	v_pk_fma_f32 v[86:87], v[86:87], v[146:147], v[94:95] op_sel:[1,0,0] op_sel_hi:[0,0,1] neg_lo:[0,0,1] neg_hi:[0,0,1]
	v_pk_mul_f32 v[94:95], v[88:89], v[150:151] op_sel:[0,1]
	v_mov_b32_e32 v91, v87
	v_pk_fma_f32 v[86:87], v[88:89], v[146:147], v[94:95] op_sel:[1,1,0] op_sel_hi:[0,1,1]
	v_pk_fma_f32 v[88:89], v[88:89], v[146:147], v[94:95] op_sel:[1,1,0] op_sel_hi:[0,1,1] neg_lo:[0,0,1] neg_hi:[0,0,1]
	v_pk_mul_f32 v[94:95], v[82:83], v[152:153] op_sel_hi:[1,0]
	v_mov_b32_e32 v64, v153
	v_mov_b32_e32 v87, v89
	v_pk_fma_f32 v[88:89], v[82:83], v[148:149], v[94:95] op_sel:[1,0,0] op_sel_hi:[0,1,1]
	v_pk_fma_f32 v[82:83], v[82:83], v[148:149], v[94:95] op_sel:[1,0,0] op_sel_hi:[0,0,1] neg_lo:[0,0,1] neg_hi:[0,0,1]
	v_pk_mul_f32 v[94:95], v[84:85], v[64:65] op_sel_hi:[1,0]
	v_mov_b32_e32 v64, v149
	v_mov_b32_e32 v89, v83
	v_pk_fma_f32 v[82:83], v[84:85], v[64:65], v[94:95] op_sel:[1,0,0] op_sel_hi:[0,0,1]
	v_pk_fma_f32 v[84:85], v[84:85], v[64:65], v[94:95] op_sel:[1,0,0] op_sel_hi:[0,0,1] neg_lo:[0,0,1] neg_hi:[0,0,1]
	v_mov_b32_e32 v83, v85
	s_and_saveexec_b64 s[28:29], s[26:27]
	v_pk_add_f32 v[126:127], v[90:91], v[126:127]
	v_pk_add_f32 v[124:125], v[86:87], v[124:125]
	v_pk_add_f32 v[122:123], v[88:89], v[122:123]
	v_pk_add_f32 v[128:129], v[82:83], v[128:129]
	s_or_b64 exec, exec, s[28:29]
	v_pk_mul_f32 v[84:85], v[214:215], v[90:91]
	v_pk_mul_f32 v[86:87], v[214:215], v[86:87]
	v_pk_mov_b32 v[84:85], v[84:85], v[84:85] op_sel:[1,0]
	v_pk_mov_b32 v[86:87], v[86:87], v[86:87] op_sel:[1,0]
	v_cvt_pk_bf16_f32 v84, v84, v85
	v_cvt_pk_bf16_f32 v85, v86, v87
	v_pk_mul_f32 v[86:87], v[214:215], v[88:89]
	v_pk_mul_f32 v[82:83], v[214:215], v[82:83]
	v_pk_mov_b32 v[86:87], v[86:87], v[86:87] op_sel:[1,0]
	v_pk_mov_b32 v[82:83], v[82:83], v[82:83] op_sel:[1,0]
	v_add_u32_e32 v64, v92, v178
	v_cvt_pk_bf16_f32 v86, v86, v87
	v_cvt_pk_bf16_f32 v87, v82, v83
	v_lshl_add_u64 v[82:83], v[64:65], 1, s[84:85]
	global_store_dwordx4 v[82:83], v[84:87], off nt
	v_mov_b32_e32 v64, v145
	s_nop 0
	v_pk_mul_f32 v[84:85], v[78:79], v[142:143] op_sel_hi:[1,0]
	s_nop 0
	v_pk_fma_f32 v[82:83], v[78:79], v[138:139], v[84:85] op_sel:[1,0,0] op_sel_hi:[0,1,1]
	v_pk_fma_f32 v[78:79], v[78:79], v[138:139], v[84:85] op_sel:[1,0,0] op_sel_hi:[0,0,1] neg_lo:[0,0,1] neg_hi:[0,0,1]
	v_pk_mul_f32 v[84:85], v[80:81], v[142:143] op_sel:[0,1]
	v_mov_b32_e32 v83, v79
	v_pk_fma_f32 v[78:79], v[80:81], v[138:139], v[84:85] op_sel:[1,1,0] op_sel_hi:[0,1,1]
	v_pk_fma_f32 v[80:81], v[80:81], v[138:139], v[84:85] op_sel:[1,1,0] op_sel_hi:[0,1,1] neg_lo:[0,0,1] neg_hi:[0,0,1]
	v_pk_mul_f32 v[84:85], v[74:75], v[144:145] op_sel_hi:[1,0]
	v_mov_b32_e32 v79, v81
	v_pk_fma_f32 v[80:81], v[74:75], v[140:141], v[84:85] op_sel:[1,0,0] op_sel_hi:[0,1,1]
	v_pk_fma_f32 v[74:75], v[74:75], v[140:141], v[84:85] op_sel:[1,0,0] op_sel_hi:[0,0,1] neg_lo:[0,0,1] neg_hi:[0,0,1]
; __device__ __forceinline__ unsigned pk2(float lo, float hi) { f32x2_t v = {lo, hi}; bf16x2_t b = __builtin_convertvector(v, bf16x2_t); return __builtin_bit_cast(unsigned, b); }
; template <int K> __device__ __forceinline__ float swz_xor(float v) { return __int_as_float(__builtin_amdgcn_ds_swizzle(__float_as_int(v), (K << 10) | 0x1f)); }
;     __device__ __forceinline__ void operator()(const f32x4 (&acc)[2][2][4][2], const Unit& u, int wr, int wc, int fr, int fq) const {
;     ...
;                     for (int i = 0; i < 8; ++i) {
;                         const int ai = i >> 2, m = i & 3, row = row0 + ai * 128 + m * 16;
;                         const f32x4 v0 = acc[ai][bj][m][0], v1 = acc[ai][bj][m][1];
;                         float r[8];
;                         r[0] = v0[0] * c4[i][0] - v0[1] * s4[i][0]; r[1] = v0[0] * s4[i][0] + v0[1] * c4[i][0];
;                         r[2] = v0[2] * c4[i][1] - v0[3] * s4[i][1]; r[3] = v0[2] * s4[i][1] + v0[3] * c4[i][1];
;                         r[4] = v1[0] * c4[i][2] - v1[1] * s4[i][2]; r[5] = v1[0] * s4[i][2] + v1[1] * c4[i][2];
;                         r[6] = v1[2] * c4[i][3] - v1[3] * s4[i][3]; r[7] = v1[2] * s4[i][3] + v1[3] * c4[i][3];
;                         if (ksum_on) {
; #pragma unroll
;                             for (int j = 0; j < 8; ++j) ks[j] += r[j];
;                         }
;                         u32x4 w; w.x = pk2(r[0] * sc, r[1] * sc); w.y = pk2(r[2] * sc, r[3] * sc); w.z = pk2(r[4] * sc, r[5] * sc); w.w = pk2(r[6] * sc, r[7] * sc);
;                         __builtin_nontemporal_store(w, (u32x4*)(qkv + (unsigned)(row * LDQ + col)));
;                     }
;                     if (ksum_on) {
; #pragma unroll
;                         for (int j = 0; j < 8; ++j) {
;                             float v = ks[j];
;                             v += swz_xor<1>(v); v += swz_xor<2>(v); v += swz_xor<4>(v); v += swz_xor<8>(v);
;                             ks[j] = v;
;                         }
;                         if (fr == 0) {
;                             float* dst = kmean + (size_t)(((u.pm >> 3) * 6 + (head - 12)) * 8 + (u.pm & 7)) * 64 + dc;
; #pragma unroll
;                             for (int j = 0; j < 8; ++j) atomicAdd(dst + j, ks[j]);
;                         }
	v_pk_mul_f32 v[84:85], v[76:77], v[64:65] op_sel_hi:[1,0]
	v_mov_b32_e32 v64, v141
	v_mov_b32_e32 v81, v75
	v_pk_fma_f32 v[74:75], v[76:77], v[64:65], v[84:85] op_sel:[1,0,0] op_sel_hi:[0,0,1]
	v_pk_fma_f32 v[76:77], v[76:77], v[64:65], v[84:85] op_sel:[1,0,0] op_sel_hi:[0,0,1] neg_lo:[0,0,1] neg_hi:[0,0,1]
	v_mov_b32_e32 v75, v77
	s_and_saveexec_b64 s[28:29], s[26:27]
	v_pk_add_f32 v[126:127], v[82:83], v[126:127]
	v_pk_add_f32 v[124:125], v[78:79], v[124:125]
	v_pk_add_f32 v[122:123], v[80:81], v[122:123]
	v_pk_add_f32 v[128:129], v[74:75], v[128:129]
	s_or_b64 exec, exec, s[28:29]
	v_pk_mul_f32 v[76:77], v[214:215], v[82:83]
	v_pk_mul_f32 v[78:79], v[214:215], v[78:79]
	v_pk_mov_b32 v[76:77], v[76:77], v[76:77] op_sel:[1,0]
	v_pk_mov_b32 v[78:79], v[78:79], v[78:79] op_sel:[1,0]
	v_cvt_pk_bf16_f32 v76, v76, v77
	v_cvt_pk_bf16_f32 v77, v78, v79
	v_pk_mul_f32 v[78:79], v[214:215], v[80:81]
	v_pk_mul_f32 v[74:75], v[214:215], v[74:75]
	v_pk_mov_b32 v[78:79], v[78:79], v[78:79] op_sel:[1,0]
	v_pk_mov_b32 v[74:75], v[74:75], v[74:75] op_sel:[1,0]
	v_add_u32_e32 v64, v92, v108
	v_cvt_pk_bf16_f32 v78, v78, v79
	v_cvt_pk_bf16_f32 v79, v74, v75
	v_lshl_add_u64 v[74:75], v[64:65], 1, s[84:85]
	global_store_dwordx4 v[74:75], v[76:79], off nt
	v_mov_b32_e32 v64, v137
	s_nop 0
	v_pk_mul_f32 v[76:77], v[70:71], v[134:135] op_sel_hi:[1,0]
	s_nop 0
	v_pk_fma_f32 v[74:75], v[70:71], v[130:131], v[76:77] op_sel:[1,0,0] op_sel_hi:[0,1,1]
	v_pk_fma_f32 v[70:71], v[70:71], v[130:131], v[76:77] op_sel:[1,0,0] op_sel_hi:[0,0,1] neg_lo:[0,0,1] neg_hi:[0,0,1]
	v_pk_mul_f32 v[76:77], v[72:73], v[134:135] op_sel:[0,1]
	v_mov_b32_e32 v75, v71
	v_pk_fma_f32 v[70:71], v[72:73], v[130:131], v[76:77] op_sel:[1,1,0] op_sel_hi:[0,1,1]
	v_pk_fma_f32 v[72:73], v[72:73], v[130:131], v[76:77] op_sel:[1,1,0] op_sel_hi:[0,1,1] neg_lo:[0,0,1] neg_hi:[0,0,1]
	v_pk_mul_f32 v[76:77], v[66:67], v[136:137] op_sel_hi:[1,0]
	v_mov_b32_e32 v71, v73
	v_pk_fma_f32 v[72:73], v[66:67], v[132:133], v[76:77] op_sel:[1,0,0] op_sel_hi:[0,1,1]
	v_pk_fma_f32 v[66:67], v[66:67], v[132:133], v[76:77] op_sel:[1,0,0] op_sel_hi:[0,0,1] neg_lo:[0,0,1] neg_hi:[0,0,1]
	v_pk_mul_f32 v[76:77], v[68:69], v[64:65] op_sel_hi:[1,0]
	v_mov_b32_e32 v64, v133
	v_mov_b32_e32 v73, v67
	v_pk_fma_f32 v[66:67], v[68:69], v[64:65], v[76:77] op_sel:[1,0,0] op_sel_hi:[0,0,1]
	v_pk_fma_f32 v[68:69], v[68:69], v[64:65], v[76:77] op_sel:[1,0,0] op_sel_hi:[0,0,1] neg_lo:[0,0,1] neg_hi:[0,0,1]
	v_mov_b32_e32 v67, v69
	s_and_saveexec_b64 s[28:29], s[26:27]
	v_pk_add_f32 v[126:127], v[74:75], v[126:127]
	v_pk_add_f32 v[124:125], v[70:71], v[124:125]
	v_pk_add_f32 v[122:123], v[72:73], v[122:123]
	v_pk_add_f32 v[128:129], v[66:67], v[128:129]
	s_or_b64 exec, exec, s[28:29]
	v_pk_mul_f32 v[68:69], v[214:215], v[74:75]
	v_pk_mul_f32 v[70:71], v[214:215], v[70:71]
	v_pk_mov_b32 v[68:69], v[68:69], v[68:69] op_sel:[1,0]
	v_pk_mov_b32 v[70:71], v[70:71], v[70:71] op_sel:[1,0]
	v_cvt_pk_bf16_f32 v68, v68, v69
	v_cvt_pk_bf16_f32 v69, v70, v71
	v_pk_mul_f32 v[70:71], v[214:215], v[72:73]
	v_pk_mul_f32 v[66:67], v[214:215], v[66:67]
	v_pk_mov_b32 v[70:71], v[70:71], v[70:71] op_sel:[1,0]
	v_pk_mov_b32 v[66:67], v[66:67], v[66:67] op_sel:[1,0]
	v_add_u32_e32 v64, v92, v100
	v_cvt_pk_bf16_f32 v70, v70, v71
	v_cvt_pk_bf16_f32 v71, v66, v67
	v_lshl_add_u64 v[66:67], v[64:65], 1, s[84:85]
	global_store_dwordx4 v[66:67], v[68:71], off nt
	s_and_saveexec_b64 s[28:29], s[26:27]
	s_cbranch_execz .LBB0_732
	ds_swizzle_b32 v66, v126 offset:swizzle(SWAP,1)
	ds_swizzle_b32 v67, v125 offset:swizzle(SWAP,1)
	ds_swizzle_b32 v71, v124 offset:swizzle(SWAP,1)
	ds_swizzle_b32 v64, v127 offset:swizzle(SWAP,1)
	ds_swizzle_b32 v72, v123 offset:swizzle(SWAP,1)
	s_waitcnt lgkmcnt(0)
	v_add_f32_e32 v66, v126, v66
	ds_swizzle_b32 v69, v66 offset:swizzle(SWAP,2)
	v_add_f32_e32 v67, v125, v67
	ds_swizzle_b32 v70, v67 offset:swizzle(SWAP,2)
	ds_swizzle_b32 v76, v129 offset:swizzle(SWAP,1)
	ds_swizzle_b32 v77, v128 offset:swizzle(SWAP,1)
	s_waitcnt lgkmcnt(0)
	v_add_f32_e32 v66, v66, v69
	ds_swizzle_b32 v69, v66 offset:swizzle(SWAP,4)
	v_add_f32_e32 v70, v67, v70
	v_add_f32_e32 v64, v127, v64
	v_add_f32_e32 v72, v123, v72
	v_add_f32_e32 v76, v129, v76
	s_waitcnt lgkmcnt(0)
	v_add_f32_e32 v67, v66, v69
	v_add_f32_e32 v69, v124, v71
	ds_swizzle_b32 v71, v69 offset:swizzle(SWAP,2)
	v_add_f32_e32 v77, v128, v77
	ds_swizzle_b32 v68, v64 offset:swizzle(SWAP,2)
	ds_swizzle_b32 v73, v70 offset:swizzle(SWAP,4)
	ds_swizzle_b32 v74, v72 offset:swizzle(SWAP,2)
	s_waitcnt lgkmcnt(0)
	v_add_f32_e32 v71, v69, v71
	ds_swizzle_b32 v75, v71 offset:swizzle(SWAP,4)
	ds_swizzle_b32 v79, v76 offset:swizzle(SWAP,2)
	ds_swizzle_b32 v80, v77 offset:swizzle(SWAP,2)
	v_add_f32_e32 v64, v64, v68
	v_add_f32_e32 v69, v70, v73
	s_waitcnt lgkmcnt(0)
	v_add_f32_e32 v71, v71, v75
	ds_swizzle_b32 v75, v122 offset:swizzle(SWAP,1)
	v_add_f32_e32 v73, v72, v74
	v_add_f32_e32 v79, v76, v79
	v_add_f32_e32 v80, v77, v80
	ds_swizzle_b32 v68, v64 offset:swizzle(SWAP,4)
	s_waitcnt lgkmcnt(0)
	v_add_f32_e32 v75, v122, v75
	ds_swizzle_b32 v78, v75 offset:swizzle(SWAP,2)
	ds_swizzle_b32 v74, v73 offset:swizzle(SWAP,4)
	ds_swizzle_b32 v81, v79 offset:swizzle(SWAP,4)
	ds_swizzle_b32 v82, v80 offset:swizzle(SWAP,4)
	v_add_f32_e32 v64, v64, v68
	s_waitcnt lgkmcnt(0)
	v_add_f32_e32 v75, v75, v78
	ds_swizzle_b32 v78, v75 offset:swizzle(SWAP,4)
	v_add_f32_e32 v73, v73, v74
	v_add_f32_e32 v77, v79, v81
	v_add_f32_e32 v79, v80, v82
	ds_swizzle_b32 v66, v64 offset:swizzle(SWAP,8)
	s_waitcnt lgkmcnt(0)
	v_add_f32_e32 v75, v75, v78
	ds_swizzle_b32 v68, v67 offset:swizzle(SWAP,8)
	ds_swizzle_b32 v70, v69 offset:swizzle(SWAP,8)
	ds_swizzle_b32 v72, v71 offset:swizzle(SWAP,8)
	ds_swizzle_b32 v74, v73 offset:swizzle(SWAP,8)
	ds_swizzle_b32 v76, v75 offset:swizzle(SWAP,8)
	ds_swizzle_b32 v78, v77 offset:swizzle(SWAP,8)
	ds_swizzle_b32 v80, v79 offset:swizzle(SWAP,8)
	s_and_b64 exec, exec, s[0:1]
	s_cbranch_execz .LBB0_732
	s_lshr_b32 s17, s46, 3
	s_waitcnt lgkmcnt(0)
	v_add_f32_e32 v68, v67, v68
	v_add_f32_e32 v64, v64, v66
	v_mad_u64_u32 v[66:67], s[26:27], s17, 6, v[216:217]
	s_and_b32 s17, s46, 7
	v_lshl_or_b32 v66, v66, 3, s17
	v_ashrrev_i32_e32 v67, 31, v66
	v_lshlrev_b64 v[66:67], 8, v[66:67]
	v_lshl_add_u64 v[66:67], v[194:195], 0, v[66:67]
	v_add_f32_e32 v79, v79, v80
	v_add_f32_e32 v77, v77, v78
	v_add_f32_e32 v75, v75, v76
	v_add_f32_e32 v73, v73, v74
	v_add_f32_e32 v71, v71, v72
	v_add_f32_e32 v69, v69, v70
	flat_atomic_add_f32 v[66:67], v64
	flat_atomic_add_f32 v[66:67], v68 offset:4
	flat_atomic_add_f32 v[66:67], v69 offset:8
	flat_atomic_add_f32 v[66:67], v71 offset:12
	flat_atomic_add_f32 v[66:67], v73 offset:16
	flat_atomic_add_f32 v[66:67], v75 offset:20
	flat_atomic_add_f32 v[66:67], v77 offset:24
	flat_atomic_add_f32 v[66:67], v79 offset:28

; __device__ __forceinline__ unsigned pk2(float lo, float hi) { f32x2_t v = {lo, hi}; bf16x2_t b = __builtin_convertvector(v, bf16x2_t); return __builtin_bit_cast(unsigned, b); }
; __device__ __forceinline__ float sigmoidf_(float x) { return __builtin_amdgcn_rcpf(1.0f + __expf(-x)); }
;     __device__ __forceinline__ void operator()(const f32x4 (&acc)[2][2][4][2], const Unit& u, int wr, int wc, int fr, int fq) const {
;     ...
;             } else {
;                 const int gcol = col - LDQ;
;                 const f32x4 b0 = *(const f32x4*)(bgate + gcol), b1 = *(const f32x4*)(bgate + gcol + 4);
; #pragma unroll
;                 for (int ai = 0; ai < 2; ++ai)
; #pragma unroll
;                     for (int m = 0; m < 4; ++m) {
;                         const int row = row0 + ai * 128 + m * 16;
;                         const f32x4 v0 = acc[ai][bj][m][0] + b0, v1 = acc[ai][bj][m][1] + b1;
;                         u32x4 w; w.x = pk2(sigmoidf_(v0[0]), sigmoidf_(v0[1])); w.y = pk2(sigmoidf_(v0[2]), sigmoidf_(v0[3]));
;                         w.z = pk2(sigmoidf_(v1[0]), sigmoidf_(v1[1])); w.w = pk2(sigmoidf_(v1[2]), sigmoidf_(v1[3]));
;                         __builtin_nontemporal_store(w, (u32x4*)(gates + (unsigned)(row * NG + gcol)));
;                     }
.LBB0_734:
	s_andn2_b64 vcc, exec, s[24:25]
	s_mov_b64 s[2:3], -1
	s_cbranch_vccnz .LBB0_736
	s_waitcnt lgkmcnt(0)
	v_add_u32_e32 v74, 0xffffee80, v200
	v_ashrrev_i32_e32 v75, 31, v74
	v_lshl_add_u64 v[70:71], v[74:75], 2, s[6:7]
	global_load_dwordx4 v[66:69], v[70:71], off offset:16
	s_nop 0
	global_load_dwordx4 v[70:73], v[70:71], off
	s_waitcnt vmcnt(0)
	v_pk_add_f32 v[82:83], v[56:57], v[66:67]
	v_pk_add_f32 v[76:77], v[60:61], v[70:71]
	v_pk_add_f32 v[78:79], v[62:63], v[72:73]
	v_mul_f32_e32 v64, 0xbfb8aa3b, v76
	v_mul_f32_e32 v75, 0xbfb8aa3b, v77
	v_exp_f32_e32 v64, v64
	v_exp_f32_e32 v75, v75
	v_pk_add_f32 v[80:81], v[58:59], v[68:69]
	v_add_f32_e32 v64, 1.0, v64
	v_add_f32_e32 v75, 1.0, v75
	v_rcp_f32_e32 v64, v64
	v_rcp_f32_e32 v75, v75
	s_nop 0
	v_cvt_pk_bf16_f32 v76, v64, v75
	v_mul_f32_e32 v64, 0xbfb8aa3b, v78
	v_mul_f32_e32 v75, 0xbfb8aa3b, v79
	v_exp_f32_e32 v64, v64
	v_exp_f32_e32 v75, v75
	v_add_f32_e32 v64, 1.0, v64
	v_add_f32_e32 v75, 1.0, v75
	v_rcp_f32_e32 v64, v64
	v_rcp_f32_e32 v75, v75
	s_nop 0
	v_cvt_pk_bf16_f32 v77, v64, v75
	v_mul_f32_e32 v64, 0xbfb8aa3b, v82
	v_mul_f32_e32 v75, 0xbfb8aa3b, v83
	v_exp_f32_e32 v64, v64
	v_exp_f32_e32 v75, v75
	v_pk_add_f32 v[82:83], v[48:49], v[66:67]
	v_add_f32_e32 v64, 1.0, v64
	v_add_f32_e32 v75, 1.0, v75
	v_rcp_f32_e32 v64, v64
	v_rcp_f32_e32 v75, v75
	s_nop 0
	v_cvt_pk_bf16_f32 v78, v64, v75
	v_mul_f32_e32 v64, 0xbfb8aa3b, v80
	v_mul_f32_e32 v75, 0xbfb8aa3b, v81
	v_exp_f32_e32 v64, v64
	v_exp_f32_e32 v75, v75
	v_add_f32_e32 v64, 1.0, v64
	v_add_f32_e32 v75, 1.0, v75
	v_rcp_f32_e32 v64, v64
	v_rcp_f32_e32 v75, v75
	s_nop 0
	v_cvt_pk_bf16_f32 v79, v64, v75
	v_mad_u64_u32 v[74:75], s[2:3], v228, s76, v[74:75]
	v_mov_b32_e32 v75, v65
	v_lshl_add_u64 v[80:81], v[74:75], 1, s[36:37]
	global_store_dwordx4 v[80:81], v[76:79], off nt
	v_pk_add_f32 v[80:81], v[50:51], v[68:69]
	s_mov_b64 s[2:3], 0
	v_pk_add_f32 v[76:77], v[52:53], v[70:71]
	v_pk_add_f32 v[78:79], v[54:55], v[72:73]
	v_mul_f32_e32 v64, 0xbfb8aa3b, v76
	v_mul_f32_e32 v75, 0xbfb8aa3b, v77
	v_exp_f32_e32 v64, v64
	v_exp_f32_e32 v75, v75
	v_add_f32_e32 v64, 1.0, v64
	v_add_f32_e32 v75, 1.0, v75
	v_rcp_f32_e32 v64, v64
	v_rcp_f32_e32 v75, v75
	s_nop 0
	v_cvt_pk_bf16_f32 v76, v64, v75
	v_mul_f32_e32 v64, 0xbfb8aa3b, v78
	v_mul_f32_e32 v75, 0xbfb8aa3b, v79
	v_exp_f32_e32 v64, v64
	v_exp_f32_e32 v75, v75
	v_add_f32_e32 v64, 1.0, v64
	v_add_f32_e32 v75, 1.0, v75
	v_rcp_f32_e32 v64, v64
	v_rcp_f32_e32 v75, v75
	s_nop 0
	v_cvt_pk_bf16_f32 v77, v64, v75
	v_mul_f32_e32 v64, 0xbfb8aa3b, v82
	v_mul_f32_e32 v75, 0xbfb8aa3b, v83
	v_exp_f32_e32 v64, v64
	v_exp_f32_e32 v75, v75
	v_pk_add_f32 v[82:83], v[44:45], v[70:71]
	v_add_f32_e32 v64, 1.0, v64
	v_add_f32_e32 v75, 1.0, v75
	v_rcp_f32_e32 v64, v64
	v_rcp_f32_e32 v75, v75
	s_nop 0
	v_cvt_pk_bf16_f32 v78, v64, v75
	v_mul_f32_e32 v64, 0xbfb8aa3b, v80
	v_mul_f32_e32 v75, 0xbfb8aa3b, v81
	v_exp_f32_e32 v64, v64
	v_exp_f32_e32 v75, v75
	v_add_f32_e32 v64, 1.0, v64
	v_add_f32_e32 v75, 1.0, v75
	v_rcp_f32_e32 v64, v64
	v_rcp_f32_e32 v75, v75
	s_nop 0
	v_cvt_pk_bf16_f32 v79, v64, v75
	v_add_u32_e32 v64, 0xc000, v74
	v_lshl_add_u64 v[80:81], v[64:65], 1, s[36:37]
	v_mul_f32_e32 v64, 0xbfb8aa3b, v82
	v_mul_f32_e32 v75, 0xbfb8aa3b, v83
	v_exp_f32_e32 v64, v64
	v_exp_f32_e32 v75, v75
	global_store_dwordx4 v[80:81], v[76:79], off nt
	v_pk_add_f32 v[80:81], v[46:47], v[72:73]
	v_add_f32_e32 v64, 1.0, v64
	v_add_f32_e32 v75, 1.0, v75
	v_rcp_f32_e32 v64, v64
	v_rcp_f32_e32 v75, v75
	v_pk_add_f32 v[78:79], v[40:41], v[66:67]
	v_pk_add_f32 v[76:77], v[42:43], v[68:69]
	v_cvt_pk_bf16_f32 v82, v64, v75
	v_mul_f32_e32 v64, 0xbfb8aa3b, v80
	v_mul_f32_e32 v75, 0xbfb8aa3b, v81
	v_exp_f32_e32 v64, v64
	v_exp_f32_e32 v75, v75
	v_pk_add_f32 v[80:81], v[34:35], v[68:69]
	v_add_f32_e32 v64, 1.0, v64
	v_add_f32_e32 v75, 1.0, v75
	v_rcp_f32_e32 v64, v64
	v_rcp_f32_e32 v75, v75
	s_nop 0
	v_cvt_pk_bf16_f32 v83, v64, v75
	v_mul_f32_e32 v64, 0xbfb8aa3b, v78
	v_mul_f32_e32 v75, 0xbfb8aa3b, v79
	v_exp_f32_e32 v64, v64
	v_exp_f32_e32 v75, v75
	v_pk_add_f32 v[78:79], v[38:39], v[72:73]
	v_add_f32_e32 v64, 1.0, v64
	v_add_f32_e32 v75, 1.0, v75
	v_rcp_f32_e32 v64, v64
	v_rcp_f32_e32 v75, v75
	s_nop 0
	v_cvt_pk_bf16_f32 v84, v64, v75
	v_mul_f32_e32 v64, 0xbfb8aa3b, v76
	v_mul_f32_e32 v75, 0xbfb8aa3b, v77
	v_exp_f32_e32 v64, v64
	v_exp_f32_e32 v75, v75
	v_add_f32_e32 v64, 1.0, v64
	v_add_f32_e32 v75, 1.0, v75
	v_rcp_f32_e32 v64, v64
	v_rcp_f32_e32 v75, v75
	s_nop 0
	v_cvt_pk_bf16_f32 v85, v64, v75
	v_add_u32_e32 v64, 0x18000, v74
	v_lshl_add_u64 v[76:77], v[64:65], 1, s[36:37]
	global_store_dwordx4 v[76:77], v[82:85], off nt
	v_pk_add_f32 v[76:77], v[36:37], v[70:71]
	s_nop 0
	v_mul_f32_e32 v64, 0xbfb8aa3b, v76
	v_mul_f32_e32 v75, 0xbfb8aa3b, v77
	v_exp_f32_e32 v64, v64
	v_exp_f32_e32 v75, v75
	v_pk_add_f32 v[82:83], v[32:33], v[66:67]
	v_add_f32_e32 v64, 1.0, v64
	v_add_f32_e32 v75, 1.0, v75
	v_rcp_f32_e32 v64, v64
	v_rcp_f32_e32 v75, v75
	s_nop 0
	v_cvt_pk_bf16_f32 v76, v64, v75
	v_mul_f32_e32 v64, 0xbfb8aa3b, v78
	v_mul_f32_e32 v75, 0xbfb8aa3b, v79
	v_exp_f32_e32 v64, v64
	v_exp_f32_e32 v75, v75
	v_add_f32_e32 v64, 1.0, v64
	v_add_f32_e32 v75, 1.0, v75
	v_rcp_f32_e32 v64, v64
	v_rcp_f32_e32 v75, v75
	s_nop 0
	v_cvt_pk_bf16_f32 v77, v64, v75
	v_mul_f32_e32 v64, 0xbfb8aa3b, v82
	v_mul_f32_e32 v75, 0xbfb8aa3b, v83
	v_exp_f32_e32 v64, v64
	v_exp_f32_e32 v75, v75
	v_pk_add_f32 v[82:83], v[24:25], v[66:67]
	v_add_f32_e32 v64, 1.0, v64
	v_add_f32_e32 v75, 1.0, v75
	v_rcp_f32_e32 v64, v64
	v_rcp_f32_e32 v75, v75
	s_nop 0
	v_cvt_pk_bf16_f32 v78, v64, v75
	v_mul_f32_e32 v64, 0xbfb8aa3b, v80
	v_mul_f32_e32 v75, 0xbfb8aa3b, v81
; __device__ __forceinline__ unsigned pk2(float lo, float hi) { f32x2_t v = {lo, hi}; bf16x2_t b = __builtin_convertvector(v, bf16x2_t); return __builtin_bit_cast(unsigned, b); }
; __device__ __forceinline__ float sigmoidf_(float x) { return __builtin_amdgcn_rcpf(1.0f + __expf(-x)); }
;     __device__ __forceinline__ void operator()(const f32x4 (&acc)[2][2][4][2], const Unit& u, int wr, int wc, int fr, int fq) const {
;     ...
;             } else {
;                 const int gcol = col - LDQ;
;                 const f32x4 b0 = *(const f32x4*)(bgate + gcol), b1 = *(const f32x4*)(bgate + gcol + 4);
; #pragma unroll
;                 for (int ai = 0; ai < 2; ++ai)
; #pragma unroll
;                     for (int m = 0; m < 4; ++m) {
;                         const int row = row0 + ai * 128 + m * 16;
;                         const f32x4 v0 = acc[ai][bj][m][0] + b0, v1 = acc[ai][bj][m][1] + b1;
;                         u32x4 w; w.x = pk2(sigmoidf_(v0[0]), sigmoidf_(v0[1])); w.y = pk2(sigmoidf_(v0[2]), sigmoidf_(v0[3]));
;                         w.z = pk2(sigmoidf_(v1[0]), sigmoidf_(v1[1])); w.w = pk2(sigmoidf_(v1[2]), sigmoidf_(v1[3]));
;                         __builtin_nontemporal_store(w, (u32x4*)(gates + (unsigned)(row * NG + gcol)));
;                     }
	v_exp_f32_e32 v64, v64
	v_exp_f32_e32 v75, v75
	v_add_f32_e32 v64, 1.0, v64
	v_add_f32_e32 v75, 1.0, v75
	v_rcp_f32_e32 v64, v64
	v_rcp_f32_e32 v75, v75
	s_nop 0
	v_cvt_pk_bf16_f32 v79, v64, v75
	v_add_u32_e32 v64, 0x24000, v74
	v_lshl_add_u64 v[80:81], v[64:65], 1, s[36:37]
	global_store_dwordx4 v[80:81], v[76:79], off nt
	v_pk_add_f32 v[80:81], v[26:27], v[68:69]
	s_nop 0
	v_pk_add_f32 v[76:77], v[28:29], v[70:71]
	v_pk_add_f32 v[78:79], v[30:31], v[72:73]
	v_mul_f32_e32 v64, 0xbfb8aa3b, v76
	v_mul_f32_e32 v75, 0xbfb8aa3b, v77
	v_exp_f32_e32 v64, v64
	v_exp_f32_e32 v75, v75
	v_add_f32_e32 v64, 1.0, v64
	v_add_f32_e32 v75, 1.0, v75
	v_rcp_f32_e32 v64, v64
	v_rcp_f32_e32 v75, v75
	s_nop 0
	v_cvt_pk_bf16_f32 v76, v64, v75
	v_mul_f32_e32 v64, 0xbfb8aa3b, v78
	v_mul_f32_e32 v75, 0xbfb8aa3b, v79
	v_exp_f32_e32 v64, v64
	v_exp_f32_e32 v75, v75
	v_add_f32_e32 v64, 1.0, v64
	v_add_f32_e32 v75, 1.0, v75
	v_rcp_f32_e32 v64, v64
	v_rcp_f32_e32 v75, v75
	s_nop 0
	v_cvt_pk_bf16_f32 v77, v64, v75
	v_mul_f32_e32 v64, 0xbfb8aa3b, v82
	v_mul_f32_e32 v75, 0xbfb8aa3b, v83
	v_exp_f32_e32 v64, v64
	v_exp_f32_e32 v75, v75
	v_pk_add_f32 v[82:83], v[16:17], v[66:67]
	v_add_f32_e32 v64, 1.0, v64
	v_add_f32_e32 v75, 1.0, v75
	v_rcp_f32_e32 v64, v64
	v_rcp_f32_e32 v75, v75
	s_nop 0
	v_cvt_pk_bf16_f32 v78, v64, v75
	v_mul_f32_e32 v64, 0xbfb8aa3b, v80
	v_mul_f32_e32 v75, 0xbfb8aa3b, v81
	v_exp_f32_e32 v64, v64
	v_exp_f32_e32 v75, v75
	v_add_f32_e32 v64, 1.0, v64
	v_add_f32_e32 v75, 1.0, v75
	v_rcp_f32_e32 v64, v64
	v_rcp_f32_e32 v75, v75
	s_nop 0
	v_cvt_pk_bf16_f32 v79, v64, v75
	v_add_u32_e32 v64, 0x60000, v74
	v_lshl_add_u64 v[80:81], v[64:65], 1, s[36:37]
	global_store_dwordx4 v[80:81], v[76:79], off nt
	v_pk_add_f32 v[80:81], v[18:19], v[68:69]
	s_nop 0
	v_pk_add_f32 v[76:77], v[20:21], v[70:71]
	v_pk_add_f32 v[78:79], v[22:23], v[72:73]
	v_mul_f32_e32 v64, 0xbfb8aa3b, v76
	v_mul_f32_e32 v75, 0xbfb8aa3b, v77
	v_exp_f32_e32 v64, v64
	v_exp_f32_e32 v75, v75
	v_add_f32_e32 v64, 1.0, v64
	v_add_f32_e32 v75, 1.0, v75
	v_rcp_f32_e32 v64, v64
	v_rcp_f32_e32 v75, v75
	s_nop 0
	v_cvt_pk_bf16_f32 v76, v64, v75
	v_mul_f32_e32 v64, 0xbfb8aa3b, v78
	v_mul_f32_e32 v75, 0xbfb8aa3b, v79
	v_exp_f32_e32 v64, v64
	v_exp_f32_e32 v75, v75
	v_add_f32_e32 v64, 1.0, v64
	v_add_f32_e32 v75, 1.0, v75
	v_rcp_f32_e32 v64, v64
	v_rcp_f32_e32 v75, v75
	s_nop 0
	v_cvt_pk_bf16_f32 v77, v64, v75
	v_mul_f32_e32 v64, 0xbfb8aa3b, v82
	v_mul_f32_e32 v75, 0xbfb8aa3b, v83
	v_exp_f32_e32 v64, v64
	v_exp_f32_e32 v75, v75
	v_pk_add_f32 v[82:83], v[8:9], v[66:67]
	v_add_f32_e32 v64, 1.0, v64
	v_add_f32_e32 v75, 1.0, v75
	v_rcp_f32_e32 v64, v64
	v_rcp_f32_e32 v75, v75
	s_nop 0
	v_cvt_pk_bf16_f32 v78, v64, v75
	v_mul_f32_e32 v64, 0xbfb8aa3b, v80
	v_mul_f32_e32 v75, 0xbfb8aa3b, v81
	v_exp_f32_e32 v64, v64
	v_exp_f32_e32 v75, v75
	v_add_f32_e32 v64, 1.0, v64
	v_add_f32_e32 v75, 1.0, v75
	v_rcp_f32_e32 v64, v64
	v_rcp_f32_e32 v75, v75
	s_nop 0
	v_cvt_pk_bf16_f32 v79, v64, v75
	v_add_u32_e32 v64, 0x6c000, v74
	v_lshl_add_u64 v[80:81], v[64:65], 1, s[36:37]
	global_store_dwordx4 v[80:81], v[76:79], off nt
	v_pk_add_f32 v[80:81], v[10:11], v[68:69]
	s_nop 0
	v_pk_add_f32 v[76:77], v[12:13], v[70:71]
	v_pk_add_f32 v[78:79], v[14:15], v[72:73]
	v_mul_f32_e32 v64, 0xbfb8aa3b, v76
	v_mul_f32_e32 v75, 0xbfb8aa3b, v77
	v_exp_f32_e32 v64, v64
	v_exp_f32_e32 v75, v75
	v_pk_add_f32 v[70:71], v[4:5], v[70:71]
	v_pk_add_f32 v[72:73], v[6:7], v[72:73]
	v_add_f32_e32 v64, 1.0, v64
	v_add_f32_e32 v75, 1.0, v75
	v_rcp_f32_e32 v64, v64
	v_rcp_f32_e32 v75, v75
	s_nop 0
	v_cvt_pk_bf16_f32 v76, v64, v75
	v_mul_f32_e32 v64, 0xbfb8aa3b, v78
	v_mul_f32_e32 v75, 0xbfb8aa3b, v79
	v_exp_f32_e32 v64, v64
	v_exp_f32_e32 v75, v75
	v_add_f32_e32 v64, 1.0, v64
	v_add_f32_e32 v75, 1.0, v75
	v_rcp_f32_e32 v64, v64
	v_rcp_f32_e32 v75, v75
	s_nop 0
	v_cvt_pk_bf16_f32 v77, v64, v75
	v_mul_f32_e32 v64, 0xbfb8aa3b, v82
	v_mul_f32_e32 v75, 0xbfb8aa3b, v83
	v_exp_f32_e32 v64, v64
	v_exp_f32_e32 v75, v75
	v_add_f32_e32 v64, 1.0, v64
	v_add_f32_e32 v75, 1.0, v75
	v_rcp_f32_e32 v64, v64
	v_rcp_f32_e32 v75, v75
	s_nop 0
	v_cvt_pk_bf16_f32 v78, v64, v75
	v_mul_f32_e32 v64, 0xbfb8aa3b, v80
	v_mul_f32_e32 v75, 0xbfb8aa3b, v81
	v_exp_f32_e32 v64, v64
	v_exp_f32_e32 v75, v75
	v_add_f32_e32 v64, 1.0, v64
	v_add_f32_e32 v75, 1.0, v75
	v_rcp_f32_e32 v64, v64
	v_rcp_f32_e32 v75, v75
	s_nop 0
	v_cvt_pk_bf16_f32 v79, v64, v75
	v_add_u32_e32 v64, 0x78000, v74
	v_lshl_add_u64 v[80:81], v[64:65], 1, s[36:37]
	global_store_dwordx4 v[80:81], v[76:79], off nt
	v_mul_f32_e32 v64, 0xbfb8aa3b, v70
	v_exp_f32_e32 v64, v64
	v_pk_add_f32 v[76:77], v[2:3], v[68:69]
	v_pk_add_f32 v[68:69], v[0:1], v[66:67]
	v_mul_f32_e32 v66, 0xbfb8aa3b, v71
	v_exp_f32_e32 v66, v66
	v_add_f32_e32 v64, 1.0, v64
	v_rcp_f32_e32 v64, v64
	v_mul_f32_e32 v67, 0xbfb8aa3b, v73
	v_add_f32_e32 v66, 1.0, v66
	v_rcp_f32_e32 v66, v66
	v_exp_f32_e32 v67, v67
	v_cvt_pk_bf16_f32 v66, v64, v66
	v_mul_f32_e32 v64, 0xbfb8aa3b, v72
	v_exp_f32_e32 v64, v64
	v_add_f32_e32 v67, 1.0, v67
	v_rcp_f32_e32 v67, v67
	v_add_f32_e32 v64, 1.0, v64
	v_rcp_f32_e32 v64, v64
	s_nop 0
	v_cvt_pk_bf16_f32 v67, v64, v67
	v_mul_f32_e32 v64, 0xbfb8aa3b, v68
	v_mul_f32_e32 v68, 0xbfb8aa3b, v69
	v_exp_f32_e32 v64, v64
	v_exp_f32_e32 v68, v68
	v_mul_f32_e32 v69, 0xbfb8aa3b, v77
	v_exp_f32_e32 v69, v69
	v_add_f32_e32 v64, 1.0, v64
	v_add_f32_e32 v68, 1.0, v68
	v_rcp_f32_e32 v64, v64
	v_rcp_f32_e32 v68, v68
	v_add_f32_e32 v69, 1.0, v69
	v_rcp_f32_e32 v69, v69
	v_cvt_pk_bf16_f32 v68, v64, v68
	v_mul_f32_e32 v64, 0xbfb8aa3b, v76
	v_exp_f32_e32 v64, v64
	s_nop 0
	v_add_f32_e32 v64, 1.0, v64
	v_rcp_f32_e32 v64, v64
	s_nop 0
	v_cvt_pk_bf16_f32 v69, v64, v69
	v_add_u32_e32 v64, 0x84000, v74
	v_lshl_add_u64 v[70:71], v[64:65], 1, s[36:37]
	global_store_dwordx4 v[70:71], v[66:69], off nt
; __device__ __forceinline__ unsigned pk2(float lo, float hi) { f32x2_t v = {lo, hi}; bf16x2_t b = __builtin_convertvector(v, bf16x2_t); return __builtin_bit_cast(unsigned, b); }
;     __device__ __forceinline__ void operator()(const f32x4 (&acc)[2][2][4][2], const Unit& u, int wr, int wc, int fr, int fq) const {
;     ...
;             if (u.pn < 18) {
;                 const int which = col / MIXW, rem = col - which * MIXW, head = rem >> 6, dc = rem & 63;
;                 const bool rope = (which < 2) && (head < 18);
;                 const bool ksum_on = (which == 1) && (head >= 12) && (head < 18);
;                 const float sc = (which == 0) ? 0.125f * 1.4426950408889634f : 1.0f;
;     ...
;                 } else {
; #pragma unroll
;                     for (int i = 0; i < 8; ++i) {
;                         const int ai = i >> 2, m = i & 3, row = row0 + ai * 128 + m * 16;
;                         const f32x4 v0 = acc[ai][bj][m][0] * sc, v1 = acc[ai][bj][m][1] * sc;
;                         u32x4 w; w.x = pk2(v0[0], v0[1]); w.y = pk2(v0[2], v0[3]); w.z = pk2(v1[0], v1[1]); w.w = pk2(v1[2], v1[3]);
;                         __builtin_nontemporal_store(w, (u32x4*)(qkv + (unsigned)(row * LDQ + col)));
;                     }
.LBB0_736:
	s_andn2_b64 vcc, exec, s[2:3]
	s_cbranch_vccnz .LBB0_761
	v_or_b32_e32 v125, 0x80, v200
	s_mov_b32 s2, 0x2aaaaaab
	v_mul_hi_i32 v64, v125, s2
	v_lshrrev_b32_e32 v66, 31, v64
	v_lshrrev_b32_e32 v64, 8, v64
	v_add_u32_e32 v64, v64, v66
	s_movk_i32 s2, 0x600
	v_mul_lo_u32 v64, v64, s2
	v_sub_u32_e32 v64, v125, v64
	v_ashrrev_i32_e32 v64, 6, v64
	s_movk_i32 s17, 0xbff
	v_cmp_lt_i32_e32 vcc, s17, v125
	v_cmp_lt_i32_e64 s[2:3], 17, v64
	v_add_u32_e32 v66, 0x67f, v200
	s_or_b64 s[2:3], vcc, s[2:3]
	v_cmp_gt_u32_e32 vcc, s17, v66
	v_mov_b32_e32 v66, 0x3e38aa3b
	s_nop 0
	v_cndmask_b32_e32 v122, 1.0, v66, vcc
	s_and_saveexec_b64 s[24:25], s[2:3]
	s_xor_b64 s[2:3], exec, s[24:25]
	s_cbranch_execz .LBB0_739
	s_movk_i32 s17, 0x1200
	s_waitcnt lgkmcnt(0)
	v_mul_lo_u32 v74, v228, s17
	v_pk_mul_f32 v[68:69], v[122:123], v[62:63] op_sel_hi:[0,1]
	v_pk_mul_f32 v[66:67], v[122:123], v[60:61] op_sel_hi:[0,1]
	v_pk_mul_f32 v[70:71], v[122:123], v[58:59] op_sel_hi:[0,1]
	v_pk_mul_f32 v[72:73], v[122:123], v[56:57] op_sel_hi:[0,1]
	v_add_u32_e32 v64, v74, v125
	v_cvt_pk_bf16_f32 v66, v66, v67
	v_cvt_pk_bf16_f32 v67, v68, v69
	v_cvt_pk_bf16_f32 v68, v72, v73
	v_cvt_pk_bf16_f32 v69, v70, v71
	v_lshl_add_u64 v[70:71], v[64:65], 1, s[84:85]
	v_add_u32_e32 v74, v200, v74
	global_store_dwordx4 v[70:71], v[66:69], off nt
	v_pk_mul_f32 v[70:71], v[122:123], v[50:51] op_sel_hi:[0,1]
	v_pk_mul_f32 v[72:73], v[122:123], v[48:49] op_sel_hi:[0,1]
	v_pk_mul_f32 v[68:69], v[122:123], v[54:55] op_sel_hi:[0,1]
	v_pk_mul_f32 v[66:67], v[122:123], v[52:53] op_sel_hi:[0,1]
	v_add_u32_e32 v64, 0x12080, v74
	v_cvt_pk_bf16_f32 v66, v66, v67
	v_cvt_pk_bf16_f32 v67, v68, v69
	v_cvt_pk_bf16_f32 v68, v72, v73
	v_cvt_pk_bf16_f32 v69, v70, v71
	v_lshl_add_u64 v[70:71], v[64:65], 1, s[84:85]
	global_store_dwordx4 v[70:71], v[66:69], off nt
	v_pk_mul_f32 v[70:71], v[122:123], v[42:43] op_sel_hi:[0,1]
	v_pk_mul_f32 v[72:73], v[122:123], v[40:41] op_sel_hi:[0,1]
	v_pk_mul_f32 v[68:69], v[122:123], v[46:47] op_sel_hi:[0,1]
	v_pk_mul_f32 v[66:67], v[122:123], v[44:45] op_sel_hi:[0,1]
	v_add_u32_e32 v64, 0x24080, v74
	v_cvt_pk_bf16_f32 v66, v66, v67
	v_cvt_pk_bf16_f32 v67, v68, v69
	v_cvt_pk_bf16_f32 v68, v72, v73
	v_cvt_pk_bf16_f32 v69, v70, v71
	v_lshl_add_u64 v[70:71], v[64:65], 1, s[84:85]
	global_store_dwordx4 v[70:71], v[66:69], off nt
	v_pk_mul_f32 v[70:71], v[122:123], v[34:35] op_sel_hi:[0,1]
	v_pk_mul_f32 v[72:73], v[122:123], v[32:33] op_sel_hi:[0,1]
	v_pk_mul_f32 v[68:69], v[122:123], v[38:39] op_sel_hi:[0,1]
	v_pk_mul_f32 v[66:67], v[122:123], v[36:37] op_sel_hi:[0,1]
	v_add_u32_e32 v64, 0x36080, v74
	v_cvt_pk_bf16_f32 v66, v66, v67
	v_cvt_pk_bf16_f32 v67, v68, v69
	v_cvt_pk_bf16_f32 v68, v72, v73
	v_cvt_pk_bf16_f32 v69, v70, v71
	v_lshl_add_u64 v[70:71], v[64:65], 1, s[84:85]
	global_store_dwordx4 v[70:71], v[66:69], off nt
	v_pk_mul_f32 v[70:71], v[122:123], v[26:27] op_sel_hi:[0,1]
	v_pk_mul_f32 v[72:73], v[122:123], v[24:25] op_sel_hi:[0,1]
	v_pk_mul_f32 v[68:69], v[122:123], v[30:31] op_sel_hi:[0,1]
	v_pk_mul_f32 v[66:67], v[122:123], v[28:29] op_sel_hi:[0,1]
	v_add_u32_e32 v64, 0x90080, v74
	v_cvt_pk_bf16_f32 v66, v66, v67
	v_cvt_pk_bf16_f32 v67, v68, v69
	v_cvt_pk_bf16_f32 v68, v72, v73
	v_cvt_pk_bf16_f32 v69, v70, v71
	v_lshl_add_u64 v[70:71], v[64:65], 1, s[84:85]
	global_store_dwordx4 v[70:71], v[66:69], off nt
	v_pk_mul_f32 v[70:71], v[122:123], v[18:19] op_sel_hi:[0,1]
	v_pk_mul_f32 v[72:73], v[122:123], v[16:17] op_sel_hi:[0,1]
	v_pk_mul_f32 v[68:69], v[122:123], v[22:23] op_sel_hi:[0,1]
	v_pk_mul_f32 v[66:67], v[122:123], v[20:21] op_sel_hi:[0,1]
	v_add_u32_e32 v64, 0xa2080, v74
	v_cvt_pk_bf16_f32 v66, v66, v67
	v_cvt_pk_bf16_f32 v67, v68, v69
	v_cvt_pk_bf16_f32 v68, v72, v73
	v_cvt_pk_bf16_f32 v69, v70, v71
	v_lshl_add_u64 v[70:71], v[64:65], 1, s[84:85]
	global_store_dwordx4 v[70:71], v[66:69], off nt
	v_pk_mul_f32 v[70:71], v[122:123], v[10:11] op_sel_hi:[0,1]
	v_pk_mul_f32 v[72:73], v[122:123], v[8:9] op_sel_hi:[0,1]
	v_pk_mul_f32 v[68:69], v[122:123], v[14:15] op_sel_hi:[0,1]
	v_pk_mul_f32 v[66:67], v[122:123], v[12:13] op_sel_hi:[0,1]
	v_add_u32_e32 v64, 0xb4080, v74
	v_cvt_pk_bf16_f32 v66, v66, v67
	v_cvt_pk_bf16_f32 v67, v68, v69
	v_cvt_pk_bf16_f32 v68, v72, v73
	v_cvt_pk_bf16_f32 v69, v70, v71
	v_lshl_add_u64 v[70:71], v[64:65], 1, s[84:85]
	global_store_dwordx4 v[70:71], v[66:69], off nt
	v_pk_mul_f32 v[70:71], v[122:123], v[2:3] op_sel_hi:[0,1]
	v_pk_mul_f32 v[72:73], v[122:123], v[0:1] op_sel_hi:[0,1]
	v_pk_mul_f32 v[68:69], v[122:123], v[6:7] op_sel_hi:[0,1]
	v_pk_mul_f32 v[66:67], v[122:123], v[4:5] op_sel_hi:[0,1]
	v_add_u32_e32 v64, 0xc6080, v74
	v_cvt_pk_bf16_f32 v66, v66, v67
	v_cvt_pk_bf16_f32 v67, v68, v69
	v_cvt_pk_bf16_f32 v68, v72, v73
	v_cvt_pk_bf16_f32 v69, v70, v71
	v_lshl_add_u64 v[70:71], v[64:65], 1, s[84:85]
	global_store_dwordx4 v[70:71], v[66:69], off nt
; __device__ __forceinline__ unsigned pk2(float lo, float hi) { f32x2_t v = {lo, hi}; bf16x2_t b = __builtin_convertvector(v, bf16x2_t); return __builtin_bit_cast(unsigned, b); }
;     __device__ __forceinline__ void operator()(const f32x4 (&acc)[2][2][4][2], const Unit& u, int wr, int wc, int fr, int fq) const {
;     ...
;                 if (rope) {
;                     f32x4 c4[8], s4[8];
; #pragma unroll
;                     for (int i = 0; i < 8; ++i) { const int pos = (row0 + (i >> 2) * 128 + (i & 3) * 16) & (SEQ - 1);
;                         c4[i] = *(const f32x4*)(cosT + (unsigned)(pos * 32 + (dc >> 1))); s4[i] = *(const f32x4*)(sinT + (unsigned)(pos * 32 + (dc >> 1))); }
;                     float ks[8];
; #pragma unroll
;                     for (int j = 0; j < 8; ++j) ks[j] = 0.f;
; #pragma unroll
;                     for (int i = 0; i < 8; ++i) {
;                         const int ai = i >> 2, m = i & 3, row = row0 + ai * 128 + m * 16;
;                         const f32x4 v0 = acc[ai][bj][m][0], v1 = acc[ai][bj][m][1];
;                         float r[8];
;                         r[0] = v0[0] * c4[i][0] - v0[1] * s4[i][0]; r[1] = v0[0] * s4[i][0] + v0[1] * c4[i][0];
;                         r[2] = v0[2] * c4[i][1] - v0[3] * s4[i][1]; r[3] = v0[2] * s4[i][1] + v0[3] * c4[i][1];
;                         r[4] = v1[0] * c4[i][2] - v1[1] * s4[i][2]; r[5] = v1[0] * s4[i][2] + v1[1] * c4[i][2];
;                         r[6] = v1[2] * c4[i][3] - v1[3] * s4[i][3]; r[7] = v1[2] * s4[i][3] + v1[3] * c4[i][3];
;                         if (ksum_on) {
; #pragma unroll
;                             for (int j = 0; j < 8; ++j) ks[j] += r[j];
;                         }
;                         u32x4 w; w.x = pk2(r[0] * sc, r[1] * sc); w.y = pk2(r[2] * sc, r[3] * sc); w.z = pk2(r[4] * sc, r[5] * sc); w.w = pk2(r[6] * sc, r[7] * sc);
;                         __builtin_nontemporal_store(w, (u32x4*)(qkv + (unsigned)(row * LDQ + col)));
.LBB0_739:
	s_andn2_saveexec_b64 s[2:3], s[2:3]
	s_cbranch_execz .LBB0_760
	s_addk_i32 s15, 0xfa80
	s_cmpk_lt_u32 s15, 0x600
	s_waitcnt lgkmcnt(0)
	v_lshlrev_b32_e32 v70, 5, v228
	s_mov_b32 s15, 0xf9e0
	v_add_u32_e32 v124, -12, v64
	v_and_or_b32 v64, v70, s15, v226
	v_lshlrev_b32_e32 v64, 2, v64
	v_lshl_add_u64 v[66:67], s[8:9], 0, v[64:65]
	flat_load_dwordx4 v[130:133], v[66:67]
	v_lshl_add_u64 v[66:67], s[10:11], 0, v[64:65]
	flat_load_dwordx4 v[134:137], v[66:67]
	v_or_b32_e32 v66, 0x800, v64
	v_mov_b32_e32 v67, v65
	v_lshl_add_u64 v[68:69], s[8:9], 0, v[66:67]
	v_lshl_add_u64 v[66:67], s[10:11], 0, v[66:67]
	flat_load_dwordx4 v[114:117], v[68:69]
	flat_load_dwordx4 v[118:121], v[66:67]
	v_or_b32_e32 v66, 0x1000, v64
	v_mov_b32_e32 v67, v65
	v_lshl_add_u64 v[68:69], s[8:9], 0, v[66:67]
	v_lshl_add_u64 v[66:67], s[10:11], 0, v[66:67]
	v_or_b32_e32 v64, 0x1800, v64
	flat_load_dwordx4 v[106:109], v[68:69]
	flat_load_dwordx4 v[110:113], v[66:67]
	v_lshl_add_u64 v[66:67], s[8:9], 0, v[64:65]
	flat_load_dwordx4 v[98:101], v[66:67]
	v_lshl_add_u64 v[66:67], s[10:11], 0, v[64:65]
	v_add_u32_e32 v64, 0x1000, v70
	v_and_or_b32 v64, v64, s15, v226
	v_lshlrev_b32_e32 v64, 2, v64
	flat_load_dwordx4 v[102:105], v[66:67]
	v_lshl_add_u64 v[66:67], s[8:9], 0, v[64:65]
	flat_load_dwordx4 v[90:93], v[66:67]
	v_lshl_add_u64 v[66:67], s[10:11], 0, v[64:65]
	flat_load_dwordx4 v[94:97], v[66:67]
	v_or_b32_e32 v66, 0x800, v64
	v_mov_b32_e32 v67, v65
	v_lshl_add_u64 v[68:69], s[8:9], 0, v[66:67]
	v_lshl_add_u64 v[66:67], s[10:11], 0, v[66:67]
	flat_load_dwordx4 v[82:85], v[68:69]
	flat_load_dwordx4 v[86:89], v[66:67]
	v_or_b32_e32 v66, 0x1000, v64
	v_mov_b32_e32 v67, v65
	v_lshl_add_u64 v[68:69], s[8:9], 0, v[66:67]
	v_lshl_add_u64 v[66:67], s[10:11], 0, v[66:67]
	v_or_b32_e32 v64, 0x1800, v64
	flat_load_dwordx4 v[74:77], v[68:69]
	flat_load_dwordx4 v[78:81], v[66:67]
	v_lshl_add_u64 v[66:67], s[8:9], 0, v[64:65]
	v_lshl_add_u64 v[70:71], s[10:11], 0, v[64:65]
	flat_load_dwordx4 v[66:69], v[66:67]
	s_cselect_b64 s[24:25], -1, 0
	flat_load_dwordx4 v[70:73], v[70:71]
	v_cmp_gt_u32_e32 vcc, 6, v124
	v_mov_b32_e32 v64, v65
	s_and_b64 s[24:25], s[24:25], vcc
	s_waitcnt vmcnt(0) lgkmcnt(0)
	v_pk_mul_f32 v[128:129], v[60:61], v[134:135] op_sel_hi:[1,0]
	s_nop 0
	v_pk_fma_f32 v[126:127], v[60:61], v[130:131], v[128:129] op_sel:[1,0,0] op_sel_hi:[0,1,1]
	v_pk_fma_f32 v[60:61], v[60:61], v[130:131], v[128:129] op_sel:[1,0,0] op_sel_hi:[0,0,1] neg_lo:[0,0,1] neg_hi:[0,0,1]
	v_mov_b32_e32 v127, v61
	v_pk_mul_f32 v[60:61], v[62:63], v[134:135] op_sel:[0,1]
	s_nop 0
	v_pk_fma_f32 v[128:129], v[62:63], v[130:131], v[60:61] op_sel:[1,1,0] op_sel_hi:[0,1,1]
	v_pk_fma_f32 v[60:61], v[62:63], v[130:131], v[60:61] op_sel:[1,1,0] op_sel_hi:[0,1,1] neg_lo:[0,0,1] neg_hi:[0,0,1]
	v_mov_b32_e32 v129, v61
	v_pk_mul_f32 v[60:61], v[56:57], v[136:137] op_sel_hi:[1,0]
	v_mov_b64_e32 v[62:63], v[64:65]
	v_pk_fma_f32 v[130:131], v[56:57], v[132:133], v[60:61] op_sel:[1,0,0] op_sel_hi:[0,1,1]
	v_pk_fma_f32 v[56:57], v[56:57], v[132:133], v[60:61] op_sel:[1,0,0] op_sel_hi:[0,0,1] neg_lo:[0,0,1] neg_hi:[0,0,1]
	v_mov_b32_e32 v56, v137
	v_mov_b32_e32 v131, v57
	v_pk_mul_f32 v[56:57], v[58:59], v[56:57] op_sel_hi:[1,0]
	v_mov_b32_e32 v60, v133
	v_pk_fma_f32 v[132:133], v[58:59], v[60:61], v[56:57] op_sel:[1,0,0] op_sel_hi:[0,0,1]
	v_pk_fma_f32 v[56:57], v[58:59], v[60:61], v[56:57] op_sel:[1,0,0] op_sel_hi:[0,0,1] neg_lo:[0,0,1] neg_hi:[0,0,1]
	v_mov_b32_e32 v133, v57
	v_mov_b64_e32 v[60:61], v[64:65]
	v_mov_b64_e32 v[58:59], v[64:65]
	v_mov_b64_e32 v[56:57], v[64:65]
	s_and_saveexec_b64 s[26:27], s[24:25]
	v_pk_add_f32 v[60:61], v[126:127], 0 op_sel_hi:[1,0]
	v_pk_add_f32 v[58:59], v[128:129], 0 op_sel_hi:[1,0]
	v_pk_add_f32 v[56:57], v[130:131], 0 op_sel_hi:[1,0]
	v_pk_add_f32 v[62:63], v[132:133], 0 op_sel_hi:[1,0]
	s_or_b64 exec, exec, s[26:27]
	v_pk_mul_f32 v[126:127], v[122:123], v[126:127] op_sel_hi:[0,1]
	v_pk_mul_f32 v[128:129], v[122:123], v[128:129] op_sel_hi:[0,1]
	v_pk_mov_b32 v[126:127], v[126:127], v[126:127] op_sel:[1,0]
	v_pk_mov_b32 v[128:129], v[128:129], v[128:129] op_sel:[1,0]
	v_cvt_pk_bf16_f32 v126, v126, v127
	v_cvt_pk_bf16_f32 v127, v128, v129
	v_pk_mul_f32 v[128:129], v[122:123], v[130:131] op_sel_hi:[0,1]
	v_pk_mul_f32 v[130:131], v[122:123], v[132:133] op_sel_hi:[0,1]
	v_pk_mov_b32 v[128:129], v[128:129], v[128:129] op_sel:[1,0]
	v_pk_mov_b32 v[130:131], v[130:131], v[130:131] op_sel:[1,0]
	s_movk_i32 s15, 0x1200
	v_cvt_pk_bf16_f32 v128, v128, v129
	v_cvt_pk_bf16_f32 v129, v130, v131
	v_mul_lo_u32 v130, v228, s15
	v_add_u32_e32 v64, v130, v125
	v_lshl_add_u64 v[132:133], v[64:65], 1, s[84:85]
	global_store_dwordx4 v[132:133], v[126:129], off nt
	v_mov_b32_e32 v64, v117
	s_nop 0
	v_pk_mul_f32 v[128:129], v[52:53], v[118:119] op_sel:[1,0] op_sel_hi:[0,0]
	v_pk_mul_f32 v[118:119], v[54:55], v[118:119] op_sel:[1,1] op_sel_hi:[0,1]
	v_pk_fma_f32 v[126:127], v[52:53], v[114:115], v[128:129] op_sel_hi:[1,0,1] neg_lo:[0,0,1] neg_hi:[0,0,1]
	v_pk_fma_f32 v[128:129], v[52:53], v[114:115], v[128:129] op_sel_hi:[1,0,1]
	v_pk_fma_f32 v[52:53], v[54:55], v[114:115], v[118:119] op_sel:[0,1,0] neg_lo:[0,0,1] neg_hi:[0,0,1]
	v_pk_fma_f32 v[114:115], v[54:55], v[114:115], v[118:119] op_sel:[0,1,0]
	v_pk_mul_f32 v[118:119], v[48:49], v[120:121] op_sel:[1,0] op_sel_hi:[0,0]
	v_pk_fma_f32 v[54:55], v[48:49], v[116:117], v[118:119] op_sel_hi:[1,0,1] neg_lo:[0,0,1] neg_hi:[0,0,1]
	v_pk_fma_f32 v[118:119], v[48:49], v[116:117], v[118:119] op_sel_hi:[1,0,1]
	v_mov_b32_e32 v48, v121
	v_pk_mul_f32 v[120:121], v[50:51], v[48:49] op_sel:[1,0] op_sel_hi:[0,0]
; __device__ __forceinline__ unsigned pk2(float lo, float hi) { f32x2_t v = {lo, hi}; bf16x2_t b = __builtin_convertvector(v, bf16x2_t); return __builtin_bit_cast(unsigned, b); }
;     __device__ __forceinline__ void operator()(const f32x4 (&acc)[2][2][4][2], const Unit& u, int wr, int wc, int fr, int fq) const {
;     ...
;                     for (int i = 0; i < 8; ++i) {
;                         const int ai = i >> 2, m = i & 3, row = row0 + ai * 128 + m * 16;
;                         const f32x4 v0 = acc[ai][bj][m][0], v1 = acc[ai][bj][m][1];
;                         float r[8];
;                         r[0] = v0[0] * c4[i][0] - v0[1] * s4[i][0]; r[1] = v0[0] * s4[i][0] + v0[1] * c4[i][0];
;                         r[2] = v0[2] * c4[i][1] - v0[3] * s4[i][1]; r[3] = v0[2] * s4[i][1] + v0[3] * c4[i][1];
;                         r[4] = v1[0] * c4[i][2] - v1[1] * s4[i][2]; r[5] = v1[0] * s4[i][2] + v1[1] * c4[i][2];
;                         r[6] = v1[2] * c4[i][3] - v1[3] * s4[i][3]; r[7] = v1[2] * s4[i][3] + v1[3] * c4[i][3];
;                         if (ksum_on) {
; #pragma unroll
;                             for (int j = 0; j < 8; ++j) ks[j] += r[j];
;                         }
;                         u32x4 w; w.x = pk2(r[0] * sc, r[1] * sc); w.y = pk2(r[2] * sc, r[3] * sc); w.z = pk2(r[4] * sc, r[5] * sc); w.w = pk2(r[6] * sc, r[7] * sc);
;                         __builtin_nontemporal_store(w, (u32x4*)(qkv + (unsigned)(row * LDQ + col)));
	v_pk_fma_f32 v[48:49], v[50:51], v[64:65], v[120:121] op_sel_hi:[1,0,1] neg_lo:[0,0,1] neg_hi:[0,0,1]
	v_pk_fma_f32 v[50:51], v[50:51], v[64:65], v[120:121] op_sel_hi:[1,0,1]
	s_and_saveexec_b64 s[26:27], s[24:25]
	v_pk_mov_b32 v[116:117], v[128:129], v[126:127] op_sel:[1,0]
	s_nop 0
	v_pk_add_f32 v[60:61], v[116:117], v[60:61]
	v_pk_mov_b32 v[116:117], v[114:115], v[52:53] op_sel:[1,0]
	s_nop 0
	v_pk_add_f32 v[58:59], v[116:117], v[58:59]
	v_pk_mov_b32 v[116:117], v[118:119], v[54:55] op_sel:[1,0]
	s_nop 0
	v_pk_add_f32 v[56:57], v[116:117], v[56:57]
	v_pk_mov_b32 v[116:117], v[50:51], v[48:49] op_sel:[1,0]
	s_nop 0
	v_pk_add_f32 v[62:63], v[116:117], v[62:63]
	s_or_b64 exec, exec, s[26:27]
	v_mov_b32_e32 v123, v122
	v_mov_b32_e32 v127, v129
	v_mov_b32_e32 v53, v115
	v_mov_b32_e32 v55, v119
	v_mov_b32_e32 v49, v51
	v_pk_mul_f32 v[50:51], v[122:123], v[126:127]
	v_pk_mul_f32 v[52:53], v[122:123], v[52:53]
	v_add_u32_e32 v114, 0x12080, v200
	v_cvt_pk_bf16_f32 v50, v50, v51
	v_cvt_pk_bf16_f32 v51, v52, v53
	v_pk_mul_f32 v[52:53], v[122:123], v[54:55]
	v_pk_mul_f32 v[48:49], v[122:123], v[48:49]
	v_add_u32_e32 v64, v114, v130
	v_cvt_pk_bf16_f32 v52, v52, v53
	v_cvt_pk_bf16_f32 v53, v48, v49
	v_lshl_add_u64 v[48:49], v[64:65], 1, s[84:85]
	global_store_dwordx4 v[48:49], v[50:53], off nt
	v_pk_mul_f32 v[54:55], v[40:41], v[112:113] op_sel:[1,0] op_sel_hi:[0,0]
	v_mov_b32_e32 v64, v109
	v_pk_mul_f32 v[50:51], v[44:45], v[110:111] op_sel:[1,0] op_sel_hi:[0,0]
	v_pk_mul_f32 v[52:53], v[46:47], v[110:111] op_sel:[1,1] op_sel_hi:[0,1]
	v_pk_fma_f32 v[48:49], v[44:45], v[106:107], v[50:51] op_sel_hi:[1,0,1] neg_lo:[0,0,1] neg_hi:[0,0,1]
	v_pk_fma_f32 v[50:51], v[44:45], v[106:107], v[50:51] op_sel_hi:[1,0,1]
	v_pk_fma_f32 v[44:45], v[46:47], v[106:107], v[52:53] op_sel:[0,1,0] neg_lo:[0,0,1] neg_hi:[0,0,1]
	v_pk_fma_f32 v[52:53], v[46:47], v[106:107], v[52:53] op_sel:[0,1,0]
	v_pk_fma_f32 v[46:47], v[40:41], v[108:109], v[54:55] op_sel_hi:[1,0,1] neg_lo:[0,0,1] neg_hi:[0,0,1]
	v_pk_fma_f32 v[54:55], v[40:41], v[108:109], v[54:55] op_sel_hi:[1,0,1]
	v_mov_b32_e32 v40, v113
	v_pk_mul_f32 v[106:107], v[42:43], v[40:41] op_sel:[1,0] op_sel_hi:[0,0]
	v_pk_fma_f32 v[40:41], v[42:43], v[64:65], v[106:107] op_sel_hi:[1,0,1] neg_lo:[0,0,1] neg_hi:[0,0,1]
	v_pk_fma_f32 v[42:43], v[42:43], v[64:65], v[106:107] op_sel_hi:[1,0,1]
	s_and_saveexec_b64 s[26:27], s[24:25]
	v_pk_mov_b32 v[106:107], v[50:51], v[48:49] op_sel:[1,0]
	s_nop 0
	v_pk_add_f32 v[60:61], v[106:107], v[60:61]
	v_pk_mov_b32 v[106:107], v[52:53], v[44:45] op_sel:[1,0]
	s_nop 0
	v_pk_add_f32 v[58:59], v[106:107], v[58:59]
	v_pk_mov_b32 v[106:107], v[54:55], v[46:47] op_sel:[1,0]
	s_nop 0
	v_pk_add_f32 v[56:57], v[106:107], v[56:57]
	v_pk_mov_b32 v[106:107], v[42:43], v[40:41] op_sel:[1,0]
	s_nop 0
	v_pk_add_f32 v[62:63], v[106:107], v[62:63]
	s_or_b64 exec, exec, s[26:27]
	v_mov_b32_e32 v49, v51
	v_mov_b32_e32 v45, v53
	v_mov_b32_e32 v41, v43
	v_pk_mul_f32 v[42:43], v[122:123], v[48:49]
	v_mov_b32_e32 v47, v55
	v_cvt_pk_bf16_f32 v48, v42, v43
	v_pk_mul_f32 v[42:43], v[122:123], v[44:45]
	v_pk_mul_f32 v[40:41], v[122:123], v[40:41]
	v_cvt_pk_bf16_f32 v49, v42, v43
	v_pk_mul_f32 v[42:43], v[122:123], v[46:47]
	v_cvt_pk_bf16_f32 v51, v40, v41
	v_cvt_pk_bf16_f32 v50, v42, v43
	v_add_u32_e32 v42, 0x24080, v200
	v_add_u32_e32 v64, v42, v130
	v_lshl_add_u64 v[40:41], v[64:65], 1, s[84:85]
	v_pk_mul_f32 v[44:45], v[36:37], v[102:103] op_sel_hi:[1,0]
	global_store_dwordx4 v[40:41], v[48:51], off nt
	v_pk_fma_f32 v[40:41], v[36:37], v[98:99], v[44:45] op_sel:[1,0,0] op_sel_hi:[0,1,1]
	v_pk_fma_f32 v[36:37], v[36:37], v[98:99], v[44:45] op_sel:[1,0,0] op_sel_hi:[0,0,1] neg_lo:[0,0,1] neg_hi:[0,0,1]
	v_pk_mul_f32 v[44:45], v[38:39], v[102:103] op_sel:[0,1]
	v_mov_b32_e32 v41, v37
	v_pk_fma_f32 v[36:37], v[38:39], v[98:99], v[44:45] op_sel:[1,1,0] op_sel_hi:[0,1,1]
	v_pk_fma_f32 v[38:39], v[38:39], v[98:99], v[44:45] op_sel:[1,1,0] op_sel_hi:[0,1,1] neg_lo:[0,0,1] neg_hi:[0,0,1]
	v_pk_mul_f32 v[44:45], v[32:33], v[104:105] op_sel_hi:[1,0]
	v_mov_b32_e32 v37, v39
	v_pk_fma_f32 v[38:39], v[32:33], v[100:101], v[44:45] op_sel:[1,0,0] op_sel_hi:[0,1,1]
	v_pk_fma_f32 v[32:33], v[32:33], v[100:101], v[44:45] op_sel:[1,0,0] op_sel_hi:[0,0,1] neg_lo:[0,0,1] neg_hi:[0,0,1]
	v_mov_b32_e32 v32, v105
	v_pk_mul_f32 v[44:45], v[34:35], v[32:33] op_sel_hi:[1,0]
	v_mov_b32_e32 v46, v101
	v_mov_b32_e32 v39, v33
	v_pk_fma_f32 v[32:33], v[34:35], v[46:47], v[44:45] op_sel:[1,0,0] op_sel_hi:[0,0,1]
	v_pk_fma_f32 v[34:35], v[34:35], v[46:47], v[44:45] op_sel:[1,0,0] op_sel_hi:[0,0,1] neg_lo:[0,0,1] neg_hi:[0,0,1]
	v_mov_b32_e32 v33, v35
	s_and_saveexec_b64 s[26:27], s[24:25]
	v_pk_add_f32 v[60:61], v[40:41], v[60:61]
	v_pk_add_f32 v[58:59], v[36:37], v[58:59]
	v_pk_add_f32 v[56:57], v[38:39], v[56:57]
	v_pk_add_f32 v[62:63], v[32:33], v[62:63]
	s_or_b64 exec, exec, s[26:27]
	v_pk_mul_f32 v[34:35], v[122:123], v[40:41]
	v_pk_mul_f32 v[32:33], v[122:123], v[32:33]
	v_pk_mov_b32 v[34:35], v[34:35], v[34:35] op_sel:[1,0]
	v_pk_mov_b32 v[32:33], v[32:33], v[32:33] op_sel:[1,0]
	v_cvt_pk_bf16_f32 v44, v34, v35
	v_pk_mul_f32 v[34:35], v[122:123], v[36:37]
	v_cvt_pk_bf16_f32 v47, v32, v33
	v_pk_mov_b32 v[34:35], v[34:35], v[34:35] op_sel:[1,0]
	v_pk_mul_f32 v[36:37], v[28:29], v[94:95] op_sel_hi:[1,0]
	v_cvt_pk_bf16_f32 v45, v34, v35
	v_pk_mul_f32 v[34:35], v[122:123], v[38:39]
	v_mov_b32_e32 v38, v93
	v_pk_mov_b32 v[34:35], v[34:35], v[34:35] op_sel:[1,0]
	s_nop 0
	v_cvt_pk_bf16_f32 v46, v34, v35
	v_add_u32_e32 v34, 0x36080, v200
	v_add_u32_e32 v64, v34, v130
	v_lshl_add_u64 v[32:33], v[64:65], 1, s[84:85]
	global_store_dwordx4 v[32:33], v[44:47], off nt
; __device__ __forceinline__ unsigned pk2(float lo, float hi) { f32x2_t v = {lo, hi}; bf16x2_t b = __builtin_convertvector(v, bf16x2_t); return __builtin_bit_cast(unsigned, b); }
;     __device__ __forceinline__ void operator()(const f32x4 (&acc)[2][2][4][2], const Unit& u, int wr, int wc, int fr, int fq) const {
;     ...
;                     for (int i = 0; i < 8; ++i) {
;                         const int ai = i >> 2, m = i & 3, row = row0 + ai * 128 + m * 16;
;                         const f32x4 v0 = acc[ai][bj][m][0], v1 = acc[ai][bj][m][1];
;                         float r[8];
;                         r[0] = v0[0] * c4[i][0] - v0[1] * s4[i][0]; r[1] = v0[0] * s4[i][0] + v0[1] * c4[i][0];
;                         r[2] = v0[2] * c4[i][1] - v0[3] * s4[i][1]; r[3] = v0[2] * s4[i][1] + v0[3] * c4[i][1];
;                         r[4] = v1[0] * c4[i][2] - v1[1] * s4[i][2]; r[5] = v1[0] * s4[i][2] + v1[1] * c4[i][2];
;                         r[6] = v1[2] * c4[i][3] - v1[3] * s4[i][3]; r[7] = v1[2] * s4[i][3] + v1[3] * c4[i][3];
;                         if (ksum_on) {
; #pragma unroll
;                             for (int j = 0; j < 8; ++j) ks[j] += r[j];
;                         }
;                         u32x4 w; w.x = pk2(r[0] * sc, r[1] * sc); w.y = pk2(r[2] * sc, r[3] * sc); w.z = pk2(r[4] * sc, r[5] * sc); w.w = pk2(r[6] * sc, r[7] * sc);
;                         __builtin_nontemporal_store(w, (u32x4*)(qkv + (unsigned)(row * LDQ + col)));
	v_pk_fma_f32 v[32:33], v[28:29], v[90:91], v[36:37] op_sel:[1,0,0] op_sel_hi:[0,1,1]
	v_pk_fma_f32 v[28:29], v[28:29], v[90:91], v[36:37] op_sel:[1,0,0] op_sel_hi:[0,0,1] neg_lo:[0,0,1] neg_hi:[0,0,1]
	v_pk_mul_f32 v[36:37], v[30:31], v[94:95] op_sel:[0,1]
	v_mov_b32_e32 v33, v29
	v_pk_fma_f32 v[28:29], v[30:31], v[90:91], v[36:37] op_sel:[1,1,0] op_sel_hi:[0,1,1]
	v_pk_fma_f32 v[30:31], v[30:31], v[90:91], v[36:37] op_sel:[1,1,0] op_sel_hi:[0,1,1] neg_lo:[0,0,1] neg_hi:[0,0,1]
	v_pk_mul_f32 v[36:37], v[24:25], v[96:97] op_sel_hi:[1,0]
	v_mov_b32_e32 v29, v31
	v_pk_fma_f32 v[30:31], v[24:25], v[92:93], v[36:37] op_sel:[1,0,0] op_sel_hi:[0,1,1]
	v_pk_fma_f32 v[24:25], v[24:25], v[92:93], v[36:37] op_sel:[1,0,0] op_sel_hi:[0,0,1] neg_lo:[0,0,1] neg_hi:[0,0,1]
	v_mov_b32_e32 v24, v97
	v_pk_mul_f32 v[36:37], v[26:27], v[24:25] op_sel_hi:[1,0]
	v_mov_b32_e32 v31, v25
	v_pk_fma_f32 v[24:25], v[26:27], v[38:39], v[36:37] op_sel:[1,0,0] op_sel_hi:[0,0,1]
	v_pk_fma_f32 v[26:27], v[26:27], v[38:39], v[36:37] op_sel:[1,0,0] op_sel_hi:[0,0,1] neg_lo:[0,0,1] neg_hi:[0,0,1]
	v_mov_b32_e32 v25, v27
	s_and_saveexec_b64 s[26:27], s[24:25]
	v_pk_add_f32 v[60:61], v[32:33], v[60:61]
	v_pk_add_f32 v[58:59], v[28:29], v[58:59]
	v_pk_add_f32 v[56:57], v[30:31], v[56:57]
	v_pk_add_f32 v[62:63], v[24:25], v[62:63]
	s_or_b64 exec, exec, s[26:27]
	v_pk_mul_f32 v[26:27], v[122:123], v[32:33]
	v_pk_mul_f32 v[24:25], v[122:123], v[24:25]
	v_pk_mov_b32 v[26:27], v[26:27], v[26:27] op_sel:[1,0]
	v_pk_mov_b32 v[24:25], v[24:25], v[24:25] op_sel:[1,0]
	v_cvt_pk_bf16_f32 v36, v26, v27
	v_pk_mul_f32 v[26:27], v[122:123], v[28:29]
	v_cvt_pk_bf16_f32 v39, v24, v25
	v_pk_mov_b32 v[26:27], v[26:27], v[26:27] op_sel:[1,0]
	v_pk_mul_f32 v[28:29], v[20:21], v[86:87] op_sel_hi:[1,0]
	v_cvt_pk_bf16_f32 v37, v26, v27
	v_pk_mul_f32 v[26:27], v[122:123], v[30:31]
	v_mov_b32_e32 v30, v85
	v_pk_mov_b32 v[26:27], v[26:27], v[26:27] op_sel:[1,0]
	s_nop 0
	v_cvt_pk_bf16_f32 v38, v26, v27
	v_add_u32_e32 v26, 0x90000, v130
	v_add_u32_e32 v64, v26, v125
	v_lshl_add_u64 v[24:25], v[64:65], 1, s[84:85]
	global_store_dwordx4 v[24:25], v[36:39], off nt
	v_pk_fma_f32 v[24:25], v[20:21], v[82:83], v[28:29] op_sel:[1,0,0] op_sel_hi:[0,1,1]
	v_pk_fma_f32 v[20:21], v[20:21], v[82:83], v[28:29] op_sel:[1,0,0] op_sel_hi:[0,0,1] neg_lo:[0,0,1] neg_hi:[0,0,1]
	v_pk_mul_f32 v[28:29], v[22:23], v[86:87] op_sel:[0,1]
	v_mov_b32_e32 v25, v21
	v_pk_fma_f32 v[20:21], v[22:23], v[82:83], v[28:29] op_sel:[1,1,0] op_sel_hi:[0,1,1]
	v_pk_fma_f32 v[22:23], v[22:23], v[82:83], v[28:29] op_sel:[1,1,0] op_sel_hi:[0,1,1] neg_lo:[0,0,1] neg_hi:[0,0,1]
	v_pk_mul_f32 v[28:29], v[16:17], v[88:89] op_sel_hi:[1,0]
	v_mov_b32_e32 v21, v23
	v_pk_fma_f32 v[22:23], v[16:17], v[84:85], v[28:29] op_sel:[1,0,0] op_sel_hi:[0,1,1]
	v_pk_fma_f32 v[16:17], v[16:17], v[84:85], v[28:29] op_sel:[1,0,0] op_sel_hi:[0,0,1] neg_lo:[0,0,1] neg_hi:[0,0,1]
	v_mov_b32_e32 v16, v89
	v_pk_mul_f32 v[28:29], v[18:19], v[16:17] op_sel_hi:[1,0]
	v_mov_b32_e32 v23, v17
	v_pk_fma_f32 v[16:17], v[18:19], v[30:31], v[28:29] op_sel:[1,0,0] op_sel_hi:[0,0,1]
	v_pk_fma_f32 v[18:19], v[18:19], v[30:31], v[28:29] op_sel:[1,0,0] op_sel_hi:[0,0,1] neg_lo:[0,0,1] neg_hi:[0,0,1]
	v_mov_b32_e32 v17, v19
	s_and_saveexec_b64 s[26:27], s[24:25]
	v_pk_add_f32 v[60:61], v[24:25], v[60:61]
	v_pk_add_f32 v[58:59], v[20:21], v[58:59]
	v_pk_add_f32 v[56:57], v[22:23], v[56:57]
	v_pk_add_f32 v[62:63], v[16:17], v[62:63]
	s_or_b64 exec, exec, s[26:27]
	v_pk_mul_f32 v[18:19], v[122:123], v[24:25]
	v_pk_mul_f32 v[20:21], v[122:123], v[20:21]
	v_pk_mov_b32 v[18:19], v[18:19], v[18:19] op_sel:[1,0]
	v_pk_mov_b32 v[20:21], v[20:21], v[20:21] op_sel:[1,0]
	v_cvt_pk_bf16_f32 v18, v18, v19
	v_cvt_pk_bf16_f32 v19, v20, v21
	v_pk_mul_f32 v[20:21], v[122:123], v[22:23]
	v_pk_mul_f32 v[16:17], v[122:123], v[16:17]
	v_pk_mov_b32 v[20:21], v[20:21], v[20:21] op_sel:[1,0]
	v_pk_mov_b32 v[16:17], v[16:17], v[16:17] op_sel:[1,0]
	v_add_u32_e32 v64, v26, v114
	v_cvt_pk_bf16_f32 v20, v20, v21
	v_cvt_pk_bf16_f32 v21, v16, v17
	v_lshl_add_u64 v[16:17], v[64:65], 1, s[84:85]
	global_store_dwordx4 v[16:17], v[18:21], off nt
	s_nop 1
	v_pk_mul_f32 v[18:19], v[12:13], v[78:79] op_sel_hi:[1,0]
	v_mov_b32_e32 v20, v77
	v_pk_fma_f32 v[16:17], v[12:13], v[74:75], v[18:19] op_sel:[1,0,0] op_sel_hi:[0,1,1]
	v_pk_fma_f32 v[12:13], v[12:13], v[74:75], v[18:19] op_sel:[1,0,0] op_sel_hi:[0,0,1] neg_lo:[0,0,1] neg_hi:[0,0,1]
	v_pk_mul_f32 v[18:19], v[14:15], v[78:79] op_sel:[0,1]
	v_mov_b32_e32 v17, v13
	v_pk_fma_f32 v[12:13], v[14:15], v[74:75], v[18:19] op_sel:[1,1,0] op_sel_hi:[0,1,1]
	v_pk_fma_f32 v[14:15], v[14:15], v[74:75], v[18:19] op_sel:[1,1,0] op_sel_hi:[0,1,1] neg_lo:[0,0,1] neg_hi:[0,0,1]
	v_pk_mul_f32 v[18:19], v[8:9], v[80:81] op_sel_hi:[1,0]
	v_mov_b32_e32 v13, v15
	v_pk_fma_f32 v[14:15], v[8:9], v[76:77], v[18:19] op_sel:[1,0,0] op_sel_hi:[0,1,1]
	v_pk_fma_f32 v[8:9], v[8:9], v[76:77], v[18:19] op_sel:[1,0,0] op_sel_hi:[0,0,1] neg_lo:[0,0,1] neg_hi:[0,0,1]
	v_mov_b32_e32 v8, v81
	v_pk_mul_f32 v[18:19], v[10:11], v[8:9] op_sel_hi:[1,0]
	v_mov_b32_e32 v15, v9
	v_pk_fma_f32 v[8:9], v[10:11], v[20:21], v[18:19] op_sel:[1,0,0] op_sel_hi:[0,0,1]
	v_pk_fma_f32 v[10:11], v[10:11], v[20:21], v[18:19] op_sel:[1,0,0] op_sel_hi:[0,0,1] neg_lo:[0,0,1] neg_hi:[0,0,1]
	v_mov_b32_e32 v9, v11
	s_and_saveexec_b64 s[26:27], s[24:25]
	v_pk_add_f32 v[60:61], v[16:17], v[60:61]
	v_pk_add_f32 v[58:59], v[12:13], v[58:59]
	v_pk_add_f32 v[56:57], v[14:15], v[56:57]
	v_pk_add_f32 v[62:63], v[8:9], v[62:63]
	s_or_b64 exec, exec, s[26:27]
	v_pk_mul_f32 v[10:11], v[122:123], v[16:17]
	v_pk_mul_f32 v[12:13], v[122:123], v[12:13]
; __device__ __forceinline__ unsigned pk2(float lo, float hi) { f32x2_t v = {lo, hi}; bf16x2_t b = __builtin_convertvector(v, bf16x2_t); return __builtin_bit_cast(unsigned, b); }
; template <int K> __device__ __forceinline__ float swz_xor(float v) { return __int_as_float(__builtin_amdgcn_ds_swizzle(__float_as_int(v), (K << 10) | 0x1f)); }
;     __device__ __forceinline__ void operator()(const f32x4 (&acc)[2][2][4][2], const Unit& u, int wr, int wc, int fr, int fq) const {
;     ...
;                     for (int i = 0; i < 8; ++i) {
;                         const int ai = i >> 2, m = i & 3, row = row0 + ai * 128 + m * 16;
;                         const f32x4 v0 = acc[ai][bj][m][0], v1 = acc[ai][bj][m][1];
;                         float r[8];
;                         r[0] = v0[0] * c4[i][0] - v0[1] * s4[i][0]; r[1] = v0[0] * s4[i][0] + v0[1] * c4[i][0];
;                         r[2] = v0[2] * c4[i][1] - v0[3] * s4[i][1]; r[3] = v0[2] * s4[i][1] + v0[3] * c4[i][1];
;                         r[4] = v1[0] * c4[i][2] - v1[1] * s4[i][2]; r[5] = v1[0] * s4[i][2] + v1[1] * c4[i][2];
;                         r[6] = v1[2] * c4[i][3] - v1[3] * s4[i][3]; r[7] = v1[2] * s4[i][3] + v1[3] * c4[i][3];
;                         if (ksum_on) {
; #pragma unroll
;                             for (int j = 0; j < 8; ++j) ks[j] += r[j];
;                         }
;                         u32x4 w; w.x = pk2(r[0] * sc, r[1] * sc); w.y = pk2(r[2] * sc, r[3] * sc); w.z = pk2(r[4] * sc, r[5] * sc); w.w = pk2(r[6] * sc, r[7] * sc);
;                         __builtin_nontemporal_store(w, (u32x4*)(qkv + (unsigned)(row * LDQ + col)));
;                     }
;                     if (ksum_on) {
; #pragma unroll
;                         for (int j = 0; j < 8; ++j) {
;                             float v = ks[j];
;                             v += swz_xor<1>(v); v += swz_xor<2>(v); v += swz_xor<4>(v); v += swz_xor<8>(v);
;                             ks[j] = v;
;                         }
;                         if (fr == 0) {
;                             float* dst = kmean + (size_t)(((u.pm >> 3) * 6 + (head - 12)) * 8 + (u.pm & 7)) * 64 + dc;
; #pragma unroll
;                             for (int j = 0; j < 8; ++j) atomicAdd(dst + j, ks[j]);
;                         }
	v_pk_mov_b32 v[10:11], v[10:11], v[10:11] op_sel:[1,0]
	v_pk_mov_b32 v[12:13], v[12:13], v[12:13] op_sel:[1,0]
	v_cvt_pk_bf16_f32 v10, v10, v11
	v_cvt_pk_bf16_f32 v11, v12, v13
	v_pk_mul_f32 v[12:13], v[122:123], v[14:15]
	v_pk_mul_f32 v[8:9], v[122:123], v[8:9]
	v_pk_mov_b32 v[12:13], v[12:13], v[12:13] op_sel:[1,0]
	v_pk_mov_b32 v[8:9], v[8:9], v[8:9] op_sel:[1,0]
	v_add_u32_e32 v64, v26, v42
	v_cvt_pk_bf16_f32 v12, v12, v13
	v_cvt_pk_bf16_f32 v13, v8, v9
	v_lshl_add_u64 v[8:9], v[64:65], 1, s[84:85]
	global_store_dwordx4 v[8:9], v[10:13], off nt
	s_nop 1
	v_pk_mul_f32 v[10:11], v[4:5], v[70:71] op_sel_hi:[1,0]
	v_mov_b32_e32 v12, v69
	v_pk_fma_f32 v[8:9], v[4:5], v[66:67], v[10:11] op_sel:[1,0,0] op_sel_hi:[0,1,1]
	v_pk_fma_f32 v[4:5], v[4:5], v[66:67], v[10:11] op_sel:[1,0,0] op_sel_hi:[0,0,1] neg_lo:[0,0,1] neg_hi:[0,0,1]
	v_pk_mul_f32 v[10:11], v[6:7], v[70:71] op_sel:[0,1]
	v_mov_b32_e32 v9, v5
	v_pk_fma_f32 v[4:5], v[6:7], v[66:67], v[10:11] op_sel:[1,1,0] op_sel_hi:[0,1,1]
	v_pk_fma_f32 v[6:7], v[6:7], v[66:67], v[10:11] op_sel:[1,1,0] op_sel_hi:[0,1,1] neg_lo:[0,0,1] neg_hi:[0,0,1]
	v_pk_mul_f32 v[10:11], v[0:1], v[72:73] op_sel_hi:[1,0]
	v_mov_b32_e32 v5, v7
	v_pk_fma_f32 v[6:7], v[0:1], v[68:69], v[10:11] op_sel:[1,0,0] op_sel_hi:[0,1,1]
	v_pk_fma_f32 v[0:1], v[0:1], v[68:69], v[10:11] op_sel:[1,0,0] op_sel_hi:[0,0,1] neg_lo:[0,0,1] neg_hi:[0,0,1]
	v_mov_b32_e32 v0, v73
	v_pk_mul_f32 v[10:11], v[2:3], v[0:1] op_sel_hi:[1,0]
	v_mov_b32_e32 v7, v1
	v_pk_fma_f32 v[0:1], v[2:3], v[12:13], v[10:11] op_sel:[1,0,0] op_sel_hi:[0,0,1]
	v_pk_fma_f32 v[2:3], v[2:3], v[12:13], v[10:11] op_sel:[1,0,0] op_sel_hi:[0,0,1] neg_lo:[0,0,1] neg_hi:[0,0,1]
	v_mov_b32_e32 v1, v3
	s_and_saveexec_b64 s[26:27], s[24:25]
	v_pk_add_f32 v[60:61], v[8:9], v[60:61]
	v_pk_add_f32 v[58:59], v[4:5], v[58:59]
	v_pk_add_f32 v[56:57], v[6:7], v[56:57]
	v_pk_add_f32 v[62:63], v[0:1], v[62:63]
	s_or_b64 exec, exec, s[26:27]
	v_pk_mul_f32 v[2:3], v[122:123], v[8:9]
	v_pk_mul_f32 v[4:5], v[122:123], v[4:5]
	v_pk_mov_b32 v[2:3], v[2:3], v[2:3] op_sel:[1,0]
	v_pk_mov_b32 v[4:5], v[4:5], v[4:5] op_sel:[1,0]
	v_cvt_pk_bf16_f32 v2, v2, v3
	v_cvt_pk_bf16_f32 v3, v4, v5
	v_pk_mul_f32 v[4:5], v[122:123], v[6:7]
	v_pk_mul_f32 v[0:1], v[122:123], v[0:1]
	v_pk_mov_b32 v[4:5], v[4:5], v[4:5] op_sel:[1,0]
	v_pk_mov_b32 v[0:1], v[0:1], v[0:1] op_sel:[1,0]
	v_add_u32_e32 v64, v26, v34
	v_cvt_pk_bf16_f32 v4, v4, v5
	v_cvt_pk_bf16_f32 v5, v0, v1
	v_lshl_add_u64 v[0:1], v[64:65], 1, s[84:85]
	global_store_dwordx4 v[0:1], v[2:5], off nt
	s_and_saveexec_b64 s[26:27], s[24:25]
	s_cbranch_execz .LBB0_759
	ds_swizzle_b32 v1, v60 offset:swizzle(SWAP,1)
	ds_swizzle_b32 v2, v59 offset:swizzle(SWAP,1)
	ds_swizzle_b32 v6, v58 offset:swizzle(SWAP,1)
	ds_swizzle_b32 v0, v61 offset:swizzle(SWAP,1)
	ds_swizzle_b32 v7, v57 offset:swizzle(SWAP,1)
	s_waitcnt lgkmcnt(0)
	v_add_f32_e32 v1, v60, v1
	ds_swizzle_b32 v4, v1 offset:swizzle(SWAP,2)
	v_add_f32_e32 v2, v59, v2
	ds_swizzle_b32 v5, v2 offset:swizzle(SWAP,2)
	ds_swizzle_b32 v11, v63 offset:swizzle(SWAP,1)
	ds_swizzle_b32 v12, v62 offset:swizzle(SWAP,1)
	s_waitcnt lgkmcnt(0)
	v_add_f32_e32 v1, v1, v4
	ds_swizzle_b32 v4, v1 offset:swizzle(SWAP,4)
	v_add_f32_e32 v5, v2, v5
	v_add_f32_e32 v0, v61, v0
	v_add_f32_e32 v7, v57, v7
	v_add_f32_e32 v11, v63, v11
	s_waitcnt lgkmcnt(0)
	v_add_f32_e32 v2, v1, v4
	v_add_f32_e32 v4, v58, v6
	ds_swizzle_b32 v6, v4 offset:swizzle(SWAP,2)
	v_add_f32_e32 v12, v62, v12
	ds_swizzle_b32 v3, v0 offset:swizzle(SWAP,2)
	ds_swizzle_b32 v8, v5 offset:swizzle(SWAP,4)
	ds_swizzle_b32 v9, v7 offset:swizzle(SWAP,2)
	s_waitcnt lgkmcnt(0)
	v_add_f32_e32 v6, v4, v6
	ds_swizzle_b32 v10, v6 offset:swizzle(SWAP,4)
	ds_swizzle_b32 v14, v11 offset:swizzle(SWAP,2)
	ds_swizzle_b32 v15, v12 offset:swizzle(SWAP,2)
	v_add_f32_e32 v0, v0, v3
	v_add_f32_e32 v4, v5, v8
	s_waitcnt lgkmcnt(0)
	v_add_f32_e32 v6, v6, v10
	ds_swizzle_b32 v10, v56 offset:swizzle(SWAP,1)
	v_add_f32_e32 v8, v7, v9
	v_add_f32_e32 v14, v11, v14
	v_add_f32_e32 v15, v12, v15
	ds_swizzle_b32 v3, v0 offset:swizzle(SWAP,4)
	s_waitcnt lgkmcnt(0)
	v_add_f32_e32 v10, v56, v10
	ds_swizzle_b32 v13, v10 offset:swizzle(SWAP,2)
	ds_swizzle_b32 v9, v8 offset:swizzle(SWAP,4)
	ds_swizzle_b32 v16, v14 offset:swizzle(SWAP,4)
	ds_swizzle_b32 v17, v15 offset:swizzle(SWAP,4)
	v_add_f32_e32 v0, v0, v3
	s_waitcnt lgkmcnt(0)
	v_add_f32_e32 v10, v10, v13
	ds_swizzle_b32 v13, v10 offset:swizzle(SWAP,4)
	v_add_f32_e32 v8, v8, v9
	v_add_f32_e32 v12, v14, v16
	v_add_f32_e32 v14, v15, v17
	ds_swizzle_b32 v1, v0 offset:swizzle(SWAP,8)
	s_waitcnt lgkmcnt(0)
	v_add_f32_e32 v10, v10, v13
	ds_swizzle_b32 v3, v2 offset:swizzle(SWAP,8)
	ds_swizzle_b32 v5, v4 offset:swizzle(SWAP,8)
	ds_swizzle_b32 v7, v6 offset:swizzle(SWAP,8)
	ds_swizzle_b32 v9, v8 offset:swizzle(SWAP,8)
	ds_swizzle_b32 v11, v10 offset:swizzle(SWAP,8)
	ds_swizzle_b32 v13, v12 offset:swizzle(SWAP,8)
	ds_swizzle_b32 v15, v14 offset:swizzle(SWAP,8)
	s_and_b64 exec, exec, s[0:1]
	s_cbranch_execz .LBB0_759
	s_lshr_b32 s15, s46, 3
	s_waitcnt lgkmcnt(0)
	v_add_f32_e32 v2, v2, v3
	v_add_f32_e32 v3, v0, v1
	v_mad_u64_u32 v[0:1], s[24:25], s15, 6, v[124:125]
	s_and_b32 s15, s46, 7
	v_lshl_or_b32 v0, v0, 3, s15
	v_ashrrev_i32_e32 v1, 31, v0
	v_lshlrev_b64 v[0:1], 8, v[0:1]
	v_lshl_add_u64 v[0:1], v[194:195], 0, v[0:1]
	v_add_f32_e32 v14, v14, v15
	v_add_f32_e32 v12, v12, v13
	v_add_f32_e32 v10, v10, v11
	v_add_f32_e32 v8, v8, v9
	v_add_f32_e32 v6, v6, v7
	v_add_f32_e32 v4, v4, v5
	flat_atomic_add_f32 v[0:1], v3
	flat_atomic_add_f32 v[0:1], v2 offset:4
	flat_atomic_add_f32 v[0:1], v4 offset:8
	flat_atomic_add_f32 v[0:1], v6 offset:12
	flat_atomic_add_f32 v[0:1], v8 offset:16
	flat_atomic_add_f32 v[0:1], v10 offset:20
	flat_atomic_add_f32 v[0:1], v12 offset:24
	flat_atomic_add_f32 v[0:1], v14 offset:28
